# scan finish blocks re-associated by row pairs (no staging moves, interleaved reductions); GDN 5b pack via packed sign flip; fwd-subst masked update
# speedup vs baseline: 1.0134x; 1.0007x over previous
; #define LAS __attribute__((address_space(3)))
; __device__ __forceinline__ f32x4 unpack4(const v2u w) { f32x4 r; r[0] = bflo(w.x); r[1] = bfhi(w.x); r[2] = bflo(w.y); r[3] = bfhi(w.y); return r; }
; template <bool GDN, int NT> __device__ __forceinline__ void scan_load(const Frame& F, int b, int h, int dir, const ScanLane& L, int s, ScanOps<NT>& o) {
;     ...
;         const char* zq = upin((const char*)F.Z + ((size_t)chunk_row0(b, cidx) * ZW + ZC_LQ + h * 64) * 2);
; #pragma unroll
;         for (int ks = 0; ks < 2; ++ks) { o.Qf[ks] = ldu<bf16x8>(zq + ks * 64, L.zq); o.Mf[ks] = o.Qf[ks]; }
;         const char* base = (const char*)F.PM + (size_t)ud * 20480;
;         const char* bO = upin(base); const char* bB = upin(base + 10240);
; #pragma unroll
;         for (int pr = 0; pr < 2; ++pr) { const v4u qb = ldun<v4u>(bB + pr * 1024, L.o16p), qo = ldun<v4u>(bO + pr * 1024, L.o16p);
;             o.bv[2 * pr] = (v2u){qb.x, qb.y}; o.bv[2 * pr + 1] = (v2u){qb.z, qb.w}; o.ov[2 * pr] = (v2u){qo.x, qo.y}; o.ov[2 * pr + 1] = (v2u){qo.z, qo.w}; }
;         o.bv[4] = ldun<v2u>(bB + 2048, L.o8); o.ov[4] = ldun<v2u>(bO + 2048, L.o8);
;         o.wi = ldu<f32x4>(upin((const char*)F.WI + (size_t)ud * 256), L.wi);
;     ...
;     const float gl = ((const LAS float*)(St + 4 * 80 * 72))[(dir ? (s < 4 ? 3 - s : 39 - s) : s) * 2 + dir];
;     f32x4 O[NT];
; #pragma unroll
;     for (int t = 0; t < NT; ++t) {
;         const LAS bf16_t* sp2 = Sb + (16 * t + lr) * 72 + 8 * lq;
;         const bf16x8 s0 = *(const LAS bf16x8*)sp2, s1 = *(const LAS bf16x8*)(sp2 + 32);
;         const f32x4 bv = unpack4(use.bv[t]), ov = unpack4(use.ov[t]);
;         if (GDN) {
;             f32x4 o = ov, sn = S[t] * gl + bv;
;             o = __builtin_amdgcn_mfma_f32_16x16x32_bf16(use.Qf[0], s0, o, 0, 0, 0); o = __builtin_amdgcn_mfma_f32_16x16x32_bf16(use.Qf[1], s1, o, 0, 0, 0);
;             sn = __builtin_amdgcn_mfma_f32_16x16x32_bf16(use.Mf[0], s0, sn, 0, 0, 0); sn = __builtin_amdgcn_mfma_f32_16x16x32_bf16(use.Mf[1], s1, sn, 0, 0, 0);
;             S[t] = sn; O[t] = o;
;         } else {
;             f32x4 o = {0.f, 0.f, 0.f, 0.f};
;             o = __builtin_amdgcn_mfma_f32_16x16x32_bf16(use.Qf[0], s0, o, 0, 0, 0); o = __builtin_amdgcn_mfma_f32_16x16x32_bf16(use.Qf[1], s1, o, 0, 0, 0);
;             S[t] = S[t] * gl + bv; O[t] = o * use.wi + ov; }
.LBB0_346:
	s_add_i32 s0, s25, 5
	s_min_u32 s3, s0, 33
	s_add_i32 s6, s3, 2
	s_sub_i32 s3, 37, s3
	s_and_b64 s[4:5], s[90:91], exec
	s_cselect_b32 s3, s6, s3
	s_lshl_b32 s4, s3, 6
	s_add_i32 s4, s4, s33
	s_add_i32 s3, s3, s31
	s_mulk_i32 s4, 0xd00
	s_lshl_b32 s3, s3, 1
	s_or_b32 s4, s36, s4
	s_mov_b32 s5, s37
	s_add_i32 s92, s3, s68
	s_lshl_b64 s[4:5], s[4:5], 1
	s_add_u32 s4, s16, s4
	s_addc_u32 s5, s17, s5
	global_load_dwordx4 v[24:27], v28, s[4:5]
	global_load_dwordx4 v[20:23], v28, s[4:5] offset:64
	s_mul_i32 s4, s92, 0x5000
	v_readlane_b32 s5, v254, 46
	s_mul_hi_u32 s3, s92, 0x5000
	s_add_u32 s4, s5, s4
	v_readlane_b32 s5, v254, 47
	s_addc_u32 s5, s5, s3
	s_mov_b64 s[6:7], s[4:5]
	s_add_u32 s4, s4, 0x2800
	s_addc_u32 s5, s5, 0
	s_nop 0
	global_load_dwordx4 v[44:47], v32, s[4:5] nt
	global_load_dwordx4 v[28:31], v32, s[4:5] offset:1024 nt
	global_load_dwordx4 v[52:55], v32, s[6:7] nt
	s_nop 0
	global_load_dwordx4 v[32:35], v32, s[6:7] offset:1024 nt
	s_nop 0
	global_load_dwordx2 v[140:141], v100, s[4:5] offset:2048 nt
	global_load_dwordx2 v[138:139], v100, s[6:7] offset:2048 nt
	s_lshl_b64 s[4:5], s[92:93], 8
	v_readlane_b32 s6, v254, 52
	v_readlane_b32 s7, v254, 53
	s_add_u32 s4, s6, s4
	s_addc_u32 s5, s7, s5
	s_add_i32 s3, s24, 37
	v_lshl_add_u64 v[184:185], s[4:5], 0, v[0:1]
	s_and_b64 s[4:5], s[90:91], exec
	s_cselect_b32 s0, s0, s3
	s_lshl_b32 s0, s0, 3
	s_add_i32 s0, s34, s0
	v_mov_b32_e32 v0, s0
	ds_read_b32 v0, v0 offset:46080
	ds_read_b128 v[100:103], v203 offset:11520
	ds_read_b128 v[104:107], v203 offset:11584
	ds_read_b128 v[212:215], v203 offset:13824
	ds_read_b128 v[216:219], v203 offset:13888
	ds_read_b128 v[224:227], v203 offset:16128
	ds_read_b128 v[242:245], v203 offset:16192
	s_waitcnt lgkmcnt(5)
	v_mfma_f32_16x16x32_bf16 v[100:103], v[56:59], v[100:103], 0
	v_lshlrev_b32_e32 v108, 16, v84
	v_and_b32_e32 v109, 0xffff0000, v84
	v_lshlrev_b32_e32 v110, 16, v85
	s_waitcnt lgkmcnt(4)
	v_mfma_f32_16x16x32_bf16 v[100:103], v[48:51], v[104:107], v[100:103]
	v_and_b32_e32 v111, 0xffff0000, v85
	v_lshlrev_b32_e32 v112, 16, v88
	v_and_b32_e32 v113, 0xffff0000, v88
	v_lshlrev_b32_e32 v114, 16, v89
	v_and_b32_e32 v115, 0xffff0000, v89
	v_pk_fma_f32 v[150:151], v[192:193], v[0:1], v[110:111] op_sel_hi:[1,0,1]
	v_pk_fma_f32 v[148:149], v[190:191], v[0:1], v[108:109] op_sel_hi:[1,0,1]
	v_pk_fma_f32 v[108:109], v[74:75], v[102:103], v[114:115]
	v_pk_fma_f32 v[110:111], v[72:73], v[100:101], v[112:113]
	s_waitcnt lgkmcnt(3)
	v_mfma_f32_16x16x32_bf16 v[100:103], v[56:59], v[212:215], 0
	v_lshlrev_b32_e32 v112, 16, v86
	v_and_b32_e32 v113, 0xffff0000, v86
	v_lshlrev_b32_e32 v114, 16, v87
	s_waitcnt lgkmcnt(2)
	v_mfma_f32_16x16x32_bf16 v[100:103], v[48:51], v[216:219], v[100:103]
	ds_read_b128 v[212:215], v203 offset:18432
	ds_read_b128 v[216:219], v203 offset:18496
	v_and_b32_e32 v115, 0xffff0000, v87
	v_lshlrev_b32_e32 v116, 16, v90
	v_and_b32_e32 v117, 0xffff0000, v90
	v_lshlrev_b32_e32 v118, 16, v91
	v_and_b32_e32 v119, 0xffff0000, v91
	v_pk_fma_f32 v[152:153], v[188:189], v[0:1], v[114:115] op_sel_hi:[1,0,1]
	v_pk_fma_f32 v[154:155], v[154:155], v[0:1], v[112:113] op_sel_hi:[1,0,1]
	s_nop 0
	v_pk_fma_f32 v[112:113], v[74:75], v[102:103], v[118:119]
	v_pk_fma_f32 v[114:115], v[72:73], v[100:101], v[116:117]
	s_waitcnt lgkmcnt(3)
	v_mfma_f32_16x16x32_bf16 v[100:103], v[56:59], v[224:227], 0
	v_lshlrev_b32_e32 v116, 16, v76
	v_and_b32_e32 v117, 0xffff0000, v76
	v_lshlrev_b32_e32 v118, 16, v77
	s_waitcnt lgkmcnt(2)
; template <int N> __device__ __forceinline__ float row16_bcast(float v) { return dppf<0x150 + N>(v); }
; __device__ __forceinline__ float frcp(float x) { return __builtin_amdgcn_rcpf(x); }
;     ...
;         } else {
;             f32x4 o = {0.f, 0.f, 0.f, 0.f};
;             o = __builtin_amdgcn_mfma_f32_16x16x32_bf16(use.Qf[0], s0, o, 0, 0, 0); o = __builtin_amdgcn_mfma_f32_16x16x32_bf16(use.Qf[1], s1, o, 0, 0, 0);
;             S[t] = S[t] * gl + bv; O[t] = o * use.wi + ov; }
;     }
;     if (!GDN) {
; #pragma unroll
;         for (int i = 0; i < 4; ++i) { const float den = row16_bcast<0>(O[NT - 1][i]), fl = row16_bcast<1>(O[NT - 1][i]); const float dv = frcp(fmaxf(fabsf(den), fl));
; #pragma unroll
;             for (int t = 0; t < 4; ++t) O[t][i] *= dv; }
;     }
	v_mfma_f32_16x16x32_bf16 v[100:103], v[48:51], v[242:245], v[100:103]
	ds_read_b128 v[224:227], v203 offset:20736
	ds_read_b128 v[242:245], v203 offset:20800
	v_and_b32_e32 v119, 0xffff0000, v77
	v_lshlrev_b32_e32 v160, 16, v80
	v_and_b32_e32 v161, 0xffff0000, v80
	v_lshlrev_b32_e32 v166, 16, v81
	v_and_b32_e32 v167, 0xffff0000, v81
	v_pk_fma_f32 v[156:157], v[186:187], v[0:1], v[118:119] op_sel_hi:[1,0,1]
	v_pk_fma_f32 v[158:159], v[182:183], v[0:1], v[116:117] op_sel_hi:[1,0,1]
	s_nop 0
	v_pk_fma_f32 v[116:117], v[74:75], v[102:103], v[166:167]
	v_pk_fma_f32 v[118:119], v[72:73], v[100:101], v[160:161]
	s_waitcnt lgkmcnt(3)
	v_mfma_f32_16x16x32_bf16 v[100:103], v[56:59], v[212:215], 0
	v_lshlrev_b32_e32 v166, 16, v78
	v_and_b32_e32 v167, 0xffff0000, v78
	v_lshlrev_b32_e32 v160, 16, v79
	s_waitcnt lgkmcnt(2)
	v_mfma_f32_16x16x32_bf16 v[100:103], v[48:51], v[216:219], v[100:103]
	v_and_b32_e32 v161, 0xffff0000, v79
	v_lshlrev_b32_e32 v168, 16, v82
	v_and_b32_e32 v169, 0xffff0000, v82
	v_lshlrev_b32_e32 v170, 16, v83
	v_and_b32_e32 v171, 0xffff0000, v83
	v_pk_fma_f32 v[160:161], v[162:163], v[0:1], v[160:161] op_sel_hi:[1,0,1]
	v_pk_fma_f32 v[162:163], v[178:179], v[0:1], v[166:167] op_sel_hi:[1,0,1]
	s_nop 0
	v_pk_fma_f32 v[166:167], v[74:75], v[102:103], v[170:171]
	v_pk_fma_f32 v[168:169], v[72:73], v[100:101], v[168:169]
	s_waitcnt lgkmcnt(1)
	v_mfma_f32_16x16x32_bf16 v[100:103], v[56:59], v[224:227], 0
	v_lshlrev_b32_e32 v174, 16, v2
	v_and_b32_e32 v175, 0xffff0000, v2
	v_lshlrev_b32_e32 v176, 16, v3
	s_waitcnt lgkmcnt(0)
	v_mfma_f32_16x16x32_bf16 v[100:103], v[48:51], v[242:245], v[100:103]
	v_and_b32_e32 v177, 0xffff0000, v3
	v_lshlrev_b32_e32 v170, 16, v144
	v_and_b32_e32 v171, 0xffff0000, v144
	v_lshlrev_b32_e32 v172, 16, v145
	v_and_b32_e32 v173, 0xffff0000, v145
	s_nop 2
	v_pk_fma_f32 v[100:101], v[72:73], v[100:101], v[174:175]
	v_pk_fma_f32 v[102:103], v[74:75], v[102:103], v[176:177]
	v_pk_fma_f32 v[178:179], v[164:165], v[0:1], v[172:173] op_sel_hi:[1,0,1]
	v_mov_b32_dpp v104, v100 row_newbcast:0 row_mask:0xf bank_mask:0xf bound_ctrl:1
	v_mov_b32_dpp v100, v100 row_newbcast:1 row_mask:0xf bank_mask:0xf bound_ctrl:1
	v_max_f32_e32 v100, v100, v100
	v_max_f32_e64 v104, |v104|, |v104|
	v_max_f32_e32 v100, v104, v100
	v_rcp_f32_e32 v100, v100
	v_mov_b32_dpp v104, v101 row_newbcast:0 row_mask:0xf bank_mask:0xf bound_ctrl:1
	v_mov_b32_dpp v101, v101 row_newbcast:1 row_mask:0xf bank_mask:0xf bound_ctrl:1
	v_max_f32_e32 v101, v101, v101
	v_max_f32_e64 v104, |v104|, |v104|
	v_max_f32_e32 v101, v104, v101
	v_rcp_f32_e32 v101, v101
	v_mov_b32_dpp v104, v102 row_newbcast:0 row_mask:0xf bank_mask:0xf bound_ctrl:1
	v_mov_b32_dpp v102, v102 row_newbcast:1 row_mask:0xf bank_mask:0xf bound_ctrl:1
	v_max_f32_e32 v102, v102, v102
	v_max_f32_e64 v104, |v104|, |v104|
	v_max_f32_e32 v102, v104, v102
	v_rcp_f32_e32 v102, v102
	v_mov_b32_dpp v104, v103 row_newbcast:0 row_mask:0xf bank_mask:0xf bound_ctrl:1
	v_mov_b32_dpp v103, v103 row_newbcast:1 row_mask:0xf bank_mask:0xf bound_ctrl:1
	v_max_f32_e32 v103, v103, v103
	v_max_f32_e64 v104, |v104|, |v104|
	v_max_f32_e32 v103, v104, v103
	v_rcp_f32_e32 v103, v103
	v_pk_fma_f32 v[164:165], v[180:181], v[0:1], v[170:171] op_sel_hi:[1,0,1]
	v_pk_mul_f32 v[104:105], v[110:111], v[100:101]
	s_add_i32 s3, s24, -6
	v_pk_mul_f32 v[106:107], v[108:109], v[102:103]
	v_pk_mul_f32 v[108:109], v[114:115], v[100:101]
	v_pk_mul_f32 v[110:111], v[112:113], v[102:103]
	v_pk_mul_f32 v[112:113], v[118:119], v[100:101]
	v_pk_mul_f32 v[114:115], v[116:117], v[102:103]
	v_pk_mul_f32 v[116:117], v[168:169], v[100:101]
	v_pk_mul_f32 v[118:119], v[166:167], v[102:103]
	s_mov_b64 s[20:21], 0
	v_mov_b32_e32 v183, v179
	v_mov_b32_e32 v182, v178
	v_mov_b32_e32 v181, v165
	v_mov_b32_e32 v180, v164

; __device__ __forceinline__ float row16_sum(float v) { v += dppf<0xB1>(v); v += dppf<0x4E>(v); v += dppf<0x141>(v); v += dppf<0x140>(v); return v; }
; __device__ __forceinline__ float frsq(float x) { return __builtin_amdgcn_rsqf(x); }
; __device__ __forceinline__ v2u pack4(const f32x4 v) { v2u r; r.x = pk2(v[0], v[1]); r.y = pk2(v[2], v[3]); return r; }
; __device__ __forceinline__ f32x4 unpack4(const v2u w) { f32x4 r; r[0] = bflo(w.x); r[1] = bfhi(w.x); r[2] = bflo(w.y); r[3] = bfhi(w.y); return r; }
; __device__ __forceinline__ const char* upin(const char* p) { asm volatile("" : "+s"(p)); return p; }
; __device__ __forceinline__ char* upin(char* p) { asm volatile("" : "+s"(p)); return p; }
; template <bool GDN> __device__ __forceinline__ void scan_finish(const Frame& F, int b, int h, int dir, const ScanLane& L, int s, float* PEND, const f32x4 (&Oin)[4], const ScanFin& f) {
;     ...
;         f32x4 O[4]; float ss[4] = {0.f, 0.f, 0.f, 0.f};
; #pragma unroll
;         for (int t = 0; t < 4; ++t)
;             { const f32x4 pv = unpack4(f.pend[t]);
; #pragma unroll
;             for (int i = 0; i < 4; ++i) { O[t][i] = Oin[t][i] + pv[i]; ss[i] += O[t][i] * O[t][i]; } }
; #pragma unroll
;         for (int i = 0; i < 4; ++i) ss[i] = frsq(row16_sum(ss[i]) * (1.f / 64.f) + EPS);
;         char* mp = (char*)F.MIX + ((size_t)row0 * 1024 + (GDN ? 0 : 768) + h * 64) * 2;
; #pragma unroll
;         for (int i = 0; i < 4; ++i) { const f32x4 g = unpack4(f.gz[i]); f32x4 ov;
; #pragma unroll
;             for (int t = 0; t < 4; ++t) ov[t] = O[t][i] * ss[i] * g[t];
;             stu<v2u>(upin(mp + i * 2048), L.mix, pack4(ov)); }
.LBB0_352:
	s_add_i32 s0, s25, -1
	s_cmp_eq_u32 s25, 0
	s_cselect_b64 s[10:11], -1, 0
	s_and_b64 vcc, exec, s[10:11]
	s_waitcnt lgkmcnt(0)
	s_barrier
	s_cbranch_vccnz .LBB0_357
	s_add_i32 s1, s24, 43
	s_and_b64 s[4:5], s[90:91], exec
	s_cselect_b32 s1, s0, s1
	s_cmp_lt_u32 s25, 5
	s_cselect_b32 s3, 2, 20
	s_cmp_lt_u32 s0, s3
	s_mov_b64 s[12:13], -1
	s_cbranch_scc1 .LBB0_355
	s_lshl_b32 s3, s1, 6
	s_cmp_lt_i32 s1, 4
	s_cselect_b32 s4, s63, s33
	s_add_i32 s4, s4, s3
	s_ashr_i32 s5, s4, 31
	s_lshl_b64 s[4:5], s[4:5], 11
	s_add_u32 s3, s26, s4
	s_addc_u32 s4, s27, s5
	s_add_u32 s6, s3, 0x600
	s_addc_u32 s7, s4, 0
	v_lshlrev_b32_e32 v208, 16, v12
	v_and_b32_e32 v209, 0xffff0000, v12
	v_lshlrev_b32_e32 v210, 16, v13
	v_and_b32_e32 v211, 0xffff0000, v13
	v_pk_add_f32 v[212:213], v[104:105], v[208:209]
	v_pk_add_f32 v[214:215], v[106:107], v[210:211]
	v_pk_mul_f32 v[204:205], v[212:213], v[212:213]
	v_pk_mul_f32 v[206:207], v[214:215], v[214:215]
	v_lshlrev_b32_e32 v208, 16, v14
	v_and_b32_e32 v209, 0xffff0000, v14
	v_lshlrev_b32_e32 v210, 16, v15
	v_and_b32_e32 v211, 0xffff0000, v15
	v_pk_add_f32 v[216:217], v[108:109], v[208:209]
	v_pk_add_f32 v[218:219], v[110:111], v[210:211]
	v_pk_fma_f32 v[204:205], v[216:217], v[216:217], v[204:205]
	v_pk_fma_f32 v[206:207], v[218:219], v[218:219], v[206:207]
	v_lshlrev_b32_e32 v208, 16, v16
	v_and_b32_e32 v209, 0xffff0000, v16
	v_lshlrev_b32_e32 v210, 16, v17
	v_and_b32_e32 v211, 0xffff0000, v17
	v_pk_add_f32 v[224:225], v[112:113], v[208:209]
	v_pk_add_f32 v[226:227], v[114:115], v[210:211]
	v_pk_fma_f32 v[204:205], v[224:225], v[224:225], v[204:205]
	v_pk_fma_f32 v[206:207], v[226:227], v[226:227], v[206:207]
	v_lshlrev_b32_e32 v208, 16, v18
	v_and_b32_e32 v209, 0xffff0000, v18
	v_lshlrev_b32_e32 v210, 16, v19
	v_and_b32_e32 v211, 0xffff0000, v19
	v_pk_add_f32 v[242:243], v[116:117], v[208:209]
	v_pk_add_f32 v[244:245], v[118:119], v[210:211]
	v_pk_fma_f32 v[204:205], v[242:243], v[242:243], v[204:205]
	v_pk_fma_f32 v[206:207], v[244:245], v[244:245], v[206:207]
	s_nop 1
	v_add_f32_dpp v204, v204, v204 quad_perm:[1,0,3,2] row_mask:0xf bank_mask:0xf bound_ctrl:1
	v_add_f32_dpp v205, v205, v205 quad_perm:[1,0,3,2] row_mask:0xf bank_mask:0xf bound_ctrl:1
	v_add_f32_dpp v206, v206, v206 quad_perm:[1,0,3,2] row_mask:0xf bank_mask:0xf bound_ctrl:1
	v_add_f32_dpp v207, v207, v207 quad_perm:[1,0,3,2] row_mask:0xf bank_mask:0xf bound_ctrl:1
	v_add_f32_dpp v204, v204, v204 quad_perm:[2,3,0,1] row_mask:0xf bank_mask:0xf bound_ctrl:1
	v_add_f32_dpp v205, v205, v205 quad_perm:[2,3,0,1] row_mask:0xf bank_mask:0xf bound_ctrl:1
	v_add_f32_dpp v206, v206, v206 quad_perm:[2,3,0,1] row_mask:0xf bank_mask:0xf bound_ctrl:1
	v_add_f32_dpp v207, v207, v207 quad_perm:[2,3,0,1] row_mask:0xf bank_mask:0xf bound_ctrl:1
	v_add_f32_dpp v204, v204, v204 row_half_mirror row_mask:0xf bank_mask:0xf bound_ctrl:1
	v_add_f32_dpp v205, v205, v205 row_half_mirror row_mask:0xf bank_mask:0xf bound_ctrl:1
	v_add_f32_dpp v206, v206, v206 row_half_mirror row_mask:0xf bank_mask:0xf bound_ctrl:1
	v_add_f32_dpp v207, v207, v207 row_half_mirror row_mask:0xf bank_mask:0xf bound_ctrl:1
	v_add_f32_dpp v204, v204, v204 row_mirror row_mask:0xf bank_mask:0xf bound_ctrl:1
	v_add_f32_dpp v205, v205, v205 row_mirror row_mask:0xf bank_mask:0xf bound_ctrl:1
	v_add_f32_dpp v206, v206, v206 row_mirror row_mask:0xf bank_mask:0xf bound_ctrl:1
	v_add_f32_dpp v207, v207, v207 row_mirror row_mask:0xf bank_mask:0xf bound_ctrl:1
	v_fmamk_f32 v204, v204, 0x3c800000, v231
	v_fmamk_f32 v205, v205, 0x3c800000, v231
	v_fmamk_f32 v206, v206, 0x3c800000, v231
	v_fmamk_f32 v207, v207, 0x3c800000, v231
	v_rsq_f32_e32 v204, v204
	v_rsq_f32_e32 v205, v205
	v_rsq_f32_e32 v206, v206
	v_rsq_f32_e32 v207, v207
	v_lshlrev_b32_e32 v208, 16, v130
	v_lshlrev_b32_e32 v209, 16, v132
	v_lshlrev_b32_e32 v210, 16, v134
	v_lshlrev_b32_e32 v211, 16, v136
	v_pk_mul_f32 v[212:213], v[212:213], v[204:205]
	v_pk_mul_f32 v[214:215], v[214:215], v[206:207]
	v_pk_mul_f32 v[212:213], v[212:213], v[208:209]
	v_pk_mul_f32 v[214:215], v[214:215], v[210:211]
	v_and_b32_e32 v208, 0xffff0000, v130
	v_and_b32_e32 v209, 0xffff0000, v132
	v_and_b32_e32 v210, 0xffff0000, v134
	v_and_b32_e32 v211, 0xffff0000, v136
	v_pk_mul_f32 v[216:217], v[216:217], v[204:205]
	v_pk_mul_f32 v[218:219], v[218:219], v[206:207]
	v_pk_mul_f32 v[216:217], v[216:217], v[208:209]
	v_pk_mul_f32 v[218:219], v[218:219], v[210:211]
	v_lshlrev_b32_e32 v208, 16, v131
	v_lshlrev_b32_e32 v209, 16, v133
	v_lshlrev_b32_e32 v210, 16, v135
	v_lshlrev_b32_e32 v211, 16, v137
	v_pk_mul_f32 v[224:225], v[224:225], v[204:205]
	v_pk_mul_f32 v[226:227], v[226:227], v[206:207]
	v_pk_mul_f32 v[224:225], v[224:225], v[208:209]
	v_pk_mul_f32 v[226:227], v[226:227], v[210:211]
	v_and_b32_e32 v208, 0xffff0000, v131
	v_and_b32_e32 v209, 0xffff0000, v133
	v_and_b32_e32 v210, 0xffff0000, v135
	v_and_b32_e32 v211, 0xffff0000, v137
	v_pk_mul_f32 v[242:243], v[242:243], v[204:205]
	v_pk_mul_f32 v[244:245], v[244:245], v[206:207]
	v_pk_mul_f32 v[242:243], v[242:243], v[208:209]
	v_pk_mul_f32 v[244:245], v[244:245], v[210:211]
	v_cvt_pk_bf16_f32 v208, v212, v216
	v_cvt_pk_bf16_f32 v209, v224, v242
	global_store_dwordx2 v189, v[208:209], s[6:7]
	v_cvt_pk_bf16_f32 v210, v213, v217
	v_cvt_pk_bf16_f32 v211, v225, v243
	s_add_u32 s6, s3, 0xe00
	s_addc_u32 s7, s4, 0
	global_store_dwordx2 v189, v[210:211], s[6:7]
	v_cvt_pk_bf16_f32 v204, v214, v218
	v_cvt_pk_bf16_f32 v205, v226, v244
	s_mov_b64 s[12:13], 0
	s_add_u32 s6, s3, 0x1600
	s_addc_u32 s7, s4, 0
	global_store_dwordx2 v189, v[204:205], s[6:7]
	v_cvt_pk_bf16_f32 v206, v215, v219
	v_cvt_pk_bf16_f32 v207, v227, v245
	s_add_u32 s6, s3, 0x1e00
	s_addc_u32 s7, s4, 0
	global_store_dwordx2 v189, v[206:207], s[6:7]

; __device__ __forceinline__ float row16_sum(float v) { v += dppf<0xB1>(v); v += dppf<0x4E>(v); v += dppf<0x141>(v); v += dppf<0x140>(v); return v; }
; __device__ __forceinline__ float frsq(float x) { return __builtin_amdgcn_rsqf(x); }
; __device__ __forceinline__ v2u pack4(const f32x4 v) { v2u r; r.x = pk2(v[0], v[1]); r.y = pk2(v[2], v[3]); return r; }
; __device__ __forceinline__ f32x4 unpack4(const v2u w) { f32x4 r; r[0] = bflo(w.x); r[1] = bfhi(w.x); r[2] = bflo(w.y); r[3] = bfhi(w.y); return r; }
; __device__ __forceinline__ const char* upin(const char* p) { asm volatile("" : "+s"(p)); return p; }
; __device__ __forceinline__ char* upin(char* p) { asm volatile("" : "+s"(p)); return p; }
; template <bool GDN> __device__ __forceinline__ void scan_finish(const Frame& F, int b, int h, int dir, const ScanLane& L, int s, float* PEND, const f32x4 (&Oin)[4], const ScanFin& f) {
;     ...
;         f32x4 O[4]; float ss[4] = {0.f, 0.f, 0.f, 0.f};
; #pragma unroll
;         for (int t = 0; t < 4; ++t)
;             { const f32x4 pv = unpack4(f.pend[t]);
; #pragma unroll
;             for (int i = 0; i < 4; ++i) { O[t][i] = Oin[t][i] + pv[i]; ss[i] += O[t][i] * O[t][i]; } }
; #pragma unroll
;         for (int i = 0; i < 4; ++i) ss[i] = frsq(row16_sum(ss[i]) * (1.f / 64.f) + EPS);
;         char* mp = (char*)F.MIX + ((size_t)row0 * 1024 + (GDN ? 0 : 768) + h * 64) * 2;
; #pragma unroll
;         for (int i = 0; i < 4; ++i) { const f32x4 g = unpack4(f.gz[i]); f32x4 ov;
; #pragma unroll
;             for (int t = 0; t < 4; ++t) ov[t] = O[t][i] * ss[i] * g[t];
;             stu<v2u>(upin(mp + i * 2048), L.mix, pack4(ov)); }
.LBB0_385:
	s_cmp_gt_u32 s25, 3
	s_cselect_b32 s5, 39, 3
	s_add_i32 s5, s5, s24
	s_add_i32 s1, s5, 3
	s_and_b64 s[6:7], s[90:91], exec
	s_cselect_b32 s1, s25, s1
	s_cmp_lt_u32 s4, 5
	s_cselect_b32 s3, 2, 20
	s_cmp_lt_u32 s25, s3
	s_mov_b64 s[12:13], -1
	s_cbranch_scc1 .LBB0_387
	s_lshl_b32 s3, s1, 6
	s_cmp_lt_i32 s1, 4
	s_cselect_b32 s6, s63, s33
	s_add_i32 s6, s6, s3
	s_ashr_i32 s7, s6, 31
	s_lshl_b64 s[6:7], s[6:7], 11
	s_add_u32 s3, s26, s6
	s_addc_u32 s6, s27, s7
	s_add_u32 s8, s3, 0x600
	s_addc_u32 s9, s6, 0
	v_lshlrev_b32_e32 v208, 16, v4
	v_and_b32_e32 v209, 0xffff0000, v4
	v_lshlrev_b32_e32 v210, 16, v5
	v_and_b32_e32 v211, 0xffff0000, v5
	v_pk_add_f32 v[212:213], v[104:105], v[208:209]
	v_pk_add_f32 v[214:215], v[106:107], v[210:211]
	v_pk_mul_f32 v[204:205], v[212:213], v[212:213]
	v_pk_mul_f32 v[206:207], v[214:215], v[214:215]
	v_lshlrev_b32_e32 v208, 16, v6
	v_and_b32_e32 v209, 0xffff0000, v6
	v_lshlrev_b32_e32 v210, 16, v7
	v_and_b32_e32 v211, 0xffff0000, v7
	v_pk_add_f32 v[216:217], v[108:109], v[208:209]
	v_pk_add_f32 v[218:219], v[110:111], v[210:211]
	v_pk_fma_f32 v[204:205], v[216:217], v[216:217], v[204:205]
	v_pk_fma_f32 v[206:207], v[218:219], v[218:219], v[206:207]
	v_lshlrev_b32_e32 v208, 16, v8
	v_and_b32_e32 v209, 0xffff0000, v8
	v_lshlrev_b32_e32 v210, 16, v9
	v_and_b32_e32 v211, 0xffff0000, v9
	v_pk_add_f32 v[224:225], v[112:113], v[208:209]
	v_pk_add_f32 v[226:227], v[114:115], v[210:211]
	v_pk_fma_f32 v[204:205], v[224:225], v[224:225], v[204:205]
	v_pk_fma_f32 v[206:207], v[226:227], v[226:227], v[206:207]
	v_lshlrev_b32_e32 v208, 16, v10
	v_and_b32_e32 v209, 0xffff0000, v10
	v_lshlrev_b32_e32 v210, 16, v11
	v_and_b32_e32 v211, 0xffff0000, v11
	v_pk_add_f32 v[242:243], v[116:117], v[208:209]
	v_pk_add_f32 v[244:245], v[118:119], v[210:211]
	v_pk_fma_f32 v[204:205], v[242:243], v[242:243], v[204:205]
	v_pk_fma_f32 v[206:207], v[244:245], v[244:245], v[206:207]
	s_nop 1
	v_add_f32_dpp v204, v204, v204 quad_perm:[1,0,3,2] row_mask:0xf bank_mask:0xf bound_ctrl:1
	v_add_f32_dpp v205, v205, v205 quad_perm:[1,0,3,2] row_mask:0xf bank_mask:0xf bound_ctrl:1
	v_add_f32_dpp v206, v206, v206 quad_perm:[1,0,3,2] row_mask:0xf bank_mask:0xf bound_ctrl:1
	v_add_f32_dpp v207, v207, v207 quad_perm:[1,0,3,2] row_mask:0xf bank_mask:0xf bound_ctrl:1
	v_add_f32_dpp v204, v204, v204 quad_perm:[2,3,0,1] row_mask:0xf bank_mask:0xf bound_ctrl:1
	v_add_f32_dpp v205, v205, v205 quad_perm:[2,3,0,1] row_mask:0xf bank_mask:0xf bound_ctrl:1
	v_add_f32_dpp v206, v206, v206 quad_perm:[2,3,0,1] row_mask:0xf bank_mask:0xf bound_ctrl:1
	v_add_f32_dpp v207, v207, v207 quad_perm:[2,3,0,1] row_mask:0xf bank_mask:0xf bound_ctrl:1
	v_add_f32_dpp v204, v204, v204 row_half_mirror row_mask:0xf bank_mask:0xf bound_ctrl:1
	v_add_f32_dpp v205, v205, v205 row_half_mirror row_mask:0xf bank_mask:0xf bound_ctrl:1
	v_add_f32_dpp v206, v206, v206 row_half_mirror row_mask:0xf bank_mask:0xf bound_ctrl:1
	v_add_f32_dpp v207, v207, v207 row_half_mirror row_mask:0xf bank_mask:0xf bound_ctrl:1
	v_add_f32_dpp v204, v204, v204 row_mirror row_mask:0xf bank_mask:0xf bound_ctrl:1
	v_add_f32_dpp v205, v205, v205 row_mirror row_mask:0xf bank_mask:0xf bound_ctrl:1
	v_add_f32_dpp v206, v206, v206 row_mirror row_mask:0xf bank_mask:0xf bound_ctrl:1
	v_add_f32_dpp v207, v207, v207 row_mirror row_mask:0xf bank_mask:0xf bound_ctrl:1
	v_fmamk_f32 v204, v204, 0x3c800000, v231
	v_fmamk_f32 v205, v205, 0x3c800000, v231
	v_fmamk_f32 v206, v206, 0x3c800000, v231
	v_fmamk_f32 v207, v207, 0x3c800000, v231
	v_rsq_f32_e32 v204, v204
	v_rsq_f32_e32 v205, v205
	v_rsq_f32_e32 v206, v206
	v_rsq_f32_e32 v207, v207
	v_lshlrev_b32_e32 v208, 16, v122
	v_lshlrev_b32_e32 v209, 16, v124
	v_lshlrev_b32_e32 v210, 16, v126
	v_lshlrev_b32_e32 v211, 16, v128
	v_pk_mul_f32 v[212:213], v[212:213], v[204:205]
	v_pk_mul_f32 v[214:215], v[214:215], v[206:207]
	v_pk_mul_f32 v[212:213], v[212:213], v[208:209]
	v_pk_mul_f32 v[214:215], v[214:215], v[210:211]
	v_and_b32_e32 v208, 0xffff0000, v122
	v_and_b32_e32 v209, 0xffff0000, v124
	v_and_b32_e32 v210, 0xffff0000, v126
	v_and_b32_e32 v211, 0xffff0000, v128
	v_pk_mul_f32 v[216:217], v[216:217], v[204:205]
	v_pk_mul_f32 v[218:219], v[218:219], v[206:207]
	v_pk_mul_f32 v[216:217], v[216:217], v[208:209]
	v_pk_mul_f32 v[218:219], v[218:219], v[210:211]
	v_lshlrev_b32_e32 v208, 16, v123
	v_lshlrev_b32_e32 v209, 16, v125
	v_lshlrev_b32_e32 v210, 16, v127
	v_lshlrev_b32_e32 v211, 16, v129
	v_pk_mul_f32 v[224:225], v[224:225], v[204:205]
	v_pk_mul_f32 v[226:227], v[226:227], v[206:207]
	v_pk_mul_f32 v[224:225], v[224:225], v[208:209]
	v_pk_mul_f32 v[226:227], v[226:227], v[210:211]
	v_and_b32_e32 v208, 0xffff0000, v123
	v_and_b32_e32 v209, 0xffff0000, v125
	v_and_b32_e32 v210, 0xffff0000, v127
	v_and_b32_e32 v211, 0xffff0000, v129
	v_pk_mul_f32 v[242:243], v[242:243], v[204:205]
	v_pk_mul_f32 v[244:245], v[244:245], v[206:207]
	v_pk_mul_f32 v[242:243], v[242:243], v[208:209]
	v_pk_mul_f32 v[244:245], v[244:245], v[210:211]
	v_cvt_pk_bf16_f32 v208, v212, v216
	v_cvt_pk_bf16_f32 v209, v224, v242
	global_store_dwordx2 v39, v[208:209], s[8:9]
	v_cvt_pk_bf16_f32 v210, v213, v217
	v_cvt_pk_bf16_f32 v211, v225, v243
	s_add_u32 s8, s3, 0xe00
	s_addc_u32 s9, s6, 0
	global_store_dwordx2 v39, v[210:211], s[8:9]
	v_cvt_pk_bf16_f32 v204, v214, v218
	v_cvt_pk_bf16_f32 v205, v226, v244
	s_mov_b64 s[12:13], 0
	s_add_u32 s8, s3, 0x1600
	s_addc_u32 s9, s6, 0
	global_store_dwordx2 v39, v[204:205], s[8:9]
	v_cvt_pk_bf16_f32 v206, v215, v219
	v_cvt_pk_bf16_f32 v207, v227, v245
	s_add_u32 s8, s3, 0x1e00
	s_addc_u32 s9, s6, 0
	global_store_dwordx2 v39, v[206:207], s[8:9]

; template <bool GDN, int NT> __device__ __forceinline__ void scan_load(const Frame& F, int b, int h, int dir, const ScanLane& L, int s, ScanOps<NT>& o) {
;     ...
;         const char* zq = upin((const char*)F.Z + ((size_t)chunk_row0(b, cidx) * ZW + ZC_LQ + h * 64) * 2);
; #pragma unroll
;         for (int ks = 0; ks < 2; ++ks) { o.Qf[ks] = ldu<bf16x8>(zq + ks * 64, L.zq); o.Mf[ks] = o.Qf[ks]; }
;         const char* base = (const char*)F.PM + (size_t)ud * 20480;
;         const char* bO = upin(base); const char* bB = upin(base + 10240);
; #pragma unroll
;         for (int pr = 0; pr < 2; ++pr) { const v4u qb = ldun<v4u>(bB + pr * 1024, L.o16p), qo = ldun<v4u>(bO + pr * 1024, L.o16p);
;             o.bv[2 * pr] = (v2u){qb.x, qb.y}; o.bv[2 * pr + 1] = (v2u){qb.z, qb.w}; o.ov[2 * pr] = (v2u){qo.x, qo.y}; o.ov[2 * pr + 1] = (v2u){qo.z, qo.w}; }
;         o.bv[4] = ldun<v2u>(bB + 2048, L.o8); o.ov[4] = ldun<v2u>(bO + 2048, L.o8);
;         o.wi = ldu<f32x4>(upin((const char*)F.WI + (size_t)ud * 256), L.wi);
;     ...
;     const float gl = ((const LAS float*)(St + 4 * 80 * 72))[(dir ? (s < 4 ? 3 - s : 39 - s) : s) * 2 + dir];
;     f32x4 O[NT];
; #pragma unroll
;     for (int t = 0; t < NT; ++t) {
;         const LAS bf16_t* sp2 = Sb + (16 * t + lr) * 72 + 8 * lq;
;         const bf16x8 s0 = *(const LAS bf16x8*)sp2, s1 = *(const LAS bf16x8*)(sp2 + 32);
;         const f32x4 bv = unpack4(use.bv[t]), ov = unpack4(use.ov[t]);
;         if (GDN) {
;             f32x4 o = ov, sn = S[t] * gl + bv;
;             o = __builtin_amdgcn_mfma_f32_16x16x32_bf16(use.Qf[0], s0, o, 0, 0, 0); o = __builtin_amdgcn_mfma_f32_16x16x32_bf16(use.Qf[1], s1, o, 0, 0, 0);
;             sn = __builtin_amdgcn_mfma_f32_16x16x32_bf16(use.Mf[0], s0, sn, 0, 0, 0); sn = __builtin_amdgcn_mfma_f32_16x16x32_bf16(use.Mf[1], s1, sn, 0, 0, 0);
;             S[t] = sn; O[t] = o;
;         } else {
;             f32x4 o = {0.f, 0.f, 0.f, 0.f};
;             o = __builtin_amdgcn_mfma_f32_16x16x32_bf16(use.Qf[0], s0, o, 0, 0, 0); o = __builtin_amdgcn_mfma_f32_16x16x32_bf16(use.Qf[1], s1, o, 0, 0, 0);
;             S[t] = S[t] * gl + bv; O[t] = o * use.wi + ov; }
;     }
;     if (!GDN) {
; #pragma unroll
;         for (int i = 0; i < 4; ++i) { const float den = row16_bcast<0>(O[NT - 1][i]), fl = row16_bcast<1>(O[NT - 1][i]); const float dv = frcp(fmaxf(fabsf(den), fl));
; #pragma unroll
.LBB0_396:
	s_min_u32 s1, s4, 33
	s_add_i32 s8, s1, 2
	s_and_b64 s[6:7], exec, s[10:11]
	s_cselect_b32 s1, 3, 39
	s_sub_i32 s9, s1, s8
	s_and_b64 s[6:7], s[90:91], exec
	s_cselect_b32 s6, s8, s9
	s_lshl_b32 s7, s6, 6
	s_cmp_lt_i32 s6, 4
	s_cselect_b32 s8, s63, s33
	s_add_i32 s7, s8, s7
	s_mul_i32 s8, s7, 0xd00
	s_add_i32 s6, s6, s31
	s_ashr_i32 s9, s8, 31
	s_lshl_b32 s6, s6, 1
	s_or_b64 s[8:9], s[36:37], s[8:9]
	s_add_i32 s6, s6, s68
	s_lshl_b64 s[8:9], s[8:9], 1
	s_add_u32 s8, s16, s8
	s_addc_u32 s9, s17, s9
	global_load_dwordx4 v[40:43], v36, s[8:9]
	s_nop 0
	global_load_dwordx4 v[36:39], v36, s[8:9] offset:64
	s_ashr_i32 s7, s6, 31
	s_mul_i32 s8, s6, 0x5000
	v_readlane_b32 s10, v254, 46
	s_mul_hi_i32 s9, s6, 0x5000
	s_add_u32 s8, s10, s8
	v_readlane_b32 s10, v254, 47
	s_addc_u32 s9, s10, s9
	s_mov_b64 s[10:11], s[8:9]
	s_add_u32 s8, s8, 0x2800
	s_addc_u32 s9, s9, 0
	global_load_dwordx4 v[92:95], v60, s[8:9] nt
	global_load_dwordx4 v[64:67], v60, s[8:9] offset:1024 nt
	global_load_dwordx4 v[96:99], v60, s[10:11] nt
	global_load_dwordx4 v[68:71], v60, s[10:11] offset:1024 nt
	global_load_dwordx2 v[146:147], v61, s[8:9] offset:2048 nt
	global_load_dwordx2 v[142:143], v61, s[10:11] offset:2048 nt
	s_lshl_b64 s[6:7], s[6:7], 8
	v_readlane_b32 s8, v254, 52
	v_readlane_b32 s9, v254, 53
	s_add_u32 s6, s8, s6
	s_addc_u32 s7, s9, s7
	global_load_dwordx4 v[60:63], v0, s[6:7]
	s_add_i32 s5, s5, 2
	s_and_b64 s[6:7], s[90:91], exec
	s_cselect_b32 s5, s4, s5
	s_lshl_b32 s6, s5, 3
	s_add_i32 s6, s34, s6
	v_mov_b32_e32 v0, s6
	v_add_u32_e32 v203, v201, v121
	ds_read_b128 v[104:107], v203 offset:11520
	ds_read_b32 v0, v0 offset:46080
	ds_read_b128 v[108:111], v203 offset:11584
	ds_read_b128 v[212:215], v203 offset:13824
	ds_read_b128 v[216:219], v203 offset:13888
	ds_read_b128 v[224:227], v203 offset:16128
	ds_read_b128 v[242:245], v203 offset:18432
	s_waitcnt lgkmcnt(6)
	v_mfma_f32_16x16x32_bf16 v[104:107], v[24:27], v[104:107], 0
	v_lshlrev_b32_e32 v116, 16, v44
	v_and_b32_e32 v117, 0xffff0000, v44
	v_lshlrev_b32_e32 v118, 16, v45
	v_and_b32_e32 v119, 0xffff0000, v45
	s_waitcnt lgkmcnt(4)
	v_mfma_f32_16x16x32_bf16 v[104:107], v[20:23], v[108:111], v[104:107]
	v_pk_fma_f32 v[180:181], v[150:151], v[0:1], v[118:119] op_sel_hi:[1,0,1]
	v_pk_fma_f32 v[182:183], v[148:149], v[0:1], v[116:117] op_sel_hi:[1,0,1]
	s_waitcnt lgkmcnt(3)
	v_mfma_f32_16x16x32_bf16 v[112:115], v[24:27], v[212:215], 0
	v_lshlrev_b32_e32 v148, 16, v46
	s_waitcnt lgkmcnt(2)
	v_mfma_f32_16x16x32_bf16 v[108:111], v[20:23], v[216:219], v[112:115]
	ds_read_b128 v[212:215], v203 offset:16192
	ds_read_b128 v[216:219], v203 offset:18496
	v_and_b32_e32 v149, 0xffff0000, v46
	v_lshlrev_b32_e32 v150, 16, v47
	v_and_b32_e32 v151, 0xffff0000, v47
	s_waitcnt lgkmcnt(3)
	v_mfma_f32_16x16x32_bf16 v[116:119], v[24:27], v[224:227], 0
	v_fma_f32 v150, v152, v0, v150
	v_fma_f32 v151, v153, v0, v151
	v_pk_fma_f32 v[154:155], v[154:155], v[0:1], v[148:149] op_sel_hi:[1,0,1]
	v_lshlrev_b32_e32 v152, 16, v28
	v_and_b32_e32 v153, 0xffff0000, v28
	v_lshlrev_b32_e32 v148, 16, v29
	v_and_b32_e32 v149, 0xffff0000, v29
	s_waitcnt lgkmcnt(1)
	v_mfma_f32_16x16x32_bf16 v[112:115], v[20:23], v[212:215], v[116:119]
	v_fma_f32 v148, v156, v0, v148
	v_fma_f32 v149, v157, v0, v149
	v_pk_fma_f32 v[152:153], v[158:159], v[0:1], v[152:153] op_sel_hi:[1,0,1]
	v_lshlrev_b32_e32 v170, 16, v30
	v_mfma_f32_16x16x32_bf16 v[156:159], v[24:27], v[242:245], 0
	ds_read_b128 v[224:227], v203 offset:20736
	ds_read_b128 v[242:245], v203 offset:20800
	v_and_b32_e32 v171, 0xffff0000, v30
	v_lshlrev_b32_e32 v172, 16, v31
	s_waitcnt lgkmcnt(2)
	v_mfma_f32_16x16x32_bf16 v[116:119], v[20:23], v[216:219], v[156:159]
	v_and_b32_e32 v173, 0xffff0000, v31
	v_pk_fma_f32 v[184:185], v[160:161], v[0:1], v[172:173] op_sel_hi:[1,0,1]
	v_pk_fma_f32 v[160:161], v[162:163], v[0:1], v[170:171] op_sel_hi:[1,0,1]
	s_waitcnt lgkmcnt(1)
	v_mfma_f32_16x16x32_bf16 v[166:169], v[24:27], v[224:227], 0
	v_lshlrev_b32_e32 v162, 16, v140
	v_and_b32_e32 v163, 0xffff0000, v140
	v_lshlrev_b32_e32 v172, 16, v138
	s_waitcnt lgkmcnt(0)
	v_mfma_f32_16x16x32_bf16 v[166:169], v[20:23], v[242:245], v[166:169]
	v_and_b32_e32 v173, 0xffff0000, v138
	v_lshlrev_b32_e32 v174, 16, v139
	v_and_b32_e32 v175, 0xffff0000, v139
	v_lshlrev_b32_e32 v170, 16, v141
	v_and_b32_e32 v171, 0xffff0000, v141
	v_pk_fma_f32 v[158:159], v[164:165], v[0:1], v[162:163] op_sel_hi:[1,0,1]
	s_nop 0
	v_pk_fma_f32 v[168:169], v[102:103], v[168:169], v[174:175]
	v_pk_fma_f32 v[162:163], v[100:101], v[166:167], v[172:173]
	v_pk_fma_f32 v[156:157], v[178:179], v[0:1], v[170:171] op_sel_hi:[1,0,1]
	v_mov_b32_dpp v165, v168 row_newbcast:0 row_mask:0xf bank_mask:0xf bound_ctrl:1
	v_mov_b32_dpp v187, v162 row_newbcast:0 row_mask:0xf bank_mask:0xf bound_ctrl:1
	v_mov_b32_dpp v193, v162 row_newbcast:1 row_mask:0xf bank_mask:0xf bound_ctrl:1
	v_mov_b32_dpp v179, v163 row_newbcast:0 row_mask:0xf bank_mask:0xf bound_ctrl:1
	v_mov_b32_dpp v186, v163 row_newbcast:1 row_mask:0xf bank_mask:0xf bound_ctrl:1
	v_mov_b32_dpp v178, v168 row_newbcast:1 row_mask:0xf bank_mask:0xf bound_ctrl:1
	v_mov_b32_dpp v163, v169 row_newbcast:0 row_mask:0xf bank_mask:0xf bound_ctrl:1
	v_mov_b32_dpp v164, v169 row_newbcast:1 row_mask:0xf bank_mask:0xf bound_ctrl:1
	v_mov_b32_e32 v0, v120
	v_mov_b32_e32 v191, v197
	v_mov_b32_e32 v188, v194
	v_mov_b32_e32 v190, v196
	v_mov_b32_e32 v192, v199
	v_mov_b32_e32 v166, v198
	v_mov_b32_e32 v162, v200
	v_mov_b32_e32 v189, v195
	s_cmp_gt_u32 s25, 33
	s_cbranch_scc1 .LBB0_398
	v_cvt_pk_bf16_f32 v166, v182, v183
	v_cvt_pk_bf16_f32 v167, v180, v181
	ds_write_b64 v202, v[166:167]
	v_cvt_pk_bf16_f32 v166, v154, v155
	v_cvt_pk_bf16_f32 v167, v150, v151
	ds_write_b64 v202, v[166:167] offset:2304
	v_cvt_pk_bf16_f32 v166, v152, v153
	v_cvt_pk_bf16_f32 v167, v148, v149
	ds_write_b64 v202, v[166:167] offset:4608
	v_cvt_pk_bf16_f32 v166, v160, v161
	v_cvt_pk_bf16_f32 v167, v184, v185
	ds_write_b64 v202, v[166:167] offset:6912
	v_cvt_pk_bf16_f32 v166, v158, v159
	v_cvt_pk_bf16_f32 v167, v156, v157
	ds_write_b64 v202, v[166:167] offset:9216

; __device__ __forceinline__ float row16_sum(float v) { v += dppf<0xB1>(v); v += dppf<0x4E>(v); v += dppf<0x141>(v); v += dppf<0x140>(v); return v; }
; __device__ __forceinline__ float frsq(float x) { return __builtin_amdgcn_rsqf(x); }
; __device__ __forceinline__ v2u pack4(const f32x4 v) { v2u r; r.x = pk2(v[0], v[1]); r.y = pk2(v[2], v[3]); return r; }
; __device__ __forceinline__ f32x4 unpack4(const v2u w) { f32x4 r; r[0] = bflo(w.x); r[1] = bfhi(w.x); r[2] = bflo(w.y); r[3] = bfhi(w.y); return r; }
; __device__ __forceinline__ const char* upin(const char* p) { asm volatile("" : "+s"(p)); return p; }
; __device__ __forceinline__ char* upin(char* p) { asm volatile("" : "+s"(p)); return p; }
; template <bool GDN> __device__ __forceinline__ void scan_finish(const Frame& F, int b, int h, int dir, const ScanLane& L, int s, float* PEND, const f32x4 (&Oin)[4], const ScanFin& f) {
;     ...
;         f32x4 O[4]; float ss[4] = {0.f, 0.f, 0.f, 0.f};
; #pragma unroll
;         for (int t = 0; t < 4; ++t)
;             { const f32x4 pv = unpack4(f.pend[t]);
; #pragma unroll
;             for (int i = 0; i < 4; ++i) { O[t][i] = Oin[t][i] + pv[i]; ss[i] += O[t][i] * O[t][i]; } }
; #pragma unroll
;         for (int i = 0; i < 4; ++i) ss[i] = frsq(row16_sum(ss[i]) * (1.f / 64.f) + EPS);
;         char* mp = (char*)F.MIX + ((size_t)row0 * 1024 + (GDN ? 0 : 768) + h * 64) * 2;
; #pragma unroll
;         for (int i = 0; i < 4; ++i) { const f32x4 g = unpack4(f.gz[i]); f32x4 ov;
; #pragma unroll
;             for (int t = 0; t < 4; ++t) ov[t] = O[t][i] * ss[i] * g[t];
;             stu<v2u>(upin(mp + i * 2048), L.mix, pack4(ov)); }
.LBB0_434:
	s_lshl_b32 s3, s4, 6
	s_cmp_lt_i32 s4, 4
	s_cselect_b32 s5, s63, s33
	s_add_i32 s6, s5, s3
	s_ashr_i32 s7, s6, 31
	s_lshl_b64 s[6:7], s[6:7], 11
	s_add_u32 s3, s26, s6
	s_addc_u32 s5, s27, s7
	s_add_u32 s6, s3, 0x600
	s_addc_u32 s7, s5, 0
	v_lshlrev_b32_e32 v208, 16, v4
	v_and_b32_e32 v209, 0xffff0000, v4
	v_lshlrev_b32_e32 v210, 16, v5
	v_and_b32_e32 v211, 0xffff0000, v5
	v_pk_add_f32 v[212:213], v[50:51], v[208:209]
	v_pk_add_f32 v[214:215], v[2:3], v[210:211]
	v_pk_mul_f32 v[204:205], v[212:213], v[212:213]
	v_pk_mul_f32 v[206:207], v[214:215], v[214:215]
	v_lshlrev_b32_e32 v208, 16, v6
	v_and_b32_e32 v209, 0xffff0000, v6
	v_lshlrev_b32_e32 v210, 16, v7
	v_and_b32_e32 v211, 0xffff0000, v7
	v_pk_add_f32 v[216:217], v[112:113], v[208:209]
	v_pk_add_f32 v[218:219], v[118:119], v[210:211]
	v_pk_fma_f32 v[204:205], v[216:217], v[216:217], v[204:205]
	v_pk_fma_f32 v[206:207], v[218:219], v[218:219], v[206:207]
	v_lshlrev_b32_e32 v208, 16, v8
	v_and_b32_e32 v209, 0xffff0000, v8
	v_lshlrev_b32_e32 v210, 16, v9
	v_and_b32_e32 v211, 0xffff0000, v9
	v_pk_add_f32 v[224:225], v[56:57], v[208:209]
	v_pk_add_f32 v[226:227], v[48:49], v[210:211]
	v_pk_fma_f32 v[204:205], v[224:225], v[224:225], v[204:205]
	v_pk_fma_f32 v[206:207], v[226:227], v[226:227], v[206:207]
	v_lshlrev_b32_e32 v208, 16, v10
	v_and_b32_e32 v209, 0xffff0000, v10
	v_lshlrev_b32_e32 v210, 16, v11
	v_and_b32_e32 v211, 0xffff0000, v11
	v_pk_add_f32 v[242:243], v[114:115], v[208:209]
	v_pk_add_f32 v[244:245], v[116:117], v[210:211]
	v_pk_fma_f32 v[204:205], v[242:243], v[242:243], v[204:205]
	v_pk_fma_f32 v[206:207], v[244:245], v[244:245], v[206:207]
	s_nop 1
	v_add_f32_dpp v204, v204, v204 quad_perm:[1,0,3,2] row_mask:0xf bank_mask:0xf bound_ctrl:1
	v_add_f32_dpp v205, v205, v205 quad_perm:[1,0,3,2] row_mask:0xf bank_mask:0xf bound_ctrl:1
	v_add_f32_dpp v206, v206, v206 quad_perm:[1,0,3,2] row_mask:0xf bank_mask:0xf bound_ctrl:1
	v_add_f32_dpp v207, v207, v207 quad_perm:[1,0,3,2] row_mask:0xf bank_mask:0xf bound_ctrl:1
	v_add_f32_dpp v204, v204, v204 quad_perm:[2,3,0,1] row_mask:0xf bank_mask:0xf bound_ctrl:1
	v_add_f32_dpp v205, v205, v205 quad_perm:[2,3,0,1] row_mask:0xf bank_mask:0xf bound_ctrl:1
	v_add_f32_dpp v206, v206, v206 quad_perm:[2,3,0,1] row_mask:0xf bank_mask:0xf bound_ctrl:1
	v_add_f32_dpp v207, v207, v207 quad_perm:[2,3,0,1] row_mask:0xf bank_mask:0xf bound_ctrl:1
	v_add_f32_dpp v204, v204, v204 row_half_mirror row_mask:0xf bank_mask:0xf bound_ctrl:1
	v_add_f32_dpp v205, v205, v205 row_half_mirror row_mask:0xf bank_mask:0xf bound_ctrl:1
	v_add_f32_dpp v206, v206, v206 row_half_mirror row_mask:0xf bank_mask:0xf bound_ctrl:1
	v_add_f32_dpp v207, v207, v207 row_half_mirror row_mask:0xf bank_mask:0xf bound_ctrl:1
	v_add_f32_dpp v204, v204, v204 row_mirror row_mask:0xf bank_mask:0xf bound_ctrl:1
	v_add_f32_dpp v205, v205, v205 row_mirror row_mask:0xf bank_mask:0xf bound_ctrl:1
	v_add_f32_dpp v206, v206, v206 row_mirror row_mask:0xf bank_mask:0xf bound_ctrl:1
	v_add_f32_dpp v207, v207, v207 row_mirror row_mask:0xf bank_mask:0xf bound_ctrl:1
	v_fmamk_f32 v204, v204, 0x3c800000, v231
	v_fmamk_f32 v205, v205, 0x3c800000, v231
	v_fmamk_f32 v206, v206, 0x3c800000, v231
	v_fmamk_f32 v207, v207, 0x3c800000, v231
	v_rsq_f32_e32 v204, v204
	v_rsq_f32_e32 v205, v205
	v_rsq_f32_e32 v206, v206
	v_rsq_f32_e32 v207, v207
	v_lshlrev_b32_e32 v208, 16, v122
	v_lshlrev_b32_e32 v209, 16, v124
	v_lshlrev_b32_e32 v210, 16, v126
	v_lshlrev_b32_e32 v211, 16, v128
	v_pk_mul_f32 v[212:213], v[212:213], v[204:205]
	v_pk_mul_f32 v[214:215], v[214:215], v[206:207]
	v_pk_mul_f32 v[212:213], v[212:213], v[208:209]
	v_pk_mul_f32 v[214:215], v[214:215], v[210:211]
	v_and_b32_e32 v208, 0xffff0000, v122
	v_and_b32_e32 v209, 0xffff0000, v124
	v_and_b32_e32 v210, 0xffff0000, v126
	v_and_b32_e32 v211, 0xffff0000, v128
	v_pk_mul_f32 v[216:217], v[216:217], v[204:205]
	v_pk_mul_f32 v[218:219], v[218:219], v[206:207]
	v_pk_mul_f32 v[216:217], v[216:217], v[208:209]
	v_pk_mul_f32 v[218:219], v[218:219], v[210:211]
	v_lshlrev_b32_e32 v208, 16, v123
	v_lshlrev_b32_e32 v209, 16, v125
	v_lshlrev_b32_e32 v210, 16, v127
	v_lshlrev_b32_e32 v211, 16, v129
	v_pk_mul_f32 v[224:225], v[224:225], v[204:205]
	v_pk_mul_f32 v[226:227], v[226:227], v[206:207]
	v_pk_mul_f32 v[224:225], v[224:225], v[208:209]
	v_pk_mul_f32 v[226:227], v[226:227], v[210:211]
	v_and_b32_e32 v208, 0xffff0000, v123
	v_and_b32_e32 v209, 0xffff0000, v125
	v_and_b32_e32 v210, 0xffff0000, v127
	v_and_b32_e32 v211, 0xffff0000, v129
	v_pk_mul_f32 v[242:243], v[242:243], v[204:205]
	v_pk_mul_f32 v[244:245], v[244:245], v[206:207]
	v_pk_mul_f32 v[242:243], v[242:243], v[208:209]
	v_pk_mul_f32 v[244:245], v[244:245], v[210:211]
	v_cvt_pk_bf16_f32 v208, v212, v216
	v_cvt_pk_bf16_f32 v209, v224, v242
	global_store_dwordx2 v75, v[208:209], s[6:7]
	v_cvt_pk_bf16_f32 v210, v213, v217
	v_cvt_pk_bf16_f32 v211, v225, v243
	s_add_u32 s6, s3, 0xe00
	s_addc_u32 s7, s5, 0
	global_store_dwordx2 v75, v[210:211], s[6:7]
	v_cvt_pk_bf16_f32 v204, v214, v218
	v_cvt_pk_bf16_f32 v205, v226, v244
	s_add_u32 s6, s3, 0x1600
	s_addc_u32 s7, s5, 0
	global_store_dwordx2 v75, v[204:205], s[6:7]
	v_cvt_pk_bf16_f32 v206, v215, v219
	v_cvt_pk_bf16_f32 v207, v227, v245
	s_add_u32 s6, s3, 0x1e00
	s_addc_u32 s7, s5, 0
	global_store_dwordx2 v75, v[206:207], s[6:7]
	s_cbranch_execz .LBB0_450

; template <bool GDN, int NT> __device__ __forceinline__ void scan_load(const Frame& F, int b, int h, int dir, const ScanLane& L, int s, ScanOps<NT>& o) {
;     ...
;         const char* zq = upin((const char*)F.Z + ((size_t)chunk_row0(b, cidx) * ZW + ZC_LQ + h * 64) * 2);
; #pragma unroll
;         for (int ks = 0; ks < 2; ++ks) { o.Qf[ks] = ldu<bf16x8>(zq + ks * 64, L.zq); o.Mf[ks] = o.Qf[ks]; }
;         const char* base = (const char*)F.PM + (size_t)ud * 20480;
;         const char* bO = upin(base); const char* bB = upin(base + 10240);
; #pragma unroll
;         for (int pr = 0; pr < 2; ++pr) { const v4u qb = ldun<v4u>(bB + pr * 1024, L.o16p), qo = ldun<v4u>(bO + pr * 1024, L.o16p);
;             o.bv[2 * pr] = (v2u){qb.x, qb.y}; o.bv[2 * pr + 1] = (v2u){qb.z, qb.w}; o.ov[2 * pr] = (v2u){qo.x, qo.y}; o.ov[2 * pr + 1] = (v2u){qo.z, qo.w}; }
;         o.bv[4] = ldun<v2u>(bB + 2048, L.o8); o.ov[4] = ldun<v2u>(bO + 2048, L.o8);
;         o.wi = ldu<f32x4>(upin((const char*)F.WI + (size_t)ud * 256), L.wi);
;     ...
;     const float gl = ((const LAS float*)(St + 4 * 80 * 72))[(dir ? (s < 4 ? 3 - s : 39 - s) : s) * 2 + dir];
;     f32x4 O[NT];
; #pragma unroll
;     for (int t = 0; t < NT; ++t) {
;         const LAS bf16_t* sp2 = Sb + (16 * t + lr) * 72 + 8 * lq;
;         const bf16x8 s0 = *(const LAS bf16x8*)sp2, s1 = *(const LAS bf16x8*)(sp2 + 32);
;         const f32x4 bv = unpack4(use.bv[t]), ov = unpack4(use.ov[t]);
;         if (GDN) {
;             f32x4 o = ov, sn = S[t] * gl + bv;
;             o = __builtin_amdgcn_mfma_f32_16x16x32_bf16(use.Qf[0], s0, o, 0, 0, 0); o = __builtin_amdgcn_mfma_f32_16x16x32_bf16(use.Qf[1], s1, o, 0, 0, 0);
;             sn = __builtin_amdgcn_mfma_f32_16x16x32_bf16(use.Mf[0], s0, sn, 0, 0, 0); sn = __builtin_amdgcn_mfma_f32_16x16x32_bf16(use.Mf[1], s1, sn, 0, 0, 0);
;             S[t] = sn; O[t] = o;
;         } else {
;             f32x4 o = {0.f, 0.f, 0.f, 0.f};
;             o = __builtin_amdgcn_mfma_f32_16x16x32_bf16(use.Qf[0], s0, o, 0, 0, 0); o = __builtin_amdgcn_mfma_f32_16x16x32_bf16(use.Qf[1], s1, o, 0, 0, 0);
;             S[t] = S[t] * gl + bv; O[t] = o * use.wi + ov; }
;     }
;     if (!GDN) {
; #pragma unroll
;         for (int i = 0; i < 4; ++i) { const float den = row16_bcast<0>(O[NT - 1][i]), fl = row16_bcast<1>(O[NT - 1][i]); const float dv = frcp(fmaxf(fabsf(den), fl));
; #pragma unroll
.LBB0_437:
	s_add_i32 s8, s25, 3
	s_min_u32 s4, s8, 33
	s_add_i32 s6, s4, 2
	s_sub_i32 s7, 37, s4
	s_and_b64 s[4:5], s[90:91], exec
	s_cselect_b32 s4, s6, s7
	s_lshl_b32 s5, s4, 6
	s_add_i32 s5, s5, s33
	s_add_i32 s4, s4, s31
	s_lshl_b32 s4, s4, 1
	s_mulk_i32 s5, 0xd00
	s_add_i32 s92, s4, s68
	s_or_b32 s4, s36, s5
	s_mov_b32 s5, s37
	s_lshl_b64 s[4:5], s[4:5], 1
	s_add_u32 s4, s16, s4
	s_addc_u32 s5, s17, s5
	global_load_dwordx4 v[56:59], v74, s[4:5]
	global_load_dwordx4 v[48:51], v74, s[4:5] offset:64
	s_mul_i32 s4, s92, 0x5000
	v_readlane_b32 s6, v254, 46
	s_mul_hi_u32 s5, s92, 0x5000
	s_add_u32 s4, s6, s4
	v_readlane_b32 s6, v254, 47
	s_addc_u32 s5, s6, s5
	s_mov_b64 s[6:7], s[4:5]
	s_add_u32 s4, s4, 0x2800
	s_addc_u32 s5, s5, 0
	global_load_dwordx4 v[84:87], v73, s[4:5] nt
	global_load_dwordx4 v[76:79], v73, s[4:5] offset:1024 nt
	global_load_dwordx4 v[88:91], v73, s[6:7] nt
	global_load_dwordx4 v[80:83], v73, s[6:7] offset:1024 nt
	global_load_dwordx2 v[144:145], v72, s[4:5] offset:2048 nt
	global_load_dwordx2 v[2:3], v72, s[6:7] offset:2048 nt
	s_lshl_b64 s[4:5], s[92:93], 8
	v_readlane_b32 s6, v254, 52
	v_readlane_b32 s7, v254, 53
	s_add_u32 s4, s6, s4
	s_addc_u32 s5, s7, s5
	global_load_dwordx4 v[72:75], v0, s[4:5]
	s_add_i32 s1, s1, s24
	s_and_b64 s[4:5], s[90:91], exec
	s_cselect_b32 s1, s8, s1
	ds_read_b128 v[104:107], v203 offset:11520
	s_lshl_b32 s4, s1, 3
	s_add_i32 s4, s34, s4
	v_mov_b32_e32 v0, s4
	ds_read_b32 v0, v0 offset:46080
	ds_read_b128 v[108:111], v203 offset:11584
	ds_read_b128 v[212:215], v203 offset:13824
	ds_read_b128 v[216:219], v203 offset:13888
	ds_read_b128 v[224:227], v203 offset:16128
	ds_read_b128 v[242:245], v203 offset:16192
	s_waitcnt lgkmcnt(6)
	v_mfma_f32_16x16x32_bf16 v[104:107], v[40:43], v[104:107], 0
	v_lshlrev_b32_e32 v112, 16, v92
	v_and_b32_e32 v113, 0xffff0000, v92
	v_lshlrev_b32_e32 v114, 16, v93
	s_waitcnt lgkmcnt(4)
	v_mfma_f32_16x16x32_bf16 v[104:107], v[36:39], v[108:111], v[104:107]
	v_and_b32_e32 v115, 0xffff0000, v93
	v_pk_fma_f32 v[192:193], v[180:181], v[0:1], v[114:115] op_sel_hi:[1,0,1]
	v_pk_fma_f32 v[190:191], v[182:183], v[0:1], v[112:113] op_sel_hi:[1,0,1]
	s_waitcnt lgkmcnt(3)
	v_mfma_f32_16x16x32_bf16 v[108:111], v[40:43], v[212:215], 0
	v_lshlrev_b32_e32 v116, 16, v94
	v_and_b32_e32 v117, 0xffff0000, v94
	v_lshlrev_b32_e32 v118, 16, v95
	s_waitcnt lgkmcnt(2)
	v_mfma_f32_16x16x32_bf16 v[108:111], v[36:39], v[216:219], v[108:111]
	ds_read_b128 v[212:215], v203 offset:18432
	ds_read_b128 v[216:219], v203 offset:18496
	v_and_b32_e32 v119, 0xffff0000, v95
	v_pk_fma_f32 v[188:189], v[150:151], v[0:1], v[118:119] op_sel_hi:[1,0,1]
	v_pk_fma_f32 v[154:155], v[154:155], v[0:1], v[116:117] op_sel_hi:[1,0,1]
	s_waitcnt lgkmcnt(3)
	v_mfma_f32_16x16x32_bf16 v[112:115], v[40:43], v[224:227], 0
	v_lshlrev_b32_e32 v150, 16, v64
	v_and_b32_e32 v151, 0xffff0000, v64
	v_lshlrev_b32_e32 v162, 16, v65
	s_waitcnt lgkmcnt(2)
	v_mfma_f32_16x16x32_bf16 v[112:115], v[36:39], v[242:245], v[112:115]
	ds_read_b128 v[224:227], v203 offset:20736
	ds_read_b128 v[242:245], v203 offset:20800
	v_and_b32_e32 v163, 0xffff0000, v65
	v_pk_fma_f32 v[186:187], v[148:149], v[0:1], v[162:163] op_sel_hi:[1,0,1]
	v_pk_fma_f32 v[182:183], v[152:153], v[0:1], v[150:151] op_sel_hi:[1,0,1]
	s_waitcnt lgkmcnt(3)
	v_mfma_f32_16x16x32_bf16 v[116:119], v[40:43], v[212:215], 0
	v_lshlrev_b32_e32 v152, 16, v66
	v_and_b32_e32 v153, 0xffff0000, v66
	v_lshlrev_b32_e32 v168, 16, v142
	s_waitcnt lgkmcnt(2)
	v_mfma_f32_16x16x32_bf16 v[116:119], v[36:39], v[216:219], v[116:119]
	v_and_b32_e32 v169, 0xffff0000, v142
	v_lshlrev_b32_e32 v170, 16, v143
	s_waitcnt lgkmcnt(1)
	v_mfma_f32_16x16x32_bf16 v[148:151], v[40:43], v[224:227], 0
	v_and_b32_e32 v171, 0xffff0000, v143
	v_lshlrev_b32_e32 v162, 16, v67
	v_and_b32_e32 v163, 0xffff0000, v67
	s_waitcnt lgkmcnt(0)
	v_mfma_f32_16x16x32_bf16 v[148:151], v[36:39], v[242:245], v[148:151]
	v_fma_f32 v178, v160, v0, v152
	v_fma_f32 v179, v161, v0, v153
	v_lshlrev_b32_e32 v152, 16, v146
	v_and_b32_e32 v153, 0xffff0000, v146
	v_lshlrev_b32_e32 v160, 16, v147
	v_and_b32_e32 v161, 0xffff0000, v147
	s_nop 0
	v_pk_fma_f32 v[150:151], v[62:63], v[150:151], v[170:171]
	v_pk_fma_f32 v[148:149], v[60:61], v[148:149], v[168:169]
	v_pk_fma_f32 v[162:163], v[184:185], v[0:1], v[162:163] op_sel_hi:[1,0,1]
	v_pk_fma_f32 v[164:165], v[156:157], v[0:1], v[160:161] op_sel_hi:[1,0,1]
	v_pk_fma_f32 v[180:181], v[158:159], v[0:1], v[152:153] op_sel_hi:[1,0,1]
	v_mov_b32_dpp v184, v148 row_newbcast:0 row_mask:0xf bank_mask:0xf bound_ctrl:1
	v_mov_b32_dpp v185, v148 row_newbcast:1 row_mask:0xf bank_mask:0xf bound_ctrl:1
	v_mov_b32_dpp v160, v149 row_newbcast:0 row_mask:0xf bank_mask:0xf bound_ctrl:1
	v_mov_b32_dpp v161, v149 row_newbcast:1 row_mask:0xf bank_mask:0xf bound_ctrl:1
	v_mov_b32_dpp v158, v150 row_newbcast:0 row_mask:0xf bank_mask:0xf bound_ctrl:1
	v_mov_b32_dpp v159, v150 row_newbcast:1 row_mask:0xf bank_mask:0xf bound_ctrl:1
	v_mov_b32_dpp v156, v151 row_newbcast:0 row_mask:0xf bank_mask:0xf bound_ctrl:1
	v_mov_b32_dpp v157, v151 row_newbcast:1 row_mask:0xf bank_mask:0xf bound_ctrl:1
	v_mov_b32_e32 v148, v194
	v_mov_b32_e32 v150, v196
	v_mov_b32_e32 v152, v199
	v_mov_b32_e32 v166, v198
	v_mov_b32_e32 v153, v200
	v_mov_b32_e32 v149, v195
	v_mov_b32_e32 v0, v120
	v_mov_b32_e32 v151, v197
	s_cmp_gt_u32 s25, 31
	s_cbranch_scc1 .LBB0_451
	v_cvt_pk_bf16_f32 v166, v190, v191
	v_cvt_pk_bf16_f32 v167, v192, v193
	ds_write_b64 v202, v[166:167]
	v_cvt_pk_bf16_f32 v166, v154, v155
	v_cvt_pk_bf16_f32 v167, v188, v189
	ds_write_b64 v202, v[166:167] offset:2304
	v_cvt_pk_bf16_f32 v166, v182, v183
	v_cvt_pk_bf16_f32 v167, v186, v187
	ds_write_b64 v202, v[166:167] offset:4608
	v_cvt_pk_bf16_f32 v166, v178, v179
	v_cvt_pk_bf16_f32 v167, v162, v163
	ds_write_b64 v202, v[166:167] offset:6912
	v_cvt_pk_bf16_f32 v166, v180, v181
	v_cvt_pk_bf16_f32 v167, v164, v165
	ds_write_b64 v202, v[166:167] offset:9216
	s_sub_i32 s4, s25, 17
	s_cmp_gt_u32 s4, 14
	s_mov_b64 s[10:11], -1
	s_cbranch_scc1 .LBB0_452

; __device__ __forceinline__ float row16_sum(float v) { v += dppf<0xB1>(v); v += dppf<0x4E>(v); v += dppf<0x141>(v); v += dppf<0x140>(v); return v; }
; __device__ __forceinline__ float frsq(float x) { return __builtin_amdgcn_rsqf(x); }
; __device__ __forceinline__ v2u pack4(const f32x4 v) { v2u r; r.x = pk2(v[0], v[1]); r.y = pk2(v[2], v[3]); return r; }
; __device__ __forceinline__ f32x4 unpack4(const v2u w) { f32x4 r; r[0] = bflo(w.x); r[1] = bfhi(w.x); r[2] = bflo(w.y); r[3] = bfhi(w.y); return r; }
; __device__ __forceinline__ const char* upin(const char* p) { asm volatile("" : "+s"(p)); return p; }
; __device__ __forceinline__ char* upin(char* p) { asm volatile("" : "+s"(p)); return p; }
; template <bool GDN> __device__ __forceinline__ void scan_finish(const Frame& F, int b, int h, int dir, const ScanLane& L, int s, float* PEND, const f32x4 (&Oin)[4], const ScanFin& f) {
;     ...
;         f32x4 O[4]; float ss[4] = {0.f, 0.f, 0.f, 0.f};
; #pragma unroll
;         for (int t = 0; t < 4; ++t)
;             { const f32x4 pv = unpack4(f.pend[t]);
; #pragma unroll
;             for (int i = 0; i < 4; ++i) { O[t][i] = Oin[t][i] + pv[i]; ss[i] += O[t][i] * O[t][i]; } }
; #pragma unroll
;         for (int i = 0; i < 4; ++i) ss[i] = frsq(row16_sum(ss[i]) * (1.f / 64.f) + EPS);
;         char* mp = (char*)F.MIX + ((size_t)row0 * 1024 + (GDN ? 0 : 768) + h * 64) * 2;
; #pragma unroll
;         for (int i = 0; i < 4; ++i) { const f32x4 g = unpack4(f.gz[i]); f32x4 ov;
; #pragma unroll
;             for (int t = 0; t < 4; ++t) ov[t] = O[t][i] * ss[i] * g[t];
;             stu<v2u>(upin(mp + i * 2048), L.mix, pack4(ov)); }
.LBB0_469:
	s_lshl_b32 s1, s0, 6
	s_cmp_lt_i32 s0, 4
	s_cselect_b32 s3, s63, s33
	s_add_i32 s4, s3, s1
	s_ashr_i32 s5, s4, 31
	s_lshl_b64 s[4:5], s[4:5], 11
	s_add_u32 s1, s26, s4
	s_addc_u32 s3, s27, s5
	s_add_u32 s4, s1, 0x600
	s_addc_u32 s5, s3, 0
	v_lshlrev_b32_e32 v208, 16, v4
	v_and_b32_e32 v209, 0xffff0000, v4
	v_lshlrev_b32_e32 v210, 16, v5
	v_and_b32_e32 v211, 0xffff0000, v5
	v_pk_add_f32 v[212:213], v[24:25], v[208:209]
	v_pk_add_f32 v[214:215], v[20:21], v[210:211]
	v_pk_mul_f32 v[204:205], v[212:213], v[212:213]
	v_pk_mul_f32 v[206:207], v[214:215], v[214:215]
	v_lshlrev_b32_e32 v208, 16, v6
	v_and_b32_e32 v209, 0xffff0000, v6
	v_lshlrev_b32_e32 v210, 16, v7
	v_and_b32_e32 v211, 0xffff0000, v7
	v_pk_add_f32 v[216:217], v[104:105], v[208:209]
	v_pk_add_f32 v[218:219], v[110:111], v[210:211]
	v_pk_fma_f32 v[204:205], v[216:217], v[216:217], v[204:205]
	v_pk_fma_f32 v[206:207], v[218:219], v[218:219], v[206:207]
	v_lshlrev_b32_e32 v208, 16, v8
	v_and_b32_e32 v209, 0xffff0000, v8
	v_lshlrev_b32_e32 v210, 16, v9
	v_and_b32_e32 v211, 0xffff0000, v9
	v_pk_add_f32 v[224:225], v[26:27], v[208:209]
	v_pk_add_f32 v[226:227], v[22:23], v[210:211]
	v_pk_fma_f32 v[204:205], v[224:225], v[224:225], v[204:205]
	v_pk_fma_f32 v[206:207], v[226:227], v[226:227], v[206:207]
	v_lshlrev_b32_e32 v208, 16, v10
	v_and_b32_e32 v209, 0xffff0000, v10
	v_lshlrev_b32_e32 v210, 16, v11
	v_and_b32_e32 v211, 0xffff0000, v11
	v_pk_add_f32 v[242:243], v[106:107], v[208:209]
	v_pk_add_f32 v[244:245], v[108:109], v[210:211]
	v_pk_fma_f32 v[204:205], v[242:243], v[242:243], v[204:205]
	v_pk_fma_f32 v[206:207], v[244:245], v[244:245], v[206:207]
	s_nop 1
	v_add_f32_dpp v204, v204, v204 quad_perm:[1,0,3,2] row_mask:0xf bank_mask:0xf bound_ctrl:1
	v_add_f32_dpp v205, v205, v205 quad_perm:[1,0,3,2] row_mask:0xf bank_mask:0xf bound_ctrl:1
	v_add_f32_dpp v206, v206, v206 quad_perm:[1,0,3,2] row_mask:0xf bank_mask:0xf bound_ctrl:1
	v_add_f32_dpp v207, v207, v207 quad_perm:[1,0,3,2] row_mask:0xf bank_mask:0xf bound_ctrl:1
	v_add_f32_dpp v204, v204, v204 quad_perm:[2,3,0,1] row_mask:0xf bank_mask:0xf bound_ctrl:1
	v_add_f32_dpp v205, v205, v205 quad_perm:[2,3,0,1] row_mask:0xf bank_mask:0xf bound_ctrl:1
	v_add_f32_dpp v206, v206, v206 quad_perm:[2,3,0,1] row_mask:0xf bank_mask:0xf bound_ctrl:1
	v_add_f32_dpp v207, v207, v207 quad_perm:[2,3,0,1] row_mask:0xf bank_mask:0xf bound_ctrl:1
	v_add_f32_dpp v204, v204, v204 row_half_mirror row_mask:0xf bank_mask:0xf bound_ctrl:1
	v_add_f32_dpp v205, v205, v205 row_half_mirror row_mask:0xf bank_mask:0xf bound_ctrl:1
	v_add_f32_dpp v206, v206, v206 row_half_mirror row_mask:0xf bank_mask:0xf bound_ctrl:1
	v_add_f32_dpp v207, v207, v207 row_half_mirror row_mask:0xf bank_mask:0xf bound_ctrl:1
	v_add_f32_dpp v204, v204, v204 row_mirror row_mask:0xf bank_mask:0xf bound_ctrl:1
	v_add_f32_dpp v205, v205, v205 row_mirror row_mask:0xf bank_mask:0xf bound_ctrl:1
	v_add_f32_dpp v206, v206, v206 row_mirror row_mask:0xf bank_mask:0xf bound_ctrl:1
	v_add_f32_dpp v207, v207, v207 row_mirror row_mask:0xf bank_mask:0xf bound_ctrl:1
	v_fmamk_f32 v204, v204, 0x3c800000, v231
	v_fmamk_f32 v205, v205, 0x3c800000, v231
	v_fmamk_f32 v206, v206, 0x3c800000, v231
	v_fmamk_f32 v207, v207, 0x3c800000, v231
	v_rsq_f32_e32 v204, v204
	v_rsq_f32_e32 v205, v205
	v_rsq_f32_e32 v206, v206
	v_rsq_f32_e32 v207, v207
	v_lshlrev_b32_e32 v208, 16, v122
	v_lshlrev_b32_e32 v209, 16, v124
	v_lshlrev_b32_e32 v210, 16, v126
	v_lshlrev_b32_e32 v211, 16, v128
	v_pk_mul_f32 v[212:213], v[212:213], v[204:205]
	v_pk_mul_f32 v[214:215], v[214:215], v[206:207]
	v_pk_mul_f32 v[212:213], v[212:213], v[208:209]
	v_pk_mul_f32 v[214:215], v[214:215], v[210:211]
	v_and_b32_e32 v208, 0xffff0000, v122
	v_and_b32_e32 v209, 0xffff0000, v124
	v_and_b32_e32 v210, 0xffff0000, v126
	v_and_b32_e32 v211, 0xffff0000, v128
	v_pk_mul_f32 v[216:217], v[216:217], v[204:205]
	v_pk_mul_f32 v[218:219], v[218:219], v[206:207]
	v_pk_mul_f32 v[216:217], v[216:217], v[208:209]
	v_pk_mul_f32 v[218:219], v[218:219], v[210:211]
	v_lshlrev_b32_e32 v208, 16, v123
	v_lshlrev_b32_e32 v209, 16, v125
	v_lshlrev_b32_e32 v210, 16, v127
	v_lshlrev_b32_e32 v211, 16, v129
	v_pk_mul_f32 v[224:225], v[224:225], v[204:205]
	v_pk_mul_f32 v[226:227], v[226:227], v[206:207]
	v_pk_mul_f32 v[224:225], v[224:225], v[208:209]
	v_pk_mul_f32 v[226:227], v[226:227], v[210:211]
	v_and_b32_e32 v208, 0xffff0000, v123
	v_and_b32_e32 v209, 0xffff0000, v125
	v_and_b32_e32 v210, 0xffff0000, v127
	v_and_b32_e32 v211, 0xffff0000, v129
	v_pk_mul_f32 v[242:243], v[242:243], v[204:205]
	v_pk_mul_f32 v[244:245], v[244:245], v[206:207]
	v_pk_mul_f32 v[242:243], v[242:243], v[208:209]
	v_pk_mul_f32 v[244:245], v[244:245], v[210:211]
	v_cvt_pk_bf16_f32 v208, v212, v216
	v_cvt_pk_bf16_f32 v209, v224, v242
	global_store_dwordx2 v31, v[208:209], s[4:5]
	v_cvt_pk_bf16_f32 v210, v213, v217
	v_cvt_pk_bf16_f32 v211, v225, v243
	s_add_u32 s4, s1, 0xe00
	s_addc_u32 s5, s3, 0
	global_store_dwordx2 v31, v[210:211], s[4:5]
	v_cvt_pk_bf16_f32 v204, v214, v218
	v_cvt_pk_bf16_f32 v205, v226, v244
	s_add_u32 s4, s1, 0x1600
	s_addc_u32 s5, s3, 0
	global_store_dwordx2 v31, v[204:205], s[4:5]
	v_cvt_pk_bf16_f32 v206, v215, v219
	v_cvt_pk_bf16_f32 v207, v227, v245
	s_add_u32 s4, s1, 0x1e00
	s_addc_u32 s5, s3, 0
	global_store_dwordx2 v31, v[206:207], s[4:5]
	s_cbranch_execz .LBB0_474

; #define LAS __attribute__((address_space(3)))
; __device__ __forceinline__ f32x4 unpack4(const v2u w) { f32x4 r; r[0] = bflo(w.x); r[1] = bfhi(w.x); r[2] = bflo(w.y); r[3] = bfhi(w.y); return r; }
; template <class T> __device__ __forceinline__ T ldun(const void* ubase, unsigned boff) { return __builtin_nontemporal_load((const GAS T*)((const GAS char*)ubase + boff)); }
; __device__ __forceinline__ const char* upin(const char* p) { asm volatile("" : "+s"(p)); return p; }
; __device__ __forceinline__ char* upin(char* p) { asm volatile("" : "+s"(p)); return p; }
; template <bool GDN, int NT> __device__ __forceinline__ void scan_load(const Frame& F, int b, int h, int dir, const ScanLane& L, int s, ScanOps<NT>& o) {
;     ...
;         const char* base = (const char*)F.PG + (size_t)ud * 32768;
;         const char* bM = upin(base); const char* bB = upin(base + 8192); const char* bQ = upin(base + 16384); const char* bO = upin(base + 24576);
; #pragma unroll
;         for (int ks = 0; ks < 2; ++ks) { o.Mf[ks] = ldun<bf16x8>(bM + ks * 1024, L.o16); o.Qf[ks] = ldun<bf16x8>(bQ + ks * 1024, L.o16); }
; #pragma unroll
;         for (int pr = 0; pr < 2; ++pr) { const v4u qb = ldun<v4u>(bB + pr * 1024, L.o16p), qo = ldun<v4u>(bO + pr * 1024, L.o16p);
;             o.bv[2 * pr] = (v2u){qb.x, qb.y}; o.bv[2 * pr + 1] = (v2u){qb.z, qb.w}; o.ov[2 * pr] = (v2u){qo.x, qo.y}; o.ov[2 * pr + 1] = (v2u){qo.z, qo.w}; }
;         o.wi = (f32x4){1.f, 1.f, 1.f, 1.f};
;     ...
;     const float gl = ((const LAS float*)(St + 4 * 80 * 72))[(dir ? (s < 4 ? 3 - s : 39 - s) : s) * 2 + dir];
;     f32x4 O[NT];
; #pragma unroll
;     for (int t = 0; t < NT; ++t) {
;         const LAS bf16_t* sp2 = Sb + (16 * t + lr) * 72 + 8 * lq;
;         const bf16x8 s0 = *(const LAS bf16x8*)sp2, s1 = *(const LAS bf16x8*)(sp2 + 32);
;         const f32x4 bv = unpack4(use.bv[t]), ov = unpack4(use.ov[t]);
;         if (GDN) {
;             f32x4 o = ov, sn = S[t] * gl + bv;
;             o = __builtin_amdgcn_mfma_f32_16x16x32_bf16(use.Qf[0], s0, o, 0, 0, 0); o = __builtin_amdgcn_mfma_f32_16x16x32_bf16(use.Qf[1], s1, o, 0, 0, 0);
;             sn = __builtin_amdgcn_mfma_f32_16x16x32_bf16(use.Mf[0], s0, sn, 0, 0, 0); sn = __builtin_amdgcn_mfma_f32_16x16x32_bf16(use.Mf[1], s1, sn, 0, 0, 0);
;             S[t] = sn; O[t] = o;
.LBB0_481:
	s_add_i32 s0, s23, 5
	s_min_u32 s3, s0, 33
	s_add_i32 s6, s3, 2
	s_sub_i32 s3, 37, s3
	s_and_b64 s[4:5], s[90:91], exec
	s_cselect_b32 s3, s6, s3
	s_add_i32 s3, s3, s30
	s_lshl_b32 s3, s3, 1
	s_add_i32 s4, s3, s68
	s_ashr_i32 s5, s4, 31
	s_lshl_b64 s[4:5], s[4:5], 15
	s_add_u32 s4, s35, s4
	s_addc_u32 s5, s43, s5
	s_add_u32 s8, s4, 0x2000
	s_addc_u32 s9, s5, 0
	s_add_u32 s10, s4, 0x4000
	s_addc_u32 s11, s5, 0
	s_mov_b64 s[6:7], s[4:5]
	s_add_u32 s4, s4, 0x6000
	s_addc_u32 s5, s5, 0
	global_load_dwordx4 v[70:73], v18, s[8:9] nt
	global_load_dwordx4 v[66:69], v18, s[4:5] nt
	global_load_dwordx4 v[22:25], v18, s[8:9] offset:1024 nt
	s_nop 0
	global_load_dwordx4 v[18:21], v18, s[4:5] offset:1024 nt
	s_add_i32 s3, s22, 37
	s_and_b64 s[4:5], s[90:91], exec
	s_cselect_b32 s0, s0, s3
	s_lshl_b32 s0, s0, 3
	s_add_i32 s0, s34, s0
	v_lshl_add_u64 v[146:147], s[6:7], 0, v[0:1]
	v_lshl_add_u64 v[148:149], s[10:11], 0, v[0:1]
	v_mov_b32_e32 v0, s0
	ds_read_b32 v0, v0 offset:46080
	ds_read_b128 v[98:101], v200 offset:11520
	ds_read_b128 v[102:105], v200 offset:11584
	ds_read_b128 v[212:215], v200 offset:13824
	ds_read_b128 v[216:219], v200 offset:13888
	ds_read_b128 v[224:227], v200 offset:16128
	ds_read_b128 v[242:245], v200 offset:16192
	v_lshlrev_b32_e32 v110, 16, v94
	v_and_b32_e32 v111, 0xffff0000, v94
	v_lshlrev_b32_e32 v112, 16, v95
	v_and_b32_e32 v113, 0xffff0000, v95
	v_lshlrev_b32_e32 v106, 16, v86
	v_and_b32_e32 v107, 0xffff0000, v86
	v_lshlrev_b32_e32 v108, 16, v87
	v_and_b32_e32 v109, 0xffff0000, v87
	s_waitcnt lgkmcnt(6)
	v_pk_fma_f32 v[112:113], v[128:129], v[0:1], v[112:113] op_sel_hi:[1,0,1]
	v_pk_fma_f32 v[110:111], v[126:127], v[0:1], v[110:111] op_sel_hi:[1,0,1]
	s_waitcnt lgkmcnt(5)
	v_mfma_f32_16x16x32_bf16 v[106:109], v[46:49], v[98:101], v[106:109]
	s_mov_b64 s[6:7], 0x400
	v_lshl_add_u64 v[150:151], v[146:147], 0, s[6:7]
	v_lshl_add_u64 v[152:153], v[148:149], 0, s[6:7]
	v_mfma_f32_16x16x32_bf16 v[98:101], v[30:33], v[98:101], v[110:113]
	s_add_i32 s3, s22, -6
	s_mov_b64 s[20:21], 0
	s_waitcnt lgkmcnt(4)
	v_mfma_f32_16x16x32_bf16 v[130:133], v[34:37], v[102:105], v[106:109]
	v_lshlrev_b32_e32 v110, 16, v96
	v_and_b32_e32 v111, 0xffff0000, v96
	v_lshlrev_b32_e32 v112, 16, v97
	v_mfma_f32_16x16x32_bf16 v[126:129], v[26:29], v[102:105], v[98:101]
	s_nop 2
	v_and_b32_e32 v113, 0xffff0000, v97
	v_lshlrev_b32_e32 v106, 16, v88
	v_and_b32_e32 v107, 0xffff0000, v88
	v_lshlrev_b32_e32 v108, 16, v89
	v_and_b32_e32 v109, 0xffff0000, v89
	v_pk_fma_f32 v[112:113], v[124:125], v[0:1], v[112:113] op_sel_hi:[1,0,1]
	v_pk_fma_f32 v[110:111], v[122:123], v[0:1], v[110:111] op_sel_hi:[1,0,1]
	s_waitcnt lgkmcnt(3)
	v_mfma_f32_16x16x32_bf16 v[106:109], v[46:49], v[212:215], v[106:109]
	v_mfma_f32_16x16x32_bf16 v[98:101], v[30:33], v[212:215], v[110:113]
	s_waitcnt lgkmcnt(2)
	v_mfma_f32_16x16x32_bf16 v[134:137], v[34:37], v[216:219], v[106:109]
	v_lshlrev_b32_e32 v110, 16, v78
	v_and_b32_e32 v111, 0xffff0000, v78
	v_lshlrev_b32_e32 v112, 16, v79
	v_mfma_f32_16x16x32_bf16 v[122:125], v[26:29], v[216:219], v[98:101]
	ds_read_b128 v[212:215], v200 offset:18432
	ds_read_b128 v[216:219], v200 offset:18496
	s_nop 2
	v_and_b32_e32 v113, 0xffff0000, v79
	v_lshlrev_b32_e32 v106, 16, v74
	v_and_b32_e32 v107, 0xffff0000, v74
	v_lshlrev_b32_e32 v108, 16, v75
	v_and_b32_e32 v109, 0xffff0000, v75
	v_pk_fma_f32 v[112:113], v[116:117], v[0:1], v[112:113] op_sel_hi:[1,0,1]
	v_pk_fma_f32 v[110:111], v[114:115], v[0:1], v[110:111] op_sel_hi:[1,0,1]
	s_waitcnt lgkmcnt(3)
	v_mfma_f32_16x16x32_bf16 v[106:109], v[46:49], v[224:227], v[106:109]
	v_mfma_f32_16x16x32_bf16 v[98:101], v[30:33], v[224:227], v[110:113]
	s_waitcnt lgkmcnt(2)
	v_mfma_f32_16x16x32_bf16 v[138:141], v[34:37], v[242:245], v[106:109]
	s_nop 0
	v_lshlrev_b32_e32 v110, 16, v80
	v_and_b32_e32 v111, 0xffff0000, v80
	v_lshlrev_b32_e32 v112, 16, v81
	v_mfma_f32_16x16x32_bf16 v[114:117], v[26:29], v[242:245], v[98:101]
	s_nop 2
	v_and_b32_e32 v113, 0xffff0000, v81
	v_lshlrev_b32_e32 v106, 16, v76
	v_and_b32_e32 v107, 0xffff0000, v76
	v_lshlrev_b32_e32 v108, 16, v77
	v_and_b32_e32 v109, 0xffff0000, v77
	v_pk_fma_f32 v[112:113], v[120:121], v[0:1], v[112:113] op_sel_hi:[1,0,1]
	v_pk_fma_f32 v[110:111], v[118:119], v[0:1], v[110:111] op_sel_hi:[1,0,1]
	s_waitcnt lgkmcnt(1)
	v_mfma_f32_16x16x32_bf16 v[106:109], v[46:49], v[212:215], v[106:109]
	v_mfma_f32_16x16x32_bf16 v[98:101], v[30:33], v[212:215], v[110:113]
	s_waitcnt lgkmcnt(0)
	v_mfma_f32_16x16x32_bf16 v[142:145], v[34:37], v[216:219], v[106:109]
	v_mfma_f32_16x16x32_bf16 v[118:121], v[26:29], v[216:219], v[98:101]

; __device__ __forceinline__ float row16_sum(float v) { v += dppf<0xB1>(v); v += dppf<0x4E>(v); v += dppf<0x141>(v); v += dppf<0x140>(v); return v; }
; __device__ __forceinline__ float frsq(float x) { return __builtin_amdgcn_rsqf(x); }
; __device__ __forceinline__ v2u pack4(const f32x4 v) { v2u r; r.x = pk2(v[0], v[1]); r.y = pk2(v[2], v[3]); return r; }
; __device__ __forceinline__ f32x4 unpack4(const v2u w) { f32x4 r; r[0] = bflo(w.x); r[1] = bfhi(w.x); r[2] = bflo(w.y); r[3] = bfhi(w.y); return r; }
; __device__ __forceinline__ const char* upin(const char* p) { asm volatile("" : "+s"(p)); return p; }
; __device__ __forceinline__ char* upin(char* p) { asm volatile("" : "+s"(p)); return p; }
; template <bool GDN> __device__ __forceinline__ void scan_finish(const Frame& F, int b, int h, int dir, const ScanLane& L, int s, float* PEND, const f32x4 (&Oin)[4], const ScanFin& f) {
;     ...
;         f32x4 O[4]; float ss[4] = {0.f, 0.f, 0.f, 0.f};
; #pragma unroll
;         for (int t = 0; t < 4; ++t)
;             { const f32x4 pv = unpack4(f.pend[t]);
; #pragma unroll
;             for (int i = 0; i < 4; ++i) { O[t][i] = Oin[t][i] + pv[i]; ss[i] += O[t][i] * O[t][i]; } }
; #pragma unroll
;         for (int i = 0; i < 4; ++i) ss[i] = frsq(row16_sum(ss[i]) * (1.f / 64.f) + EPS);
;         char* mp = (char*)F.MIX + ((size_t)row0 * 1024 + (GDN ? 0 : 768) + h * 64) * 2;
; #pragma unroll
;         for (int i = 0; i < 4; ++i) { const f32x4 g = unpack4(f.gz[i]); f32x4 ov;
; #pragma unroll
;             for (int t = 0; t < 4; ++t) ov[t] = O[t][i] * ss[i] * g[t];
;             stu<v2u>(upin(mp + i * 2048), L.mix, pack4(ov)); }
.LBB0_487:
	s_add_i32 s0, s23, -1
	s_cmp_eq_u32 s23, 0
	s_cselect_b64 s[10:11], -1, 0
	s_and_b64 vcc, exec, s[10:11]
	s_waitcnt lgkmcnt(0)
	s_barrier
	s_cbranch_vccnz .LBB0_492
	s_add_i32 s1, s22, 43
	s_and_b64 s[4:5], s[90:91], exec
	s_cselect_b32 s1, s0, s1
	s_cmp_lt_u32 s23, 5
	s_cselect_b32 s3, 2, 20
	s_cmp_lt_u32 s0, s3
	s_mov_b64 s[12:13], -1
	s_cbranch_scc1 .LBB0_490
	s_cmp_lt_i32 s1, 4
	s_cselect_b32 s3, s25, s24
	s_lshl_b32 s4, s1, 6
	s_add_i32 s4, s3, s4
	s_ashr_i32 s5, s4, 31
	s_lshl_b64 s[4:5], s[4:5], 11
	s_add_u32 s18, s26, s4
	s_addc_u32 s19, s27, s5
	s_mov_b64 s[4:5], s[18:19]
	v_lshlrev_b32_e32 v208, 16, v10
	v_and_b32_e32 v209, 0xffff0000, v10
	v_lshlrev_b32_e32 v210, 16, v11
	v_and_b32_e32 v211, 0xffff0000, v11
	v_pk_add_f32 v[212:213], v[130:131], v[208:209]
	v_pk_add_f32 v[214:215], v[132:133], v[210:211]
	v_pk_mul_f32 v[204:205], v[212:213], v[212:213]
	v_pk_mul_f32 v[206:207], v[214:215], v[214:215]
	v_lshlrev_b32_e32 v208, 16, v12
	v_and_b32_e32 v209, 0xffff0000, v12
	v_lshlrev_b32_e32 v210, 16, v13
	v_and_b32_e32 v211, 0xffff0000, v13
	v_pk_add_f32 v[216:217], v[134:135], v[208:209]
	v_pk_add_f32 v[218:219], v[136:137], v[210:211]
	v_pk_fma_f32 v[204:205], v[216:217], v[216:217], v[204:205]
	v_pk_fma_f32 v[206:207], v[218:219], v[218:219], v[206:207]
	v_lshlrev_b32_e32 v208, 16, v14
	v_and_b32_e32 v209, 0xffff0000, v14
	v_lshlrev_b32_e32 v210, 16, v15
	v_and_b32_e32 v211, 0xffff0000, v15
	v_pk_add_f32 v[224:225], v[138:139], v[208:209]
	v_pk_add_f32 v[226:227], v[140:141], v[210:211]
	v_pk_fma_f32 v[204:205], v[224:225], v[224:225], v[204:205]
	v_pk_fma_f32 v[206:207], v[226:227], v[226:227], v[206:207]
	v_lshlrev_b32_e32 v208, 16, v16
	v_and_b32_e32 v209, 0xffff0000, v16
	v_lshlrev_b32_e32 v210, 16, v17
	v_and_b32_e32 v211, 0xffff0000, v17
	v_pk_add_f32 v[242:243], v[142:143], v[208:209]
	v_pk_add_f32 v[244:245], v[144:145], v[210:211]
	v_pk_fma_f32 v[204:205], v[242:243], v[242:243], v[204:205]
	v_pk_fma_f32 v[206:207], v[244:245], v[244:245], v[206:207]
	s_nop 1
	v_add_f32_dpp v204, v204, v204 quad_perm:[1,0,3,2] row_mask:0xf bank_mask:0xf bound_ctrl:1
	v_add_f32_dpp v205, v205, v205 quad_perm:[1,0,3,2] row_mask:0xf bank_mask:0xf bound_ctrl:1
	v_add_f32_dpp v206, v206, v206 quad_perm:[1,0,3,2] row_mask:0xf bank_mask:0xf bound_ctrl:1
	v_add_f32_dpp v207, v207, v207 quad_perm:[1,0,3,2] row_mask:0xf bank_mask:0xf bound_ctrl:1
	v_add_f32_dpp v204, v204, v204 quad_perm:[2,3,0,1] row_mask:0xf bank_mask:0xf bound_ctrl:1
	v_add_f32_dpp v205, v205, v205 quad_perm:[2,3,0,1] row_mask:0xf bank_mask:0xf bound_ctrl:1
	v_add_f32_dpp v206, v206, v206 quad_perm:[2,3,0,1] row_mask:0xf bank_mask:0xf bound_ctrl:1
	v_add_f32_dpp v207, v207, v207 quad_perm:[2,3,0,1] row_mask:0xf bank_mask:0xf bound_ctrl:1
	v_add_f32_dpp v204, v204, v204 row_half_mirror row_mask:0xf bank_mask:0xf bound_ctrl:1
	v_add_f32_dpp v205, v205, v205 row_half_mirror row_mask:0xf bank_mask:0xf bound_ctrl:1
	v_add_f32_dpp v206, v206, v206 row_half_mirror row_mask:0xf bank_mask:0xf bound_ctrl:1
	v_add_f32_dpp v207, v207, v207 row_half_mirror row_mask:0xf bank_mask:0xf bound_ctrl:1
	v_add_f32_dpp v204, v204, v204 row_mirror row_mask:0xf bank_mask:0xf bound_ctrl:1
	v_add_f32_dpp v205, v205, v205 row_mirror row_mask:0xf bank_mask:0xf bound_ctrl:1
	v_add_f32_dpp v206, v206, v206 row_mirror row_mask:0xf bank_mask:0xf bound_ctrl:1
	v_add_f32_dpp v207, v207, v207 row_mirror row_mask:0xf bank_mask:0xf bound_ctrl:1
	v_fmamk_f32 v204, v204, 0x3c800000, v231
	v_fmamk_f32 v205, v205, 0x3c800000, v231
	v_fmamk_f32 v206, v206, 0x3c800000, v231
	v_fmamk_f32 v207, v207, 0x3c800000, v231
	v_rsq_f32_e32 v204, v204
	v_rsq_f32_e32 v205, v205
	v_rsq_f32_e32 v206, v206
	v_rsq_f32_e32 v207, v207
	v_lshlrev_b32_e32 v208, 16, v164
	v_lshlrev_b32_e32 v209, 16, v178
	v_lshlrev_b32_e32 v210, 16, v180
	v_lshlrev_b32_e32 v211, 16, v182
	v_pk_mul_f32 v[212:213], v[212:213], v[204:205]
	v_pk_mul_f32 v[214:215], v[214:215], v[206:207]
	v_pk_mul_f32 v[212:213], v[212:213], v[208:209]
	v_pk_mul_f32 v[214:215], v[214:215], v[210:211]
	v_and_b32_e32 v208, 0xffff0000, v164
	v_and_b32_e32 v209, 0xffff0000, v178
	v_and_b32_e32 v210, 0xffff0000, v180
	v_and_b32_e32 v211, 0xffff0000, v182
	v_pk_mul_f32 v[216:217], v[216:217], v[204:205]
	v_pk_mul_f32 v[218:219], v[218:219], v[206:207]
	v_pk_mul_f32 v[216:217], v[216:217], v[208:209]
	v_pk_mul_f32 v[218:219], v[218:219], v[210:211]
	v_lshlrev_b32_e32 v208, 16, v165
	v_lshlrev_b32_e32 v209, 16, v179
	v_lshlrev_b32_e32 v210, 16, v181
	v_lshlrev_b32_e32 v211, 16, v183
	v_pk_mul_f32 v[224:225], v[224:225], v[204:205]
	v_pk_mul_f32 v[226:227], v[226:227], v[206:207]
	v_pk_mul_f32 v[224:225], v[224:225], v[208:209]
	v_pk_mul_f32 v[226:227], v[226:227], v[210:211]
	v_and_b32_e32 v208, 0xffff0000, v165
	v_and_b32_e32 v209, 0xffff0000, v179
	v_and_b32_e32 v210, 0xffff0000, v181
	v_and_b32_e32 v211, 0xffff0000, v183
	v_pk_mul_f32 v[242:243], v[242:243], v[204:205]
	v_pk_mul_f32 v[244:245], v[244:245], v[206:207]
	v_pk_mul_f32 v[242:243], v[242:243], v[208:209]
	v_pk_mul_f32 v[244:245], v[244:245], v[210:211]
	v_cvt_pk_bf16_f32 v208, v212, v216
	v_cvt_pk_bf16_f32 v209, v224, v242
	global_store_dwordx2 v149, v[208:209], s[4:5]
	v_cvt_pk_bf16_f32 v210, v213, v217
	v_cvt_pk_bf16_f32 v211, v225, v243
	s_add_u32 s4, s18, 0x800
	s_addc_u32 s5, s19, 0
	global_store_dwordx2 v149, v[210:211], s[4:5]
	v_cvt_pk_bf16_f32 v204, v214, v218
	v_cvt_pk_bf16_f32 v205, v226, v244
	s_mov_b64 s[12:13], 0
	s_add_u32 s4, s18, 0x1000
	s_addc_u32 s5, s19, 0
	global_store_dwordx2 v149, v[204:205], s[4:5]
	v_cvt_pk_bf16_f32 v206, v215, v219
	v_cvt_pk_bf16_f32 v207, v227, v245
	s_add_u32 s4, s18, 0x1800
	s_addc_u32 s5, s19, 0
	global_store_dwordx2 v149, v[206:207], s[4:5]

; #define LAS __attribute__((address_space(3)))
; __device__ __forceinline__ f32x4 unpack4(const v2u w) { f32x4 r; r[0] = bflo(w.x); r[1] = bfhi(w.x); r[2] = bflo(w.y); r[3] = bfhi(w.y); return r; }
; template <class T> __device__ __forceinline__ T ldun(const void* ubase, unsigned boff) { return __builtin_nontemporal_load((const GAS T*)((const GAS char*)ubase + boff)); }
; __device__ __forceinline__ const char* upin(const char* p) { asm volatile("" : "+s"(p)); return p; }
; __device__ __forceinline__ char* upin(char* p) { asm volatile("" : "+s"(p)); return p; }
; template <bool GDN, int NT> __device__ __forceinline__ void scan_load(const Frame& F, int b, int h, int dir, const ScanLane& L, int s, ScanOps<NT>& o) {
;     ...
;         const char* base = (const char*)F.PG + (size_t)ud * 32768;
;         const char* bM = upin(base); const char* bB = upin(base + 8192); const char* bQ = upin(base + 16384); const char* bO = upin(base + 24576);
; #pragma unroll
;         for (int ks = 0; ks < 2; ++ks) { o.Mf[ks] = ldun<bf16x8>(bM + ks * 1024, L.o16); o.Qf[ks] = ldun<bf16x8>(bQ + ks * 1024, L.o16); }
; #pragma unroll
;         for (int pr = 0; pr < 2; ++pr) { const v4u qb = ldun<v4u>(bB + pr * 1024, L.o16p), qo = ldun<v4u>(bO + pr * 1024, L.o16p);
;             o.bv[2 * pr] = (v2u){qb.x, qb.y}; o.bv[2 * pr + 1] = (v2u){qb.z, qb.w}; o.ov[2 * pr] = (v2u){qo.x, qo.y}; o.ov[2 * pr + 1] = (v2u){qo.z, qo.w}; }
;         o.wi = (f32x4){1.f, 1.f, 1.f, 1.f};
;     ...
;     const float gl = ((const LAS float*)(St + 4 * 80 * 72))[(dir ? (s < 4 ? 3 - s : 39 - s) : s) * 2 + dir];
;     f32x4 O[NT];
; #pragma unroll
;     for (int t = 0; t < NT; ++t) {
;         const LAS bf16_t* sp2 = Sb + (16 * t + lr) * 72 + 8 * lq;
;         const bf16x8 s0 = *(const LAS bf16x8*)sp2, s1 = *(const LAS bf16x8*)(sp2 + 32);
;         const f32x4 bv = unpack4(use.bv[t]), ov = unpack4(use.ov[t]);
;         if (GDN) {
;             f32x4 o = ov, sn = S[t] * gl + bv;
;             o = __builtin_amdgcn_mfma_f32_16x16x32_bf16(use.Qf[0], s0, o, 0, 0, 0); o = __builtin_amdgcn_mfma_f32_16x16x32_bf16(use.Qf[1], s1, o, 0, 0, 0);
;             sn = __builtin_amdgcn_mfma_f32_16x16x32_bf16(use.Mf[0], s0, sn, 0, 0, 0); sn = __builtin_amdgcn_mfma_f32_16x16x32_bf16(use.Mf[1], s1, sn, 0, 0, 0);
;             S[t] = sn; O[t] = o;
.LBB0_496:
	s_min_u32 s1, s23, 33
	s_add_i32 s1, s1, 2
	s_and_b64 s[4:5], exec, s[10:11]
	s_cselect_b32 s3, 3, 39
	s_sub_i32 s3, s3, s1
	s_and_b64 s[4:5], s[90:91], exec
	s_cselect_b32 s1, s1, s3
	s_add_i32 s1, s1, s30
	s_lshl_b32 s1, s1, 1
	s_add_i32 s4, s1, s68
	s_ashr_i32 s5, s4, 31
	s_lshl_b64 s[4:5], s[4:5], 15
	s_add_u32 s4, s35, s4
	s_addc_u32 s5, s43, s5
	s_add_u32 s8, s4, 0x2000
	s_addc_u32 s9, s5, 0
	s_add_u32 s12, s4, 0x4000
	s_addc_u32 s13, s5, 0
	s_mov_b64 s[6:7], s[4:5]
	s_add_u32 s4, s4, 0x6000
	s_addc_u32 s5, s5, 0
	global_load_dwordx4 v[30:33], v146, s[6:7] nt
	global_load_dwordx4 v[46:49], v146, s[12:13] nt
	global_load_dwordx4 v[26:29], v146, s[6:7] offset:1024 nt
	global_load_dwordx4 v[34:37], v146, s[12:13] offset:1024 nt
	global_load_dwordx4 v[94:97], v0, s[8:9] nt
	global_load_dwordx4 v[86:89], v0, s[4:5] nt
	global_load_dwordx4 v[78:81], v0, s[8:9] offset:1024 nt
	global_load_dwordx4 v[74:77], v0, s[4:5] offset:1024 nt
	s_cmp_gt_u32 s23, 3
	s_cselect_b32 s1, 39, 3
	s_add_i32 s1, s1, s22
	s_add_i32 s1, s1, 3
	s_and_b64 s[4:5], s[90:91], exec
	s_cselect_b32 s1, s23, s1
	s_lshl_b32 s1, s1, 3
	s_add_i32 s1, s34, s1
	v_mov_b32_e32 v0, s1
	ds_read_b32 v0, v0 offset:46080
	v_add_u32_e32 v146, v198, v155
	ds_read_b128 v[134:137], v146
	ds_read_b128 v[138:141], v146 offset:64
	ds_read_b128 v[212:215], v146 offset:2304
	ds_read_b128 v[216:219], v146 offset:2368
	ds_read_b128 v[224:227], v146 offset:4608
	ds_read_b128 v[242:245], v146 offset:4672
	v_lshlrev_b32_e32 v142, 16, v90
	v_and_b32_e32 v143, 0xffff0000, v90
	v_lshlrev_b32_e32 v90, 16, v91
	v_and_b32_e32 v91, 0xffff0000, v91
	v_lshlrev_b32_e32 v130, 16, v82
	v_and_b32_e32 v131, 0xffff0000, v82
	v_lshlrev_b32_e32 v132, 16, v83
	v_and_b32_e32 v133, 0xffff0000, v83
	s_waitcnt lgkmcnt(6)
	v_pk_fma_f32 v[128:129], v[128:129], v[0:1], v[90:91] op_sel_hi:[1,0,1]
	v_pk_fma_f32 v[126:127], v[126:127], v[0:1], v[142:143] op_sel_hi:[1,0,1]
	s_waitcnt lgkmcnt(5)
	v_mfma_f32_16x16x32_bf16 v[130:133], v[58:61], v[134:137], v[130:133]
	v_lshlrev_b32_e32 v82, 16, v84
	v_and_b32_e32 v83, 0xffff0000, v84
	v_lshlrev_b32_e32 v84, 16, v85
	v_mfma_f32_16x16x32_bf16 v[126:129], v[42:45], v[134:137], v[126:129]
	v_and_b32_e32 v85, 0xffff0000, v85
	v_lshlrev_b32_e32 v90, 16, v92
	v_and_b32_e32 v91, 0xffff0000, v92
	s_waitcnt lgkmcnt(4)
	v_mfma_f32_16x16x32_bf16 v[130:133], v[50:53], v[138:141], v[130:133]
	v_lshlrev_b32_e32 v92, 16, v93
	v_and_b32_e32 v93, 0xffff0000, v93
	v_pk_fma_f32 v[92:93], v[124:125], v[0:1], v[92:93] op_sel_hi:[1,0,1]
	v_mfma_f32_16x16x32_bf16 v[126:129], v[38:41], v[138:141], v[126:129]
	v_pk_fma_f32 v[90:91], v[122:123], v[0:1], v[90:91] op_sel_hi:[1,0,1]
	s_waitcnt lgkmcnt(3)
	v_mfma_f32_16x16x32_bf16 v[82:85], v[58:61], v[212:215], v[82:85]
	s_waitcnt lgkmcnt(2)
	v_mfma_f32_16x16x32_bf16 v[134:137], v[50:53], v[216:219], v[82:85]
	v_mfma_f32_16x16x32_bf16 v[82:85], v[42:45], v[212:215], v[90:93]
	v_lshlrev_b32_e32 v138, 16, v54
	v_and_b32_e32 v139, 0xffff0000, v54
	v_lshlrev_b32_e32 v140, 16, v55
	v_mfma_f32_16x16x32_bf16 v[122:125], v[38:41], v[216:219], v[82:85]
	ds_read_b128 v[212:215], v146 offset:6912
	ds_read_b128 v[216:219], v146 offset:6976
	s_nop 2
	v_lshlrev_b32_e32 v142, 16, v62
	v_and_b32_e32 v143, 0xffff0000, v62
	v_lshlrev_b32_e32 v62, 16, v63
	v_and_b32_e32 v63, 0xffff0000, v63
	v_and_b32_e32 v141, 0xffff0000, v55
	v_pk_fma_f32 v[116:117], v[116:117], v[0:1], v[62:63] op_sel_hi:[1,0,1]
	v_pk_fma_f32 v[114:115], v[114:115], v[0:1], v[142:143] op_sel_hi:[1,0,1]
	s_waitcnt lgkmcnt(3)
	v_mfma_f32_16x16x32_bf16 v[138:141], v[58:61], v[224:227], v[138:141]
	v_lshlrev_b32_e32 v62, 16, v64
	v_and_b32_e32 v63, 0xffff0000, v64
	v_lshlrev_b32_e32 v64, 16, v65
	v_mfma_f32_16x16x32_bf16 v[82:85], v[42:45], v[224:227], v[114:117]
	v_and_b32_e32 v65, 0xffff0000, v65
	v_lshlrev_b32_e32 v54, 16, v56
	v_and_b32_e32 v55, 0xffff0000, v56
	s_waitcnt lgkmcnt(2)
	v_mfma_f32_16x16x32_bf16 v[138:141], v[50:53], v[242:245], v[138:141]
	v_lshlrev_b32_e32 v56, 16, v57
	v_and_b32_e32 v57, 0xffff0000, v57
	v_pk_fma_f32 v[64:65], v[120:121], v[0:1], v[64:65] op_sel_hi:[1,0,1]
	v_mfma_f32_16x16x32_bf16 v[114:117], v[38:41], v[242:245], v[82:85]
	s_nop 2
	v_pk_fma_f32 v[62:63], v[118:119], v[0:1], v[62:63] op_sel_hi:[1,0,1]
	s_waitcnt lgkmcnt(1)
	v_mfma_f32_16x16x32_bf16 v[54:57], v[58:61], v[212:215], v[54:57]
	v_mfma_f32_16x16x32_bf16 v[42:45], v[42:45], v[212:215], v[62:65]
	s_waitcnt lgkmcnt(0)
	v_mfma_f32_16x16x32_bf16 v[142:145], v[50:53], v[216:219], v[54:57]
	v_mfma_f32_16x16x32_bf16 v[118:121], v[38:41], v[216:219], v[42:45]
.LBB0_497:
	s_mov_b64 s[20:21], -1
	v_readfirstlane_b32 s1, v0
	s_andn2_b64 vcc, exec, s[18:19]
	v_readfirstlane_b32 s3, v0
	s_cbranch_vccnz .LBB0_482
	v_mov_b32_e32 v50, v154
	v_mov_b32_e32 v40, v197
	v_mov_b32_e32 v0, v192
	v_mov_b32_e32 v39, v192
	v_mov_b32_e32 v41, v196
	v_mov_b32_e32 v38, v194
	v_mov_b32_e32 v42, v193
	v_mov_b32_e32 v43, v195
	s_add_i32 s4, s23, 1
	v_cvt_pk_bf16_f32 v42, v126, v127
	v_cvt_pk_bf16_f32 v43, v128, v129
	ds_write_b64 v199, v[42:43] offset:11520
	v_cvt_pk_bf16_f32 v42, v122, v123
	v_cvt_pk_bf16_f32 v43, v124, v125
	ds_write_b64 v199, v[42:43] offset:13824
	v_cvt_pk_bf16_f32 v42, v114, v115
	v_cvt_pk_bf16_f32 v43, v116, v117
	ds_write_b64 v199, v[42:43] offset:16128
	v_cvt_pk_bf16_f32 v42, v118, v119
	v_cvt_pk_bf16_f32 v43, v120, v121
	s_cmp_lt_i32 s4, 21
	ds_write_b64 v199, v[42:43] offset:18432
	s_cbranch_scc1 .LBB0_502
	s_cmp_lg_u32 s4, 21
	s_mov_b64 s[12:13], -1
	s_cselect_b64 s[14:15], -1, 0
	s_cbranch_execz .LBB0_503
	s_branch .LBB0_504

; __device__ __forceinline__ float row16_sum(float v) { v += dppf<0xB1>(v); v += dppf<0x4E>(v); v += dppf<0x141>(v); v += dppf<0x140>(v); return v; }
; __device__ __forceinline__ float frsq(float x) { return __builtin_amdgcn_rsqf(x); }
; __device__ __forceinline__ v2u pack4(const f32x4 v) { v2u r; r.x = pk2(v[0], v[1]); r.y = pk2(v[2], v[3]); return r; }
; __device__ __forceinline__ f32x4 unpack4(const v2u w) { f32x4 r; r[0] = bflo(w.x); r[1] = bfhi(w.x); r[2] = bflo(w.y); r[3] = bfhi(w.y); return r; }
; __device__ __forceinline__ const char* upin(const char* p) { asm volatile("" : "+s"(p)); return p; }
; __device__ __forceinline__ char* upin(char* p) { asm volatile("" : "+s"(p)); return p; }
; template <bool GDN> __device__ __forceinline__ void scan_finish(const Frame& F, int b, int h, int dir, const ScanLane& L, int s, float* PEND, const f32x4 (&Oin)[4], const ScanFin& f) {
;     ...
;         f32x4 O[4]; float ss[4] = {0.f, 0.f, 0.f, 0.f};
; #pragma unroll
;         for (int t = 0; t < 4; ++t)
;             { const f32x4 pv = unpack4(f.pend[t]);
; #pragma unroll
;             for (int i = 0; i < 4; ++i) { O[t][i] = Oin[t][i] + pv[i]; ss[i] += O[t][i] * O[t][i]; } }
; #pragma unroll
;         for (int i = 0; i < 4; ++i) ss[i] = frsq(row16_sum(ss[i]) * (1.f / 64.f) + EPS);
;         char* mp = (char*)F.MIX + ((size_t)row0 * 1024 + (GDN ? 0 : 768) + h * 64) * 2;
; #pragma unroll
;         for (int i = 0; i < 4; ++i) { const f32x4 g = unpack4(f.gz[i]); f32x4 ov;
; #pragma unroll
;             for (int t = 0; t < 4; ++t) ov[t] = O[t][i] * ss[i] * g[t];
;             stu<v2u>(upin(mp + i * 2048), L.mix, pack4(ov)); }
.LBB0_520:
	s_cmp_gt_u32 s23, 3
	s_cselect_b32 s5, 39, 3
	s_add_i32 s5, s5, s22
	s_add_i32 s1, s5, 3
	s_and_b64 s[6:7], s[90:91], exec
	s_cselect_b32 s1, s23, s1
	s_cmp_lt_u32 s4, 5
	s_cselect_b32 s3, 2, 20
	s_cmp_lt_u32 s23, s3
	s_mov_b64 s[12:13], -1
	s_cbranch_scc1 .LBB0_522
	s_cmp_lt_i32 s1, 4
	s_cselect_b32 s3, s25, s24
	s_lshl_b32 s6, s1, 6
	s_add_i32 s6, s3, s6
	s_ashr_i32 s7, s6, 31
	s_lshl_b64 s[6:7], s[6:7], 11
	s_add_u32 s18, s26, s6
	s_addc_u32 s19, s27, s7
	s_mov_b64 s[6:7], s[18:19]
	v_lshlrev_b32_e32 v208, 16, v2
	v_and_b32_e32 v209, 0xffff0000, v2
	v_lshlrev_b32_e32 v210, 16, v3
	v_and_b32_e32 v211, 0xffff0000, v3
	v_pk_add_f32 v[212:213], v[130:131], v[208:209]
	v_pk_add_f32 v[214:215], v[132:133], v[210:211]
	v_pk_mul_f32 v[204:205], v[212:213], v[212:213]
	v_pk_mul_f32 v[206:207], v[214:215], v[214:215]
	v_lshlrev_b32_e32 v208, 16, v4
	v_and_b32_e32 v209, 0xffff0000, v4
	v_lshlrev_b32_e32 v210, 16, v5
	v_and_b32_e32 v211, 0xffff0000, v5
	v_pk_add_f32 v[216:217], v[134:135], v[208:209]
	v_pk_add_f32 v[218:219], v[136:137], v[210:211]
	v_pk_fma_f32 v[204:205], v[216:217], v[216:217], v[204:205]
	v_pk_fma_f32 v[206:207], v[218:219], v[218:219], v[206:207]
	v_lshlrev_b32_e32 v208, 16, v6
	v_and_b32_e32 v209, 0xffff0000, v6
	v_lshlrev_b32_e32 v210, 16, v7
	v_and_b32_e32 v211, 0xffff0000, v7
	v_pk_add_f32 v[224:225], v[138:139], v[208:209]
	v_pk_add_f32 v[226:227], v[140:141], v[210:211]
	v_pk_fma_f32 v[204:205], v[224:225], v[224:225], v[204:205]
	v_pk_fma_f32 v[206:207], v[226:227], v[226:227], v[206:207]
	v_lshlrev_b32_e32 v208, 16, v8
	v_and_b32_e32 v209, 0xffff0000, v8
	v_lshlrev_b32_e32 v210, 16, v9
	v_and_b32_e32 v211, 0xffff0000, v9
	v_pk_add_f32 v[242:243], v[142:143], v[208:209]
	v_pk_add_f32 v[244:245], v[144:145], v[210:211]
	v_pk_fma_f32 v[204:205], v[242:243], v[242:243], v[204:205]
	v_pk_fma_f32 v[206:207], v[244:245], v[244:245], v[206:207]
	s_nop 1
	v_add_f32_dpp v204, v204, v204 quad_perm:[1,0,3,2] row_mask:0xf bank_mask:0xf bound_ctrl:1
	v_add_f32_dpp v205, v205, v205 quad_perm:[1,0,3,2] row_mask:0xf bank_mask:0xf bound_ctrl:1
	v_add_f32_dpp v206, v206, v206 quad_perm:[1,0,3,2] row_mask:0xf bank_mask:0xf bound_ctrl:1
	v_add_f32_dpp v207, v207, v207 quad_perm:[1,0,3,2] row_mask:0xf bank_mask:0xf bound_ctrl:1
	v_add_f32_dpp v204, v204, v204 quad_perm:[2,3,0,1] row_mask:0xf bank_mask:0xf bound_ctrl:1
	v_add_f32_dpp v205, v205, v205 quad_perm:[2,3,0,1] row_mask:0xf bank_mask:0xf bound_ctrl:1
	v_add_f32_dpp v206, v206, v206 quad_perm:[2,3,0,1] row_mask:0xf bank_mask:0xf bound_ctrl:1
	v_add_f32_dpp v207, v207, v207 quad_perm:[2,3,0,1] row_mask:0xf bank_mask:0xf bound_ctrl:1
	v_add_f32_dpp v204, v204, v204 row_half_mirror row_mask:0xf bank_mask:0xf bound_ctrl:1
	v_add_f32_dpp v205, v205, v205 row_half_mirror row_mask:0xf bank_mask:0xf bound_ctrl:1
	v_add_f32_dpp v206, v206, v206 row_half_mirror row_mask:0xf bank_mask:0xf bound_ctrl:1
	v_add_f32_dpp v207, v207, v207 row_half_mirror row_mask:0xf bank_mask:0xf bound_ctrl:1
	v_add_f32_dpp v204, v204, v204 row_mirror row_mask:0xf bank_mask:0xf bound_ctrl:1
	v_add_f32_dpp v205, v205, v205 row_mirror row_mask:0xf bank_mask:0xf bound_ctrl:1
	v_add_f32_dpp v206, v206, v206 row_mirror row_mask:0xf bank_mask:0xf bound_ctrl:1
	v_add_f32_dpp v207, v207, v207 row_mirror row_mask:0xf bank_mask:0xf bound_ctrl:1
	v_fmamk_f32 v204, v204, 0x3c800000, v231
	v_fmamk_f32 v205, v205, 0x3c800000, v231
	v_fmamk_f32 v206, v206, 0x3c800000, v231
	v_fmamk_f32 v207, v207, 0x3c800000, v231
	v_rsq_f32_e32 v204, v204
	v_rsq_f32_e32 v205, v205
	v_rsq_f32_e32 v206, v206
	v_rsq_f32_e32 v207, v207
	v_lshlrev_b32_e32 v208, 16, v156
	v_lshlrev_b32_e32 v209, 16, v158
	v_lshlrev_b32_e32 v210, 16, v160
	v_lshlrev_b32_e32 v211, 16, v162
	v_pk_mul_f32 v[212:213], v[212:213], v[204:205]
	v_pk_mul_f32 v[214:215], v[214:215], v[206:207]
	v_pk_mul_f32 v[212:213], v[212:213], v[208:209]
	v_pk_mul_f32 v[214:215], v[214:215], v[210:211]
	v_and_b32_e32 v208, 0xffff0000, v156
	v_and_b32_e32 v209, 0xffff0000, v158
	v_and_b32_e32 v210, 0xffff0000, v160
	v_and_b32_e32 v211, 0xffff0000, v162
	v_pk_mul_f32 v[216:217], v[216:217], v[204:205]
	v_pk_mul_f32 v[218:219], v[218:219], v[206:207]
	v_pk_mul_f32 v[216:217], v[216:217], v[208:209]
	v_pk_mul_f32 v[218:219], v[218:219], v[210:211]
	v_lshlrev_b32_e32 v208, 16, v157
	v_lshlrev_b32_e32 v209, 16, v159
	v_lshlrev_b32_e32 v210, 16, v161
	v_lshlrev_b32_e32 v211, 16, v163
	v_pk_mul_f32 v[224:225], v[224:225], v[204:205]
	v_pk_mul_f32 v[226:227], v[226:227], v[206:207]
	v_pk_mul_f32 v[224:225], v[224:225], v[208:209]
	v_pk_mul_f32 v[226:227], v[226:227], v[210:211]
	v_and_b32_e32 v208, 0xffff0000, v157
	v_and_b32_e32 v209, 0xffff0000, v159
	v_and_b32_e32 v210, 0xffff0000, v161
	v_and_b32_e32 v211, 0xffff0000, v163
	v_pk_mul_f32 v[242:243], v[242:243], v[204:205]
	v_pk_mul_f32 v[244:245], v[244:245], v[206:207]
	v_pk_mul_f32 v[242:243], v[242:243], v[208:209]
	v_pk_mul_f32 v[244:245], v[244:245], v[210:211]
	v_cvt_pk_bf16_f32 v208, v212, v216
	v_cvt_pk_bf16_f32 v209, v224, v242
	global_store_dwordx2 v40, v[208:209], s[6:7]
	v_cvt_pk_bf16_f32 v210, v213, v217
	v_cvt_pk_bf16_f32 v211, v225, v243
	s_add_u32 s6, s18, 0x800
	s_addc_u32 s7, s19, 0
	global_store_dwordx2 v40, v[210:211], s[6:7]
	v_cvt_pk_bf16_f32 v204, v214, v218
	v_cvt_pk_bf16_f32 v205, v226, v244
	s_mov_b64 s[12:13], 0
	s_add_u32 s6, s18, 0x1000
	s_addc_u32 s7, s19, 0
	global_store_dwordx2 v40, v[204:205], s[6:7]
	v_cvt_pk_bf16_f32 v206, v215, v219
	v_cvt_pk_bf16_f32 v207, v227, v245
	s_add_u32 s6, s18, 0x1800
	s_addc_u32 s7, s19, 0
	global_store_dwordx2 v40, v[206:207], s[6:7]

; #define LAS __attribute__((address_space(3)))
; __device__ __forceinline__ f32x4 unpack4(const v2u w) { f32x4 r; r[0] = bflo(w.x); r[1] = bfhi(w.x); r[2] = bflo(w.y); r[3] = bfhi(w.y); return r; }
; template <class T> __device__ __forceinline__ T ldun(const void* ubase, unsigned boff) { return __builtin_nontemporal_load((const GAS T*)((const GAS char*)ubase + boff)); }
; __device__ __forceinline__ const char* upin(const char* p) { asm volatile("" : "+s"(p)); return p; }
; __device__ __forceinline__ char* upin(char* p) { asm volatile("" : "+s"(p)); return p; }
; template <bool GDN, int NT> __device__ __forceinline__ void scan_load(const Frame& F, int b, int h, int dir, const ScanLane& L, int s, ScanOps<NT>& o) {
;     ...
;         const char* base = (const char*)F.PG + (size_t)ud * 32768;
;         const char* bM = upin(base); const char* bB = upin(base + 8192); const char* bQ = upin(base + 16384); const char* bO = upin(base + 24576);
; #pragma unroll
;         for (int ks = 0; ks < 2; ++ks) { o.Mf[ks] = ldun<bf16x8>(bM + ks * 1024, L.o16); o.Qf[ks] = ldun<bf16x8>(bQ + ks * 1024, L.o16); }
; #pragma unroll
;         for (int pr = 0; pr < 2; ++pr) { const v4u qb = ldun<v4u>(bB + pr * 1024, L.o16p), qo = ldun<v4u>(bO + pr * 1024, L.o16p);
;             o.bv[2 * pr] = (v2u){qb.x, qb.y}; o.bv[2 * pr + 1] = (v2u){qb.z, qb.w}; o.ov[2 * pr] = (v2u){qo.x, qo.y}; o.ov[2 * pr + 1] = (v2u){qo.z, qo.w}; }
;         o.wi = (f32x4){1.f, 1.f, 1.f, 1.f};
;     ...
;     const float gl = ((const LAS float*)(St + 4 * 80 * 72))[(dir ? (s < 4 ? 3 - s : 39 - s) : s) * 2 + dir];
;     f32x4 O[NT];
; #pragma unroll
;     for (int t = 0; t < NT; ++t) {
;         const LAS bf16_t* sp2 = Sb + (16 * t + lr) * 72 + 8 * lq;
;         const bf16x8 s0 = *(const LAS bf16x8*)sp2, s1 = *(const LAS bf16x8*)(sp2 + 32);
;         const f32x4 bv = unpack4(use.bv[t]), ov = unpack4(use.ov[t]);
;         if (GDN) {
;             f32x4 o = ov, sn = S[t] * gl + bv;
;             o = __builtin_amdgcn_mfma_f32_16x16x32_bf16(use.Qf[0], s0, o, 0, 0, 0); o = __builtin_amdgcn_mfma_f32_16x16x32_bf16(use.Qf[1], s1, o, 0, 0, 0);
;             sn = __builtin_amdgcn_mfma_f32_16x16x32_bf16(use.Mf[0], s0, sn, 0, 0, 0); sn = __builtin_amdgcn_mfma_f32_16x16x32_bf16(use.Mf[1], s1, sn, 0, 0, 0);
;             S[t] = sn; O[t] = o;
.LBB0_531:
	s_min_u32 s1, s4, 33
	s_add_i32 s8, s1, 2
	s_and_b64 s[6:7], exec, s[10:11]
	s_cselect_b32 s1, 3, 39
	s_sub_i32 s9, s1, s8
	s_and_b64 s[6:7], s[90:91], exec
	s_cselect_b32 s6, s8, s9
	s_add_i32 s6, s6, s30
	s_lshl_b32 s6, s6, 1
	s_add_i32 s6, s6, s68
	s_ashr_i32 s7, s6, 31
	s_lshl_b64 s[6:7], s[6:7], 15
	s_add_u32 s6, s35, s6
	s_addc_u32 s7, s43, s7
	s_add_u32 s10, s6, 0x2000
	s_addc_u32 s11, s7, 0
	s_add_u32 s12, s6, 0x4000
	s_addc_u32 s13, s7, 0
	s_mov_b64 s[8:9], s[6:7]
	s_add_u32 s6, s6, 0x6000
	s_addc_u32 s7, s7, 0
	global_load_dwordx4 v[42:45], v50, s[8:9] nt
	global_load_dwordx4 v[58:61], v50, s[12:13] nt
	global_load_dwordx4 v[38:41], v50, s[8:9] offset:1024 nt
	s_nop 0
	global_load_dwordx4 v[50:53], v50, s[12:13] offset:1024 nt
	s_nop 0
	global_load_dwordx4 v[90:93], v0, s[10:11] nt
	global_load_dwordx4 v[82:85], v0, s[6:7] nt
	global_load_dwordx4 v[62:65], v0, s[10:11] offset:1024 nt
	global_load_dwordx4 v[54:57], v0, s[6:7] offset:1024 nt
	s_add_i32 s5, s5, 2
	s_and_b64 s[6:7], s[90:91], exec
	s_cselect_b32 s5, s4, s5
	s_lshl_b32 s6, s5, 3
	s_add_i32 s6, s34, s6
	v_mov_b32_e32 v0, s6
	ds_read_b32 v0, v0 offset:46080
	v_add_u32_e32 v200, v198, v155
	ds_read_b128 v[134:137], v200 offset:11520
	ds_read_b128 v[138:141], v200 offset:11584
	ds_read_b128 v[212:215], v200 offset:13824
	ds_read_b128 v[216:219], v200 offset:13888
	ds_read_b128 v[224:227], v200 offset:16128
	ds_read_b128 v[242:245], v200 offset:16192
	v_lshlrev_b32_e32 v142, 16, v70
	v_and_b32_e32 v143, 0xffff0000, v70
	v_lshlrev_b32_e32 v144, 16, v71
	v_and_b32_e32 v145, 0xffff0000, v71
	v_lshlrev_b32_e32 v130, 16, v66
	v_and_b32_e32 v131, 0xffff0000, v66
	v_lshlrev_b32_e32 v132, 16, v67
	v_and_b32_e32 v133, 0xffff0000, v67
	s_waitcnt lgkmcnt(6)
	v_pk_fma_f32 v[128:129], v[128:129], v[0:1], v[144:145] op_sel_hi:[1,0,1]
	v_pk_fma_f32 v[126:127], v[126:127], v[0:1], v[142:143] op_sel_hi:[1,0,1]
	s_waitcnt lgkmcnt(5)
	v_mfma_f32_16x16x32_bf16 v[130:133], v[110:113], v[134:137], v[130:133]
	v_lshlrev_b32_e32 v146, 16, v72
	v_and_b32_e32 v147, 0xffff0000, v72
	v_lshlrev_b32_e32 v148, 16, v73
	v_mfma_f32_16x16x32_bf16 v[126:129], v[102:105], v[134:137], v[126:129]
	v_and_b32_e32 v149, 0xffff0000, v73
	v_lshlrev_b32_e32 v134, 16, v68
	v_and_b32_e32 v135, 0xffff0000, v68
	s_waitcnt lgkmcnt(4)
	v_mfma_f32_16x16x32_bf16 v[130:133], v[106:109], v[138:141], v[130:133]
	v_lshlrev_b32_e32 v136, 16, v69
	v_and_b32_e32 v137, 0xffff0000, v69
	v_pk_fma_f32 v[124:125], v[124:125], v[0:1], v[148:149] op_sel_hi:[1,0,1]
	v_mfma_f32_16x16x32_bf16 v[126:129], v[98:101], v[138:141], v[126:129]
	v_pk_fma_f32 v[122:123], v[122:123], v[0:1], v[146:147] op_sel_hi:[1,0,1]
	v_lshlrev_b32_e32 v150, 16, v22
	s_waitcnt lgkmcnt(3)
	v_mfma_f32_16x16x32_bf16 v[134:137], v[110:113], v[212:215], v[134:137]
	v_and_b32_e32 v151, 0xffff0000, v22
	v_lshlrev_b32_e32 v152, 16, v23
	v_and_b32_e32 v153, 0xffff0000, v23
	v_mfma_f32_16x16x32_bf16 v[122:125], v[102:105], v[212:215], v[122:125]
	v_lshlrev_b32_e32 v138, 16, v18
	v_and_b32_e32 v139, 0xffff0000, v18
	v_lshlrev_b32_e32 v140, 16, v19
	s_waitcnt lgkmcnt(2)
	v_mfma_f32_16x16x32_bf16 v[134:137], v[106:109], v[216:219], v[134:137]
	v_and_b32_e32 v141, 0xffff0000, v19
	v_pk_fma_f32 v[116:117], v[116:117], v[0:1], v[152:153] op_sel_hi:[1,0,1]
	v_pk_fma_f32 v[114:115], v[114:115], v[0:1], v[150:151] op_sel_hi:[1,0,1]
	v_mfma_f32_16x16x32_bf16 v[122:125], v[98:101], v[216:219], v[122:125]
	ds_read_b128 v[212:215], v200 offset:18432
	ds_read_b128 v[216:219], v200 offset:18496
	v_lshlrev_b32_e32 v166, 16, v24
	v_and_b32_e32 v167, 0xffff0000, v24
	s_waitcnt lgkmcnt(3)
	v_mfma_f32_16x16x32_bf16 v[138:141], v[110:113], v[224:227], v[138:141]
	v_lshlrev_b32_e32 v168, 16, v25
	v_and_b32_e32 v169, 0xffff0000, v25
	v_pk_fma_f32 v[120:121], v[120:121], v[0:1], v[168:169] op_sel_hi:[1,0,1]
	v_mfma_f32_16x16x32_bf16 v[114:117], v[102:105], v[224:227], v[114:117]
	v_lshlrev_b32_e32 v142, 16, v20
	v_and_b32_e32 v143, 0xffff0000, v20
	v_lshlrev_b32_e32 v144, 16, v21
	s_waitcnt lgkmcnt(2)
	v_mfma_f32_16x16x32_bf16 v[138:141], v[106:109], v[242:245], v[138:141]
	v_and_b32_e32 v145, 0xffff0000, v21
	v_pk_fma_f32 v[118:119], v[118:119], v[0:1], v[166:167] op_sel_hi:[1,0,1]
	v_mov_b32_e32 v201, v154
	v_mfma_f32_16x16x32_bf16 v[114:117], v[98:101], v[242:245], v[114:117]
	v_mov_b32_e32 v0, v192
	v_mov_b32_e32 v202, v194
	s_waitcnt lgkmcnt(1)
	v_mfma_f32_16x16x32_bf16 v[142:145], v[110:113], v[212:215], v[142:145]
	s_cmp_gt_u32 s23, 33
	v_mfma_f32_16x16x32_bf16 v[118:121], v[102:105], v[212:215], v[118:121]
	v_mov_b32_e32 v147, v193
	v_mov_b32_e32 v148, v195
	v_mov_b32_e32 v146, v197
	s_waitcnt lgkmcnt(0)
	v_mfma_f32_16x16x32_bf16 v[142:145], v[106:109], v[216:219], v[142:145]
	v_mov_b32_e32 v149, v196
	v_mfma_f32_16x16x32_bf16 v[118:121], v[98:101], v[216:219], v[118:121]
	v_mov_b32_e32 v152, v192
	s_cbranch_scc1 .LBB0_533
	v_cvt_pk_bf16_f32 v148, v126, v127
	v_cvt_pk_bf16_f32 v149, v128, v129
	ds_write_b64 v199, v[148:149]
	v_cvt_pk_bf16_f32 v148, v122, v123
	v_cvt_pk_bf16_f32 v149, v124, v125
	ds_write_b64 v199, v[148:149] offset:2304
	v_cvt_pk_bf16_f32 v148, v114, v115
	v_cvt_pk_bf16_f32 v149, v116, v117
	ds_write_b64 v199, v[148:149] offset:4608
	v_cvt_pk_bf16_f32 v148, v118, v119
	v_cvt_pk_bf16_f32 v149, v120, v121
	ds_write_b64 v199, v[148:149] offset:6912

; __device__ __forceinline__ float row16_sum(float v) { v += dppf<0xB1>(v); v += dppf<0x4E>(v); v += dppf<0x141>(v); v += dppf<0x140>(v); return v; }
; __device__ __forceinline__ float frsq(float x) { return __builtin_amdgcn_rsqf(x); }
; __device__ __forceinline__ v2u pack4(const f32x4 v) { v2u r; r.x = pk2(v[0], v[1]); r.y = pk2(v[2], v[3]); return r; }
; __device__ __forceinline__ f32x4 unpack4(const v2u w) { f32x4 r; r[0] = bflo(w.x); r[1] = bfhi(w.x); r[2] = bflo(w.y); r[3] = bfhi(w.y); return r; }
; __device__ __forceinline__ const char* upin(const char* p) { asm volatile("" : "+s"(p)); return p; }
; __device__ __forceinline__ char* upin(char* p) { asm volatile("" : "+s"(p)); return p; }
; template <bool GDN> __device__ __forceinline__ void scan_finish(const Frame& F, int b, int h, int dir, const ScanLane& L, int s, float* PEND, const f32x4 (&Oin)[4], const ScanFin& f) {
;     ...
;         f32x4 O[4]; float ss[4] = {0.f, 0.f, 0.f, 0.f};
; #pragma unroll
;         for (int t = 0; t < 4; ++t)
;             { const f32x4 pv = unpack4(f.pend[t]);
; #pragma unroll
;             for (int i = 0; i < 4; ++i) { O[t][i] = Oin[t][i] + pv[i]; ss[i] += O[t][i] * O[t][i]; } }
; #pragma unroll
;         for (int i = 0; i < 4; ++i) ss[i] = frsq(row16_sum(ss[i]) * (1.f / 64.f) + EPS);
;         char* mp = (char*)F.MIX + ((size_t)row0 * 1024 + (GDN ? 0 : 768) + h * 64) * 2;
; #pragma unroll
;         for (int i = 0; i < 4; ++i) { const f32x4 g = unpack4(f.gz[i]); f32x4 ov;
; #pragma unroll
;             for (int t = 0; t < 4; ++t) ov[t] = O[t][i] * ss[i] * g[t];
;             stu<v2u>(upin(mp + i * 2048), L.mix, pack4(ov)); }
.LBB0_537:
	s_cmp_gt_u32 s23, 2
	s_cselect_b32 s6, 20, 2
	s_cmp_lt_u32 s4, s6
	s_mov_b64 s[10:11], -1
	s_waitcnt lgkmcnt(0)
	s_barrier
	s_cbranch_scc1 .LBB0_540
	s_cmp_lt_i32 s5, 4
	s_cselect_b32 s4, s25, s24
	s_lshl_b32 s6, s5, 6
	s_add_i32 s6, s4, s6
	s_ashr_i32 s7, s6, 31
	s_lshl_b64 s[6:7], s[6:7], 11
	s_add_u32 s10, s26, s6
	s_addc_u32 s11, s27, s7
	s_mov_b64 s[6:7], s[10:11]
	v_lshlrev_b32_e32 v208, 16, v10
	v_and_b32_e32 v209, 0xffff0000, v10
	v_lshlrev_b32_e32 v210, 16, v11
	v_and_b32_e32 v211, 0xffff0000, v11
	v_pk_add_f32 v[212:213], v[130:131], v[208:209]
	v_pk_add_f32 v[214:215], v[132:133], v[210:211]
	v_pk_mul_f32 v[204:205], v[212:213], v[212:213]
	v_pk_mul_f32 v[206:207], v[214:215], v[214:215]
	v_lshlrev_b32_e32 v208, 16, v12
	v_and_b32_e32 v209, 0xffff0000, v12
	v_lshlrev_b32_e32 v210, 16, v13
	v_and_b32_e32 v211, 0xffff0000, v13
	v_pk_add_f32 v[216:217], v[134:135], v[208:209]
	v_pk_add_f32 v[218:219], v[136:137], v[210:211]
	v_pk_fma_f32 v[204:205], v[216:217], v[216:217], v[204:205]
	v_pk_fma_f32 v[206:207], v[218:219], v[218:219], v[206:207]
	v_lshlrev_b32_e32 v208, 16, v14
	v_and_b32_e32 v209, 0xffff0000, v14
	v_lshlrev_b32_e32 v210, 16, v15
	v_and_b32_e32 v211, 0xffff0000, v15
	v_pk_add_f32 v[224:225], v[138:139], v[208:209]
	v_pk_add_f32 v[226:227], v[140:141], v[210:211]
	v_pk_fma_f32 v[204:205], v[224:225], v[224:225], v[204:205]
	v_pk_fma_f32 v[206:207], v[226:227], v[226:227], v[206:207]
	v_lshlrev_b32_e32 v208, 16, v16
	v_and_b32_e32 v209, 0xffff0000, v16
	v_lshlrev_b32_e32 v210, 16, v17
	v_and_b32_e32 v211, 0xffff0000, v17
	v_pk_add_f32 v[242:243], v[142:143], v[208:209]
	v_pk_add_f32 v[244:245], v[144:145], v[210:211]
	v_pk_fma_f32 v[204:205], v[242:243], v[242:243], v[204:205]
	v_pk_fma_f32 v[206:207], v[244:245], v[244:245], v[206:207]
	s_nop 1
	v_add_f32_dpp v204, v204, v204 quad_perm:[1,0,3,2] row_mask:0xf bank_mask:0xf bound_ctrl:1
	v_add_f32_dpp v205, v205, v205 quad_perm:[1,0,3,2] row_mask:0xf bank_mask:0xf bound_ctrl:1
	v_add_f32_dpp v206, v206, v206 quad_perm:[1,0,3,2] row_mask:0xf bank_mask:0xf bound_ctrl:1
	v_add_f32_dpp v207, v207, v207 quad_perm:[1,0,3,2] row_mask:0xf bank_mask:0xf bound_ctrl:1
	v_add_f32_dpp v204, v204, v204 quad_perm:[2,3,0,1] row_mask:0xf bank_mask:0xf bound_ctrl:1
	v_add_f32_dpp v205, v205, v205 quad_perm:[2,3,0,1] row_mask:0xf bank_mask:0xf bound_ctrl:1
	v_add_f32_dpp v206, v206, v206 quad_perm:[2,3,0,1] row_mask:0xf bank_mask:0xf bound_ctrl:1
	v_add_f32_dpp v207, v207, v207 quad_perm:[2,3,0,1] row_mask:0xf bank_mask:0xf bound_ctrl:1
	v_add_f32_dpp v204, v204, v204 row_half_mirror row_mask:0xf bank_mask:0xf bound_ctrl:1
	v_add_f32_dpp v205, v205, v205 row_half_mirror row_mask:0xf bank_mask:0xf bound_ctrl:1
	v_add_f32_dpp v206, v206, v206 row_half_mirror row_mask:0xf bank_mask:0xf bound_ctrl:1
	v_add_f32_dpp v207, v207, v207 row_half_mirror row_mask:0xf bank_mask:0xf bound_ctrl:1
	v_add_f32_dpp v204, v204, v204 row_mirror row_mask:0xf bank_mask:0xf bound_ctrl:1
	v_add_f32_dpp v205, v205, v205 row_mirror row_mask:0xf bank_mask:0xf bound_ctrl:1
	v_add_f32_dpp v206, v206, v206 row_mirror row_mask:0xf bank_mask:0xf bound_ctrl:1
	v_add_f32_dpp v207, v207, v207 row_mirror row_mask:0xf bank_mask:0xf bound_ctrl:1
	v_fmamk_f32 v204, v204, 0x3c800000, v231
	v_fmamk_f32 v205, v205, 0x3c800000, v231
	v_fmamk_f32 v206, v206, 0x3c800000, v231
	v_fmamk_f32 v207, v207, 0x3c800000, v231
	v_rsq_f32_e32 v204, v204
	v_rsq_f32_e32 v205, v205
	v_rsq_f32_e32 v206, v206
	v_rsq_f32_e32 v207, v207
	v_lshlrev_b32_e32 v208, 16, v164
	v_lshlrev_b32_e32 v209, 16, v178
	v_lshlrev_b32_e32 v210, 16, v180
	v_lshlrev_b32_e32 v211, 16, v182
	v_pk_mul_f32 v[212:213], v[212:213], v[204:205]
	v_pk_mul_f32 v[214:215], v[214:215], v[206:207]
	v_pk_mul_f32 v[212:213], v[212:213], v[208:209]
	v_pk_mul_f32 v[214:215], v[214:215], v[210:211]
	v_and_b32_e32 v208, 0xffff0000, v164
	v_and_b32_e32 v209, 0xffff0000, v178
	v_and_b32_e32 v210, 0xffff0000, v180
	v_and_b32_e32 v211, 0xffff0000, v182
	v_pk_mul_f32 v[216:217], v[216:217], v[204:205]
	v_pk_mul_f32 v[218:219], v[218:219], v[206:207]
	v_pk_mul_f32 v[216:217], v[216:217], v[208:209]
	v_pk_mul_f32 v[218:219], v[218:219], v[210:211]
	v_lshlrev_b32_e32 v208, 16, v165
	v_lshlrev_b32_e32 v209, 16, v179
	v_lshlrev_b32_e32 v210, 16, v181
	v_lshlrev_b32_e32 v211, 16, v183
	v_pk_mul_f32 v[224:225], v[224:225], v[204:205]
	v_pk_mul_f32 v[226:227], v[226:227], v[206:207]
	v_pk_mul_f32 v[224:225], v[224:225], v[208:209]
	v_pk_mul_f32 v[226:227], v[226:227], v[210:211]
	v_and_b32_e32 v208, 0xffff0000, v165
	v_and_b32_e32 v209, 0xffff0000, v179
	v_and_b32_e32 v210, 0xffff0000, v181
	v_and_b32_e32 v211, 0xffff0000, v183
	v_pk_mul_f32 v[242:243], v[242:243], v[204:205]
	v_pk_mul_f32 v[244:245], v[244:245], v[206:207]
	v_pk_mul_f32 v[242:243], v[242:243], v[208:209]
	v_pk_mul_f32 v[244:245], v[244:245], v[210:211]
	v_cvt_pk_bf16_f32 v208, v212, v216
	v_cvt_pk_bf16_f32 v209, v224, v242
	global_store_dwordx2 v146, v[208:209], s[6:7]
	v_cvt_pk_bf16_f32 v210, v213, v217
	v_cvt_pk_bf16_f32 v211, v225, v243
	s_add_u32 s6, s10, 0x800
	s_addc_u32 s7, s11, 0
	global_store_dwordx2 v146, v[210:211], s[6:7]
	v_cvt_pk_bf16_f32 v204, v214, v218
	v_cvt_pk_bf16_f32 v205, v226, v244
	s_add_u32 s6, s10, 0x1000
	s_addc_u32 s7, s11, 0
	global_store_dwordx2 v146, v[204:205], s[6:7]
	v_cvt_pk_bf16_f32 v206, v215, v219
	v_cvt_pk_bf16_f32 v207, v227, v245
	s_add_u32 s6, s10, 0x1800
	s_addc_u32 s7, s11, 0
	global_store_dwordx2 v146, v[206:207], s[6:7]
	s_cbranch_execz .LBB0_541

; __device__ __forceinline__ float row16_sum(float v) { v += dppf<0xB1>(v); v += dppf<0x4E>(v); v += dppf<0x141>(v); v += dppf<0x140>(v); return v; }
; __device__ __forceinline__ float frsq(float x) { return __builtin_amdgcn_rsqf(x); }
; __device__ __forceinline__ v2u pack4(const f32x4 v) { v2u r; r.x = pk2(v[0], v[1]); r.y = pk2(v[2], v[3]); return r; }
; __device__ __forceinline__ f32x4 unpack4(const v2u w) { f32x4 r; r[0] = bflo(w.x); r[1] = bfhi(w.x); r[2] = bflo(w.y); r[3] = bfhi(w.y); return r; }
; __device__ __forceinline__ const char* upin(const char* p) { asm volatile("" : "+s"(p)); return p; }
; __device__ __forceinline__ char* upin(char* p) { asm volatile("" : "+s"(p)); return p; }
; template <bool GDN> __device__ __forceinline__ void scan_finish(const Frame& F, int b, int h, int dir, const ScanLane& L, int s, float* PEND, const f32x4 (&Oin)[4], const ScanFin& f) {
;     ...
;         f32x4 O[4]; float ss[4] = {0.f, 0.f, 0.f, 0.f};
; #pragma unroll
;         for (int t = 0; t < 4; ++t)
;             { const f32x4 pv = unpack4(f.pend[t]);
; #pragma unroll
;             for (int i = 0; i < 4; ++i) { O[t][i] = Oin[t][i] + pv[i]; ss[i] += O[t][i] * O[t][i]; } }
; #pragma unroll
;         for (int i = 0; i < 4; ++i) ss[i] = frsq(row16_sum(ss[i]) * (1.f / 64.f) + EPS);
;         char* mp = (char*)F.MIX + ((size_t)row0 * 1024 + (GDN ? 0 : 768) + h * 64) * 2;
; #pragma unroll
;         for (int i = 0; i < 4; ++i) { const f32x4 g = unpack4(f.gz[i]); f32x4 ov;
; #pragma unroll
;             for (int t = 0; t < 4; ++t) ov[t] = O[t][i] * ss[i] * g[t];
;             stu<v2u>(upin(mp + i * 2048), L.mix, pack4(ov)); }
.LBB0_568:
	s_cmp_lt_i32 s4, 4
	s_cselect_b32 s3, s25, s24
	s_lshl_b32 s5, s4, 6
	s_add_i32 s6, s3, s5
	s_ashr_i32 s7, s6, 31
	s_lshl_b64 s[6:7], s[6:7], 11
	s_add_u32 s10, s26, s6
	s_addc_u32 s11, s27, s7
	s_mov_b64 s[6:7], s[10:11]
	v_lshlrev_b32_e32 v208, 16, v2
	v_and_b32_e32 v209, 0xffff0000, v2
	v_lshlrev_b32_e32 v210, 16, v3
	v_and_b32_e32 v211, 0xffff0000, v3
	v_pk_add_f32 v[212:213], v[130:131], v[208:209]
	v_pk_add_f32 v[214:215], v[132:133], v[210:211]
	v_pk_mul_f32 v[204:205], v[212:213], v[212:213]
	v_pk_mul_f32 v[206:207], v[214:215], v[214:215]
	v_lshlrev_b32_e32 v208, 16, v4
	v_and_b32_e32 v209, 0xffff0000, v4
	v_lshlrev_b32_e32 v210, 16, v5
	v_and_b32_e32 v211, 0xffff0000, v5
	v_pk_add_f32 v[216:217], v[134:135], v[208:209]
	v_pk_add_f32 v[218:219], v[136:137], v[210:211]
	v_pk_fma_f32 v[204:205], v[216:217], v[216:217], v[204:205]
	v_pk_fma_f32 v[206:207], v[218:219], v[218:219], v[206:207]
	v_lshlrev_b32_e32 v208, 16, v6
	v_and_b32_e32 v209, 0xffff0000, v6
	v_lshlrev_b32_e32 v210, 16, v7
	v_and_b32_e32 v211, 0xffff0000, v7
	v_pk_add_f32 v[224:225], v[138:139], v[208:209]
	v_pk_add_f32 v[226:227], v[140:141], v[210:211]
	v_pk_fma_f32 v[204:205], v[224:225], v[224:225], v[204:205]
	v_pk_fma_f32 v[206:207], v[226:227], v[226:227], v[206:207]
	v_lshlrev_b32_e32 v208, 16, v8
	v_and_b32_e32 v209, 0xffff0000, v8
	v_lshlrev_b32_e32 v210, 16, v9
	v_and_b32_e32 v211, 0xffff0000, v9
	v_pk_add_f32 v[242:243], v[142:143], v[208:209]
	v_pk_add_f32 v[244:245], v[144:145], v[210:211]
	v_pk_fma_f32 v[204:205], v[242:243], v[242:243], v[204:205]
	v_pk_fma_f32 v[206:207], v[244:245], v[244:245], v[206:207]
	s_nop 1
	v_add_f32_dpp v204, v204, v204 quad_perm:[1,0,3,2] row_mask:0xf bank_mask:0xf bound_ctrl:1
	v_add_f32_dpp v205, v205, v205 quad_perm:[1,0,3,2] row_mask:0xf bank_mask:0xf bound_ctrl:1
	v_add_f32_dpp v206, v206, v206 quad_perm:[1,0,3,2] row_mask:0xf bank_mask:0xf bound_ctrl:1
	v_add_f32_dpp v207, v207, v207 quad_perm:[1,0,3,2] row_mask:0xf bank_mask:0xf bound_ctrl:1
	v_add_f32_dpp v204, v204, v204 quad_perm:[2,3,0,1] row_mask:0xf bank_mask:0xf bound_ctrl:1
	v_add_f32_dpp v205, v205, v205 quad_perm:[2,3,0,1] row_mask:0xf bank_mask:0xf bound_ctrl:1
	v_add_f32_dpp v206, v206, v206 quad_perm:[2,3,0,1] row_mask:0xf bank_mask:0xf bound_ctrl:1
	v_add_f32_dpp v207, v207, v207 quad_perm:[2,3,0,1] row_mask:0xf bank_mask:0xf bound_ctrl:1
	v_add_f32_dpp v204, v204, v204 row_half_mirror row_mask:0xf bank_mask:0xf bound_ctrl:1
	v_add_f32_dpp v205, v205, v205 row_half_mirror row_mask:0xf bank_mask:0xf bound_ctrl:1
	v_add_f32_dpp v206, v206, v206 row_half_mirror row_mask:0xf bank_mask:0xf bound_ctrl:1
	v_add_f32_dpp v207, v207, v207 row_half_mirror row_mask:0xf bank_mask:0xf bound_ctrl:1
	v_add_f32_dpp v204, v204, v204 row_mirror row_mask:0xf bank_mask:0xf bound_ctrl:1
	v_add_f32_dpp v205, v205, v205 row_mirror row_mask:0xf bank_mask:0xf bound_ctrl:1
	v_add_f32_dpp v206, v206, v206 row_mirror row_mask:0xf bank_mask:0xf bound_ctrl:1
	v_add_f32_dpp v207, v207, v207 row_mirror row_mask:0xf bank_mask:0xf bound_ctrl:1
	v_fmamk_f32 v204, v204, 0x3c800000, v231
	v_fmamk_f32 v205, v205, 0x3c800000, v231
	v_fmamk_f32 v206, v206, 0x3c800000, v231
	v_fmamk_f32 v207, v207, 0x3c800000, v231
	v_rsq_f32_e32 v204, v204
	v_rsq_f32_e32 v205, v205
	v_rsq_f32_e32 v206, v206
	v_rsq_f32_e32 v207, v207
	v_lshlrev_b32_e32 v208, 16, v156
	v_lshlrev_b32_e32 v209, 16, v158
	v_lshlrev_b32_e32 v210, 16, v160
	v_lshlrev_b32_e32 v211, 16, v162
	v_pk_mul_f32 v[212:213], v[212:213], v[204:205]
	v_pk_mul_f32 v[214:215], v[214:215], v[206:207]
	v_pk_mul_f32 v[212:213], v[212:213], v[208:209]
	v_pk_mul_f32 v[214:215], v[214:215], v[210:211]
	v_and_b32_e32 v208, 0xffff0000, v156
	v_and_b32_e32 v209, 0xffff0000, v158
	v_and_b32_e32 v210, 0xffff0000, v160
	v_and_b32_e32 v211, 0xffff0000, v162
	v_pk_mul_f32 v[216:217], v[216:217], v[204:205]
	v_pk_mul_f32 v[218:219], v[218:219], v[206:207]
	v_pk_mul_f32 v[216:217], v[216:217], v[208:209]
	v_pk_mul_f32 v[218:219], v[218:219], v[210:211]
	v_lshlrev_b32_e32 v208, 16, v157
	v_lshlrev_b32_e32 v209, 16, v159
	v_lshlrev_b32_e32 v210, 16, v161
	v_lshlrev_b32_e32 v211, 16, v163
	v_pk_mul_f32 v[224:225], v[224:225], v[204:205]
	v_pk_mul_f32 v[226:227], v[226:227], v[206:207]
	v_pk_mul_f32 v[224:225], v[224:225], v[208:209]
	v_pk_mul_f32 v[226:227], v[226:227], v[210:211]
	v_and_b32_e32 v208, 0xffff0000, v157
	v_and_b32_e32 v209, 0xffff0000, v159
	v_and_b32_e32 v210, 0xffff0000, v161
	v_and_b32_e32 v211, 0xffff0000, v163
	v_pk_mul_f32 v[242:243], v[242:243], v[204:205]
	v_pk_mul_f32 v[244:245], v[244:245], v[206:207]
	v_pk_mul_f32 v[242:243], v[242:243], v[208:209]
	v_pk_mul_f32 v[244:245], v[244:245], v[210:211]
	v_cvt_pk_bf16_f32 v208, v212, v216
	v_cvt_pk_bf16_f32 v209, v224, v242
	global_store_dwordx2 v28, v[208:209], s[6:7]
	v_cvt_pk_bf16_f32 v210, v213, v217
	v_cvt_pk_bf16_f32 v211, v225, v243
	s_add_u32 s6, s10, 0x800
	s_addc_u32 s7, s11, 0
	global_store_dwordx2 v28, v[210:211], s[6:7]
	v_cvt_pk_bf16_f32 v204, v214, v218
	v_cvt_pk_bf16_f32 v205, v226, v244
	s_add_u32 s6, s10, 0x1000
	s_addc_u32 s7, s11, 0
	global_store_dwordx2 v28, v[204:205], s[6:7]
	v_cvt_pk_bf16_f32 v206, v215, v219
	v_cvt_pk_bf16_f32 v207, v227, v245
	s_add_u32 s6, s10, 0x1800
	s_addc_u32 s7, s11, 0
	global_store_dwordx2 v28, v[206:207], s[6:7]
	s_cbranch_execz .LBB0_581

; #define LAS __attribute__((address_space(3)))
; __device__ __forceinline__ f32x4 unpack4(const v2u w) { f32x4 r; r[0] = bflo(w.x); r[1] = bfhi(w.x); r[2] = bflo(w.y); r[3] = bfhi(w.y); return r; }
; template <class T> __device__ __forceinline__ T ldun(const void* ubase, unsigned boff) { return __builtin_nontemporal_load((const GAS T*)((const GAS char*)ubase + boff)); }
; __device__ __forceinline__ const char* upin(const char* p) { asm volatile("" : "+s"(p)); return p; }
; __device__ __forceinline__ char* upin(char* p) { asm volatile("" : "+s"(p)); return p; }
; template <bool GDN, int NT> __device__ __forceinline__ void scan_load(const Frame& F, int b, int h, int dir, const ScanLane& L, int s, ScanOps<NT>& o) {
;     ...
;         const char* base = (const char*)F.PG + (size_t)ud * 32768;
;         const char* bM = upin(base); const char* bB = upin(base + 8192); const char* bQ = upin(base + 16384); const char* bO = upin(base + 24576);
; #pragma unroll
;         for (int ks = 0; ks < 2; ++ks) { o.Mf[ks] = ldun<bf16x8>(bM + ks * 1024, L.o16); o.Qf[ks] = ldun<bf16x8>(bQ + ks * 1024, L.o16); }
; #pragma unroll
;         for (int pr = 0; pr < 2; ++pr) { const v4u qb = ldun<v4u>(bB + pr * 1024, L.o16p), qo = ldun<v4u>(bO + pr * 1024, L.o16p);
;             o.bv[2 * pr] = (v2u){qb.x, qb.y}; o.bv[2 * pr + 1] = (v2u){qb.z, qb.w}; o.ov[2 * pr] = (v2u){qo.x, qo.y}; o.ov[2 * pr + 1] = (v2u){qo.z, qo.w}; }
;         o.wi = (f32x4){1.f, 1.f, 1.f, 1.f};
;     ...
;     const float gl = ((const LAS float*)(St + 4 * 80 * 72))[(dir ? (s < 4 ? 3 - s : 39 - s) : s) * 2 + dir];
;     f32x4 O[NT];
; #pragma unroll
;     for (int t = 0; t < NT; ++t) {
;         const LAS bf16_t* sp2 = Sb + (16 * t + lr) * 72 + 8 * lq;
;         const bf16x8 s0 = *(const LAS bf16x8*)sp2, s1 = *(const LAS bf16x8*)(sp2 + 32);
;         const f32x4 bv = unpack4(use.bv[t]), ov = unpack4(use.ov[t]);
;         if (GDN) {
;             f32x4 o = ov, sn = S[t] * gl + bv;
;             o = __builtin_amdgcn_mfma_f32_16x16x32_bf16(use.Qf[0], s0, o, 0, 0, 0); o = __builtin_amdgcn_mfma_f32_16x16x32_bf16(use.Qf[1], s1, o, 0, 0, 0);
;             sn = __builtin_amdgcn_mfma_f32_16x16x32_bf16(use.Mf[0], s0, sn, 0, 0, 0); sn = __builtin_amdgcn_mfma_f32_16x16x32_bf16(use.Mf[1], s1, sn, 0, 0, 0);
;             S[t] = sn; O[t] = o;
.LBB0_571:
	s_add_i32 s12, s23, 3
	s_min_u32 s4, s12, 33
	s_add_i32 s6, s4, 2
	s_sub_i32 s7, 37, s4
	s_and_b64 s[4:5], s[90:91], exec
	s_cselect_b32 s4, s6, s7
	s_add_i32 s4, s4, s30
	s_lshl_b32 s4, s4, 1
	s_add_i32 s4, s4, s68
	s_ashr_i32 s5, s4, 31
	s_lshl_b64 s[4:5], s[4:5], 15
	s_add_u32 s4, s35, s4
	s_addc_u32 s5, s43, s5
	s_add_u32 s8, s4, 0x2000
	s_addc_u32 s9, s5, 0
	s_add_u32 s10, s4, 0x4000
	s_addc_u32 s11, s5, 0
	s_mov_b64 s[6:7], s[4:5]
	s_add_u32 s4, s4, 0x6000
	s_addc_u32 s5, s5, 0
	global_load_dwordx4 v[30:33], v34, s[6:7] nt
	global_load_dwordx4 v[46:49], v34, s[10:11] nt
	global_load_dwordx4 v[26:29], v34, s[6:7] offset:1024 nt
	s_nop 0
	global_load_dwordx4 v[34:37], v34, s[10:11] offset:1024 nt
	s_nop 0
	global_load_dwordx4 v[94:97], v0, s[8:9] nt
	global_load_dwordx4 v[86:89], v0, s[4:5] nt
	global_load_dwordx4 v[78:81], v0, s[8:9] offset:1024 nt
	global_load_dwordx4 v[74:77], v0, s[4:5] offset:1024 nt
	s_add_i32 s1, s1, s22
	s_and_b64 s[4:5], s[90:91], exec
	s_cselect_b32 s1, s12, s1
	s_lshl_b32 s4, s1, 3
	s_add_i32 s4, s34, s4
	v_mov_b32_e32 v0, s4
	ds_read_b32 v0, v0 offset:46080
	ds_read_b128 v[134:137], v200 offset:11520
	ds_read_b128 v[138:141], v200 offset:11584
	ds_read_b128 v[212:215], v200 offset:13824
	ds_read_b128 v[216:219], v200 offset:13888
	ds_read_b128 v[224:227], v200 offset:16128
	ds_read_b128 v[242:245], v200 offset:16192
	v_lshlrev_b32_e32 v142, 16, v90
	v_and_b32_e32 v143, 0xffff0000, v90
	v_lshlrev_b32_e32 v144, 16, v91
	v_and_b32_e32 v145, 0xffff0000, v91
	v_lshlrev_b32_e32 v130, 16, v82
	v_and_b32_e32 v131, 0xffff0000, v82
	v_lshlrev_b32_e32 v132, 16, v83
	v_and_b32_e32 v133, 0xffff0000, v83
	s_waitcnt lgkmcnt(6)
	v_pk_fma_f32 v[128:129], v[128:129], v[0:1], v[144:145] op_sel_hi:[1,0,1]
	v_pk_fma_f32 v[126:127], v[126:127], v[0:1], v[142:143] op_sel_hi:[1,0,1]
	s_waitcnt lgkmcnt(5)
	v_mfma_f32_16x16x32_bf16 v[130:133], v[58:61], v[134:137], v[130:133]
	v_lshlrev_b32_e32 v146, 16, v92
	v_and_b32_e32 v147, 0xffff0000, v92
	v_lshlrev_b32_e32 v148, 16, v93
	v_mfma_f32_16x16x32_bf16 v[126:129], v[42:45], v[134:137], v[126:129]
	v_and_b32_e32 v149, 0xffff0000, v93
	v_lshlrev_b32_e32 v134, 16, v84
	v_and_b32_e32 v135, 0xffff0000, v84
	s_waitcnt lgkmcnt(4)
	v_mfma_f32_16x16x32_bf16 v[130:133], v[50:53], v[138:141], v[130:133]
	v_lshlrev_b32_e32 v136, 16, v85
	v_and_b32_e32 v137, 0xffff0000, v85
	v_pk_fma_f32 v[124:125], v[124:125], v[0:1], v[148:149] op_sel_hi:[1,0,1]
	v_mfma_f32_16x16x32_bf16 v[126:129], v[38:41], v[138:141], v[126:129]
	v_pk_fma_f32 v[122:123], v[122:123], v[0:1], v[146:147] op_sel_hi:[1,0,1]
	v_lshlrev_b32_e32 v150, 16, v62
	s_waitcnt lgkmcnt(3)
	v_mfma_f32_16x16x32_bf16 v[134:137], v[58:61], v[212:215], v[134:137]
	v_and_b32_e32 v151, 0xffff0000, v62
	v_lshlrev_b32_e32 v152, 16, v63
	v_and_b32_e32 v153, 0xffff0000, v63
	v_mfma_f32_16x16x32_bf16 v[122:125], v[42:45], v[212:215], v[122:125]
	v_lshlrev_b32_e32 v138, 16, v54
	v_and_b32_e32 v139, 0xffff0000, v54
	v_lshlrev_b32_e32 v140, 16, v55
	s_waitcnt lgkmcnt(2)
	v_mfma_f32_16x16x32_bf16 v[134:137], v[50:53], v[216:219], v[134:137]
	v_and_b32_e32 v141, 0xffff0000, v55
	v_pk_fma_f32 v[116:117], v[116:117], v[0:1], v[152:153] op_sel_hi:[1,0,1]
	v_pk_fma_f32 v[114:115], v[114:115], v[0:1], v[150:151] op_sel_hi:[1,0,1]
	v_mfma_f32_16x16x32_bf16 v[122:125], v[38:41], v[216:219], v[122:125]
	ds_read_b128 v[212:215], v200 offset:18432
	ds_read_b128 v[216:219], v200 offset:18496
	v_lshlrev_b32_e32 v166, 16, v64
	v_and_b32_e32 v167, 0xffff0000, v64
	s_waitcnt lgkmcnt(3)
	v_mfma_f32_16x16x32_bf16 v[138:141], v[58:61], v[224:227], v[138:141]
	v_lshlrev_b32_e32 v168, 16, v65
	v_and_b32_e32 v169, 0xffff0000, v65
	v_pk_fma_f32 v[120:121], v[120:121], v[0:1], v[168:169] op_sel_hi:[1,0,1]
	v_mfma_f32_16x16x32_bf16 v[114:117], v[42:45], v[224:227], v[114:117]
	v_lshlrev_b32_e32 v142, 16, v56
	v_and_b32_e32 v143, 0xffff0000, v56
	v_lshlrev_b32_e32 v144, 16, v57
	s_waitcnt lgkmcnt(2)
	v_mfma_f32_16x16x32_bf16 v[138:141], v[50:53], v[242:245], v[138:141]
	v_and_b32_e32 v145, 0xffff0000, v57
	v_pk_fma_f32 v[118:119], v[118:119], v[0:1], v[166:167] op_sel_hi:[1,0,1]
	v_mov_b32_e32 v0, v192
	v_mfma_f32_16x16x32_bf16 v[114:117], v[38:41], v[242:245], v[114:117]
	s_cmp_gt_u32 s23, 31
	s_waitcnt lgkmcnt(1)
	v_mfma_f32_16x16x32_bf16 v[142:145], v[58:61], v[212:215], v[142:145]
	v_mfma_f32_16x16x32_bf16 v[118:121], v[42:45], v[212:215], v[118:121]
	v_mov_b32_e32 v146, v154
	v_mov_b32_e32 v149, v197
	v_mov_b32_e32 v148, v192
	s_waitcnt lgkmcnt(0)
	v_mfma_f32_16x16x32_bf16 v[142:145], v[50:53], v[216:219], v[142:145]
	v_mov_b32_e32 v147, v194
	v_mfma_f32_16x16x32_bf16 v[118:121], v[38:41], v[216:219], v[118:121]
	v_mov_b32_e32 v150, v196
	v_mov_b32_e32 v151, v193
	v_mov_b32_e32 v152, v195
	s_cbranch_scc1 .LBB0_582
	v_cvt_pk_bf16_f32 v150, v126, v127
	v_cvt_pk_bf16_f32 v151, v128, v129
	ds_write_b64 v199, v[150:151]
	v_cvt_pk_bf16_f32 v150, v122, v123
	v_cvt_pk_bf16_f32 v151, v124, v125
	ds_write_b64 v199, v[150:151] offset:2304
	v_cvt_pk_bf16_f32 v150, v114, v115
	v_cvt_pk_bf16_f32 v151, v116, v117
	ds_write_b64 v199, v[150:151] offset:4608
	v_cvt_pk_bf16_f32 v150, v118, v119
	v_cvt_pk_bf16_f32 v151, v120, v121
	ds_write_b64 v199, v[150:151] offset:6912
	s_sub_i32 s4, s23, 17
	s_cmp_gt_u32 s4, 14
	s_mov_b64 s[10:11], -1
	s_cbranch_scc1 .LBB0_583

; __device__ __forceinline__ float row16_sum(float v) { v += dppf<0xB1>(v); v += dppf<0x4E>(v); v += dppf<0x141>(v); v += dppf<0x140>(v); return v; }
; __device__ __forceinline__ float frsq(float x) { return __builtin_amdgcn_rsqf(x); }
; __device__ __forceinline__ v2u pack4(const f32x4 v) { v2u r; r.x = pk2(v[0], v[1]); r.y = pk2(v[2], v[3]); return r; }
; __device__ __forceinline__ f32x4 unpack4(const v2u w) { f32x4 r; r[0] = bflo(w.x); r[1] = bfhi(w.x); r[2] = bflo(w.y); r[3] = bfhi(w.y); return r; }
; __device__ __forceinline__ const char* upin(const char* p) { asm volatile("" : "+s"(p)); return p; }
; __device__ __forceinline__ char* upin(char* p) { asm volatile("" : "+s"(p)); return p; }
; template <bool GDN> __device__ __forceinline__ void scan_finish(const Frame& F, int b, int h, int dir, const ScanLane& L, int s, float* PEND, const f32x4 (&Oin)[4], const ScanFin& f) {
;     ...
;         f32x4 O[4]; float ss[4] = {0.f, 0.f, 0.f, 0.f};
; #pragma unroll
;         for (int t = 0; t < 4; ++t)
;             { const f32x4 pv = unpack4(f.pend[t]);
; #pragma unroll
;             for (int i = 0; i < 4; ++i) { O[t][i] = Oin[t][i] + pv[i]; ss[i] += O[t][i] * O[t][i]; } }
; #pragma unroll
;         for (int i = 0; i < 4; ++i) ss[i] = frsq(row16_sum(ss[i]) * (1.f / 64.f) + EPS);
;         char* mp = (char*)F.MIX + ((size_t)row0 * 1024 + (GDN ? 0 : 768) + h * 64) * 2;
; #pragma unroll
;         for (int i = 0; i < 4; ++i) { const f32x4 g = unpack4(f.gz[i]); f32x4 ov;
; #pragma unroll
;             for (int t = 0; t < 4; ++t) ov[t] = O[t][i] * ss[i] * g[t];
;             stu<v2u>(upin(mp + i * 2048), L.mix, pack4(ov)); }
.LBB0_575:
	s_cmp_lt_u32 s0, 16
	s_mov_b64 s[10:11], -1
	s_waitcnt lgkmcnt(0)
	s_barrier
	s_cbranch_scc1 .LBB0_584
	s_cmp_lt_i32 s1, 4
	s_cselect_b32 s0, s25, s24
	s_lshl_b32 s4, s1, 6
	s_add_i32 s4, s0, s4
	s_ashr_i32 s5, s4, 31
	s_lshl_b64 s[4:5], s[4:5], 11
	s_add_u32 s10, s26, s4
	s_addc_u32 s11, s27, s5
	s_mov_b64 s[4:5], s[10:11]
	v_lshlrev_b32_e32 v208, 16, v10
	v_and_b32_e32 v209, 0xffff0000, v10
	v_lshlrev_b32_e32 v210, 16, v11
	v_and_b32_e32 v211, 0xffff0000, v11
	v_pk_add_f32 v[212:213], v[130:131], v[208:209]
	v_pk_add_f32 v[214:215], v[132:133], v[210:211]
	v_pk_mul_f32 v[204:205], v[212:213], v[212:213]
	v_pk_mul_f32 v[206:207], v[214:215], v[214:215]
	v_lshlrev_b32_e32 v208, 16, v12
	v_and_b32_e32 v209, 0xffff0000, v12
	v_lshlrev_b32_e32 v210, 16, v13
	v_and_b32_e32 v211, 0xffff0000, v13
	v_pk_add_f32 v[216:217], v[134:135], v[208:209]
	v_pk_add_f32 v[218:219], v[136:137], v[210:211]
	v_pk_fma_f32 v[204:205], v[216:217], v[216:217], v[204:205]
	v_pk_fma_f32 v[206:207], v[218:219], v[218:219], v[206:207]
	v_lshlrev_b32_e32 v208, 16, v14
	v_and_b32_e32 v209, 0xffff0000, v14
	v_lshlrev_b32_e32 v210, 16, v15
	v_and_b32_e32 v211, 0xffff0000, v15
	v_pk_add_f32 v[224:225], v[138:139], v[208:209]
	v_pk_add_f32 v[226:227], v[140:141], v[210:211]
	v_pk_fma_f32 v[204:205], v[224:225], v[224:225], v[204:205]
	v_pk_fma_f32 v[206:207], v[226:227], v[226:227], v[206:207]
	v_lshlrev_b32_e32 v208, 16, v16
	v_and_b32_e32 v209, 0xffff0000, v16
	v_lshlrev_b32_e32 v210, 16, v17
	v_and_b32_e32 v211, 0xffff0000, v17
	v_pk_add_f32 v[242:243], v[142:143], v[208:209]
	v_pk_add_f32 v[244:245], v[144:145], v[210:211]
	v_pk_fma_f32 v[204:205], v[242:243], v[242:243], v[204:205]
	v_pk_fma_f32 v[206:207], v[244:245], v[244:245], v[206:207]
	s_nop 1
	v_add_f32_dpp v204, v204, v204 quad_perm:[1,0,3,2] row_mask:0xf bank_mask:0xf bound_ctrl:1
	v_add_f32_dpp v205, v205, v205 quad_perm:[1,0,3,2] row_mask:0xf bank_mask:0xf bound_ctrl:1
	v_add_f32_dpp v206, v206, v206 quad_perm:[1,0,3,2] row_mask:0xf bank_mask:0xf bound_ctrl:1
	v_add_f32_dpp v207, v207, v207 quad_perm:[1,0,3,2] row_mask:0xf bank_mask:0xf bound_ctrl:1
	v_add_f32_dpp v204, v204, v204 quad_perm:[2,3,0,1] row_mask:0xf bank_mask:0xf bound_ctrl:1
	v_add_f32_dpp v205, v205, v205 quad_perm:[2,3,0,1] row_mask:0xf bank_mask:0xf bound_ctrl:1
	v_add_f32_dpp v206, v206, v206 quad_perm:[2,3,0,1] row_mask:0xf bank_mask:0xf bound_ctrl:1
	v_add_f32_dpp v207, v207, v207 quad_perm:[2,3,0,1] row_mask:0xf bank_mask:0xf bound_ctrl:1
	v_add_f32_dpp v204, v204, v204 row_half_mirror row_mask:0xf bank_mask:0xf bound_ctrl:1
	v_add_f32_dpp v205, v205, v205 row_half_mirror row_mask:0xf bank_mask:0xf bound_ctrl:1
	v_add_f32_dpp v206, v206, v206 row_half_mirror row_mask:0xf bank_mask:0xf bound_ctrl:1
	v_add_f32_dpp v207, v207, v207 row_half_mirror row_mask:0xf bank_mask:0xf bound_ctrl:1
	v_add_f32_dpp v204, v204, v204 row_mirror row_mask:0xf bank_mask:0xf bound_ctrl:1
	v_add_f32_dpp v205, v205, v205 row_mirror row_mask:0xf bank_mask:0xf bound_ctrl:1
	v_add_f32_dpp v206, v206, v206 row_mirror row_mask:0xf bank_mask:0xf bound_ctrl:1
	v_add_f32_dpp v207, v207, v207 row_mirror row_mask:0xf bank_mask:0xf bound_ctrl:1
	v_fmamk_f32 v204, v204, 0x3c800000, v231
	v_fmamk_f32 v205, v205, 0x3c800000, v231
	v_fmamk_f32 v206, v206, 0x3c800000, v231
	v_fmamk_f32 v207, v207, 0x3c800000, v231
	v_rsq_f32_e32 v204, v204
	v_rsq_f32_e32 v205, v205
	v_rsq_f32_e32 v206, v206
	v_rsq_f32_e32 v207, v207
	v_lshlrev_b32_e32 v208, 16, v164
	v_lshlrev_b32_e32 v209, 16, v178
	v_lshlrev_b32_e32 v210, 16, v180
	v_lshlrev_b32_e32 v211, 16, v182
	v_pk_mul_f32 v[212:213], v[212:213], v[204:205]
	v_pk_mul_f32 v[214:215], v[214:215], v[206:207]
	v_pk_mul_f32 v[212:213], v[212:213], v[208:209]
	v_pk_mul_f32 v[214:215], v[214:215], v[210:211]
	v_and_b32_e32 v208, 0xffff0000, v164
	v_and_b32_e32 v209, 0xffff0000, v178
	v_and_b32_e32 v210, 0xffff0000, v180
	v_and_b32_e32 v211, 0xffff0000, v182
	v_pk_mul_f32 v[216:217], v[216:217], v[204:205]
	v_pk_mul_f32 v[218:219], v[218:219], v[206:207]
	v_pk_mul_f32 v[216:217], v[216:217], v[208:209]
	v_pk_mul_f32 v[218:219], v[218:219], v[210:211]
	v_lshlrev_b32_e32 v208, 16, v165
	v_lshlrev_b32_e32 v209, 16, v179
	v_lshlrev_b32_e32 v210, 16, v181
	v_lshlrev_b32_e32 v211, 16, v183
	v_pk_mul_f32 v[224:225], v[224:225], v[204:205]
	v_pk_mul_f32 v[226:227], v[226:227], v[206:207]
	v_pk_mul_f32 v[224:225], v[224:225], v[208:209]
	v_pk_mul_f32 v[226:227], v[226:227], v[210:211]
	v_and_b32_e32 v208, 0xffff0000, v165
	v_and_b32_e32 v209, 0xffff0000, v179
	v_and_b32_e32 v210, 0xffff0000, v181
	v_and_b32_e32 v211, 0xffff0000, v183
	v_pk_mul_f32 v[242:243], v[242:243], v[204:205]
	v_pk_mul_f32 v[244:245], v[244:245], v[206:207]
	v_pk_mul_f32 v[242:243], v[242:243], v[208:209]
	v_pk_mul_f32 v[244:245], v[244:245], v[210:211]
	v_cvt_pk_bf16_f32 v208, v212, v216
	v_cvt_pk_bf16_f32 v209, v224, v242
	global_store_dwordx2 v149, v[208:209], s[4:5]
	v_cvt_pk_bf16_f32 v210, v213, v217
	v_cvt_pk_bf16_f32 v211, v225, v243
	s_add_u32 s4, s10, 0x800
	s_addc_u32 s5, s11, 0
	global_store_dwordx2 v149, v[210:211], s[4:5]
	v_cvt_pk_bf16_f32 v204, v214, v218
	v_cvt_pk_bf16_f32 v205, v226, v244
	s_add_u32 s4, s10, 0x1000
	s_addc_u32 s5, s11, 0
	global_store_dwordx2 v149, v[204:205], s[4:5]
	v_cvt_pk_bf16_f32 v206, v215, v219
	v_cvt_pk_bf16_f32 v207, v227, v245
	s_add_u32 s4, s10, 0x1800
	s_addc_u32 s5, s11, 0
	global_store_dwordx2 v149, v[206:207], s[4:5]
	s_cbranch_execz .LBB0_585

; __device__ __forceinline__ float row16_sum(float v) { v += dppf<0xB1>(v); v += dppf<0x4E>(v); v += dppf<0x141>(v); v += dppf<0x140>(v); return v; }
; __device__ __forceinline__ float frsq(float x) { return __builtin_amdgcn_rsqf(x); }
; __device__ __forceinline__ v2u pack4(const f32x4 v) { v2u r; r.x = pk2(v[0], v[1]); r.y = pk2(v[2], v[3]); return r; }
; __device__ __forceinline__ f32x4 unpack4(const v2u w) { f32x4 r; r[0] = bflo(w.x); r[1] = bfhi(w.x); r[2] = bflo(w.y); r[3] = bfhi(w.y); return r; }
; __device__ __forceinline__ const char* upin(const char* p) { asm volatile("" : "+s"(p)); return p; }
; __device__ __forceinline__ char* upin(char* p) { asm volatile("" : "+s"(p)); return p; }
; template <bool GDN> __device__ __forceinline__ void scan_finish(const Frame& F, int b, int h, int dir, const ScanLane& L, int s, float* PEND, const f32x4 (&Oin)[4], const ScanFin& f) {
;     ...
;         f32x4 O[4]; float ss[4] = {0.f, 0.f, 0.f, 0.f};
; #pragma unroll
;         for (int t = 0; t < 4; ++t)
;             { const f32x4 pv = unpack4(f.pend[t]);
; #pragma unroll
;             for (int i = 0; i < 4; ++i) { O[t][i] = Oin[t][i] + pv[i]; ss[i] += O[t][i] * O[t][i]; } }
; #pragma unroll
;         for (int i = 0; i < 4; ++i) ss[i] = frsq(row16_sum(ss[i]) * (1.f / 64.f) + EPS);
;         char* mp = (char*)F.MIX + ((size_t)row0 * 1024 + (GDN ? 0 : 768) + h * 64) * 2;
; #pragma unroll
;         for (int i = 0; i < 4; ++i) { const f32x4 g = unpack4(f.gz[i]); f32x4 ov;
; #pragma unroll
;             for (int t = 0; t < 4; ++t) ov[t] = O[t][i] * ss[i] * g[t];
;             stu<v2u>(upin(mp + i * 2048), L.mix, pack4(ov)); }
.LBB0_602:
	s_cmp_lt_i32 s0, 4
	s_cselect_b32 s1, s25, s24
	s_lshl_b32 s3, s0, 6
	s_add_i32 s4, s1, s3
	s_ashr_i32 s5, s4, 31
	s_lshl_b64 s[4:5], s[4:5], 11
	s_add_u32 s10, s26, s4
	s_addc_u32 s11, s27, s5
	s_mov_b64 s[4:5], s[10:11]
	v_lshlrev_b32_e32 v208, 16, v2
	v_and_b32_e32 v209, 0xffff0000, v2
	v_lshlrev_b32_e32 v210, 16, v3
	v_and_b32_e32 v211, 0xffff0000, v3
	v_pk_add_f32 v[212:213], v[130:131], v[208:209]
	v_pk_add_f32 v[214:215], v[132:133], v[210:211]
	v_pk_mul_f32 v[204:205], v[212:213], v[212:213]
	v_pk_mul_f32 v[206:207], v[214:215], v[214:215]
	v_lshlrev_b32_e32 v208, 16, v4
	v_and_b32_e32 v209, 0xffff0000, v4
	v_lshlrev_b32_e32 v210, 16, v5
	v_and_b32_e32 v211, 0xffff0000, v5
	v_pk_add_f32 v[216:217], v[134:135], v[208:209]
	v_pk_add_f32 v[218:219], v[136:137], v[210:211]
	v_pk_fma_f32 v[204:205], v[216:217], v[216:217], v[204:205]
	v_pk_fma_f32 v[206:207], v[218:219], v[218:219], v[206:207]
	v_lshlrev_b32_e32 v208, 16, v6
	v_and_b32_e32 v209, 0xffff0000, v6
	v_lshlrev_b32_e32 v210, 16, v7
	v_and_b32_e32 v211, 0xffff0000, v7
	v_pk_add_f32 v[224:225], v[138:139], v[208:209]
	v_pk_add_f32 v[226:227], v[140:141], v[210:211]
	v_pk_fma_f32 v[204:205], v[224:225], v[224:225], v[204:205]
	v_pk_fma_f32 v[206:207], v[226:227], v[226:227], v[206:207]
	v_lshlrev_b32_e32 v208, 16, v8
	v_and_b32_e32 v209, 0xffff0000, v8
	v_lshlrev_b32_e32 v210, 16, v9
	v_and_b32_e32 v211, 0xffff0000, v9
	v_pk_add_f32 v[242:243], v[142:143], v[208:209]
	v_pk_add_f32 v[244:245], v[144:145], v[210:211]
	v_pk_fma_f32 v[204:205], v[242:243], v[242:243], v[204:205]
	v_pk_fma_f32 v[206:207], v[244:245], v[244:245], v[206:207]
	s_nop 1
	v_add_f32_dpp v204, v204, v204 quad_perm:[1,0,3,2] row_mask:0xf bank_mask:0xf bound_ctrl:1
	v_add_f32_dpp v205, v205, v205 quad_perm:[1,0,3,2] row_mask:0xf bank_mask:0xf bound_ctrl:1
	v_add_f32_dpp v206, v206, v206 quad_perm:[1,0,3,2] row_mask:0xf bank_mask:0xf bound_ctrl:1
	v_add_f32_dpp v207, v207, v207 quad_perm:[1,0,3,2] row_mask:0xf bank_mask:0xf bound_ctrl:1
	v_add_f32_dpp v204, v204, v204 quad_perm:[2,3,0,1] row_mask:0xf bank_mask:0xf bound_ctrl:1
	v_add_f32_dpp v205, v205, v205 quad_perm:[2,3,0,1] row_mask:0xf bank_mask:0xf bound_ctrl:1
	v_add_f32_dpp v206, v206, v206 quad_perm:[2,3,0,1] row_mask:0xf bank_mask:0xf bound_ctrl:1
	v_add_f32_dpp v207, v207, v207 quad_perm:[2,3,0,1] row_mask:0xf bank_mask:0xf bound_ctrl:1
	v_add_f32_dpp v204, v204, v204 row_half_mirror row_mask:0xf bank_mask:0xf bound_ctrl:1
	v_add_f32_dpp v205, v205, v205 row_half_mirror row_mask:0xf bank_mask:0xf bound_ctrl:1
	v_add_f32_dpp v206, v206, v206 row_half_mirror row_mask:0xf bank_mask:0xf bound_ctrl:1
	v_add_f32_dpp v207, v207, v207 row_half_mirror row_mask:0xf bank_mask:0xf bound_ctrl:1
	v_add_f32_dpp v204, v204, v204 row_mirror row_mask:0xf bank_mask:0xf bound_ctrl:1
	v_add_f32_dpp v205, v205, v205 row_mirror row_mask:0xf bank_mask:0xf bound_ctrl:1
	v_add_f32_dpp v206, v206, v206 row_mirror row_mask:0xf bank_mask:0xf bound_ctrl:1
	v_add_f32_dpp v207, v207, v207 row_mirror row_mask:0xf bank_mask:0xf bound_ctrl:1
	v_fmamk_f32 v204, v204, 0x3c800000, v231
	v_fmamk_f32 v205, v205, 0x3c800000, v231
	v_fmamk_f32 v206, v206, 0x3c800000, v231
	v_fmamk_f32 v207, v207, 0x3c800000, v231
	v_rsq_f32_e32 v204, v204
	v_rsq_f32_e32 v205, v205
	v_rsq_f32_e32 v206, v206
	v_rsq_f32_e32 v207, v207
	v_lshlrev_b32_e32 v208, 16, v156
	v_lshlrev_b32_e32 v209, 16, v158
	v_lshlrev_b32_e32 v210, 16, v160
	v_lshlrev_b32_e32 v211, 16, v162
	v_pk_mul_f32 v[212:213], v[212:213], v[204:205]
	v_pk_mul_f32 v[214:215], v[214:215], v[206:207]
	v_pk_mul_f32 v[212:213], v[212:213], v[208:209]
	v_pk_mul_f32 v[214:215], v[214:215], v[210:211]
	v_and_b32_e32 v208, 0xffff0000, v156
	v_and_b32_e32 v209, 0xffff0000, v158
	v_and_b32_e32 v210, 0xffff0000, v160
	v_and_b32_e32 v211, 0xffff0000, v162
	v_pk_mul_f32 v[216:217], v[216:217], v[204:205]
	v_pk_mul_f32 v[218:219], v[218:219], v[206:207]
	v_pk_mul_f32 v[216:217], v[216:217], v[208:209]
	v_pk_mul_f32 v[218:219], v[218:219], v[210:211]
	v_lshlrev_b32_e32 v208, 16, v157
	v_lshlrev_b32_e32 v209, 16, v159
	v_lshlrev_b32_e32 v210, 16, v161
	v_lshlrev_b32_e32 v211, 16, v163
	v_pk_mul_f32 v[224:225], v[224:225], v[204:205]
	v_pk_mul_f32 v[226:227], v[226:227], v[206:207]
	v_pk_mul_f32 v[224:225], v[224:225], v[208:209]
	v_pk_mul_f32 v[226:227], v[226:227], v[210:211]
	v_and_b32_e32 v208, 0xffff0000, v157
	v_and_b32_e32 v209, 0xffff0000, v159
	v_and_b32_e32 v210, 0xffff0000, v161
	v_and_b32_e32 v211, 0xffff0000, v163
	v_pk_mul_f32 v[242:243], v[242:243], v[204:205]
	v_pk_mul_f32 v[244:245], v[244:245], v[206:207]
	v_pk_mul_f32 v[242:243], v[242:243], v[208:209]
	v_pk_mul_f32 v[244:245], v[244:245], v[210:211]
	v_cvt_pk_bf16_f32 v208, v212, v216
	v_cvt_pk_bf16_f32 v209, v224, v242
	global_store_dwordx2 v21, v[208:209], s[4:5]
	v_cvt_pk_bf16_f32 v210, v213, v217
	v_cvt_pk_bf16_f32 v211, v225, v243
	s_add_u32 s4, s10, 0x800
	s_addc_u32 s5, s11, 0
	global_store_dwordx2 v21, v[210:211], s[4:5]
	v_cvt_pk_bf16_f32 v204, v214, v218
	v_cvt_pk_bf16_f32 v205, v226, v244
	s_add_u32 s4, s10, 0x1000
	s_addc_u32 s5, s11, 0
	global_store_dwordx2 v21, v[204:205], s[4:5]
	v_cvt_pk_bf16_f32 v206, v215, v219
	v_cvt_pk_bf16_f32 v207, v227, v245
	s_add_u32 s4, s10, 0x1800
	s_addc_u32 s5, s11, 0
	global_store_dwordx2 v21, v[206:207], s[4:5]
	s_cbranch_execz .LBB0_607

; #define LAS __attribute__((address_space(3)))
; __device__ __forceinline__ float fexp(float x) { return __builtin_amdgcn_exp2f(x * 1.4426950408889634f); }
; __device__ __forceinline__ v2u pack4(const f32x4 v) { v2u r; r.x = pk2(v[0], v[1]); r.y = pk2(v[2], v[3]); return r; }
;     ...
; #pragma unroll
;     for (int k2 = 0; k2 < 2; ++k2) {
;         const int tt = 2 * w + k2, mt = tt >> 2, nt = tt & 3;
;         f32x4 accG = {0.f, 0.f, 0.f, 0.f}, accQ = {0.f, 0.f, 0.f, 0.f};
;         accG = mma_ll<2>(Ks + mt * 16 * 72, 72, Ks + nt * 16 * 72, 72, accG, lane);
;         accQ = mma_ll<2>(Ks + mt * 16 * 72, 72, Qs + nt * 16 * 72, 72, accQ, lane);
;         const int n = nt * 16 + lr, m0 = mt * 16 + 4 * lq;
; #pragma unroll
;         for (int d = 0; d < 2; ++d) {
;             const float gcn = gcS[d * 64 + n], bn = bS[d * 64 + n];
;             f32x4 av, tv;
; #pragma unroll
;             for (int i = 0; i < 4; ++i) { const int m = m0 + i; const float gcm = gcS[d * 64 + m];
;                 const bool strict = d == 0 ? (m < n) : (m > n); const bool incl = d == 0 ? (m <= n) : (m >= n);
;                 const float e = fexp(incl ? (gcn - gcm) : 0.f);
;                 av[i] = strict ? bn * accG[i] * e : 0.f; tv[i] = incl ? 0.125f * accQ[i] * e : 0.f; }
; #pragma unroll
;             for (int i = 0; i < 4; ++i) { const int si = d ? 63 - n : n, sj = d ? 63 - (m0 + i) : m0 + i; As[d * 4352 + (si >> 1) * 136 + sj * 2 + (si & 1)] = av[i]; }
;             *(LAS v2u*)(At + d * 4608 + n * 72 + m0) = pack4(tv);
;         }
;     }
.LBB0_642:
	s_lshl_b32 s0, s28, 1
	s_and_b32 s1, s0, 2
	s_lshl_b32 s0, s28, 3
	s_and_b32 s3, s0, -16
	v_lshrrev_b32_e32 v7, 1, v52
	v_and_b32_e32 v109, 15, v52
	s_mul_i32 s4, s3, 0x90
	v_and_b32_e32 v0, 24, v7
	v_lshrrev_b32_e32 v13, 4, v53
	s_add_i32 s4, s4, 0
	v_mul_u32_u24_e32 v113, 0x90, v109
	v_lshlrev_b32_e32 v117, 1, v0
	v_add3_u32 v12, s4, v113, v117
	s_movk_i32 s4, 0x90
	v_lshlrev_b32_e32 v17, 2, v13
	v_mad_u32_u24 v121, v109, s4, 0
	v_or_b32_e32 v15, s3, v17
	v_readlane_b32 s3, v253, 55
	v_add_u32_e32 v14, v121, v117
	s_waitcnt lgkmcnt(0)
	v_lshl_add_u32 v16, v15, 1, s3
	s_mul_i32 s3, s1, 0x900
	s_barrier
	v_add_u32_e32 v6, s3, v14
	ds_read_b128 v[8:11], v12 offset:9216
	ds_read_b128 v[2:5], v6 offset:9216
	ds_read_b128 v[22:25], v12 offset:9280
	ds_read_b128 v[26:29], v6 offset:9280
	s_waitcnt lgkmcnt(2)
	v_mfma_f32_16x16x32_bf16 v[2:5], v[8:11], v[2:5], 0
	v_lshl_or_b32 v20, s1, 4, v109
	v_cmp_gt_i32_e64 s[40:41], v15, v20
	v_cmp_lt_i32_e32 vcc, v15, v20
	s_waitcnt lgkmcnt(0)
	v_mfma_f32_16x16x32_bf16 v[2:5], v[22:25], v[26:29], v[2:5]
	ds_read_b128 v[26:29], v6
	v_or_b32_e32 v34, 2, v15
	v_cmp_gt_i32_e64 s[46:47], v34, v20
	s_waitcnt lgkmcnt(0)
	v_mfma_f32_16x16x32_bf16 v[8:11], v[8:11], v[26:29], 0
	ds_read_b128 v[26:29], v6 offset:64
	v_lshl_add_u32 v6, v15, 2, 0
	v_or_b32_e32 v36, 3, v15
	s_waitcnt lgkmcnt(0)
	v_mfma_f32_16x16x32_bf16 v[8:11], v[22:25], v[26:29], v[8:11]
	v_lshl_add_u32 v27, v20, 2, 0
	ds_read_b32 v28, v27 offset:37888
	ds_read_b32 v29, v27 offset:37376
	ds_read_b128 v[22:25], v6 offset:37888
	s_nop 3
	v_mul_f32_e32 v31, 0x3e000000, v8
	v_mul_f32_e32 v33, 0x3e000000, v9
	v_mul_f32_e32 v35, 0x3e000000, v10
	s_waitcnt lgkmcnt(1)
	v_mul_f32_e32 v30, v2, v29
	s_waitcnt lgkmcnt(0)
	v_sub_f32_e32 v22, v28, v22
	v_mul_f32_e32 v22, 0x3fb8aa3b, v22
	v_cndmask_b32_e64 v22, v22, 0, s[40:41]
	v_exp_f32_e32 v22, v22
	v_cmp_gt_i32_e64 s[50:51], v36, v20
	v_or_b32_e32 v32, 1, v15
	v_and_b32_e32 v18, 1, v52
	v_mul_f32_e32 v30, v30, v22
	v_mul_f32_e32 v8, v31, v22
	v_sub_f32_e32 v22, v28, v23
	v_mul_f32_e32 v22, 0x3fb8aa3b, v22
	v_cndmask_b32_e32 v22, 0, v22, vcc
	v_exp_f32_e32 v22, v22
	v_mul_f32_e32 v23, v3, v29
	v_mad_u32_u24 v26, v20, s4, v16
	v_cmp_lt_i32_e64 s[42:43], v32, v20
	v_mul_f32_e32 v23, v23, v22
	v_mul_f32_e32 v9, v33, v22
	v_sub_f32_e32 v22, v28, v24
	v_mul_f32_e32 v22, 0x3fb8aa3b, v22
	v_cndmask_b32_e64 v22, v22, 0, s[46:47]
	v_exp_f32_e32 v22, v22
	v_mul_f32_e32 v24, v4, v29
	v_cmp_lt_i32_e64 s[44:45], v34, v20
	v_cmp_lt_i32_e64 s[48:49], v36, v20
	v_mul_f32_e32 v24, v24, v22
	v_mul_f32_e32 v10, v35, v22
	v_sub_f32_e32 v22, v28, v25
	v_mul_f32_e32 v22, 0x3fb8aa3b, v22
	v_cndmask_b32_e64 v22, v22, 0, s[50:51]
	v_exp_f32_e32 v22, v22
	v_mul_f32_e32 v25, v5, v29
	v_mul_f32_e32 v28, 0x3e000000, v11
	v_lshrrev_b32_e32 v20, 1, v20
	v_mul_f32_e32 v25, v25, v22
	v_mul_f32_e32 v11, v28, v22
	v_mul_u32_u24_e32 v22, 0x220, v20
	v_lshlrev_b32_e32 v18, 2, v18
	v_lshlrev_b32_e32 v0, 3, v15
	v_add3_u32 v22, 0, v22, v18
	v_cndmask_b32_e32 v30, 0, v30, vcc
	v_add_u32_e32 v29, v22, v0
	ds_write_b32 v29, v30 offset:38912
	v_lshlrev_b32_e32 v30, 3, v32
	v_cndmask_b32_e64 v8, v8, 0, s[40:41]
	v_cndmask_b32_e64 v23, 0, v23, s[42:43]
	v_cndmask_b32_e32 v9, 0, v9, vcc
	v_cndmask_b32_e64 v10, v10, 0, s[46:47]
	v_cndmask_b32_e64 v11, v11, 0, s[50:51]
	v_add_u32_e32 v29, v22, v30
	v_lshlrev_b32_e32 v37, 3, v34
	v_lshlrev_b32_e32 v38, 3, v36
	v_cndmask_b32_e64 v24, 0, v24, s[44:45]
	v_cndmask_b32_e64 v25, 0, v25, s[48:49]
	ds_write_b32 v29, v23 offset:38912
	v_add_u32_e32 v23, v22, v37
	v_add_u32_e32 v22, v22, v38
	v_cvt_pk_bf16_f32 v8, v8, v9
	v_cvt_pk_bf16_f32 v9, v10, v11
	ds_write_b32 v23, v24 offset:38912
	ds_write_b32 v22, v25 offset:38912
	ds_write_b64 v26, v[8:9]
	ds_read_b32 v22, v27 offset:38144
	ds_read_b32 v23, v27 offset:37632
	ds_read_b128 v[8:11], v6 offset:38144
	v_bitop3_b32 v19, v52, 1, v52 bitop3:0xc
	v_xor_b32_e32 v20, 31, v20
	v_mul_u32_u24_e32 v20, 0x220, v20
	s_waitcnt lgkmcnt(1)
	v_mul_f32_e32 v2, v2, v23
	s_waitcnt lgkmcnt(0)
	v_sub_f32_e32 v8, v22, v8
	v_mul_f32_e32 v8, 0x3fb8aa3b, v8
	v_sub_f32_e32 v9, v22, v9
	v_cndmask_b32_e64 v8, v8, 0, vcc
	v_mul_f32_e32 v9, 0x3fb8aa3b, v9
	v_sub_f32_e32 v10, v22, v10
	v_exp_f32_e32 v8, v8
	v_cndmask_b32_e64 v9, v9, 0, s[42:43]
	v_mul_f32_e32 v10, 0x3fb8aa3b, v10
	v_sub_f32_e32 v11, v22, v11
	v_exp_f32_e32 v9, v9
	v_cndmask_b32_e64 v10, v10, 0, s[44:45]
	v_mul_f32_e32 v11, 0x3fb8aa3b, v11
	v_exp_f32_e32 v10, v10
	v_cndmask_b32_e64 v11, v11, 0, s[48:49]
	v_exp_f32_e32 v11, v11
	v_lshlrev_b32_e32 v19, 2, v19
	v_mul_f32_e32 v2, v2, v8
	v_mul_f32_e32 v3, v3, v23
	v_add3_u32 v20, 0, v20, v19
	v_cndmask_b32_e64 v2, 0, v2, s[40:41]
	v_mul_f32_e32 v3, v3, v9
	v_mul_f32_e32 v4, v4, v23
	v_sub_u32_e32 v22, v20, v0
	v_cndmask_b32_e64 v3, v3, 0, vcc
	v_mul_f32_e32 v4, v4, v10
	v_mul_f32_e32 v5, v5, v23
	ds_write_b32 v22, v2 offset:56824
	v_sub_u32_e32 v2, v20, v30
	v_mul_f32_e32 v8, v31, v8
	v_mul_f32_e32 v9, v33, v9
	v_cndmask_b32_e64 v4, 0, v4, s[46:47]
	v_mul_f32_e32 v10, v35, v10
	v_mul_f32_e32 v5, v5, v11
	v_mul_f32_e32 v11, v28, v11
	ds_write_b32 v2, v3 offset:56824
	v_sub_u32_e32 v2, v20, v37
	v_cndmask_b32_e64 v8, v8, 0, vcc
	v_cndmask_b32_e64 v9, v9, 0, s[42:43]
	v_cndmask_b32_e64 v10, v10, 0, s[44:45]
	v_cndmask_b32_e64 v5, 0, v5, s[50:51]
	v_cndmask_b32_e64 v11, v11, 0, s[48:49]
	ds_write_b32 v2, v4 offset:56824
	v_sub_u32_e32 v2, v20, v38
	ds_write_b32 v2, v5 offset:56824
	v_cvt_pk_bf16_f32 v2, v8, v9
	v_cvt_pk_bf16_f32 v3, v10, v11
	s_or_b32 s1, s1, 1
	ds_write_b64 v26, v[2:3] offset:9216
	s_mul_i32 s3, s1, 0x900
	v_add_u32_e32 v14, s3, v14
	ds_read_b128 v[8:11], v12 offset:9216
	ds_read_b128 v[2:5], v14 offset:9216
	ds_read_b128 v[22:25], v12 offset:9280
	ds_read_b128 v[26:29], v14 offset:9280
	s_waitcnt lgkmcnt(2)
; #define LAS __attribute__((address_space(3)))
; __device__ __forceinline__ float fexp(float x) { return __builtin_amdgcn_exp2f(x * 1.4426950408889634f); }
; __device__ __forceinline__ v2u pack4(const f32x4 v) { v2u r; r.x = pk2(v[0], v[1]); r.y = pk2(v[2], v[3]); return r; }
;     ...
; #pragma unroll
;     for (int k2 = 0; k2 < 2; ++k2) {
;         const int tt = 2 * w + k2, mt = tt >> 2, nt = tt & 3;
;         f32x4 accG = {0.f, 0.f, 0.f, 0.f}, accQ = {0.f, 0.f, 0.f, 0.f};
;         accG = mma_ll<2>(Ks + mt * 16 * 72, 72, Ks + nt * 16 * 72, 72, accG, lane);
;         accQ = mma_ll<2>(Ks + mt * 16 * 72, 72, Qs + nt * 16 * 72, 72, accQ, lane);
;         const int n = nt * 16 + lr, m0 = mt * 16 + 4 * lq;
; #pragma unroll
;         for (int d = 0; d < 2; ++d) {
;             const float gcn = gcS[d * 64 + n], bn = bS[d * 64 + n];
;             f32x4 av, tv;
; #pragma unroll
;             for (int i = 0; i < 4; ++i) { const int m = m0 + i; const float gcm = gcS[d * 64 + m];
;                 const bool strict = d == 0 ? (m < n) : (m > n); const bool incl = d == 0 ? (m <= n) : (m >= n);
;                 const float e = fexp(incl ? (gcn - gcm) : 0.f);
;                 av[i] = strict ? bn * accG[i] * e : 0.f; tv[i] = incl ? 0.125f * accQ[i] * e : 0.f; }
; #pragma unroll
;             for (int i = 0; i < 4; ++i) { const int si = d ? 63 - n : n, sj = d ? 63 - (m0 + i) : m0 + i; As[d * 4352 + (si >> 1) * 136 + sj * 2 + (si & 1)] = av[i]; }
;             *(LAS v2u*)(At + d * 4608 + n * 72 + m0) = pack4(tv);
;         }
;     }
	v_mfma_f32_16x16x32_bf16 v[2:5], v[8:11], v[2:5], 0
	v_lshl_or_b32 v12, s1, 4, v109
	v_cmp_lt_i32_e32 vcc, v15, v12
	v_cmp_gt_i32_e64 s[40:41], v15, v12
	s_waitcnt lgkmcnt(0)
	v_mfma_f32_16x16x32_bf16 v[2:5], v[22:25], v[26:29], v[2:5]
	ds_read_b128 v[26:29], v14
	v_cmp_gt_i32_e64 s[46:47], v34, v12
	v_cmp_gt_i32_e64 s[50:51], v36, v12
	s_waitcnt lgkmcnt(0)
	v_mfma_f32_16x16x32_bf16 v[8:11], v[8:11], v[26:29], 0
	ds_read_b128 v[26:29], v14 offset:64
	v_mad_u32_u24 v14, v12, s4, v16
	v_lshl_add_u32 v16, v12, 2, 0
	s_waitcnt lgkmcnt(0)
	v_mfma_f32_16x16x32_bf16 v[8:11], v[22:25], v[26:29], v[8:11]
	ds_read_b32 v20, v16 offset:37888
	ds_read_b32 v26, v16 offset:37376
	ds_read_b128 v[22:25], v6 offset:37888
	v_cmp_lt_i32_e64 s[42:43], v32, v12
	v_cmp_lt_i32_e64 s[44:45], v34, v12
	s_nop 2
	v_mul_f32_e32 v27, 0x3e000000, v8
	v_mul_f32_e32 v28, 0x3e000000, v9
	s_waitcnt lgkmcnt(0)
	v_sub_f32_e32 v15, v20, v22
	v_mul_f32_e32 v15, 0x3fb8aa3b, v15
	v_cndmask_b32_e64 v15, v15, 0, s[40:41]
	v_exp_f32_e32 v15, v15
	v_mul_f32_e32 v22, v2, v26
	v_mul_f32_e32 v29, 0x3e000000, v10
	v_cmp_lt_i32_e64 s[48:49], v36, v12
	v_mul_f32_e32 v22, v22, v15
	v_mul_f32_e32 v8, v27, v15
	v_sub_f32_e32 v15, v20, v23
	v_mul_f32_e32 v15, 0x3fb8aa3b, v15
	v_cndmask_b32_e32 v15, 0, v15, vcc
	v_exp_f32_e32 v15, v15
	v_mul_f32_e32 v23, v3, v26
	v_lshrrev_b32_e32 v12, 1, v12
	v_cndmask_b32_e32 v22, 0, v22, vcc
	v_mul_f32_e32 v23, v23, v15
	v_mul_f32_e32 v9, v28, v15
	v_sub_f32_e32 v15, v20, v24
	v_mul_f32_e32 v15, 0x3fb8aa3b, v15
	v_cndmask_b32_e64 v15, v15, 0, s[46:47]
	v_exp_f32_e32 v15, v15
	v_mul_f32_e32 v24, v4, v26
	v_cndmask_b32_e64 v8, v8, 0, s[40:41]
	v_cndmask_b32_e64 v23, 0, v23, s[42:43]
	v_mul_f32_e32 v24, v24, v15
	v_mul_f32_e32 v10, v29, v15
	v_sub_f32_e32 v15, v20, v25
	v_mul_f32_e32 v15, 0x3fb8aa3b, v15
	v_cndmask_b32_e64 v15, v15, 0, s[50:51]
	v_exp_f32_e32 v15, v15
	v_mul_f32_e32 v20, v5, v26
	v_mul_f32_e32 v25, 0x3e000000, v11
	v_cndmask_b32_e32 v9, 0, v9, vcc
	v_mul_f32_e32 v20, v20, v15
	v_mul_f32_e32 v11, v25, v15
	v_mul_u32_u24_e32 v15, 0x220, v12
	v_add3_u32 v15, 0, v15, v18
	v_add_u32_e32 v18, v15, v0
	v_cndmask_b32_e64 v10, v10, 0, s[46:47]
	v_cndmask_b32_e64 v11, v11, 0, s[50:51]
	ds_write_b32 v18, v22 offset:38912
	v_add_u32_e32 v18, v15, v30
	v_cndmask_b32_e64 v24, 0, v24, s[44:45]
	v_cndmask_b32_e64 v20, 0, v20, s[48:49]
	ds_write_b32 v18, v23 offset:38912
	v_add_u32_e32 v18, v15, v37
	v_add_u32_e32 v15, v15, v38
	v_cvt_pk_bf16_f32 v8, v8, v9
	v_cvt_pk_bf16_f32 v9, v10, v11
	ds_write_b32 v18, v24 offset:38912
	ds_write_b32 v15, v20 offset:38912
	ds_write_b64 v14, v[8:9]
	ds_read_b32 v15, v16 offset:38144
	ds_read_b32 v16, v16 offset:37632
	ds_read_b128 v[8:11], v6 offset:38144
	s_movk_i32 s92, 0x90
	s_waitcnt lgkmcnt(1)
	v_mul_f32_e32 v2, v2, v16
	s_waitcnt lgkmcnt(0)
	v_sub_f32_e32 v6, v15, v8
	v_mul_f32_e32 v6, 0x3fb8aa3b, v6
	v_sub_f32_e32 v8, v15, v9
	v_cndmask_b32_e64 v6, v6, 0, vcc
	v_mul_f32_e32 v8, 0x3fb8aa3b, v8
	v_sub_f32_e32 v9, v15, v10
	v_sub_f32_e32 v10, v15, v11
	v_exp_f32_e32 v6, v6
	v_cndmask_b32_e64 v8, v8, 0, s[42:43]
	v_mul_f32_e32 v9, 0x3fb8aa3b, v9
	v_mul_f32_e32 v10, 0x3fb8aa3b, v10
	v_exp_f32_e32 v8, v8
	v_cndmask_b32_e64 v9, v9, 0, s[44:45]
	v_cndmask_b32_e64 v10, v10, 0, s[48:49]
	v_exp_f32_e32 v9, v9
	v_exp_f32_e32 v10, v10
	v_xor_b32_e32 v11, 31, v12
	v_mul_u32_u24_e32 v11, 0x220, v11
	v_mul_f32_e32 v2, v2, v6
	v_mul_f32_e32 v3, v3, v16
	v_add3_u32 v11, 0, v11, v19
	v_cndmask_b32_e64 v2, 0, v2, s[40:41]
	v_mul_f32_e32 v3, v3, v8
	v_mul_f32_e32 v4, v4, v16
	v_mul_f32_e32 v5, v5, v16
	v_sub_u32_e32 v0, v11, v0
	v_mul_f32_e32 v6, v27, v6
	v_cndmask_b32_e64 v3, v3, 0, vcc
	v_mul_f32_e32 v8, v28, v8
	v_mul_f32_e32 v4, v4, v9
	v_mul_f32_e32 v9, v29, v9
	v_mul_f32_e32 v5, v5, v10
	v_mul_f32_e32 v10, v25, v10
	ds_write_b32 v0, v2 offset:56824
	v_sub_u32_e32 v0, v11, v30
	v_cndmask_b32_e64 v6, v6, 0, vcc
	v_cndmask_b32_e64 v8, v8, 0, s[42:43]
	v_cndmask_b32_e64 v4, 0, v4, s[46:47]
	v_cndmask_b32_e64 v9, v9, 0, s[44:45]
	v_cndmask_b32_e64 v10, v10, 0, s[48:49]
	ds_write_b32 v0, v3 offset:56824
	v_sub_u32_e32 v0, v11, v37
	v_cndmask_b32_e64 v5, 0, v5, s[50:51]
	ds_write_b32 v0, v4 offset:56824
	v_sub_u32_e32 v0, v11, v38
	v_cvt_pk_bf16_f32 v2, v6, v8
	v_cvt_pk_bf16_f32 v3, v9, v10
	s_andn2_b64 vcc, exec, s[10:11]
	ds_write_b32 v0, v5 offset:56824
	ds_write_b64 v14, v[2:3] offset:9216
	s_waitcnt lgkmcnt(0)
	s_barrier
; #define LAS __attribute__((address_space(3)))
; __device__ __forceinline__ float fexp(float x) { return __builtin_amdgcn_exp2f(x * 1.4426950408889634f); }
;     ...
;     if (w < 2) {
;         const int d = w; const LAS float* Ad = As + d * 4352;
;         float tr[64]; int lane_o = lane;
; #pragma unroll
;         for (int ip = 0; ip < 32; ++ip) {
;             const int i0 = 2 * ip;
;             f32x4 rv[32];
; #pragma unroll
;             for (int jp = 0; jp <= ip; ++jp) rv[jp] = *(const LAS f32x4*)(Ad + ip * 136 + 4 * jp);
;             asm volatile("" : "+v"(lane_o) :: "memory");
;             f32x2_ a0 = {0.f, 0.f}, a1 = {0.f, 0.f}, a2 = {0.f, 0.f}, a3 = {0.f, 0.f};
; #pragma unroll
;             for (int jp = 0; jp < ip; ++jp) {
;                 const f32x2_ ta = {tr[2 * jp], tr[2 * jp]}, tb = {tr[2 * jp + 1], tr[2 * jp + 1]};
;                 const f32x2_ va = {rv[jp][0], rv[jp][1]}, vb = {rv[jp][2], rv[jp][3]};
;                 if (jp & 1) { a2 += va * ta; a3 += vb * tb; } else { a0 += va * ta; a1 += vb * tb; }
;             }
;             const f32x2_ sum = (a0 + a1) + (a2 + a3);
;             const float t0 = (lane_o == i0 ? 1.f : 0.f) - sum[0];
;             tr[i0] = t0;
;             tr[i0 + 1] = (lane_o == i0 + 1 ? 1.f : 0.f) - sum[1] - rv[ip][1] * t0;
;         }
;         const int pb = d ? 63 - lane : lane; const float sb = bS[d * 64 + pb], sbe = sb * fexp(gcS[d * 64 + pb]);
	s_waitcnt vmcnt(0) lgkmcnt(0)
	v_mbcnt_lo_u32_b32 v0, -1, 0
	v_mbcnt_hi_u32_b32 v0, -1, v0
	s_and_b32 s1, s28, 1
	s_lshr_b32 s3, s28, 1
	s_mov_b32 s4, 0x11111111
	s_mov_b32 s5, 0x11111111
	s_mov_b32 s6, 0x22222222
	s_mov_b32 s7, 0x22222222
	s_mov_b32 s8, 0x44444444
	s_mov_b32 s9, 0x44444444
	s_mov_b32 s10, 0x88888888
	s_mov_b32 s11, 0x88888888
	v_and_b32_e32 v6, 3, v0
	v_lshrrev_b32_e32 v12, 2, v0
	s_lshl_b32 s29, s3, 4
	v_add_u32_e32 v12, s29, v12
	s_mul_i32 s29, s1, 0x4400
	s_add_i32 s29, s29, 0x9800
	v_lshlrev_b32_e32 v14, 4, v6
	v_add_u32_e32 v14, s29, v14
	s_mul_i32 s29, s1, 0x3f
	v_xor_b32_e32 v16, s29, v12
	s_lshl_b32 s29, s1, 8
	s_add_i32 s29, s29, 0x9200
	v_lshl_add_u32 v223, v16, 2, s29
	ds_read_b32 v56, v223
	ds_read_b32 v224, v223 offset:512
	s_mul_i32 s29, s1, 0x3
	v_xor_b32_e32 v223, s29, v6
	v_mul_u32_u24_e32 v223, 0x120, v223
	v_lshl_add_u32 v64, v16, 1, v223
	s_mul_i32 s29, s1, 0x4800
	s_add_i32 s29, s29, 0x12800
	v_add_u32_e32 v64, s29, v64
	v_lshlrev_b32_e32 v223, 1, v6
	v_sub_u32_e32 v68, v12, v223
	v_add_u32_e32 v112, -1, v68
	v_cmp_eq_u32_e64 s[12:13], 0, v68
	v_cmp_eq_u32_e64 s[14:15], 0, v112
	s_nop 0
	v_cndmask_b32_e64 v2, 0, 1.0, s[12:13]
	v_cndmask_b32_e64 v3, 0, 1.0, s[14:15]
	v_cmp_eq_u32_e64 s[12:13], 8, v68
	v_cmp_eq_u32_e64 s[14:15], 8, v112
	s_nop 0
	v_cndmask_b32_e64 v4, 0, 1.0, s[12:13]
	v_cndmask_b32_e64 v5, 0, 1.0, s[14:15]
	v_cmp_eq_u32_e64 s[12:13], 16, v68
	v_cmp_eq_u32_e64 s[14:15], 16, v112
	s_nop 0
	v_cndmask_b32_e64 v8, 0, 1.0, s[12:13]
	v_cndmask_b32_e64 v9, 0, 1.0, s[14:15]
	v_cmp_eq_u32_e64 s[12:13], 24, v68
	v_cmp_eq_u32_e64 s[14:15], 24, v112
	s_nop 0
	v_cndmask_b32_e64 v10, 0, 1.0, s[12:13]
	v_cndmask_b32_e64 v11, 0, 1.0, s[14:15]
	v_cmp_eq_u32_e64 s[12:13], 32, v68
	v_cmp_eq_u32_e64 s[14:15], 32, v112
	s_nop 0
	v_cndmask_b32_e64 v18, 0, 1.0, s[12:13]
	v_cndmask_b32_e64 v19, 0, 1.0, s[14:15]
	v_cmp_eq_u32_e64 s[12:13], 40, v68
	v_cmp_eq_u32_e64 s[14:15], 40, v112
	s_nop 0
	v_cndmask_b32_e64 v50, 0, 1.0, s[12:13]
	v_cndmask_b32_e64 v51, 0, 1.0, s[14:15]
	v_cmp_eq_u32_e64 s[12:13], 48, v68
	v_cmp_eq_u32_e64 s[14:15], 48, v112
	s_nop 0
	v_cndmask_b32_e64 v54, 0, 1.0, s[12:13]
	v_cndmask_b32_e64 v55, 0, 1.0, s[14:15]
	v_cmp_eq_u32_e64 s[12:13], 56, v68
	v_cmp_eq_u32_e64 s[14:15], 56, v112
	s_nop 0
	v_cndmask_b32_e64 v58, 0, 1.0, s[12:13]
	v_cndmask_b32_e64 v59, 0, 1.0, s[14:15]
	v_cmp_eq_u32_e64 s[12:13], 0, v6
	s_nop 1
	v_cndmask_b32_e64 v68, 0, -1.0, s[12:13]
	v_cmp_eq_u32_e64 s[14:15], 1, v6
	s_nop 1
	v_cndmask_b32_e64 v112, 0, -1.0, s[14:15]
	v_cmp_eq_u32_e64 s[12:13], 2, v6
	s_nop 1
	v_cndmask_b32_e64 v116, 0, -1.0, s[12:13]
	v_cmp_eq_u32_e64 s[14:15], 3, v6
	s_nop 1
	v_cndmask_b32_e64 v120, 0, -1.0, s[14:15]
	s_waitcnt lgkmcnt(0)
	v_mul_f32_e32 v224, 0x3fb8aa3b, v224
	v_exp_f32_e32 v224, v224
	s_nop 0
	v_mul_f32_e32 v60, v56, v224
	s_cmp_eq_u32 s3, 0
	s_cbranch_scc1 .Lfs_ent0
	s_cmp_eq_u32 s3, 1
	s_cbranch_scc1 .Lfs_ent1
	s_cmp_eq_u32 s3, 2
	s_cbranch_scc1 .Lfs_ent2
	s_branch .Lfs_ent3
.Lfs_ent0:
	ds_read_b128 v[70:73], v14 offset:0
	ds_read_b128 v[122:125], v14 offset:544
	s_waitcnt lgkmcnt(1)
	v_pk_fma_f32 v[62:63], v[70:71], v[2:3], 0 op_sel_hi:[1,0,0]
	v_pk_fma_f32 v[62:63], v[72:73], v[2:3], v[62:63] op_sel:[0,1,0] op_sel_hi:[1,1,1]
	s_nop 1
	v_add_f32_dpp v62, v62, v62 quad_perm:[1,0,3,2] row_mask:0xf bank_mask:0xf bound_ctrl:1
	v_add_f32_dpp v63, v63, v63 quad_perm:[1,0,3,2] row_mask:0xf bank_mask:0xf bound_ctrl:1
	s_nop 0
	v_add_f32_dpp v62, v62, v62 quad_perm:[2,3,0,1] row_mask:0xf bank_mask:0xf bound_ctrl:1
	v_add_f32_dpp v63, v63, v63 quad_perm:[2,3,0,1] row_mask:0xf bank_mask:0xf bound_ctrl:1
	v_fma_f32 v63, -v71, v62, v63
	v_pk_fma_f32 v[2:3], v[62:63], v[68:69], v[2:3] op_sel_hi:[1,0,1]
	ds_read_b128 v[70:73], v14 offset:1088
	s_waitcnt lgkmcnt(1)
	v_pk_fma_f32 v[62:63], v[122:123], v[2:3], 0 op_sel_hi:[1,0,0]
	v_pk_fma_f32 v[62:63], v[124:125], v[2:3], v[62:63] op_sel:[0,1,0] op_sel_hi:[1,1,1]
	s_nop 1
	v_add_f32_dpp v62, v62, v62 quad_perm:[1,0,3,2] row_mask:0xf bank_mask:0xf bound_ctrl:1
	v_add_f32_dpp v63, v63, v63 quad_perm:[1,0,3,2] row_mask:0xf bank_mask:0xf bound_ctrl:1
	s_nop 0
	v_add_f32_dpp v62, v62, v62 quad_perm:[2,3,0,1] row_mask:0xf bank_mask:0xf bound_ctrl:1
	v_add_f32_dpp v63, v63, v63 quad_perm:[2,3,0,1] row_mask:0xf bank_mask:0xf bound_ctrl:1
	v_fma_f32 v63, -v123, v62, v63
	v_pk_fma_f32 v[2:3], v[62:63], v[112:113], v[2:3] op_sel_hi:[1,0,1]
	ds_read_b128 v[122:125], v14 offset:1632
	s_waitcnt lgkmcnt(1)
	v_pk_fma_f32 v[62:63], v[70:71], v[2:3], 0 op_sel_hi:[1,0,0]
	v_pk_fma_f32 v[62:63], v[72:73], v[2:3], v[62:63] op_sel:[0,1,0] op_sel_hi:[1,1,1]
	s_nop 1
	v_add_f32_dpp v62, v62, v62 quad_perm:[1,0,3,2] row_mask:0xf bank_mask:0xf bound_ctrl:1
	v_add_f32_dpp v63, v63, v63 quad_perm:[1,0,3,2] row_mask:0xf bank_mask:0xf bound_ctrl:1
	s_nop 0
	v_add_f32_dpp v62, v62, v62 quad_perm:[2,3,0,1] row_mask:0xf bank_mask:0xf bound_ctrl:1
	v_add_f32_dpp v63, v63, v63 quad_perm:[2,3,0,1] row_mask:0xf bank_mask:0xf bound_ctrl:1
	v_fma_f32 v63, -v71, v62, v63
	v_pk_fma_f32 v[2:3], v[62:63], v[116:117], v[2:3] op_sel_hi:[1,0,1]
	ds_read_b128 v[70:73], v14 offset:2176
	ds_read_b128 v[74:77], v14 offset:2240
	s_waitcnt lgkmcnt(2)
	v_pk_fma_f32 v[62:63], v[122:123], v[2:3], 0 op_sel_hi:[1,0,0]
	v_pk_fma_f32 v[62:63], v[124:125], v[2:3], v[62:63] op_sel:[0,1,0] op_sel_hi:[1,1,1]
	s_nop 1
	v_add_f32_dpp v62, v62, v62 quad_perm:[1,0,3,2] row_mask:0xf bank_mask:0xf bound_ctrl:1
	v_add_f32_dpp v63, v63, v63 quad_perm:[1,0,3,2] row_mask:0xf bank_mask:0xf bound_ctrl:1
	s_nop 0
	v_add_f32_dpp v62, v62, v62 quad_perm:[2,3,0,1] row_mask:0xf bank_mask:0xf bound_ctrl:1
	v_add_f32_dpp v63, v63, v63 quad_perm:[2,3,0,1] row_mask:0xf bank_mask:0xf bound_ctrl:1
	v_fma_f32 v63, -v123, v62, v63
	v_pk_fma_f32 v[2:3], v[62:63], v[120:121], v[2:3] op_sel_hi:[1,0,1]
	ds_read_b128 v[122:125], v14 offset:2720
	ds_read_b128 v[126:129], v14 offset:2784
	s_waitcnt lgkmcnt(2)
; #define LAS __attribute__((address_space(3)))
;     ...
;     if (w < 2) {
;         const int d = w; const LAS float* Ad = As + d * 4352;
;         float tr[64]; int lane_o = lane;
; #pragma unroll
;         for (int ip = 0; ip < 32; ++ip) {
;             const int i0 = 2 * ip;
;             f32x4 rv[32];
; #pragma unroll
;             for (int jp = 0; jp <= ip; ++jp) rv[jp] = *(const LAS f32x4*)(Ad + ip * 136 + 4 * jp);
;             asm volatile("" : "+v"(lane_o) :: "memory");
;             f32x2_ a0 = {0.f, 0.f}, a1 = {0.f, 0.f}, a2 = {0.f, 0.f}, a3 = {0.f, 0.f};
; #pragma unroll
;             for (int jp = 0; jp < ip; ++jp) {
;                 const f32x2_ ta = {tr[2 * jp], tr[2 * jp]}, tb = {tr[2 * jp + 1], tr[2 * jp + 1]};
;                 const f32x2_ va = {rv[jp][0], rv[jp][1]}, vb = {rv[jp][2], rv[jp][3]};
;                 if (jp & 1) { a2 += va * ta; a3 += vb * tb; } else { a0 += va * ta; a1 += vb * tb; }
;             }
;             const f32x2_ sum = (a0 + a1) + (a2 + a3);
;             const float t0 = (lane_o == i0 ? 1.f : 0.f) - sum[0];
;             tr[i0] = t0;
;             tr[i0 + 1] = (lane_o == i0 + 1 ? 1.f : 0.f) - sum[1] - rv[ip][1] * t0;
;         }
	v_pk_fma_f32 v[62:63], v[74:75], v[4:5], 0 op_sel_hi:[1,0,0]
	v_pk_fma_f32 v[62:63], v[76:77], v[4:5], v[62:63] op_sel:[0,1,0] op_sel_hi:[1,1,1]
	v_pk_fma_f32 v[62:63], v[70:71], v[2:3], v[62:63] op_sel_hi:[1,0,1]
	v_pk_fma_f32 v[62:63], v[72:73], v[2:3], v[62:63] op_sel:[0,1,0] op_sel_hi:[1,1,1]
	s_nop 1
	v_add_f32_dpp v62, v62, v62 quad_perm:[1,0,3,2] row_mask:0xf bank_mask:0xf bound_ctrl:1
	v_add_f32_dpp v63, v63, v63 quad_perm:[1,0,3,2] row_mask:0xf bank_mask:0xf bound_ctrl:1
	s_nop 0
	v_add_f32_dpp v62, v62, v62 quad_perm:[2,3,0,1] row_mask:0xf bank_mask:0xf bound_ctrl:1
	v_add_f32_dpp v63, v63, v63 quad_perm:[2,3,0,1] row_mask:0xf bank_mask:0xf bound_ctrl:1
	v_fma_f32 v63, -v75, v62, v63
	v_pk_fma_f32 v[4:5], v[62:63], v[68:69], v[4:5] op_sel_hi:[1,0,1]
	ds_read_b128 v[70:73], v14 offset:3264
	ds_read_b128 v[74:77], v14 offset:3328
	s_waitcnt lgkmcnt(2)
	v_pk_fma_f32 v[62:63], v[122:123], v[2:3], 0 op_sel_hi:[1,0,0]
	v_pk_fma_f32 v[62:63], v[124:125], v[2:3], v[62:63] op_sel:[0,1,0] op_sel_hi:[1,1,1]
	v_pk_fma_f32 v[62:63], v[126:127], v[4:5], v[62:63] op_sel_hi:[1,0,1]
	v_pk_fma_f32 v[62:63], v[128:129], v[4:5], v[62:63] op_sel:[0,1,0] op_sel_hi:[1,1,1]
	s_nop 1
	v_add_f32_dpp v62, v62, v62 quad_perm:[1,0,3,2] row_mask:0xf bank_mask:0xf bound_ctrl:1
	v_add_f32_dpp v63, v63, v63 quad_perm:[1,0,3,2] row_mask:0xf bank_mask:0xf bound_ctrl:1
	s_nop 0
	v_add_f32_dpp v62, v62, v62 quad_perm:[2,3,0,1] row_mask:0xf bank_mask:0xf bound_ctrl:1
	v_add_f32_dpp v63, v63, v63 quad_perm:[2,3,0,1] row_mask:0xf bank_mask:0xf bound_ctrl:1
	v_fma_f32 v63, -v127, v62, v63
	v_pk_fma_f32 v[4:5], v[62:63], v[112:113], v[4:5] op_sel_hi:[1,0,1]
	ds_read_b128 v[122:125], v14 offset:3808
	ds_read_b128 v[126:129], v14 offset:3872
	s_waitcnt lgkmcnt(2)
	v_pk_fma_f32 v[62:63], v[70:71], v[2:3], 0 op_sel_hi:[1,0,0]
	v_pk_fma_f32 v[62:63], v[72:73], v[2:3], v[62:63] op_sel:[0,1,0] op_sel_hi:[1,1,1]
	v_pk_fma_f32 v[62:63], v[74:75], v[4:5], v[62:63] op_sel_hi:[1,0,1]
	v_pk_fma_f32 v[62:63], v[76:77], v[4:5], v[62:63] op_sel:[0,1,0] op_sel_hi:[1,1,1]
	s_nop 1
	v_add_f32_dpp v62, v62, v62 quad_perm:[1,0,3,2] row_mask:0xf bank_mask:0xf bound_ctrl:1
	v_add_f32_dpp v63, v63, v63 quad_perm:[1,0,3,2] row_mask:0xf bank_mask:0xf bound_ctrl:1
	s_nop 0
	v_add_f32_dpp v62, v62, v62 quad_perm:[2,3,0,1] row_mask:0xf bank_mask:0xf bound_ctrl:1
	v_add_f32_dpp v63, v63, v63 quad_perm:[2,3,0,1] row_mask:0xf bank_mask:0xf bound_ctrl:1
	v_fma_f32 v63, -v75, v62, v63
	v_pk_fma_f32 v[4:5], v[62:63], v[116:117], v[4:5] op_sel_hi:[1,0,1]
	ds_read_b128 v[70:73], v14 offset:4352
	ds_read_b128 v[74:77], v14 offset:4416
	ds_read_b128 v[78:81], v14 offset:4480
	s_waitcnt lgkmcnt(3)
	v_pk_fma_f32 v[62:63], v[122:123], v[2:3], 0 op_sel_hi:[1,0,0]
	v_pk_fma_f32 v[62:63], v[124:125], v[2:3], v[62:63] op_sel:[0,1,0] op_sel_hi:[1,1,1]
	v_pk_fma_f32 v[62:63], v[126:127], v[4:5], v[62:63] op_sel_hi:[1,0,1]
	v_pk_fma_f32 v[62:63], v[128:129], v[4:5], v[62:63] op_sel:[0,1,0] op_sel_hi:[1,1,1]
	s_nop 1
	v_add_f32_dpp v62, v62, v62 quad_perm:[1,0,3,2] row_mask:0xf bank_mask:0xf bound_ctrl:1
	v_add_f32_dpp v63, v63, v63 quad_perm:[1,0,3,2] row_mask:0xf bank_mask:0xf bound_ctrl:1
	s_nop 0
	v_add_f32_dpp v62, v62, v62 quad_perm:[2,3,0,1] row_mask:0xf bank_mask:0xf bound_ctrl:1
	v_add_f32_dpp v63, v63, v63 quad_perm:[2,3,0,1] row_mask:0xf bank_mask:0xf bound_ctrl:1
	v_fma_f32 v63, -v127, v62, v63
	v_pk_fma_f32 v[4:5], v[62:63], v[120:121], v[4:5] op_sel_hi:[1,0,1]
	ds_read_b128 v[122:125], v14 offset:4896
	ds_read_b128 v[126:129], v14 offset:4960
	ds_read_b128 v[130:133], v14 offset:5024
	s_waitcnt lgkmcnt(3)
	v_pk_fma_f32 v[62:63], v[70:71], v[2:3], 0 op_sel_hi:[1,0,0]
	v_pk_fma_f32 v[62:63], v[72:73], v[2:3], v[62:63] op_sel:[0,1,0] op_sel_hi:[1,1,1]
	v_pk_fma_f32 v[62:63], v[78:79], v[8:9], v[62:63] op_sel_hi:[1,0,1]
	v_pk_fma_f32 v[62:63], v[80:81], v[8:9], v[62:63] op_sel:[0,1,0] op_sel_hi:[1,1,1]
	v_pk_fma_f32 v[62:63], v[74:75], v[4:5], v[62:63] op_sel_hi:[1,0,1]
	v_pk_fma_f32 v[62:63], v[76:77], v[4:5], v[62:63] op_sel:[0,1,0] op_sel_hi:[1,1,1]
	s_nop 1
	v_add_f32_dpp v62, v62, v62 quad_perm:[1,0,3,2] row_mask:0xf bank_mask:0xf bound_ctrl:1
	v_add_f32_dpp v63, v63, v63 quad_perm:[1,0,3,2] row_mask:0xf bank_mask:0xf bound_ctrl:1
	s_nop 0
	v_add_f32_dpp v62, v62, v62 quad_perm:[2,3,0,1] row_mask:0xf bank_mask:0xf bound_ctrl:1
	v_add_f32_dpp v63, v63, v63 quad_perm:[2,3,0,1] row_mask:0xf bank_mask:0xf bound_ctrl:1
	v_fma_f32 v63, -v79, v62, v63
	v_pk_fma_f32 v[8:9], v[62:63], v[68:69], v[8:9] op_sel_hi:[1,0,1]
	ds_read_b128 v[70:73], v14 offset:5440
	ds_read_b128 v[74:77], v14 offset:5504
	ds_read_b128 v[78:81], v14 offset:5568
	s_waitcnt lgkmcnt(3)
	v_pk_fma_f32 v[62:63], v[122:123], v[2:3], 0 op_sel_hi:[1,0,0]
	v_pk_fma_f32 v[62:63], v[124:125], v[2:3], v[62:63] op_sel:[0,1,0] op_sel_hi:[1,1,1]
	v_pk_fma_f32 v[62:63], v[126:127], v[4:5], v[62:63] op_sel_hi:[1,0,1]
	v_pk_fma_f32 v[62:63], v[128:129], v[4:5], v[62:63] op_sel:[0,1,0] op_sel_hi:[1,1,1]
	v_pk_fma_f32 v[62:63], v[130:131], v[8:9], v[62:63] op_sel_hi:[1,0,1]
	v_pk_fma_f32 v[62:63], v[132:133], v[8:9], v[62:63] op_sel:[0,1,0] op_sel_hi:[1,1,1]
	s_nop 1
	v_add_f32_dpp v62, v62, v62 quad_perm:[1,0,3,2] row_mask:0xf bank_mask:0xf bound_ctrl:1
	v_add_f32_dpp v63, v63, v63 quad_perm:[1,0,3,2] row_mask:0xf bank_mask:0xf bound_ctrl:1
	s_nop 0
	v_add_f32_dpp v62, v62, v62 quad_perm:[2,3,0,1] row_mask:0xf bank_mask:0xf bound_ctrl:1
	v_add_f32_dpp v63, v63, v63 quad_perm:[2,3,0,1] row_mask:0xf bank_mask:0xf bound_ctrl:1
	v_fma_f32 v63, -v131, v62, v63
	v_pk_fma_f32 v[8:9], v[62:63], v[112:113], v[8:9] op_sel_hi:[1,0,1]
	ds_read_b128 v[122:125], v14 offset:5984
	ds_read_b128 v[126:129], v14 offset:6048
	ds_read_b128 v[130:133], v14 offset:6112
	s_waitcnt lgkmcnt(3)
; #define LAS __attribute__((address_space(3)))
;     ...
;     if (w < 2) {
;         const int d = w; const LAS float* Ad = As + d * 4352;
;         float tr[64]; int lane_o = lane;
; #pragma unroll
;         for (int ip = 0; ip < 32; ++ip) {
;             const int i0 = 2 * ip;
;             f32x4 rv[32];
; #pragma unroll
;             for (int jp = 0; jp <= ip; ++jp) rv[jp] = *(const LAS f32x4*)(Ad + ip * 136 + 4 * jp);
;             asm volatile("" : "+v"(lane_o) :: "memory");
;             f32x2_ a0 = {0.f, 0.f}, a1 = {0.f, 0.f}, a2 = {0.f, 0.f}, a3 = {0.f, 0.f};
; #pragma unroll
;             for (int jp = 0; jp < ip; ++jp) {
;                 const f32x2_ ta = {tr[2 * jp], tr[2 * jp]}, tb = {tr[2 * jp + 1], tr[2 * jp + 1]};
;                 const f32x2_ va = {rv[jp][0], rv[jp][1]}, vb = {rv[jp][2], rv[jp][3]};
;                 if (jp & 1) { a2 += va * ta; a3 += vb * tb; } else { a0 += va * ta; a1 += vb * tb; }
;             }
;             const f32x2_ sum = (a0 + a1) + (a2 + a3);
;             const float t0 = (lane_o == i0 ? 1.f : 0.f) - sum[0];
;             tr[i0] = t0;
;             tr[i0 + 1] = (lane_o == i0 + 1 ? 1.f : 0.f) - sum[1] - rv[ip][1] * t0;
;         }
	v_pk_fma_f32 v[62:63], v[70:71], v[2:3], 0 op_sel_hi:[1,0,0]
	v_pk_fma_f32 v[62:63], v[72:73], v[2:3], v[62:63] op_sel:[0,1,0] op_sel_hi:[1,1,1]
	v_pk_fma_f32 v[62:63], v[74:75], v[4:5], v[62:63] op_sel_hi:[1,0,1]
	v_pk_fma_f32 v[62:63], v[76:77], v[4:5], v[62:63] op_sel:[0,1,0] op_sel_hi:[1,1,1]
	v_pk_fma_f32 v[62:63], v[78:79], v[8:9], v[62:63] op_sel_hi:[1,0,1]
	v_pk_fma_f32 v[62:63], v[80:81], v[8:9], v[62:63] op_sel:[0,1,0] op_sel_hi:[1,1,1]
	s_nop 1
	v_add_f32_dpp v62, v62, v62 quad_perm:[1,0,3,2] row_mask:0xf bank_mask:0xf bound_ctrl:1
	v_add_f32_dpp v63, v63, v63 quad_perm:[1,0,3,2] row_mask:0xf bank_mask:0xf bound_ctrl:1
	s_nop 0
	v_add_f32_dpp v62, v62, v62 quad_perm:[2,3,0,1] row_mask:0xf bank_mask:0xf bound_ctrl:1
	v_add_f32_dpp v63, v63, v63 quad_perm:[2,3,0,1] row_mask:0xf bank_mask:0xf bound_ctrl:1
	v_fma_f32 v63, -v79, v62, v63
	v_pk_fma_f32 v[8:9], v[62:63], v[116:117], v[8:9] op_sel_hi:[1,0,1]
	ds_read_b128 v[70:73], v14 offset:6528
	ds_read_b128 v[74:77], v14 offset:6592
	ds_read_b128 v[78:81], v14 offset:6656
	ds_read_b128 v[82:85], v14 offset:6720
	s_waitcnt lgkmcnt(4)
	v_pk_fma_f32 v[62:63], v[122:123], v[2:3], 0 op_sel_hi:[1,0,0]
	v_pk_fma_f32 v[62:63], v[124:125], v[2:3], v[62:63] op_sel:[0,1,0] op_sel_hi:[1,1,1]
	v_pk_fma_f32 v[62:63], v[126:127], v[4:5], v[62:63] op_sel_hi:[1,0,1]
	v_pk_fma_f32 v[62:63], v[128:129], v[4:5], v[62:63] op_sel:[0,1,0] op_sel_hi:[1,1,1]
	v_pk_fma_f32 v[62:63], v[130:131], v[8:9], v[62:63] op_sel_hi:[1,0,1]
	v_pk_fma_f32 v[62:63], v[132:133], v[8:9], v[62:63] op_sel:[0,1,0] op_sel_hi:[1,1,1]
	s_nop 1
	v_add_f32_dpp v62, v62, v62 quad_perm:[1,0,3,2] row_mask:0xf bank_mask:0xf bound_ctrl:1
	v_add_f32_dpp v63, v63, v63 quad_perm:[1,0,3,2] row_mask:0xf bank_mask:0xf bound_ctrl:1
	s_nop 0
	v_add_f32_dpp v62, v62, v62 quad_perm:[2,3,0,1] row_mask:0xf bank_mask:0xf bound_ctrl:1
	v_add_f32_dpp v63, v63, v63 quad_perm:[2,3,0,1] row_mask:0xf bank_mask:0xf bound_ctrl:1
	v_fma_f32 v63, -v131, v62, v63
	v_pk_fma_f32 v[8:9], v[62:63], v[120:121], v[8:9] op_sel_hi:[1,0,1]
	ds_read_b128 v[122:125], v14 offset:7072
	ds_read_b128 v[126:129], v14 offset:7136
	ds_read_b128 v[130:133], v14 offset:7200
	ds_read_b128 v[38:41], v14 offset:7264
	s_waitcnt lgkmcnt(4)
	v_pk_fma_f32 v[62:63], v[70:71], v[2:3], 0 op_sel_hi:[1,0,0]
	v_pk_fma_f32 v[62:63], v[72:73], v[2:3], v[62:63] op_sel:[0,1,0] op_sel_hi:[1,1,1]
	v_pk_fma_f32 v[62:63], v[74:75], v[4:5], v[62:63] op_sel_hi:[1,0,1]
	v_pk_fma_f32 v[62:63], v[76:77], v[4:5], v[62:63] op_sel:[0,1,0] op_sel_hi:[1,1,1]
	v_pk_fma_f32 v[62:63], v[82:83], v[10:11], v[62:63] op_sel_hi:[1,0,1]
	v_pk_fma_f32 v[62:63], v[84:85], v[10:11], v[62:63] op_sel:[0,1,0] op_sel_hi:[1,1,1]
	v_pk_fma_f32 v[62:63], v[78:79], v[8:9], v[62:63] op_sel_hi:[1,0,1]
	v_pk_fma_f32 v[62:63], v[80:81], v[8:9], v[62:63] op_sel:[0,1,0] op_sel_hi:[1,1,1]
	s_nop 1
	v_add_f32_dpp v62, v62, v62 quad_perm:[1,0,3,2] row_mask:0xf bank_mask:0xf bound_ctrl:1
	v_add_f32_dpp v63, v63, v63 quad_perm:[1,0,3,2] row_mask:0xf bank_mask:0xf bound_ctrl:1
	s_nop 0
	v_add_f32_dpp v62, v62, v62 quad_perm:[2,3,0,1] row_mask:0xf bank_mask:0xf bound_ctrl:1
	v_add_f32_dpp v63, v63, v63 quad_perm:[2,3,0,1] row_mask:0xf bank_mask:0xf bound_ctrl:1
	v_fma_f32 v63, -v83, v62, v63
	v_pk_fma_f32 v[10:11], v[62:63], v[68:69], v[10:11] op_sel_hi:[1,0,1]
	ds_read_b128 v[70:73], v14 offset:7616
	ds_read_b128 v[74:77], v14 offset:7680
	ds_read_b128 v[78:81], v14 offset:7744
	ds_read_b128 v[82:85], v14 offset:7808
	s_waitcnt lgkmcnt(4)
	v_pk_fma_f32 v[62:63], v[122:123], v[2:3], 0 op_sel_hi:[1,0,0]
	v_pk_fma_f32 v[62:63], v[124:125], v[2:3], v[62:63] op_sel:[0,1,0] op_sel_hi:[1,1,1]
	v_pk_fma_f32 v[62:63], v[126:127], v[4:5], v[62:63] op_sel_hi:[1,0,1]
	v_pk_fma_f32 v[62:63], v[128:129], v[4:5], v[62:63] op_sel:[0,1,0] op_sel_hi:[1,1,1]
	v_pk_fma_f32 v[62:63], v[130:131], v[8:9], v[62:63] op_sel_hi:[1,0,1]
	v_pk_fma_f32 v[62:63], v[132:133], v[8:9], v[62:63] op_sel:[0,1,0] op_sel_hi:[1,1,1]
	v_pk_fma_f32 v[62:63], v[38:39], v[10:11], v[62:63] op_sel_hi:[1,0,1]
	v_pk_fma_f32 v[62:63], v[40:41], v[10:11], v[62:63] op_sel:[0,1,0] op_sel_hi:[1,1,1]
	s_nop 1
	v_add_f32_dpp v62, v62, v62 quad_perm:[1,0,3,2] row_mask:0xf bank_mask:0xf bound_ctrl:1
	v_add_f32_dpp v63, v63, v63 quad_perm:[1,0,3,2] row_mask:0xf bank_mask:0xf bound_ctrl:1
	s_nop 0
	v_add_f32_dpp v62, v62, v62 quad_perm:[2,3,0,1] row_mask:0xf bank_mask:0xf bound_ctrl:1
	v_add_f32_dpp v63, v63, v63 quad_perm:[2,3,0,1] row_mask:0xf bank_mask:0xf bound_ctrl:1
	v_fma_f32 v63, -v39, v62, v63
	v_pk_fma_f32 v[10:11], v[62:63], v[112:113], v[10:11] op_sel_hi:[1,0,1]
	ds_read_b128 v[122:125], v14 offset:8160
	ds_read_b128 v[126:129], v14 offset:8224
	ds_read_b128 v[130:133], v14 offset:8288
	ds_read_b128 v[38:41], v14 offset:8352
	s_waitcnt lgkmcnt(4)
	v_pk_fma_f32 v[62:63], v[70:71], v[2:3], 0 op_sel_hi:[1,0,0]
	v_pk_fma_f32 v[62:63], v[72:73], v[2:3], v[62:63] op_sel:[0,1,0] op_sel_hi:[1,1,1]
	v_pk_fma_f32 v[62:63], v[74:75], v[4:5], v[62:63] op_sel_hi:[1,0,1]
	v_pk_fma_f32 v[62:63], v[76:77], v[4:5], v[62:63] op_sel:[0,1,0] op_sel_hi:[1,1,1]
	v_pk_fma_f32 v[62:63], v[78:79], v[8:9], v[62:63] op_sel_hi:[1,0,1]
	v_pk_fma_f32 v[62:63], v[80:81], v[8:9], v[62:63] op_sel:[0,1,0] op_sel_hi:[1,1,1]
	v_pk_fma_f32 v[62:63], v[82:83], v[10:11], v[62:63] op_sel_hi:[1,0,1]
	v_pk_fma_f32 v[62:63], v[84:85], v[10:11], v[62:63] op_sel:[0,1,0] op_sel_hi:[1,1,1]
	s_nop 1
	v_add_f32_dpp v62, v62, v62 quad_perm:[1,0,3,2] row_mask:0xf bank_mask:0xf bound_ctrl:1
	v_add_f32_dpp v63, v63, v63 quad_perm:[1,0,3,2] row_mask:0xf bank_mask:0xf bound_ctrl:1
	s_nop 0
	v_add_f32_dpp v62, v62, v62 quad_perm:[2,3,0,1] row_mask:0xf bank_mask:0xf bound_ctrl:1
	v_add_f32_dpp v63, v63, v63 quad_perm:[2,3,0,1] row_mask:0xf bank_mask:0xf bound_ctrl:1
	v_fma_f32 v63, -v83, v62, v63
	v_pk_fma_f32 v[10:11], v[62:63], v[116:117], v[10:11] op_sel_hi:[1,0,1]
	ds_read_b128 v[70:73], v14 offset:8704
	ds_read_b128 v[74:77], v14 offset:8768
	ds_read_b128 v[78:81], v14 offset:8832
	ds_read_b128 v[82:85], v14 offset:8896
	ds_read_b128 v[86:89], v14 offset:8960
	s_waitcnt lgkmcnt(5)
; #define LAS __attribute__((address_space(3)))
;     ...
;     if (w < 2) {
;         const int d = w; const LAS float* Ad = As + d * 4352;
;         float tr[64]; int lane_o = lane;
; #pragma unroll
;         for (int ip = 0; ip < 32; ++ip) {
;             const int i0 = 2 * ip;
;             f32x4 rv[32];
; #pragma unroll
;             for (int jp = 0; jp <= ip; ++jp) rv[jp] = *(const LAS f32x4*)(Ad + ip * 136 + 4 * jp);
;             asm volatile("" : "+v"(lane_o) :: "memory");
;             f32x2_ a0 = {0.f, 0.f}, a1 = {0.f, 0.f}, a2 = {0.f, 0.f}, a3 = {0.f, 0.f};
; #pragma unroll
;             for (int jp = 0; jp < ip; ++jp) {
;                 const f32x2_ ta = {tr[2 * jp], tr[2 * jp]}, tb = {tr[2 * jp + 1], tr[2 * jp + 1]};
;                 const f32x2_ va = {rv[jp][0], rv[jp][1]}, vb = {rv[jp][2], rv[jp][3]};
;                 if (jp & 1) { a2 += va * ta; a3 += vb * tb; } else { a0 += va * ta; a1 += vb * tb; }
;             }
;             const f32x2_ sum = (a0 + a1) + (a2 + a3);
;             const float t0 = (lane_o == i0 ? 1.f : 0.f) - sum[0];
;             tr[i0] = t0;
;             tr[i0 + 1] = (lane_o == i0 + 1 ? 1.f : 0.f) - sum[1] - rv[ip][1] * t0;
;         }
	v_pk_fma_f32 v[62:63], v[122:123], v[2:3], 0 op_sel_hi:[1,0,0]
	v_pk_fma_f32 v[62:63], v[124:125], v[2:3], v[62:63] op_sel:[0,1,0] op_sel_hi:[1,1,1]
	v_pk_fma_f32 v[62:63], v[126:127], v[4:5], v[62:63] op_sel_hi:[1,0,1]
	v_pk_fma_f32 v[62:63], v[128:129], v[4:5], v[62:63] op_sel:[0,1,0] op_sel_hi:[1,1,1]
	v_pk_fma_f32 v[62:63], v[130:131], v[8:9], v[62:63] op_sel_hi:[1,0,1]
	v_pk_fma_f32 v[62:63], v[132:133], v[8:9], v[62:63] op_sel:[0,1,0] op_sel_hi:[1,1,1]
	v_pk_fma_f32 v[62:63], v[38:39], v[10:11], v[62:63] op_sel_hi:[1,0,1]
	v_pk_fma_f32 v[62:63], v[40:41], v[10:11], v[62:63] op_sel:[0,1,0] op_sel_hi:[1,1,1]
	s_nop 1
	v_add_f32_dpp v62, v62, v62 quad_perm:[1,0,3,2] row_mask:0xf bank_mask:0xf bound_ctrl:1
	v_add_f32_dpp v63, v63, v63 quad_perm:[1,0,3,2] row_mask:0xf bank_mask:0xf bound_ctrl:1
	s_nop 0
	v_add_f32_dpp v62, v62, v62 quad_perm:[2,3,0,1] row_mask:0xf bank_mask:0xf bound_ctrl:1
	v_add_f32_dpp v63, v63, v63 quad_perm:[2,3,0,1] row_mask:0xf bank_mask:0xf bound_ctrl:1
	v_fma_f32 v63, -v39, v62, v63
	v_pk_fma_f32 v[10:11], v[62:63], v[120:121], v[10:11] op_sel_hi:[1,0,1]
	ds_read_b128 v[122:125], v14 offset:9248
	ds_read_b128 v[126:129], v14 offset:9312
	ds_read_b128 v[130:133], v14 offset:9376
	ds_read_b128 v[38:41], v14 offset:9440
	ds_read_b128 v[42:45], v14 offset:9504
	s_waitcnt lgkmcnt(5)
	v_pk_fma_f32 v[62:63], v[70:71], v[2:3], 0 op_sel_hi:[1,0,0]
	v_pk_fma_f32 v[62:63], v[72:73], v[2:3], v[62:63] op_sel:[0,1,0] op_sel_hi:[1,1,1]
	v_pk_fma_f32 v[62:63], v[74:75], v[4:5], v[62:63] op_sel_hi:[1,0,1]
	v_pk_fma_f32 v[62:63], v[76:77], v[4:5], v[62:63] op_sel:[0,1,0] op_sel_hi:[1,1,1]
	v_pk_fma_f32 v[62:63], v[78:79], v[8:9], v[62:63] op_sel_hi:[1,0,1]
	v_pk_fma_f32 v[62:63], v[80:81], v[8:9], v[62:63] op_sel:[0,1,0] op_sel_hi:[1,1,1]
	v_pk_fma_f32 v[62:63], v[86:87], v[18:19], v[62:63] op_sel_hi:[1,0,1]
	v_pk_fma_f32 v[62:63], v[88:89], v[18:19], v[62:63] op_sel:[0,1,0] op_sel_hi:[1,1,1]
	v_pk_fma_f32 v[62:63], v[82:83], v[10:11], v[62:63] op_sel_hi:[1,0,1]
	v_pk_fma_f32 v[62:63], v[84:85], v[10:11], v[62:63] op_sel:[0,1,0] op_sel_hi:[1,1,1]
	s_nop 1
	v_add_f32_dpp v62, v62, v62 quad_perm:[1,0,3,2] row_mask:0xf bank_mask:0xf bound_ctrl:1
	v_add_f32_dpp v63, v63, v63 quad_perm:[1,0,3,2] row_mask:0xf bank_mask:0xf bound_ctrl:1
	s_nop 0
	v_add_f32_dpp v62, v62, v62 quad_perm:[2,3,0,1] row_mask:0xf bank_mask:0xf bound_ctrl:1
	v_add_f32_dpp v63, v63, v63 quad_perm:[2,3,0,1] row_mask:0xf bank_mask:0xf bound_ctrl:1
	v_fma_f32 v63, -v87, v62, v63
	v_pk_fma_f32 v[18:19], v[62:63], v[68:69], v[18:19] op_sel_hi:[1,0,1]
	ds_read_b128 v[70:73], v14 offset:9792
	ds_read_b128 v[74:77], v14 offset:9856
	ds_read_b128 v[78:81], v14 offset:9920
	ds_read_b128 v[82:85], v14 offset:9984
	ds_read_b128 v[86:89], v14 offset:10048
	s_waitcnt lgkmcnt(5)
	v_pk_fma_f32 v[62:63], v[122:123], v[2:3], 0 op_sel_hi:[1,0,0]
	v_pk_fma_f32 v[62:63], v[124:125], v[2:3], v[62:63] op_sel:[0,1,0] op_sel_hi:[1,1,1]
	v_pk_fma_f32 v[62:63], v[126:127], v[4:5], v[62:63] op_sel_hi:[1,0,1]
	v_pk_fma_f32 v[62:63], v[128:129], v[4:5], v[62:63] op_sel:[0,1,0] op_sel_hi:[1,1,1]
	v_pk_fma_f32 v[62:63], v[130:131], v[8:9], v[62:63] op_sel_hi:[1,0,1]
	v_pk_fma_f32 v[62:63], v[132:133], v[8:9], v[62:63] op_sel:[0,1,0] op_sel_hi:[1,1,1]
	v_pk_fma_f32 v[62:63], v[38:39], v[10:11], v[62:63] op_sel_hi:[1,0,1]
	v_pk_fma_f32 v[62:63], v[40:41], v[10:11], v[62:63] op_sel:[0,1,0] op_sel_hi:[1,1,1]
	v_pk_fma_f32 v[62:63], v[42:43], v[18:19], v[62:63] op_sel_hi:[1,0,1]
	v_pk_fma_f32 v[62:63], v[44:45], v[18:19], v[62:63] op_sel:[0,1,0] op_sel_hi:[1,1,1]
	s_nop 1
	v_add_f32_dpp v62, v62, v62 quad_perm:[1,0,3,2] row_mask:0xf bank_mask:0xf bound_ctrl:1
	v_add_f32_dpp v63, v63, v63 quad_perm:[1,0,3,2] row_mask:0xf bank_mask:0xf bound_ctrl:1
	s_nop 0
	v_add_f32_dpp v62, v62, v62 quad_perm:[2,3,0,1] row_mask:0xf bank_mask:0xf bound_ctrl:1
	v_add_f32_dpp v63, v63, v63 quad_perm:[2,3,0,1] row_mask:0xf bank_mask:0xf bound_ctrl:1
	v_fma_f32 v63, -v43, v62, v63
	v_pk_fma_f32 v[18:19], v[62:63], v[112:113], v[18:19] op_sel_hi:[1,0,1]
	ds_read_b128 v[122:125], v14 offset:10336
	ds_read_b128 v[126:129], v14 offset:10400
	ds_read_b128 v[130:133], v14 offset:10464
	ds_read_b128 v[38:41], v14 offset:10528
	ds_read_b128 v[42:45], v14 offset:10592
	s_waitcnt lgkmcnt(5)
	v_pk_fma_f32 v[62:63], v[70:71], v[2:3], 0 op_sel_hi:[1,0,0]
	v_pk_fma_f32 v[62:63], v[72:73], v[2:3], v[62:63] op_sel:[0,1,0] op_sel_hi:[1,1,1]
	v_pk_fma_f32 v[62:63], v[74:75], v[4:5], v[62:63] op_sel_hi:[1,0,1]
	v_pk_fma_f32 v[62:63], v[76:77], v[4:5], v[62:63] op_sel:[0,1,0] op_sel_hi:[1,1,1]
	v_pk_fma_f32 v[62:63], v[78:79], v[8:9], v[62:63] op_sel_hi:[1,0,1]
	v_pk_fma_f32 v[62:63], v[80:81], v[8:9], v[62:63] op_sel:[0,1,0] op_sel_hi:[1,1,1]
	v_pk_fma_f32 v[62:63], v[82:83], v[10:11], v[62:63] op_sel_hi:[1,0,1]
	v_pk_fma_f32 v[62:63], v[84:85], v[10:11], v[62:63] op_sel:[0,1,0] op_sel_hi:[1,1,1]
	v_pk_fma_f32 v[62:63], v[86:87], v[18:19], v[62:63] op_sel_hi:[1,0,1]
	v_pk_fma_f32 v[62:63], v[88:89], v[18:19], v[62:63] op_sel:[0,1,0] op_sel_hi:[1,1,1]
	s_nop 1
	v_add_f32_dpp v62, v62, v62 quad_perm:[1,0,3,2] row_mask:0xf bank_mask:0xf bound_ctrl:1
	v_add_f32_dpp v63, v63, v63 quad_perm:[1,0,3,2] row_mask:0xf bank_mask:0xf bound_ctrl:1
	s_nop 0
	v_add_f32_dpp v62, v62, v62 quad_perm:[2,3,0,1] row_mask:0xf bank_mask:0xf bound_ctrl:1
	v_add_f32_dpp v63, v63, v63 quad_perm:[2,3,0,1] row_mask:0xf bank_mask:0xf bound_ctrl:1
	v_fma_f32 v63, -v87, v62, v63
	v_pk_fma_f32 v[18:19], v[62:63], v[116:117], v[18:19] op_sel_hi:[1,0,1]
	ds_read_b128 v[70:73], v14 offset:10880
	ds_read_b128 v[74:77], v14 offset:10944
	ds_read_b128 v[78:81], v14 offset:11008
	ds_read_b128 v[82:85], v14 offset:11072
	ds_read_b128 v[86:89], v14 offset:11136
	ds_read_b128 v[90:93], v14 offset:11200
	s_waitcnt lgkmcnt(6)
; #define LAS __attribute__((address_space(3)))
;     ...
;     if (w < 2) {
;         const int d = w; const LAS float* Ad = As + d * 4352;
;         float tr[64]; int lane_o = lane;
; #pragma unroll
;         for (int ip = 0; ip < 32; ++ip) {
;             const int i0 = 2 * ip;
;             f32x4 rv[32];
; #pragma unroll
;             for (int jp = 0; jp <= ip; ++jp) rv[jp] = *(const LAS f32x4*)(Ad + ip * 136 + 4 * jp);
;             asm volatile("" : "+v"(lane_o) :: "memory");
;             f32x2_ a0 = {0.f, 0.f}, a1 = {0.f, 0.f}, a2 = {0.f, 0.f}, a3 = {0.f, 0.f};
; #pragma unroll
;             for (int jp = 0; jp < ip; ++jp) {
;                 const f32x2_ ta = {tr[2 * jp], tr[2 * jp]}, tb = {tr[2 * jp + 1], tr[2 * jp + 1]};
;                 const f32x2_ va = {rv[jp][0], rv[jp][1]}, vb = {rv[jp][2], rv[jp][3]};
;                 if (jp & 1) { a2 += va * ta; a3 += vb * tb; } else { a0 += va * ta; a1 += vb * tb; }
;             }
;             const f32x2_ sum = (a0 + a1) + (a2 + a3);
;             const float t0 = (lane_o == i0 ? 1.f : 0.f) - sum[0];
;             tr[i0] = t0;
;             tr[i0 + 1] = (lane_o == i0 + 1 ? 1.f : 0.f) - sum[1] - rv[ip][1] * t0;
;         }
	v_pk_fma_f32 v[62:63], v[122:123], v[2:3], 0 op_sel_hi:[1,0,0]
	v_pk_fma_f32 v[62:63], v[124:125], v[2:3], v[62:63] op_sel:[0,1,0] op_sel_hi:[1,1,1]
	v_pk_fma_f32 v[62:63], v[126:127], v[4:5], v[62:63] op_sel_hi:[1,0,1]
	v_pk_fma_f32 v[62:63], v[128:129], v[4:5], v[62:63] op_sel:[0,1,0] op_sel_hi:[1,1,1]
	v_pk_fma_f32 v[62:63], v[130:131], v[8:9], v[62:63] op_sel_hi:[1,0,1]
	v_pk_fma_f32 v[62:63], v[132:133], v[8:9], v[62:63] op_sel:[0,1,0] op_sel_hi:[1,1,1]
	v_pk_fma_f32 v[62:63], v[38:39], v[10:11], v[62:63] op_sel_hi:[1,0,1]
	v_pk_fma_f32 v[62:63], v[40:41], v[10:11], v[62:63] op_sel:[0,1,0] op_sel_hi:[1,1,1]
	v_pk_fma_f32 v[62:63], v[42:43], v[18:19], v[62:63] op_sel_hi:[1,0,1]
	v_pk_fma_f32 v[62:63], v[44:45], v[18:19], v[62:63] op_sel:[0,1,0] op_sel_hi:[1,1,1]
	s_nop 1
	v_add_f32_dpp v62, v62, v62 quad_perm:[1,0,3,2] row_mask:0xf bank_mask:0xf bound_ctrl:1
	v_add_f32_dpp v63, v63, v63 quad_perm:[1,0,3,2] row_mask:0xf bank_mask:0xf bound_ctrl:1
	s_nop 0
	v_add_f32_dpp v62, v62, v62 quad_perm:[2,3,0,1] row_mask:0xf bank_mask:0xf bound_ctrl:1
	v_add_f32_dpp v63, v63, v63 quad_perm:[2,3,0,1] row_mask:0xf bank_mask:0xf bound_ctrl:1
	v_fma_f32 v63, -v43, v62, v63
	v_pk_fma_f32 v[18:19], v[62:63], v[120:121], v[18:19] op_sel_hi:[1,0,1]
	ds_read_b128 v[122:125], v14 offset:11424
	ds_read_b128 v[126:129], v14 offset:11488
	ds_read_b128 v[130:133], v14 offset:11552
	ds_read_b128 v[38:41], v14 offset:11616
	ds_read_b128 v[42:45], v14 offset:11680
	ds_read_b128 v[46:49], v14 offset:11744
	s_waitcnt lgkmcnt(6)
	v_pk_fma_f32 v[62:63], v[70:71], v[2:3], 0 op_sel_hi:[1,0,0]
	v_pk_fma_f32 v[62:63], v[72:73], v[2:3], v[62:63] op_sel:[0,1,0] op_sel_hi:[1,1,1]
	v_pk_fma_f32 v[62:63], v[74:75], v[4:5], v[62:63] op_sel_hi:[1,0,1]
	v_pk_fma_f32 v[62:63], v[76:77], v[4:5], v[62:63] op_sel:[0,1,0] op_sel_hi:[1,1,1]
	v_pk_fma_f32 v[62:63], v[78:79], v[8:9], v[62:63] op_sel_hi:[1,0,1]
	v_pk_fma_f32 v[62:63], v[80:81], v[8:9], v[62:63] op_sel:[0,1,0] op_sel_hi:[1,1,1]
	v_pk_fma_f32 v[62:63], v[82:83], v[10:11], v[62:63] op_sel_hi:[1,0,1]
	v_pk_fma_f32 v[62:63], v[84:85], v[10:11], v[62:63] op_sel:[0,1,0] op_sel_hi:[1,1,1]
	v_pk_fma_f32 v[62:63], v[90:91], v[50:51], v[62:63] op_sel_hi:[1,0,1]
	v_pk_fma_f32 v[62:63], v[92:93], v[50:51], v[62:63] op_sel:[0,1,0] op_sel_hi:[1,1,1]
	v_pk_fma_f32 v[62:63], v[86:87], v[18:19], v[62:63] op_sel_hi:[1,0,1]
	v_pk_fma_f32 v[62:63], v[88:89], v[18:19], v[62:63] op_sel:[0,1,0] op_sel_hi:[1,1,1]
	s_nop 1
	v_add_f32_dpp v62, v62, v62 quad_perm:[1,0,3,2] row_mask:0xf bank_mask:0xf bound_ctrl:1
	v_add_f32_dpp v63, v63, v63 quad_perm:[1,0,3,2] row_mask:0xf bank_mask:0xf bound_ctrl:1
	s_nop 0
	v_add_f32_dpp v62, v62, v62 quad_perm:[2,3,0,1] row_mask:0xf bank_mask:0xf bound_ctrl:1
	v_add_f32_dpp v63, v63, v63 quad_perm:[2,3,0,1] row_mask:0xf bank_mask:0xf bound_ctrl:1
	v_fma_f32 v63, -v91, v62, v63
	v_pk_fma_f32 v[50:51], v[62:63], v[68:69], v[50:51] op_sel_hi:[1,0,1]
	ds_read_b128 v[70:73], v14 offset:11968
	ds_read_b128 v[74:77], v14 offset:12032
	ds_read_b128 v[78:81], v14 offset:12096
	ds_read_b128 v[82:85], v14 offset:12160
	ds_read_b128 v[86:89], v14 offset:12224
	ds_read_b128 v[90:93], v14 offset:12288
	s_waitcnt lgkmcnt(6)
	v_pk_fma_f32 v[62:63], v[122:123], v[2:3], 0 op_sel_hi:[1,0,0]
	v_pk_fma_f32 v[62:63], v[124:125], v[2:3], v[62:63] op_sel:[0,1,0] op_sel_hi:[1,1,1]
	v_pk_fma_f32 v[62:63], v[126:127], v[4:5], v[62:63] op_sel_hi:[1,0,1]
	v_pk_fma_f32 v[62:63], v[128:129], v[4:5], v[62:63] op_sel:[0,1,0] op_sel_hi:[1,1,1]
	v_pk_fma_f32 v[62:63], v[130:131], v[8:9], v[62:63] op_sel_hi:[1,0,1]
	v_pk_fma_f32 v[62:63], v[132:133], v[8:9], v[62:63] op_sel:[0,1,0] op_sel_hi:[1,1,1]
	v_pk_fma_f32 v[62:63], v[38:39], v[10:11], v[62:63] op_sel_hi:[1,0,1]
	v_pk_fma_f32 v[62:63], v[40:41], v[10:11], v[62:63] op_sel:[0,1,0] op_sel_hi:[1,1,1]
	v_pk_fma_f32 v[62:63], v[42:43], v[18:19], v[62:63] op_sel_hi:[1,0,1]
	v_pk_fma_f32 v[62:63], v[44:45], v[18:19], v[62:63] op_sel:[0,1,0] op_sel_hi:[1,1,1]
	v_pk_fma_f32 v[62:63], v[46:47], v[50:51], v[62:63] op_sel_hi:[1,0,1]
	v_pk_fma_f32 v[62:63], v[48:49], v[50:51], v[62:63] op_sel:[0,1,0] op_sel_hi:[1,1,1]
	s_nop 1
	v_add_f32_dpp v62, v62, v62 quad_perm:[1,0,3,2] row_mask:0xf bank_mask:0xf bound_ctrl:1
	v_add_f32_dpp v63, v63, v63 quad_perm:[1,0,3,2] row_mask:0xf bank_mask:0xf bound_ctrl:1
	s_nop 0
	v_add_f32_dpp v62, v62, v62 quad_perm:[2,3,0,1] row_mask:0xf bank_mask:0xf bound_ctrl:1
	v_add_f32_dpp v63, v63, v63 quad_perm:[2,3,0,1] row_mask:0xf bank_mask:0xf bound_ctrl:1
	v_fma_f32 v63, -v47, v62, v63
	v_pk_fma_f32 v[50:51], v[62:63], v[112:113], v[50:51] op_sel_hi:[1,0,1]
	ds_read_b128 v[122:125], v14 offset:12512
	ds_read_b128 v[126:129], v14 offset:12576
	ds_read_b128 v[130:133], v14 offset:12640
	ds_read_b128 v[38:41], v14 offset:12704
	ds_read_b128 v[42:45], v14 offset:12768
	ds_read_b128 v[46:49], v14 offset:12832
	s_waitcnt lgkmcnt(6)
; #define LAS __attribute__((address_space(3)))
;     ...
;     if (w < 2) {
;         const int d = w; const LAS float* Ad = As + d * 4352;
;         float tr[64]; int lane_o = lane;
; #pragma unroll
;         for (int ip = 0; ip < 32; ++ip) {
;             const int i0 = 2 * ip;
;             f32x4 rv[32];
; #pragma unroll
;             for (int jp = 0; jp <= ip; ++jp) rv[jp] = *(const LAS f32x4*)(Ad + ip * 136 + 4 * jp);
;             asm volatile("" : "+v"(lane_o) :: "memory");
;             f32x2_ a0 = {0.f, 0.f}, a1 = {0.f, 0.f}, a2 = {0.f, 0.f}, a3 = {0.f, 0.f};
; #pragma unroll
;             for (int jp = 0; jp < ip; ++jp) {
;                 const f32x2_ ta = {tr[2 * jp], tr[2 * jp]}, tb = {tr[2 * jp + 1], tr[2 * jp + 1]};
;                 const f32x2_ va = {rv[jp][0], rv[jp][1]}, vb = {rv[jp][2], rv[jp][3]};
;                 if (jp & 1) { a2 += va * ta; a3 += vb * tb; } else { a0 += va * ta; a1 += vb * tb; }
;             }
;             const f32x2_ sum = (a0 + a1) + (a2 + a3);
;             const float t0 = (lane_o == i0 ? 1.f : 0.f) - sum[0];
;             tr[i0] = t0;
;             tr[i0 + 1] = (lane_o == i0 + 1 ? 1.f : 0.f) - sum[1] - rv[ip][1] * t0;
;         }
	v_pk_fma_f32 v[62:63], v[70:71], v[2:3], 0 op_sel_hi:[1,0,0]
	v_pk_fma_f32 v[62:63], v[72:73], v[2:3], v[62:63] op_sel:[0,1,0] op_sel_hi:[1,1,1]
	v_pk_fma_f32 v[62:63], v[74:75], v[4:5], v[62:63] op_sel_hi:[1,0,1]
	v_pk_fma_f32 v[62:63], v[76:77], v[4:5], v[62:63] op_sel:[0,1,0] op_sel_hi:[1,1,1]
	v_pk_fma_f32 v[62:63], v[78:79], v[8:9], v[62:63] op_sel_hi:[1,0,1]
	v_pk_fma_f32 v[62:63], v[80:81], v[8:9], v[62:63] op_sel:[0,1,0] op_sel_hi:[1,1,1]
	v_pk_fma_f32 v[62:63], v[82:83], v[10:11], v[62:63] op_sel_hi:[1,0,1]
	v_pk_fma_f32 v[62:63], v[84:85], v[10:11], v[62:63] op_sel:[0,1,0] op_sel_hi:[1,1,1]
	v_pk_fma_f32 v[62:63], v[86:87], v[18:19], v[62:63] op_sel_hi:[1,0,1]
	v_pk_fma_f32 v[62:63], v[88:89], v[18:19], v[62:63] op_sel:[0,1,0] op_sel_hi:[1,1,1]
	v_pk_fma_f32 v[62:63], v[90:91], v[50:51], v[62:63] op_sel_hi:[1,0,1]
	v_pk_fma_f32 v[62:63], v[92:93], v[50:51], v[62:63] op_sel:[0,1,0] op_sel_hi:[1,1,1]
	s_nop 1
	v_add_f32_dpp v62, v62, v62 quad_perm:[1,0,3,2] row_mask:0xf bank_mask:0xf bound_ctrl:1
	v_add_f32_dpp v63, v63, v63 quad_perm:[1,0,3,2] row_mask:0xf bank_mask:0xf bound_ctrl:1
	s_nop 0
	v_add_f32_dpp v62, v62, v62 quad_perm:[2,3,0,1] row_mask:0xf bank_mask:0xf bound_ctrl:1
	v_add_f32_dpp v63, v63, v63 quad_perm:[2,3,0,1] row_mask:0xf bank_mask:0xf bound_ctrl:1
	v_fma_f32 v63, -v91, v62, v63
	v_pk_fma_f32 v[50:51], v[62:63], v[116:117], v[50:51] op_sel_hi:[1,0,1]
	ds_read_b128 v[70:73], v14 offset:13056
	ds_read_b128 v[74:77], v14 offset:13120
	ds_read_b128 v[78:81], v14 offset:13184
	ds_read_b128 v[82:85], v14 offset:13248
	ds_read_b128 v[86:89], v14 offset:13312
	ds_read_b128 v[90:93], v14 offset:13376
	ds_read_b128 v[94:97], v14 offset:13440
	s_waitcnt lgkmcnt(7)
	v_pk_fma_f32 v[62:63], v[122:123], v[2:3], 0 op_sel_hi:[1,0,0]
	v_pk_fma_f32 v[62:63], v[124:125], v[2:3], v[62:63] op_sel:[0,1,0] op_sel_hi:[1,1,1]
	v_pk_fma_f32 v[62:63], v[126:127], v[4:5], v[62:63] op_sel_hi:[1,0,1]
	v_pk_fma_f32 v[62:63], v[128:129], v[4:5], v[62:63] op_sel:[0,1,0] op_sel_hi:[1,1,1]
	v_pk_fma_f32 v[62:63], v[130:131], v[8:9], v[62:63] op_sel_hi:[1,0,1]
	v_pk_fma_f32 v[62:63], v[132:133], v[8:9], v[62:63] op_sel:[0,1,0] op_sel_hi:[1,1,1]
	v_pk_fma_f32 v[62:63], v[38:39], v[10:11], v[62:63] op_sel_hi:[1,0,1]
	v_pk_fma_f32 v[62:63], v[40:41], v[10:11], v[62:63] op_sel:[0,1,0] op_sel_hi:[1,1,1]
	v_pk_fma_f32 v[62:63], v[42:43], v[18:19], v[62:63] op_sel_hi:[1,0,1]
	v_pk_fma_f32 v[62:63], v[44:45], v[18:19], v[62:63] op_sel:[0,1,0] op_sel_hi:[1,1,1]
	v_pk_fma_f32 v[62:63], v[46:47], v[50:51], v[62:63] op_sel_hi:[1,0,1]
	v_pk_fma_f32 v[62:63], v[48:49], v[50:51], v[62:63] op_sel:[0,1,0] op_sel_hi:[1,1,1]
	s_nop 1
	v_add_f32_dpp v62, v62, v62 quad_perm:[1,0,3,2] row_mask:0xf bank_mask:0xf bound_ctrl:1
	v_add_f32_dpp v63, v63, v63 quad_perm:[1,0,3,2] row_mask:0xf bank_mask:0xf bound_ctrl:1
	s_nop 0
	v_add_f32_dpp v62, v62, v62 quad_perm:[2,3,0,1] row_mask:0xf bank_mask:0xf bound_ctrl:1
	v_add_f32_dpp v63, v63, v63 quad_perm:[2,3,0,1] row_mask:0xf bank_mask:0xf bound_ctrl:1
	v_fma_f32 v63, -v47, v62, v63
	v_pk_fma_f32 v[50:51], v[62:63], v[120:121], v[50:51] op_sel_hi:[1,0,1]
	ds_read_b128 v[122:125], v14 offset:13600
	ds_read_b128 v[126:129], v14 offset:13664
	ds_read_b128 v[130:133], v14 offset:13728
	ds_read_b128 v[38:41], v14 offset:13792
	ds_read_b128 v[42:45], v14 offset:13856
	ds_read_b128 v[46:49], v14 offset:13920
	ds_read_b128 v[102:105], v14 offset:13984
	s_waitcnt lgkmcnt(7)
	v_pk_fma_f32 v[62:63], v[70:71], v[2:3], 0 op_sel_hi:[1,0,0]
	v_pk_fma_f32 v[62:63], v[72:73], v[2:3], v[62:63] op_sel:[0,1,0] op_sel_hi:[1,1,1]
	v_pk_fma_f32 v[62:63], v[74:75], v[4:5], v[62:63] op_sel_hi:[1,0,1]
	v_pk_fma_f32 v[62:63], v[76:77], v[4:5], v[62:63] op_sel:[0,1,0] op_sel_hi:[1,1,1]
	v_pk_fma_f32 v[62:63], v[78:79], v[8:9], v[62:63] op_sel_hi:[1,0,1]
	v_pk_fma_f32 v[62:63], v[80:81], v[8:9], v[62:63] op_sel:[0,1,0] op_sel_hi:[1,1,1]
	v_pk_fma_f32 v[62:63], v[82:83], v[10:11], v[62:63] op_sel_hi:[1,0,1]
	v_pk_fma_f32 v[62:63], v[84:85], v[10:11], v[62:63] op_sel:[0,1,0] op_sel_hi:[1,1,1]
	v_pk_fma_f32 v[62:63], v[86:87], v[18:19], v[62:63] op_sel_hi:[1,0,1]
	v_pk_fma_f32 v[62:63], v[88:89], v[18:19], v[62:63] op_sel:[0,1,0] op_sel_hi:[1,1,1]
	v_pk_fma_f32 v[62:63], v[94:95], v[54:55], v[62:63] op_sel_hi:[1,0,1]
	v_pk_fma_f32 v[62:63], v[96:97], v[54:55], v[62:63] op_sel:[0,1,0] op_sel_hi:[1,1,1]
	v_pk_fma_f32 v[62:63], v[90:91], v[50:51], v[62:63] op_sel_hi:[1,0,1]
	v_pk_fma_f32 v[62:63], v[92:93], v[50:51], v[62:63] op_sel:[0,1,0] op_sel_hi:[1,1,1]
	s_nop 1
	v_add_f32_dpp v62, v62, v62 quad_perm:[1,0,3,2] row_mask:0xf bank_mask:0xf bound_ctrl:1
	v_add_f32_dpp v63, v63, v63 quad_perm:[1,0,3,2] row_mask:0xf bank_mask:0xf bound_ctrl:1
	s_nop 0
	v_add_f32_dpp v62, v62, v62 quad_perm:[2,3,0,1] row_mask:0xf bank_mask:0xf bound_ctrl:1
	v_add_f32_dpp v63, v63, v63 quad_perm:[2,3,0,1] row_mask:0xf bank_mask:0xf bound_ctrl:1
	v_fma_f32 v63, -v95, v62, v63
	v_pk_fma_f32 v[54:55], v[62:63], v[68:69], v[54:55] op_sel_hi:[1,0,1]
	ds_read_b128 v[70:73], v14 offset:14144
	ds_read_b128 v[74:77], v14 offset:14208
	ds_read_b128 v[78:81], v14 offset:14272
	ds_read_b128 v[82:85], v14 offset:14336
	ds_read_b128 v[86:89], v14 offset:14400
	ds_read_b128 v[90:93], v14 offset:14464
	ds_read_b128 v[94:97], v14 offset:14528
	s_waitcnt lgkmcnt(7)
; #define LAS __attribute__((address_space(3)))
;     ...
;     if (w < 2) {
;         const int d = w; const LAS float* Ad = As + d * 4352;
;         float tr[64]; int lane_o = lane;
; #pragma unroll
;         for (int ip = 0; ip < 32; ++ip) {
;             const int i0 = 2 * ip;
;             f32x4 rv[32];
; #pragma unroll
;             for (int jp = 0; jp <= ip; ++jp) rv[jp] = *(const LAS f32x4*)(Ad + ip * 136 + 4 * jp);
;             asm volatile("" : "+v"(lane_o) :: "memory");
;             f32x2_ a0 = {0.f, 0.f}, a1 = {0.f, 0.f}, a2 = {0.f, 0.f}, a3 = {0.f, 0.f};
; #pragma unroll
;             for (int jp = 0; jp < ip; ++jp) {
;                 const f32x2_ ta = {tr[2 * jp], tr[2 * jp]}, tb = {tr[2 * jp + 1], tr[2 * jp + 1]};
;                 const f32x2_ va = {rv[jp][0], rv[jp][1]}, vb = {rv[jp][2], rv[jp][3]};
;                 if (jp & 1) { a2 += va * ta; a3 += vb * tb; } else { a0 += va * ta; a1 += vb * tb; }
;             }
;             const f32x2_ sum = (a0 + a1) + (a2 + a3);
;             const float t0 = (lane_o == i0 ? 1.f : 0.f) - sum[0];
;             tr[i0] = t0;
;             tr[i0 + 1] = (lane_o == i0 + 1 ? 1.f : 0.f) - sum[1] - rv[ip][1] * t0;
;         }
	v_pk_fma_f32 v[62:63], v[122:123], v[2:3], 0 op_sel_hi:[1,0,0]
	v_pk_fma_f32 v[62:63], v[124:125], v[2:3], v[62:63] op_sel:[0,1,0] op_sel_hi:[1,1,1]
	v_pk_fma_f32 v[62:63], v[126:127], v[4:5], v[62:63] op_sel_hi:[1,0,1]
	v_pk_fma_f32 v[62:63], v[128:129], v[4:5], v[62:63] op_sel:[0,1,0] op_sel_hi:[1,1,1]
	v_pk_fma_f32 v[62:63], v[130:131], v[8:9], v[62:63] op_sel_hi:[1,0,1]
	v_pk_fma_f32 v[62:63], v[132:133], v[8:9], v[62:63] op_sel:[0,1,0] op_sel_hi:[1,1,1]
	v_pk_fma_f32 v[62:63], v[38:39], v[10:11], v[62:63] op_sel_hi:[1,0,1]
	v_pk_fma_f32 v[62:63], v[40:41], v[10:11], v[62:63] op_sel:[0,1,0] op_sel_hi:[1,1,1]
	v_pk_fma_f32 v[62:63], v[42:43], v[18:19], v[62:63] op_sel_hi:[1,0,1]
	v_pk_fma_f32 v[62:63], v[44:45], v[18:19], v[62:63] op_sel:[0,1,0] op_sel_hi:[1,1,1]
	v_pk_fma_f32 v[62:63], v[46:47], v[50:51], v[62:63] op_sel_hi:[1,0,1]
	v_pk_fma_f32 v[62:63], v[48:49], v[50:51], v[62:63] op_sel:[0,1,0] op_sel_hi:[1,1,1]
	v_pk_fma_f32 v[62:63], v[102:103], v[54:55], v[62:63] op_sel_hi:[1,0,1]
	v_pk_fma_f32 v[62:63], v[104:105], v[54:55], v[62:63] op_sel:[0,1,0] op_sel_hi:[1,1,1]
	s_nop 1
	v_add_f32_dpp v62, v62, v62 quad_perm:[1,0,3,2] row_mask:0xf bank_mask:0xf bound_ctrl:1
	v_add_f32_dpp v63, v63, v63 quad_perm:[1,0,3,2] row_mask:0xf bank_mask:0xf bound_ctrl:1
	s_nop 0
	v_add_f32_dpp v62, v62, v62 quad_perm:[2,3,0,1] row_mask:0xf bank_mask:0xf bound_ctrl:1
	v_add_f32_dpp v63, v63, v63 quad_perm:[2,3,0,1] row_mask:0xf bank_mask:0xf bound_ctrl:1
	v_fma_f32 v63, -v103, v62, v63
	v_pk_fma_f32 v[54:55], v[62:63], v[112:113], v[54:55] op_sel_hi:[1,0,1]
	ds_read_b128 v[122:125], v14 offset:14688
	ds_read_b128 v[126:129], v14 offset:14752
	ds_read_b128 v[130:133], v14 offset:14816
	ds_read_b128 v[38:41], v14 offset:14880
	ds_read_b128 v[42:45], v14 offset:14944
	ds_read_b128 v[46:49], v14 offset:15008
	ds_read_b128 v[102:105], v14 offset:15072
	s_waitcnt lgkmcnt(7)
	v_pk_fma_f32 v[62:63], v[70:71], v[2:3], 0 op_sel_hi:[1,0,0]
	v_pk_fma_f32 v[62:63], v[72:73], v[2:3], v[62:63] op_sel:[0,1,0] op_sel_hi:[1,1,1]
	v_pk_fma_f32 v[62:63], v[74:75], v[4:5], v[62:63] op_sel_hi:[1,0,1]
	v_pk_fma_f32 v[62:63], v[76:77], v[4:5], v[62:63] op_sel:[0,1,0] op_sel_hi:[1,1,1]
	v_pk_fma_f32 v[62:63], v[78:79], v[8:9], v[62:63] op_sel_hi:[1,0,1]
	v_pk_fma_f32 v[62:63], v[80:81], v[8:9], v[62:63] op_sel:[0,1,0] op_sel_hi:[1,1,1]
	v_pk_fma_f32 v[62:63], v[82:83], v[10:11], v[62:63] op_sel_hi:[1,0,1]
	v_pk_fma_f32 v[62:63], v[84:85], v[10:11], v[62:63] op_sel:[0,1,0] op_sel_hi:[1,1,1]
	v_pk_fma_f32 v[62:63], v[86:87], v[18:19], v[62:63] op_sel_hi:[1,0,1]
	v_pk_fma_f32 v[62:63], v[88:89], v[18:19], v[62:63] op_sel:[0,1,0] op_sel_hi:[1,1,1]
	v_pk_fma_f32 v[62:63], v[90:91], v[50:51], v[62:63] op_sel_hi:[1,0,1]
	v_pk_fma_f32 v[62:63], v[92:93], v[50:51], v[62:63] op_sel:[0,1,0] op_sel_hi:[1,1,1]
	v_pk_fma_f32 v[62:63], v[94:95], v[54:55], v[62:63] op_sel_hi:[1,0,1]
	v_pk_fma_f32 v[62:63], v[96:97], v[54:55], v[62:63] op_sel:[0,1,0] op_sel_hi:[1,1,1]
	s_nop 1
	v_add_f32_dpp v62, v62, v62 quad_perm:[1,0,3,2] row_mask:0xf bank_mask:0xf bound_ctrl:1
	v_add_f32_dpp v63, v63, v63 quad_perm:[1,0,3,2] row_mask:0xf bank_mask:0xf bound_ctrl:1
	s_nop 0
	v_add_f32_dpp v62, v62, v62 quad_perm:[2,3,0,1] row_mask:0xf bank_mask:0xf bound_ctrl:1
	v_add_f32_dpp v63, v63, v63 quad_perm:[2,3,0,1] row_mask:0xf bank_mask:0xf bound_ctrl:1
	v_fma_f32 v63, -v95, v62, v63
	v_pk_fma_f32 v[54:55], v[62:63], v[116:117], v[54:55] op_sel_hi:[1,0,1]
	ds_read_b128 v[70:73], v14 offset:15232
	ds_read_b128 v[74:77], v14 offset:15296
	ds_read_b128 v[78:81], v14 offset:15360
	ds_read_b128 v[82:85], v14 offset:15424
	ds_read_b128 v[86:89], v14 offset:15488
	ds_read_b128 v[90:93], v14 offset:15552
	ds_read_b128 v[94:97], v14 offset:15616
	ds_read_b128 v[98:101], v14 offset:15680
	s_waitcnt lgkmcnt(8)
	v_pk_fma_f32 v[62:63], v[122:123], v[2:3], 0 op_sel_hi:[1,0,0]
	v_pk_fma_f32 v[62:63], v[124:125], v[2:3], v[62:63] op_sel:[0,1,0] op_sel_hi:[1,1,1]
	v_pk_fma_f32 v[62:63], v[126:127], v[4:5], v[62:63] op_sel_hi:[1,0,1]
	v_pk_fma_f32 v[62:63], v[128:129], v[4:5], v[62:63] op_sel:[0,1,0] op_sel_hi:[1,1,1]
	v_pk_fma_f32 v[62:63], v[130:131], v[8:9], v[62:63] op_sel_hi:[1,0,1]
	v_pk_fma_f32 v[62:63], v[132:133], v[8:9], v[62:63] op_sel:[0,1,0] op_sel_hi:[1,1,1]
	v_pk_fma_f32 v[62:63], v[38:39], v[10:11], v[62:63] op_sel_hi:[1,0,1]
	v_pk_fma_f32 v[62:63], v[40:41], v[10:11], v[62:63] op_sel:[0,1,0] op_sel_hi:[1,1,1]
	v_pk_fma_f32 v[62:63], v[42:43], v[18:19], v[62:63] op_sel_hi:[1,0,1]
	v_pk_fma_f32 v[62:63], v[44:45], v[18:19], v[62:63] op_sel:[0,1,0] op_sel_hi:[1,1,1]
	v_pk_fma_f32 v[62:63], v[46:47], v[50:51], v[62:63] op_sel_hi:[1,0,1]
	v_pk_fma_f32 v[62:63], v[48:49], v[50:51], v[62:63] op_sel:[0,1,0] op_sel_hi:[1,1,1]
	v_pk_fma_f32 v[62:63], v[102:103], v[54:55], v[62:63] op_sel_hi:[1,0,1]
	v_pk_fma_f32 v[62:63], v[104:105], v[54:55], v[62:63] op_sel:[0,1,0] op_sel_hi:[1,1,1]
	s_nop 1
	v_add_f32_dpp v62, v62, v62 quad_perm:[1,0,3,2] row_mask:0xf bank_mask:0xf bound_ctrl:1
	v_add_f32_dpp v63, v63, v63 quad_perm:[1,0,3,2] row_mask:0xf bank_mask:0xf bound_ctrl:1
	s_nop 0
	v_add_f32_dpp v62, v62, v62 quad_perm:[2,3,0,1] row_mask:0xf bank_mask:0xf bound_ctrl:1
	v_add_f32_dpp v63, v63, v63 quad_perm:[2,3,0,1] row_mask:0xf bank_mask:0xf bound_ctrl:1
	v_fma_f32 v63, -v103, v62, v63
	v_pk_fma_f32 v[54:55], v[62:63], v[120:121], v[54:55] op_sel_hi:[1,0,1]
	ds_read_b128 v[122:125], v14 offset:15776
	ds_read_b128 v[126:129], v14 offset:15840
	ds_read_b128 v[130:133], v14 offset:15904
	ds_read_b128 v[38:41], v14 offset:15968
	ds_read_b128 v[42:45], v14 offset:16032
	ds_read_b128 v[46:49], v14 offset:16096
	ds_read_b128 v[102:105], v14 offset:16160
	ds_read_b128 v[242:245], v14 offset:16224
	s_waitcnt lgkmcnt(8)
; #define LAS __attribute__((address_space(3)))
;     ...
;     if (w < 2) {
;         const int d = w; const LAS float* Ad = As + d * 4352;
;         float tr[64]; int lane_o = lane;
; #pragma unroll
;         for (int ip = 0; ip < 32; ++ip) {
;             const int i0 = 2 * ip;
;             f32x4 rv[32];
; #pragma unroll
;             for (int jp = 0; jp <= ip; ++jp) rv[jp] = *(const LAS f32x4*)(Ad + ip * 136 + 4 * jp);
;             asm volatile("" : "+v"(lane_o) :: "memory");
;             f32x2_ a0 = {0.f, 0.f}, a1 = {0.f, 0.f}, a2 = {0.f, 0.f}, a3 = {0.f, 0.f};
; #pragma unroll
;             for (int jp = 0; jp < ip; ++jp) {
;                 const f32x2_ ta = {tr[2 * jp], tr[2 * jp]}, tb = {tr[2 * jp + 1], tr[2 * jp + 1]};
;                 const f32x2_ va = {rv[jp][0], rv[jp][1]}, vb = {rv[jp][2], rv[jp][3]};
;                 if (jp & 1) { a2 += va * ta; a3 += vb * tb; } else { a0 += va * ta; a1 += vb * tb; }
;             }
;             const f32x2_ sum = (a0 + a1) + (a2 + a3);
;             const float t0 = (lane_o == i0 ? 1.f : 0.f) - sum[0];
;             tr[i0] = t0;
;             tr[i0 + 1] = (lane_o == i0 + 1 ? 1.f : 0.f) - sum[1] - rv[ip][1] * t0;
;         }
	v_pk_fma_f32 v[62:63], v[70:71], v[2:3], 0 op_sel_hi:[1,0,0]
	v_pk_fma_f32 v[62:63], v[72:73], v[2:3], v[62:63] op_sel:[0,1,0] op_sel_hi:[1,1,1]
	v_pk_fma_f32 v[62:63], v[74:75], v[4:5], v[62:63] op_sel_hi:[1,0,1]
	v_pk_fma_f32 v[62:63], v[76:77], v[4:5], v[62:63] op_sel:[0,1,0] op_sel_hi:[1,1,1]
	v_pk_fma_f32 v[62:63], v[78:79], v[8:9], v[62:63] op_sel_hi:[1,0,1]
	v_pk_fma_f32 v[62:63], v[80:81], v[8:9], v[62:63] op_sel:[0,1,0] op_sel_hi:[1,1,1]
	v_pk_fma_f32 v[62:63], v[82:83], v[10:11], v[62:63] op_sel_hi:[1,0,1]
	v_pk_fma_f32 v[62:63], v[84:85], v[10:11], v[62:63] op_sel:[0,1,0] op_sel_hi:[1,1,1]
	v_pk_fma_f32 v[62:63], v[86:87], v[18:19], v[62:63] op_sel_hi:[1,0,1]
	v_pk_fma_f32 v[62:63], v[88:89], v[18:19], v[62:63] op_sel:[0,1,0] op_sel_hi:[1,1,1]
	v_pk_fma_f32 v[62:63], v[90:91], v[50:51], v[62:63] op_sel_hi:[1,0,1]
	v_pk_fma_f32 v[62:63], v[92:93], v[50:51], v[62:63] op_sel:[0,1,0] op_sel_hi:[1,1,1]
	v_pk_fma_f32 v[62:63], v[98:99], v[58:59], v[62:63] op_sel_hi:[1,0,1]
	v_pk_fma_f32 v[62:63], v[100:101], v[58:59], v[62:63] op_sel:[0,1,0] op_sel_hi:[1,1,1]
	v_pk_fma_f32 v[62:63], v[94:95], v[54:55], v[62:63] op_sel_hi:[1,0,1]
	v_pk_fma_f32 v[62:63], v[96:97], v[54:55], v[62:63] op_sel:[0,1,0] op_sel_hi:[1,1,1]
	s_nop 1
	v_add_f32_dpp v62, v62, v62 quad_perm:[1,0,3,2] row_mask:0xf bank_mask:0xf bound_ctrl:1
	v_add_f32_dpp v63, v63, v63 quad_perm:[1,0,3,2] row_mask:0xf bank_mask:0xf bound_ctrl:1
	s_nop 0
	v_add_f32_dpp v62, v62, v62 quad_perm:[2,3,0,1] row_mask:0xf bank_mask:0xf bound_ctrl:1
	v_add_f32_dpp v63, v63, v63 quad_perm:[2,3,0,1] row_mask:0xf bank_mask:0xf bound_ctrl:1
	v_fma_f32 v63, -v99, v62, v63
	v_pk_fma_f32 v[58:59], v[62:63], v[68:69], v[58:59] op_sel_hi:[1,0,1]
	ds_read_b128 v[70:73], v14 offset:16320
	ds_read_b128 v[74:77], v14 offset:16384
	ds_read_b128 v[78:81], v14 offset:16448
	ds_read_b128 v[82:85], v14 offset:16512
	ds_read_b128 v[86:89], v14 offset:16576
	ds_read_b128 v[90:93], v14 offset:16640
	ds_read_b128 v[94:97], v14 offset:16704
	ds_read_b128 v[98:101], v14 offset:16768
	s_waitcnt lgkmcnt(8)
	v_pk_fma_f32 v[62:63], v[122:123], v[2:3], 0 op_sel_hi:[1,0,0]
	v_pk_fma_f32 v[62:63], v[124:125], v[2:3], v[62:63] op_sel:[0,1,0] op_sel_hi:[1,1,1]
	v_pk_fma_f32 v[62:63], v[126:127], v[4:5], v[62:63] op_sel_hi:[1,0,1]
	v_pk_fma_f32 v[62:63], v[128:129], v[4:5], v[62:63] op_sel:[0,1,0] op_sel_hi:[1,1,1]
	v_pk_fma_f32 v[62:63], v[130:131], v[8:9], v[62:63] op_sel_hi:[1,0,1]
	v_pk_fma_f32 v[62:63], v[132:133], v[8:9], v[62:63] op_sel:[0,1,0] op_sel_hi:[1,1,1]
	v_pk_fma_f32 v[62:63], v[38:39], v[10:11], v[62:63] op_sel_hi:[1,0,1]
	v_pk_fma_f32 v[62:63], v[40:41], v[10:11], v[62:63] op_sel:[0,1,0] op_sel_hi:[1,1,1]
	v_pk_fma_f32 v[62:63], v[42:43], v[18:19], v[62:63] op_sel_hi:[1,0,1]
	v_pk_fma_f32 v[62:63], v[44:45], v[18:19], v[62:63] op_sel:[0,1,0] op_sel_hi:[1,1,1]
	v_pk_fma_f32 v[62:63], v[46:47], v[50:51], v[62:63] op_sel_hi:[1,0,1]
	v_pk_fma_f32 v[62:63], v[48:49], v[50:51], v[62:63] op_sel:[0,1,0] op_sel_hi:[1,1,1]
	v_pk_fma_f32 v[62:63], v[102:103], v[54:55], v[62:63] op_sel_hi:[1,0,1]
	v_pk_fma_f32 v[62:63], v[104:105], v[54:55], v[62:63] op_sel:[0,1,0] op_sel_hi:[1,1,1]
	v_pk_fma_f32 v[62:63], v[242:243], v[58:59], v[62:63] op_sel_hi:[1,0,1]
	v_pk_fma_f32 v[62:63], v[244:245], v[58:59], v[62:63] op_sel:[0,1,0] op_sel_hi:[1,1,1]
	s_nop 1
	v_add_f32_dpp v62, v62, v62 quad_perm:[1,0,3,2] row_mask:0xf bank_mask:0xf bound_ctrl:1
	v_add_f32_dpp v63, v63, v63 quad_perm:[1,0,3,2] row_mask:0xf bank_mask:0xf bound_ctrl:1
	s_nop 0
	v_add_f32_dpp v62, v62, v62 quad_perm:[2,3,0,1] row_mask:0xf bank_mask:0xf bound_ctrl:1
	v_add_f32_dpp v63, v63, v63 quad_perm:[2,3,0,1] row_mask:0xf bank_mask:0xf bound_ctrl:1
	v_fma_f32 v63, -v243, v62, v63
	v_pk_fma_f32 v[58:59], v[62:63], v[112:113], v[58:59] op_sel_hi:[1,0,1]
	ds_read_b128 v[122:125], v14 offset:16864
	ds_read_b128 v[126:129], v14 offset:16928
	ds_read_b128 v[130:133], v14 offset:16992
	ds_read_b128 v[38:41], v14 offset:17056
	ds_read_b128 v[42:45], v14 offset:17120
	ds_read_b128 v[46:49], v14 offset:17184
	ds_read_b128 v[102:105], v14 offset:17248
	ds_read_b128 v[242:245], v14 offset:17312
	s_waitcnt lgkmcnt(8)
	v_pk_fma_f32 v[62:63], v[70:71], v[2:3], 0 op_sel_hi:[1,0,0]
	v_pk_fma_f32 v[62:63], v[72:73], v[2:3], v[62:63] op_sel:[0,1,0] op_sel_hi:[1,1,1]
	v_pk_fma_f32 v[62:63], v[74:75], v[4:5], v[62:63] op_sel_hi:[1,0,1]
	v_pk_fma_f32 v[62:63], v[76:77], v[4:5], v[62:63] op_sel:[0,1,0] op_sel_hi:[1,1,1]
	v_pk_fma_f32 v[62:63], v[78:79], v[8:9], v[62:63] op_sel_hi:[1,0,1]
	v_pk_fma_f32 v[62:63], v[80:81], v[8:9], v[62:63] op_sel:[0,1,0] op_sel_hi:[1,1,1]
	v_pk_fma_f32 v[62:63], v[82:83], v[10:11], v[62:63] op_sel_hi:[1,0,1]
	v_pk_fma_f32 v[62:63], v[84:85], v[10:11], v[62:63] op_sel:[0,1,0] op_sel_hi:[1,1,1]
	v_pk_fma_f32 v[62:63], v[86:87], v[18:19], v[62:63] op_sel_hi:[1,0,1]
	v_pk_fma_f32 v[62:63], v[88:89], v[18:19], v[62:63] op_sel:[0,1,0] op_sel_hi:[1,1,1]
	v_pk_fma_f32 v[62:63], v[90:91], v[50:51], v[62:63] op_sel_hi:[1,0,1]
	v_pk_fma_f32 v[62:63], v[92:93], v[50:51], v[62:63] op_sel:[0,1,0] op_sel_hi:[1,1,1]
	v_pk_fma_f32 v[62:63], v[94:95], v[54:55], v[62:63] op_sel_hi:[1,0,1]
	v_pk_fma_f32 v[62:63], v[96:97], v[54:55], v[62:63] op_sel:[0,1,0] op_sel_hi:[1,1,1]
	v_pk_fma_f32 v[62:63], v[98:99], v[58:59], v[62:63] op_sel_hi:[1,0,1]
	v_pk_fma_f32 v[62:63], v[100:101], v[58:59], v[62:63] op_sel:[0,1,0] op_sel_hi:[1,1,1]
	s_nop 1
	v_add_f32_dpp v62, v62, v62 quad_perm:[1,0,3,2] row_mask:0xf bank_mask:0xf bound_ctrl:1
	v_add_f32_dpp v63, v63, v63 quad_perm:[1,0,3,2] row_mask:0xf bank_mask:0xf bound_ctrl:1
	s_nop 0
	v_add_f32_dpp v62, v62, v62 quad_perm:[2,3,0,1] row_mask:0xf bank_mask:0xf bound_ctrl:1
	v_add_f32_dpp v63, v63, v63 quad_perm:[2,3,0,1] row_mask:0xf bank_mask:0xf bound_ctrl:1
	v_fma_f32 v63, -v99, v62, v63
	v_pk_fma_f32 v[58:59], v[62:63], v[116:117], v[58:59] op_sel_hi:[1,0,1]
	s_waitcnt lgkmcnt(0)
; #define LAS __attribute__((address_space(3)))
;     ...
;     if (w < 2) {
;         const int d = w; const LAS float* Ad = As + d * 4352;
;         float tr[64]; int lane_o = lane;
; #pragma unroll
;         for (int ip = 0; ip < 32; ++ip) {
;             const int i0 = 2 * ip;
;             f32x4 rv[32];
; #pragma unroll
;             for (int jp = 0; jp <= ip; ++jp) rv[jp] = *(const LAS f32x4*)(Ad + ip * 136 + 4 * jp);
;             asm volatile("" : "+v"(lane_o) :: "memory");
;             f32x2_ a0 = {0.f, 0.f}, a1 = {0.f, 0.f}, a2 = {0.f, 0.f}, a3 = {0.f, 0.f};
; #pragma unroll
;             for (int jp = 0; jp < ip; ++jp) {
;                 const f32x2_ ta = {tr[2 * jp], tr[2 * jp]}, tb = {tr[2 * jp + 1], tr[2 * jp + 1]};
;                 const f32x2_ va = {rv[jp][0], rv[jp][1]}, vb = {rv[jp][2], rv[jp][3]};
;                 if (jp & 1) { a2 += va * ta; a3 += vb * tb; } else { a0 += va * ta; a1 += vb * tb; }
;             }
;             const f32x2_ sum = (a0 + a1) + (a2 + a3);
;             const float t0 = (lane_o == i0 ? 1.f : 0.f) - sum[0];
;             tr[i0] = t0;
;             tr[i0 + 1] = (lane_o == i0 + 1 ? 1.f : 0.f) - sum[1] - rv[ip][1] * t0;
;         }
	v_pk_fma_f32 v[62:63], v[122:123], v[2:3], 0 op_sel_hi:[1,0,0]
	v_pk_fma_f32 v[62:63], v[124:125], v[2:3], v[62:63] op_sel:[0,1,0] op_sel_hi:[1,1,1]
	v_pk_fma_f32 v[62:63], v[126:127], v[4:5], v[62:63] op_sel_hi:[1,0,1]
	v_pk_fma_f32 v[62:63], v[128:129], v[4:5], v[62:63] op_sel:[0,1,0] op_sel_hi:[1,1,1]
	v_pk_fma_f32 v[62:63], v[130:131], v[8:9], v[62:63] op_sel_hi:[1,0,1]
	v_pk_fma_f32 v[62:63], v[132:133], v[8:9], v[62:63] op_sel:[0,1,0] op_sel_hi:[1,1,1]
	v_pk_fma_f32 v[62:63], v[38:39], v[10:11], v[62:63] op_sel_hi:[1,0,1]
	v_pk_fma_f32 v[62:63], v[40:41], v[10:11], v[62:63] op_sel:[0,1,0] op_sel_hi:[1,1,1]
	v_pk_fma_f32 v[62:63], v[42:43], v[18:19], v[62:63] op_sel_hi:[1,0,1]
	v_pk_fma_f32 v[62:63], v[44:45], v[18:19], v[62:63] op_sel:[0,1,0] op_sel_hi:[1,1,1]
	v_pk_fma_f32 v[62:63], v[46:47], v[50:51], v[62:63] op_sel_hi:[1,0,1]
	v_pk_fma_f32 v[62:63], v[48:49], v[50:51], v[62:63] op_sel:[0,1,0] op_sel_hi:[1,1,1]
	v_pk_fma_f32 v[62:63], v[102:103], v[54:55], v[62:63] op_sel_hi:[1,0,1]
	v_pk_fma_f32 v[62:63], v[104:105], v[54:55], v[62:63] op_sel:[0,1,0] op_sel_hi:[1,1,1]
	v_pk_fma_f32 v[62:63], v[242:243], v[58:59], v[62:63] op_sel_hi:[1,0,1]
	v_pk_fma_f32 v[62:63], v[244:245], v[58:59], v[62:63] op_sel:[0,1,0] op_sel_hi:[1,1,1]
	s_nop 1
	v_add_f32_dpp v62, v62, v62 quad_perm:[1,0,3,2] row_mask:0xf bank_mask:0xf bound_ctrl:1
	v_add_f32_dpp v63, v63, v63 quad_perm:[1,0,3,2] row_mask:0xf bank_mask:0xf bound_ctrl:1
	s_nop 0
	v_add_f32_dpp v62, v62, v62 quad_perm:[2,3,0,1] row_mask:0xf bank_mask:0xf bound_ctrl:1
	v_add_f32_dpp v63, v63, v63 quad_perm:[2,3,0,1] row_mask:0xf bank_mask:0xf bound_ctrl:1
	v_fma_f32 v63, -v243, v62, v63
	v_pk_fma_f32 v[58:59], v[62:63], v[120:121], v[58:59] op_sel_hi:[1,0,1]
	s_branch .Lfs_outsel
.Lfs_ent1:
	ds_read_b128 v[78:81], v14 offset:4480
	ds_read_b128 v[130:133], v14 offset:5024
	s_waitcnt lgkmcnt(1)
	v_pk_fma_f32 v[62:63], v[78:79], v[8:9], 0 op_sel_hi:[1,0,0]
	v_pk_fma_f32 v[62:63], v[80:81], v[8:9], v[62:63] op_sel:[0,1,0] op_sel_hi:[1,1,1]
	s_nop 1
	v_add_f32_dpp v62, v62, v62 quad_perm:[1,0,3,2] row_mask:0xf bank_mask:0xf bound_ctrl:1
	v_add_f32_dpp v63, v63, v63 quad_perm:[1,0,3,2] row_mask:0xf bank_mask:0xf bound_ctrl:1
	s_nop 0
	v_add_f32_dpp v62, v62, v62 quad_perm:[2,3,0,1] row_mask:0xf bank_mask:0xf bound_ctrl:1
	v_add_f32_dpp v63, v63, v63 quad_perm:[2,3,0,1] row_mask:0xf bank_mask:0xf bound_ctrl:1
	v_fma_f32 v63, -v79, v62, v63
	v_pk_fma_f32 v[8:9], v[62:63], v[68:69], v[8:9] op_sel_hi:[1,0,1]
	ds_read_b128 v[78:81], v14 offset:5568
	s_waitcnt lgkmcnt(1)
	v_pk_fma_f32 v[62:63], v[130:131], v[8:9], 0 op_sel_hi:[1,0,0]
	v_pk_fma_f32 v[62:63], v[132:133], v[8:9], v[62:63] op_sel:[0,1,0] op_sel_hi:[1,1,1]
	s_nop 1
	v_add_f32_dpp v62, v62, v62 quad_perm:[1,0,3,2] row_mask:0xf bank_mask:0xf bound_ctrl:1
	v_add_f32_dpp v63, v63, v63 quad_perm:[1,0,3,2] row_mask:0xf bank_mask:0xf bound_ctrl:1
	s_nop 0
	v_add_f32_dpp v62, v62, v62 quad_perm:[2,3,0,1] row_mask:0xf bank_mask:0xf bound_ctrl:1
	v_add_f32_dpp v63, v63, v63 quad_perm:[2,3,0,1] row_mask:0xf bank_mask:0xf bound_ctrl:1
	v_fma_f32 v63, -v131, v62, v63
	v_pk_fma_f32 v[8:9], v[62:63], v[112:113], v[8:9] op_sel_hi:[1,0,1]
	ds_read_b128 v[130:133], v14 offset:6112
	s_waitcnt lgkmcnt(1)
	v_pk_fma_f32 v[62:63], v[78:79], v[8:9], 0 op_sel_hi:[1,0,0]
	v_pk_fma_f32 v[62:63], v[80:81], v[8:9], v[62:63] op_sel:[0,1,0] op_sel_hi:[1,1,1]
	s_nop 1
	v_add_f32_dpp v62, v62, v62 quad_perm:[1,0,3,2] row_mask:0xf bank_mask:0xf bound_ctrl:1
	v_add_f32_dpp v63, v63, v63 quad_perm:[1,0,3,2] row_mask:0xf bank_mask:0xf bound_ctrl:1
	s_nop 0
	v_add_f32_dpp v62, v62, v62 quad_perm:[2,3,0,1] row_mask:0xf bank_mask:0xf bound_ctrl:1
	v_add_f32_dpp v63, v63, v63 quad_perm:[2,3,0,1] row_mask:0xf bank_mask:0xf bound_ctrl:1
	v_fma_f32 v63, -v79, v62, v63
	v_pk_fma_f32 v[8:9], v[62:63], v[116:117], v[8:9] op_sel_hi:[1,0,1]
	ds_read_b128 v[78:81], v14 offset:6656
	ds_read_b128 v[82:85], v14 offset:6720
	s_waitcnt lgkmcnt(2)
	v_pk_fma_f32 v[62:63], v[130:131], v[8:9], 0 op_sel_hi:[1,0,0]
	v_pk_fma_f32 v[62:63], v[132:133], v[8:9], v[62:63] op_sel:[0,1,0] op_sel_hi:[1,1,1]
	s_nop 1
	v_add_f32_dpp v62, v62, v62 quad_perm:[1,0,3,2] row_mask:0xf bank_mask:0xf bound_ctrl:1
	v_add_f32_dpp v63, v63, v63 quad_perm:[1,0,3,2] row_mask:0xf bank_mask:0xf bound_ctrl:1
	s_nop 0
	v_add_f32_dpp v62, v62, v62 quad_perm:[2,3,0,1] row_mask:0xf bank_mask:0xf bound_ctrl:1
	v_add_f32_dpp v63, v63, v63 quad_perm:[2,3,0,1] row_mask:0xf bank_mask:0xf bound_ctrl:1
	v_fma_f32 v63, -v131, v62, v63
	v_pk_fma_f32 v[8:9], v[62:63], v[120:121], v[8:9] op_sel_hi:[1,0,1]
	ds_read_b128 v[130:133], v14 offset:7200
	ds_read_b128 v[38:41], v14 offset:7264
	s_waitcnt lgkmcnt(2)
	v_pk_fma_f32 v[62:63], v[82:83], v[10:11], 0 op_sel_hi:[1,0,0]
	v_pk_fma_f32 v[62:63], v[84:85], v[10:11], v[62:63] op_sel:[0,1,0] op_sel_hi:[1,1,1]
	v_pk_fma_f32 v[62:63], v[78:79], v[8:9], v[62:63] op_sel_hi:[1,0,1]
	v_pk_fma_f32 v[62:63], v[80:81], v[8:9], v[62:63] op_sel:[0,1,0] op_sel_hi:[1,1,1]
	s_nop 1
	v_add_f32_dpp v62, v62, v62 quad_perm:[1,0,3,2] row_mask:0xf bank_mask:0xf bound_ctrl:1
	v_add_f32_dpp v63, v63, v63 quad_perm:[1,0,3,2] row_mask:0xf bank_mask:0xf bound_ctrl:1
	s_nop 0
	v_add_f32_dpp v62, v62, v62 quad_perm:[2,3,0,1] row_mask:0xf bank_mask:0xf bound_ctrl:1
	v_add_f32_dpp v63, v63, v63 quad_perm:[2,3,0,1] row_mask:0xf bank_mask:0xf bound_ctrl:1
	v_fma_f32 v63, -v83, v62, v63
	v_pk_fma_f32 v[10:11], v[62:63], v[68:69], v[10:11] op_sel_hi:[1,0,1]
	ds_read_b128 v[78:81], v14 offset:7744
	ds_read_b128 v[82:85], v14 offset:7808
	s_waitcnt lgkmcnt(2)
; #define LAS __attribute__((address_space(3)))
;     ...
;     if (w < 2) {
;         const int d = w; const LAS float* Ad = As + d * 4352;
;         float tr[64]; int lane_o = lane;
; #pragma unroll
;         for (int ip = 0; ip < 32; ++ip) {
;             const int i0 = 2 * ip;
;             f32x4 rv[32];
; #pragma unroll
;             for (int jp = 0; jp <= ip; ++jp) rv[jp] = *(const LAS f32x4*)(Ad + ip * 136 + 4 * jp);
;             asm volatile("" : "+v"(lane_o) :: "memory");
;             f32x2_ a0 = {0.f, 0.f}, a1 = {0.f, 0.f}, a2 = {0.f, 0.f}, a3 = {0.f, 0.f};
; #pragma unroll
;             for (int jp = 0; jp < ip; ++jp) {
;                 const f32x2_ ta = {tr[2 * jp], tr[2 * jp]}, tb = {tr[2 * jp + 1], tr[2 * jp + 1]};
;                 const f32x2_ va = {rv[jp][0], rv[jp][1]}, vb = {rv[jp][2], rv[jp][3]};
;                 if (jp & 1) { a2 += va * ta; a3 += vb * tb; } else { a0 += va * ta; a1 += vb * tb; }
;             }
;             const f32x2_ sum = (a0 + a1) + (a2 + a3);
;             const float t0 = (lane_o == i0 ? 1.f : 0.f) - sum[0];
;             tr[i0] = t0;
;             tr[i0 + 1] = (lane_o == i0 + 1 ? 1.f : 0.f) - sum[1] - rv[ip][1] * t0;
;         }
	v_pk_fma_f32 v[62:63], v[130:131], v[8:9], 0 op_sel_hi:[1,0,0]
	v_pk_fma_f32 v[62:63], v[132:133], v[8:9], v[62:63] op_sel:[0,1,0] op_sel_hi:[1,1,1]
	v_pk_fma_f32 v[62:63], v[38:39], v[10:11], v[62:63] op_sel_hi:[1,0,1]
	v_pk_fma_f32 v[62:63], v[40:41], v[10:11], v[62:63] op_sel:[0,1,0] op_sel_hi:[1,1,1]
	s_nop 1
	v_add_f32_dpp v62, v62, v62 quad_perm:[1,0,3,2] row_mask:0xf bank_mask:0xf bound_ctrl:1
	v_add_f32_dpp v63, v63, v63 quad_perm:[1,0,3,2] row_mask:0xf bank_mask:0xf bound_ctrl:1
	s_nop 0
	v_add_f32_dpp v62, v62, v62 quad_perm:[2,3,0,1] row_mask:0xf bank_mask:0xf bound_ctrl:1
	v_add_f32_dpp v63, v63, v63 quad_perm:[2,3,0,1] row_mask:0xf bank_mask:0xf bound_ctrl:1
	v_fma_f32 v63, -v39, v62, v63
	v_pk_fma_f32 v[10:11], v[62:63], v[112:113], v[10:11] op_sel_hi:[1,0,1]
	ds_read_b128 v[130:133], v14 offset:8288
	ds_read_b128 v[38:41], v14 offset:8352
	s_waitcnt lgkmcnt(2)
	v_pk_fma_f32 v[62:63], v[78:79], v[8:9], 0 op_sel_hi:[1,0,0]
	v_pk_fma_f32 v[62:63], v[80:81], v[8:9], v[62:63] op_sel:[0,1,0] op_sel_hi:[1,1,1]
	v_pk_fma_f32 v[62:63], v[82:83], v[10:11], v[62:63] op_sel_hi:[1,0,1]
	v_pk_fma_f32 v[62:63], v[84:85], v[10:11], v[62:63] op_sel:[0,1,0] op_sel_hi:[1,1,1]
	s_nop 1
	v_add_f32_dpp v62, v62, v62 quad_perm:[1,0,3,2] row_mask:0xf bank_mask:0xf bound_ctrl:1
	v_add_f32_dpp v63, v63, v63 quad_perm:[1,0,3,2] row_mask:0xf bank_mask:0xf bound_ctrl:1
	s_nop 0
	v_add_f32_dpp v62, v62, v62 quad_perm:[2,3,0,1] row_mask:0xf bank_mask:0xf bound_ctrl:1
	v_add_f32_dpp v63, v63, v63 quad_perm:[2,3,0,1] row_mask:0xf bank_mask:0xf bound_ctrl:1
	v_fma_f32 v63, -v83, v62, v63
	v_pk_fma_f32 v[10:11], v[62:63], v[116:117], v[10:11] op_sel_hi:[1,0,1]
	ds_read_b128 v[78:81], v14 offset:8832
	ds_read_b128 v[82:85], v14 offset:8896
	ds_read_b128 v[86:89], v14 offset:8960
	s_waitcnt lgkmcnt(3)
	v_pk_fma_f32 v[62:63], v[130:131], v[8:9], 0 op_sel_hi:[1,0,0]
	v_pk_fma_f32 v[62:63], v[132:133], v[8:9], v[62:63] op_sel:[0,1,0] op_sel_hi:[1,1,1]
	v_pk_fma_f32 v[62:63], v[38:39], v[10:11], v[62:63] op_sel_hi:[1,0,1]
	v_pk_fma_f32 v[62:63], v[40:41], v[10:11], v[62:63] op_sel:[0,1,0] op_sel_hi:[1,1,1]
	s_nop 1
	v_add_f32_dpp v62, v62, v62 quad_perm:[1,0,3,2] row_mask:0xf bank_mask:0xf bound_ctrl:1
	v_add_f32_dpp v63, v63, v63 quad_perm:[1,0,3,2] row_mask:0xf bank_mask:0xf bound_ctrl:1
	s_nop 0
	v_add_f32_dpp v62, v62, v62 quad_perm:[2,3,0,1] row_mask:0xf bank_mask:0xf bound_ctrl:1
	v_add_f32_dpp v63, v63, v63 quad_perm:[2,3,0,1] row_mask:0xf bank_mask:0xf bound_ctrl:1
	v_fma_f32 v63, -v39, v62, v63
	v_pk_fma_f32 v[10:11], v[62:63], v[120:121], v[10:11] op_sel_hi:[1,0,1]
	ds_read_b128 v[130:133], v14 offset:9376
	ds_read_b128 v[38:41], v14 offset:9440
	ds_read_b128 v[42:45], v14 offset:9504
	s_waitcnt lgkmcnt(3)
	v_pk_fma_f32 v[62:63], v[78:79], v[8:9], 0 op_sel_hi:[1,0,0]
	v_pk_fma_f32 v[62:63], v[80:81], v[8:9], v[62:63] op_sel:[0,1,0] op_sel_hi:[1,1,1]
	v_pk_fma_f32 v[62:63], v[86:87], v[18:19], v[62:63] op_sel_hi:[1,0,1]
	v_pk_fma_f32 v[62:63], v[88:89], v[18:19], v[62:63] op_sel:[0,1,0] op_sel_hi:[1,1,1]
	v_pk_fma_f32 v[62:63], v[82:83], v[10:11], v[62:63] op_sel_hi:[1,0,1]
	v_pk_fma_f32 v[62:63], v[84:85], v[10:11], v[62:63] op_sel:[0,1,0] op_sel_hi:[1,1,1]
	s_nop 1
	v_add_f32_dpp v62, v62, v62 quad_perm:[1,0,3,2] row_mask:0xf bank_mask:0xf bound_ctrl:1
	v_add_f32_dpp v63, v63, v63 quad_perm:[1,0,3,2] row_mask:0xf bank_mask:0xf bound_ctrl:1
	s_nop 0
	v_add_f32_dpp v62, v62, v62 quad_perm:[2,3,0,1] row_mask:0xf bank_mask:0xf bound_ctrl:1
	v_add_f32_dpp v63, v63, v63 quad_perm:[2,3,0,1] row_mask:0xf bank_mask:0xf bound_ctrl:1
	v_fma_f32 v63, -v87, v62, v63
	v_pk_fma_f32 v[18:19], v[62:63], v[68:69], v[18:19] op_sel_hi:[1,0,1]
	ds_read_b128 v[78:81], v14 offset:9920
	ds_read_b128 v[82:85], v14 offset:9984
	ds_read_b128 v[86:89], v14 offset:10048
	s_waitcnt lgkmcnt(3)
	v_pk_fma_f32 v[62:63], v[130:131], v[8:9], 0 op_sel_hi:[1,0,0]
	v_pk_fma_f32 v[62:63], v[132:133], v[8:9], v[62:63] op_sel:[0,1,0] op_sel_hi:[1,1,1]
	v_pk_fma_f32 v[62:63], v[38:39], v[10:11], v[62:63] op_sel_hi:[1,0,1]
	v_pk_fma_f32 v[62:63], v[40:41], v[10:11], v[62:63] op_sel:[0,1,0] op_sel_hi:[1,1,1]
	v_pk_fma_f32 v[62:63], v[42:43], v[18:19], v[62:63] op_sel_hi:[1,0,1]
	v_pk_fma_f32 v[62:63], v[44:45], v[18:19], v[62:63] op_sel:[0,1,0] op_sel_hi:[1,1,1]
	s_nop 1
	v_add_f32_dpp v62, v62, v62 quad_perm:[1,0,3,2] row_mask:0xf bank_mask:0xf bound_ctrl:1
	v_add_f32_dpp v63, v63, v63 quad_perm:[1,0,3,2] row_mask:0xf bank_mask:0xf bound_ctrl:1
	s_nop 0
	v_add_f32_dpp v62, v62, v62 quad_perm:[2,3,0,1] row_mask:0xf bank_mask:0xf bound_ctrl:1
	v_add_f32_dpp v63, v63, v63 quad_perm:[2,3,0,1] row_mask:0xf bank_mask:0xf bound_ctrl:1
	v_fma_f32 v63, -v43, v62, v63
	v_pk_fma_f32 v[18:19], v[62:63], v[112:113], v[18:19] op_sel_hi:[1,0,1]
	ds_read_b128 v[130:133], v14 offset:10464
	ds_read_b128 v[38:41], v14 offset:10528
	ds_read_b128 v[42:45], v14 offset:10592
	s_waitcnt lgkmcnt(3)
	v_pk_fma_f32 v[62:63], v[78:79], v[8:9], 0 op_sel_hi:[1,0,0]
	v_pk_fma_f32 v[62:63], v[80:81], v[8:9], v[62:63] op_sel:[0,1,0] op_sel_hi:[1,1,1]
	v_pk_fma_f32 v[62:63], v[82:83], v[10:11], v[62:63] op_sel_hi:[1,0,1]
	v_pk_fma_f32 v[62:63], v[84:85], v[10:11], v[62:63] op_sel:[0,1,0] op_sel_hi:[1,1,1]
	v_pk_fma_f32 v[62:63], v[86:87], v[18:19], v[62:63] op_sel_hi:[1,0,1]
	v_pk_fma_f32 v[62:63], v[88:89], v[18:19], v[62:63] op_sel:[0,1,0] op_sel_hi:[1,1,1]
	s_nop 1
	v_add_f32_dpp v62, v62, v62 quad_perm:[1,0,3,2] row_mask:0xf bank_mask:0xf bound_ctrl:1
	v_add_f32_dpp v63, v63, v63 quad_perm:[1,0,3,2] row_mask:0xf bank_mask:0xf bound_ctrl:1
	s_nop 0
	v_add_f32_dpp v62, v62, v62 quad_perm:[2,3,0,1] row_mask:0xf bank_mask:0xf bound_ctrl:1
	v_add_f32_dpp v63, v63, v63 quad_perm:[2,3,0,1] row_mask:0xf bank_mask:0xf bound_ctrl:1
	v_fma_f32 v63, -v87, v62, v63
	v_pk_fma_f32 v[18:19], v[62:63], v[116:117], v[18:19] op_sel_hi:[1,0,1]
	ds_read_b128 v[78:81], v14 offset:11008
	ds_read_b128 v[82:85], v14 offset:11072
	ds_read_b128 v[86:89], v14 offset:11136
	ds_read_b128 v[90:93], v14 offset:11200
	s_waitcnt lgkmcnt(4)
; #define LAS __attribute__((address_space(3)))
;     ...
;     if (w < 2) {
;         const int d = w; const LAS float* Ad = As + d * 4352;
;         float tr[64]; int lane_o = lane;
; #pragma unroll
;         for (int ip = 0; ip < 32; ++ip) {
;             const int i0 = 2 * ip;
;             f32x4 rv[32];
; #pragma unroll
;             for (int jp = 0; jp <= ip; ++jp) rv[jp] = *(const LAS f32x4*)(Ad + ip * 136 + 4 * jp);
;             asm volatile("" : "+v"(lane_o) :: "memory");
;             f32x2_ a0 = {0.f, 0.f}, a1 = {0.f, 0.f}, a2 = {0.f, 0.f}, a3 = {0.f, 0.f};
; #pragma unroll
;             for (int jp = 0; jp < ip; ++jp) {
;                 const f32x2_ ta = {tr[2 * jp], tr[2 * jp]}, tb = {tr[2 * jp + 1], tr[2 * jp + 1]};
;                 const f32x2_ va = {rv[jp][0], rv[jp][1]}, vb = {rv[jp][2], rv[jp][3]};
;                 if (jp & 1) { a2 += va * ta; a3 += vb * tb; } else { a0 += va * ta; a1 += vb * tb; }
;             }
;             const f32x2_ sum = (a0 + a1) + (a2 + a3);
;             const float t0 = (lane_o == i0 ? 1.f : 0.f) - sum[0];
;             tr[i0] = t0;
;             tr[i0 + 1] = (lane_o == i0 + 1 ? 1.f : 0.f) - sum[1] - rv[ip][1] * t0;
;         }
	v_pk_fma_f32 v[62:63], v[130:131], v[8:9], 0 op_sel_hi:[1,0,0]
	v_pk_fma_f32 v[62:63], v[132:133], v[8:9], v[62:63] op_sel:[0,1,0] op_sel_hi:[1,1,1]
	v_pk_fma_f32 v[62:63], v[38:39], v[10:11], v[62:63] op_sel_hi:[1,0,1]
	v_pk_fma_f32 v[62:63], v[40:41], v[10:11], v[62:63] op_sel:[0,1,0] op_sel_hi:[1,1,1]
	v_pk_fma_f32 v[62:63], v[42:43], v[18:19], v[62:63] op_sel_hi:[1,0,1]
	v_pk_fma_f32 v[62:63], v[44:45], v[18:19], v[62:63] op_sel:[0,1,0] op_sel_hi:[1,1,1]
	s_nop 1
	v_add_f32_dpp v62, v62, v62 quad_perm:[1,0,3,2] row_mask:0xf bank_mask:0xf bound_ctrl:1
	v_add_f32_dpp v63, v63, v63 quad_perm:[1,0,3,2] row_mask:0xf bank_mask:0xf bound_ctrl:1
	s_nop 0
	v_add_f32_dpp v62, v62, v62 quad_perm:[2,3,0,1] row_mask:0xf bank_mask:0xf bound_ctrl:1
	v_add_f32_dpp v63, v63, v63 quad_perm:[2,3,0,1] row_mask:0xf bank_mask:0xf bound_ctrl:1
	v_fma_f32 v63, -v43, v62, v63
	v_pk_fma_f32 v[18:19], v[62:63], v[120:121], v[18:19] op_sel_hi:[1,0,1]
	ds_read_b128 v[130:133], v14 offset:11552
	ds_read_b128 v[38:41], v14 offset:11616
	ds_read_b128 v[42:45], v14 offset:11680
	ds_read_b128 v[46:49], v14 offset:11744
	s_waitcnt lgkmcnt(4)
	v_pk_fma_f32 v[62:63], v[78:79], v[8:9], 0 op_sel_hi:[1,0,0]
	v_pk_fma_f32 v[62:63], v[80:81], v[8:9], v[62:63] op_sel:[0,1,0] op_sel_hi:[1,1,1]
	v_pk_fma_f32 v[62:63], v[82:83], v[10:11], v[62:63] op_sel_hi:[1,0,1]
	v_pk_fma_f32 v[62:63], v[84:85], v[10:11], v[62:63] op_sel:[0,1,0] op_sel_hi:[1,1,1]
	v_pk_fma_f32 v[62:63], v[90:91], v[50:51], v[62:63] op_sel_hi:[1,0,1]
	v_pk_fma_f32 v[62:63], v[92:93], v[50:51], v[62:63] op_sel:[0,1,0] op_sel_hi:[1,1,1]
	v_pk_fma_f32 v[62:63], v[86:87], v[18:19], v[62:63] op_sel_hi:[1,0,1]
	v_pk_fma_f32 v[62:63], v[88:89], v[18:19], v[62:63] op_sel:[0,1,0] op_sel_hi:[1,1,1]
	s_nop 1
	v_add_f32_dpp v62, v62, v62 quad_perm:[1,0,3,2] row_mask:0xf bank_mask:0xf bound_ctrl:1
	v_add_f32_dpp v63, v63, v63 quad_perm:[1,0,3,2] row_mask:0xf bank_mask:0xf bound_ctrl:1
	s_nop 0
	v_add_f32_dpp v62, v62, v62 quad_perm:[2,3,0,1] row_mask:0xf bank_mask:0xf bound_ctrl:1
	v_add_f32_dpp v63, v63, v63 quad_perm:[2,3,0,1] row_mask:0xf bank_mask:0xf bound_ctrl:1
	v_fma_f32 v63, -v91, v62, v63
	v_pk_fma_f32 v[50:51], v[62:63], v[68:69], v[50:51] op_sel_hi:[1,0,1]
	ds_read_b128 v[78:81], v14 offset:12096
	ds_read_b128 v[82:85], v14 offset:12160
	ds_read_b128 v[86:89], v14 offset:12224
	ds_read_b128 v[90:93], v14 offset:12288
	s_waitcnt lgkmcnt(4)
	v_pk_fma_f32 v[62:63], v[130:131], v[8:9], 0 op_sel_hi:[1,0,0]
	v_pk_fma_f32 v[62:63], v[132:133], v[8:9], v[62:63] op_sel:[0,1,0] op_sel_hi:[1,1,1]
	v_pk_fma_f32 v[62:63], v[38:39], v[10:11], v[62:63] op_sel_hi:[1,0,1]
	v_pk_fma_f32 v[62:63], v[40:41], v[10:11], v[62:63] op_sel:[0,1,0] op_sel_hi:[1,1,1]
	v_pk_fma_f32 v[62:63], v[42:43], v[18:19], v[62:63] op_sel_hi:[1,0,1]
	v_pk_fma_f32 v[62:63], v[44:45], v[18:19], v[62:63] op_sel:[0,1,0] op_sel_hi:[1,1,1]
	v_pk_fma_f32 v[62:63], v[46:47], v[50:51], v[62:63] op_sel_hi:[1,0,1]
	v_pk_fma_f32 v[62:63], v[48:49], v[50:51], v[62:63] op_sel:[0,1,0] op_sel_hi:[1,1,1]
	s_nop 1
	v_add_f32_dpp v62, v62, v62 quad_perm:[1,0,3,2] row_mask:0xf bank_mask:0xf bound_ctrl:1
	v_add_f32_dpp v63, v63, v63 quad_perm:[1,0,3,2] row_mask:0xf bank_mask:0xf bound_ctrl:1
	s_nop 0
	v_add_f32_dpp v62, v62, v62 quad_perm:[2,3,0,1] row_mask:0xf bank_mask:0xf bound_ctrl:1
	v_add_f32_dpp v63, v63, v63 quad_perm:[2,3,0,1] row_mask:0xf bank_mask:0xf bound_ctrl:1
	v_fma_f32 v63, -v47, v62, v63
	v_pk_fma_f32 v[50:51], v[62:63], v[112:113], v[50:51] op_sel_hi:[1,0,1]
	ds_read_b128 v[130:133], v14 offset:12640
	ds_read_b128 v[38:41], v14 offset:12704
	ds_read_b128 v[42:45], v14 offset:12768
	ds_read_b128 v[46:49], v14 offset:12832
	s_waitcnt lgkmcnt(4)
	v_pk_fma_f32 v[62:63], v[78:79], v[8:9], 0 op_sel_hi:[1,0,0]
	v_pk_fma_f32 v[62:63], v[80:81], v[8:9], v[62:63] op_sel:[0,1,0] op_sel_hi:[1,1,1]
	v_pk_fma_f32 v[62:63], v[82:83], v[10:11], v[62:63] op_sel_hi:[1,0,1]
	v_pk_fma_f32 v[62:63], v[84:85], v[10:11], v[62:63] op_sel:[0,1,0] op_sel_hi:[1,1,1]
	v_pk_fma_f32 v[62:63], v[86:87], v[18:19], v[62:63] op_sel_hi:[1,0,1]
	v_pk_fma_f32 v[62:63], v[88:89], v[18:19], v[62:63] op_sel:[0,1,0] op_sel_hi:[1,1,1]
	v_pk_fma_f32 v[62:63], v[90:91], v[50:51], v[62:63] op_sel_hi:[1,0,1]
	v_pk_fma_f32 v[62:63], v[92:93], v[50:51], v[62:63] op_sel:[0,1,0] op_sel_hi:[1,1,1]
	s_nop 1
	v_add_f32_dpp v62, v62, v62 quad_perm:[1,0,3,2] row_mask:0xf bank_mask:0xf bound_ctrl:1
	v_add_f32_dpp v63, v63, v63 quad_perm:[1,0,3,2] row_mask:0xf bank_mask:0xf bound_ctrl:1
	s_nop 0
	v_add_f32_dpp v62, v62, v62 quad_perm:[2,3,0,1] row_mask:0xf bank_mask:0xf bound_ctrl:1
	v_add_f32_dpp v63, v63, v63 quad_perm:[2,3,0,1] row_mask:0xf bank_mask:0xf bound_ctrl:1
	v_fma_f32 v63, -v91, v62, v63
	v_pk_fma_f32 v[50:51], v[62:63], v[116:117], v[50:51] op_sel_hi:[1,0,1]
	ds_read_b128 v[78:81], v14 offset:13184
	ds_read_b128 v[82:85], v14 offset:13248
	ds_read_b128 v[86:89], v14 offset:13312
	ds_read_b128 v[90:93], v14 offset:13376
	ds_read_b128 v[94:97], v14 offset:13440
	s_waitcnt lgkmcnt(5)
; #define LAS __attribute__((address_space(3)))
;     ...
;     if (w < 2) {
;         const int d = w; const LAS float* Ad = As + d * 4352;
;         float tr[64]; int lane_o = lane;
; #pragma unroll
;         for (int ip = 0; ip < 32; ++ip) {
;             const int i0 = 2 * ip;
;             f32x4 rv[32];
; #pragma unroll
;             for (int jp = 0; jp <= ip; ++jp) rv[jp] = *(const LAS f32x4*)(Ad + ip * 136 + 4 * jp);
;             asm volatile("" : "+v"(lane_o) :: "memory");
;             f32x2_ a0 = {0.f, 0.f}, a1 = {0.f, 0.f}, a2 = {0.f, 0.f}, a3 = {0.f, 0.f};
; #pragma unroll
;             for (int jp = 0; jp < ip; ++jp) {
;                 const f32x2_ ta = {tr[2 * jp], tr[2 * jp]}, tb = {tr[2 * jp + 1], tr[2 * jp + 1]};
;                 const f32x2_ va = {rv[jp][0], rv[jp][1]}, vb = {rv[jp][2], rv[jp][3]};
;                 if (jp & 1) { a2 += va * ta; a3 += vb * tb; } else { a0 += va * ta; a1 += vb * tb; }
;             }
;             const f32x2_ sum = (a0 + a1) + (a2 + a3);
;             const float t0 = (lane_o == i0 ? 1.f : 0.f) - sum[0];
;             tr[i0] = t0;
;             tr[i0 + 1] = (lane_o == i0 + 1 ? 1.f : 0.f) - sum[1] - rv[ip][1] * t0;
;         }
	v_pk_fma_f32 v[62:63], v[130:131], v[8:9], 0 op_sel_hi:[1,0,0]
	v_pk_fma_f32 v[62:63], v[132:133], v[8:9], v[62:63] op_sel:[0,1,0] op_sel_hi:[1,1,1]
	v_pk_fma_f32 v[62:63], v[38:39], v[10:11], v[62:63] op_sel_hi:[1,0,1]
	v_pk_fma_f32 v[62:63], v[40:41], v[10:11], v[62:63] op_sel:[0,1,0] op_sel_hi:[1,1,1]
	v_pk_fma_f32 v[62:63], v[42:43], v[18:19], v[62:63] op_sel_hi:[1,0,1]
	v_pk_fma_f32 v[62:63], v[44:45], v[18:19], v[62:63] op_sel:[0,1,0] op_sel_hi:[1,1,1]
	v_pk_fma_f32 v[62:63], v[46:47], v[50:51], v[62:63] op_sel_hi:[1,0,1]
	v_pk_fma_f32 v[62:63], v[48:49], v[50:51], v[62:63] op_sel:[0,1,0] op_sel_hi:[1,1,1]
	s_nop 1
	v_add_f32_dpp v62, v62, v62 quad_perm:[1,0,3,2] row_mask:0xf bank_mask:0xf bound_ctrl:1
	v_add_f32_dpp v63, v63, v63 quad_perm:[1,0,3,2] row_mask:0xf bank_mask:0xf bound_ctrl:1
	s_nop 0
	v_add_f32_dpp v62, v62, v62 quad_perm:[2,3,0,1] row_mask:0xf bank_mask:0xf bound_ctrl:1
	v_add_f32_dpp v63, v63, v63 quad_perm:[2,3,0,1] row_mask:0xf bank_mask:0xf bound_ctrl:1
	v_fma_f32 v63, -v47, v62, v63
	v_pk_fma_f32 v[50:51], v[62:63], v[120:121], v[50:51] op_sel_hi:[1,0,1]
	ds_read_b128 v[130:133], v14 offset:13728
	ds_read_b128 v[38:41], v14 offset:13792
	ds_read_b128 v[42:45], v14 offset:13856
	ds_read_b128 v[46:49], v14 offset:13920
	ds_read_b128 v[102:105], v14 offset:13984
	s_waitcnt lgkmcnt(5)
	v_pk_fma_f32 v[62:63], v[78:79], v[8:9], 0 op_sel_hi:[1,0,0]
	v_pk_fma_f32 v[62:63], v[80:81], v[8:9], v[62:63] op_sel:[0,1,0] op_sel_hi:[1,1,1]
	v_pk_fma_f32 v[62:63], v[82:83], v[10:11], v[62:63] op_sel_hi:[1,0,1]
	v_pk_fma_f32 v[62:63], v[84:85], v[10:11], v[62:63] op_sel:[0,1,0] op_sel_hi:[1,1,1]
	v_pk_fma_f32 v[62:63], v[86:87], v[18:19], v[62:63] op_sel_hi:[1,0,1]
	v_pk_fma_f32 v[62:63], v[88:89], v[18:19], v[62:63] op_sel:[0,1,0] op_sel_hi:[1,1,1]
	v_pk_fma_f32 v[62:63], v[94:95], v[54:55], v[62:63] op_sel_hi:[1,0,1]
	v_pk_fma_f32 v[62:63], v[96:97], v[54:55], v[62:63] op_sel:[0,1,0] op_sel_hi:[1,1,1]
	v_pk_fma_f32 v[62:63], v[90:91], v[50:51], v[62:63] op_sel_hi:[1,0,1]
	v_pk_fma_f32 v[62:63], v[92:93], v[50:51], v[62:63] op_sel:[0,1,0] op_sel_hi:[1,1,1]
	s_nop 1
	v_add_f32_dpp v62, v62, v62 quad_perm:[1,0,3,2] row_mask:0xf bank_mask:0xf bound_ctrl:1
	v_add_f32_dpp v63, v63, v63 quad_perm:[1,0,3,2] row_mask:0xf bank_mask:0xf bound_ctrl:1
	s_nop 0
	v_add_f32_dpp v62, v62, v62 quad_perm:[2,3,0,1] row_mask:0xf bank_mask:0xf bound_ctrl:1
	v_add_f32_dpp v63, v63, v63 quad_perm:[2,3,0,1] row_mask:0xf bank_mask:0xf bound_ctrl:1
	v_fma_f32 v63, -v95, v62, v63
	v_pk_fma_f32 v[54:55], v[62:63], v[68:69], v[54:55] op_sel_hi:[1,0,1]
	ds_read_b128 v[78:81], v14 offset:14272
	ds_read_b128 v[82:85], v14 offset:14336
	ds_read_b128 v[86:89], v14 offset:14400
	ds_read_b128 v[90:93], v14 offset:14464
	ds_read_b128 v[94:97], v14 offset:14528
	s_waitcnt lgkmcnt(5)
	v_pk_fma_f32 v[62:63], v[130:131], v[8:9], 0 op_sel_hi:[1,0,0]
	v_pk_fma_f32 v[62:63], v[132:133], v[8:9], v[62:63] op_sel:[0,1,0] op_sel_hi:[1,1,1]
	v_pk_fma_f32 v[62:63], v[38:39], v[10:11], v[62:63] op_sel_hi:[1,0,1]
	v_pk_fma_f32 v[62:63], v[40:41], v[10:11], v[62:63] op_sel:[0,1,0] op_sel_hi:[1,1,1]
	v_pk_fma_f32 v[62:63], v[42:43], v[18:19], v[62:63] op_sel_hi:[1,0,1]
	v_pk_fma_f32 v[62:63], v[44:45], v[18:19], v[62:63] op_sel:[0,1,0] op_sel_hi:[1,1,1]
	v_pk_fma_f32 v[62:63], v[46:47], v[50:51], v[62:63] op_sel_hi:[1,0,1]
	v_pk_fma_f32 v[62:63], v[48:49], v[50:51], v[62:63] op_sel:[0,1,0] op_sel_hi:[1,1,1]
	v_pk_fma_f32 v[62:63], v[102:103], v[54:55], v[62:63] op_sel_hi:[1,0,1]
	v_pk_fma_f32 v[62:63], v[104:105], v[54:55], v[62:63] op_sel:[0,1,0] op_sel_hi:[1,1,1]
	s_nop 1
	v_add_f32_dpp v62, v62, v62 quad_perm:[1,0,3,2] row_mask:0xf bank_mask:0xf bound_ctrl:1
	v_add_f32_dpp v63, v63, v63 quad_perm:[1,0,3,2] row_mask:0xf bank_mask:0xf bound_ctrl:1
	s_nop 0
	v_add_f32_dpp v62, v62, v62 quad_perm:[2,3,0,1] row_mask:0xf bank_mask:0xf bound_ctrl:1
	v_add_f32_dpp v63, v63, v63 quad_perm:[2,3,0,1] row_mask:0xf bank_mask:0xf bound_ctrl:1
	v_fma_f32 v63, -v103, v62, v63
	v_pk_fma_f32 v[54:55], v[62:63], v[112:113], v[54:55] op_sel_hi:[1,0,1]
	ds_read_b128 v[130:133], v14 offset:14816
	ds_read_b128 v[38:41], v14 offset:14880
	ds_read_b128 v[42:45], v14 offset:14944
	ds_read_b128 v[46:49], v14 offset:15008
	ds_read_b128 v[102:105], v14 offset:15072
	s_waitcnt lgkmcnt(5)
	v_pk_fma_f32 v[62:63], v[78:79], v[8:9], 0 op_sel_hi:[1,0,0]
	v_pk_fma_f32 v[62:63], v[80:81], v[8:9], v[62:63] op_sel:[0,1,0] op_sel_hi:[1,1,1]
	v_pk_fma_f32 v[62:63], v[82:83], v[10:11], v[62:63] op_sel_hi:[1,0,1]
	v_pk_fma_f32 v[62:63], v[84:85], v[10:11], v[62:63] op_sel:[0,1,0] op_sel_hi:[1,1,1]
	v_pk_fma_f32 v[62:63], v[86:87], v[18:19], v[62:63] op_sel_hi:[1,0,1]
	v_pk_fma_f32 v[62:63], v[88:89], v[18:19], v[62:63] op_sel:[0,1,0] op_sel_hi:[1,1,1]
	v_pk_fma_f32 v[62:63], v[90:91], v[50:51], v[62:63] op_sel_hi:[1,0,1]
	v_pk_fma_f32 v[62:63], v[92:93], v[50:51], v[62:63] op_sel:[0,1,0] op_sel_hi:[1,1,1]
	v_pk_fma_f32 v[62:63], v[94:95], v[54:55], v[62:63] op_sel_hi:[1,0,1]
	v_pk_fma_f32 v[62:63], v[96:97], v[54:55], v[62:63] op_sel:[0,1,0] op_sel_hi:[1,1,1]
	s_nop 1
	v_add_f32_dpp v62, v62, v62 quad_perm:[1,0,3,2] row_mask:0xf bank_mask:0xf bound_ctrl:1
	v_add_f32_dpp v63, v63, v63 quad_perm:[1,0,3,2] row_mask:0xf bank_mask:0xf bound_ctrl:1
	s_nop 0
	v_add_f32_dpp v62, v62, v62 quad_perm:[2,3,0,1] row_mask:0xf bank_mask:0xf bound_ctrl:1
	v_add_f32_dpp v63, v63, v63 quad_perm:[2,3,0,1] row_mask:0xf bank_mask:0xf bound_ctrl:1
	v_fma_f32 v63, -v95, v62, v63
	v_pk_fma_f32 v[54:55], v[62:63], v[116:117], v[54:55] op_sel_hi:[1,0,1]
	ds_read_b128 v[78:81], v14 offset:15360
	ds_read_b128 v[82:85], v14 offset:15424
	ds_read_b128 v[86:89], v14 offset:15488
	ds_read_b128 v[90:93], v14 offset:15552
	ds_read_b128 v[94:97], v14 offset:15616
	ds_read_b128 v[98:101], v14 offset:15680
	s_waitcnt lgkmcnt(6)
; #define LAS __attribute__((address_space(3)))
;     ...
;     if (w < 2) {
;         const int d = w; const LAS float* Ad = As + d * 4352;
;         float tr[64]; int lane_o = lane;
; #pragma unroll
;         for (int ip = 0; ip < 32; ++ip) {
;             const int i0 = 2 * ip;
;             f32x4 rv[32];
; #pragma unroll
;             for (int jp = 0; jp <= ip; ++jp) rv[jp] = *(const LAS f32x4*)(Ad + ip * 136 + 4 * jp);
;             asm volatile("" : "+v"(lane_o) :: "memory");
;             f32x2_ a0 = {0.f, 0.f}, a1 = {0.f, 0.f}, a2 = {0.f, 0.f}, a3 = {0.f, 0.f};
; #pragma unroll
;             for (int jp = 0; jp < ip; ++jp) {
;                 const f32x2_ ta = {tr[2 * jp], tr[2 * jp]}, tb = {tr[2 * jp + 1], tr[2 * jp + 1]};
;                 const f32x2_ va = {rv[jp][0], rv[jp][1]}, vb = {rv[jp][2], rv[jp][3]};
;                 if (jp & 1) { a2 += va * ta; a3 += vb * tb; } else { a0 += va * ta; a1 += vb * tb; }
;             }
;             const f32x2_ sum = (a0 + a1) + (a2 + a3);
;             const float t0 = (lane_o == i0 ? 1.f : 0.f) - sum[0];
;             tr[i0] = t0;
;             tr[i0 + 1] = (lane_o == i0 + 1 ? 1.f : 0.f) - sum[1] - rv[ip][1] * t0;
;         }
	v_pk_fma_f32 v[62:63], v[130:131], v[8:9], 0 op_sel_hi:[1,0,0]
	v_pk_fma_f32 v[62:63], v[132:133], v[8:9], v[62:63] op_sel:[0,1,0] op_sel_hi:[1,1,1]
	v_pk_fma_f32 v[62:63], v[38:39], v[10:11], v[62:63] op_sel_hi:[1,0,1]
	v_pk_fma_f32 v[62:63], v[40:41], v[10:11], v[62:63] op_sel:[0,1,0] op_sel_hi:[1,1,1]
	v_pk_fma_f32 v[62:63], v[42:43], v[18:19], v[62:63] op_sel_hi:[1,0,1]
	v_pk_fma_f32 v[62:63], v[44:45], v[18:19], v[62:63] op_sel:[0,1,0] op_sel_hi:[1,1,1]
	v_pk_fma_f32 v[62:63], v[46:47], v[50:51], v[62:63] op_sel_hi:[1,0,1]
	v_pk_fma_f32 v[62:63], v[48:49], v[50:51], v[62:63] op_sel:[0,1,0] op_sel_hi:[1,1,1]
	v_pk_fma_f32 v[62:63], v[102:103], v[54:55], v[62:63] op_sel_hi:[1,0,1]
	v_pk_fma_f32 v[62:63], v[104:105], v[54:55], v[62:63] op_sel:[0,1,0] op_sel_hi:[1,1,1]
	s_nop 1
	v_add_f32_dpp v62, v62, v62 quad_perm:[1,0,3,2] row_mask:0xf bank_mask:0xf bound_ctrl:1
	v_add_f32_dpp v63, v63, v63 quad_perm:[1,0,3,2] row_mask:0xf bank_mask:0xf bound_ctrl:1
	s_nop 0
	v_add_f32_dpp v62, v62, v62 quad_perm:[2,3,0,1] row_mask:0xf bank_mask:0xf bound_ctrl:1
	v_add_f32_dpp v63, v63, v63 quad_perm:[2,3,0,1] row_mask:0xf bank_mask:0xf bound_ctrl:1
	v_fma_f32 v63, -v103, v62, v63
	v_pk_fma_f32 v[54:55], v[62:63], v[120:121], v[54:55] op_sel_hi:[1,0,1]
	ds_read_b128 v[130:133], v14 offset:15904
	ds_read_b128 v[38:41], v14 offset:15968
	ds_read_b128 v[42:45], v14 offset:16032
	ds_read_b128 v[46:49], v14 offset:16096
	ds_read_b128 v[102:105], v14 offset:16160
	ds_read_b128 v[242:245], v14 offset:16224
	s_waitcnt lgkmcnt(6)
	v_pk_fma_f32 v[62:63], v[78:79], v[8:9], 0 op_sel_hi:[1,0,0]
	v_pk_fma_f32 v[62:63], v[80:81], v[8:9], v[62:63] op_sel:[0,1,0] op_sel_hi:[1,1,1]
	v_pk_fma_f32 v[62:63], v[82:83], v[10:11], v[62:63] op_sel_hi:[1,0,1]
	v_pk_fma_f32 v[62:63], v[84:85], v[10:11], v[62:63] op_sel:[0,1,0] op_sel_hi:[1,1,1]
	v_pk_fma_f32 v[62:63], v[86:87], v[18:19], v[62:63] op_sel_hi:[1,0,1]
	v_pk_fma_f32 v[62:63], v[88:89], v[18:19], v[62:63] op_sel:[0,1,0] op_sel_hi:[1,1,1]
	v_pk_fma_f32 v[62:63], v[90:91], v[50:51], v[62:63] op_sel_hi:[1,0,1]
	v_pk_fma_f32 v[62:63], v[92:93], v[50:51], v[62:63] op_sel:[0,1,0] op_sel_hi:[1,1,1]
	v_pk_fma_f32 v[62:63], v[98:99], v[58:59], v[62:63] op_sel_hi:[1,0,1]
	v_pk_fma_f32 v[62:63], v[100:101], v[58:59], v[62:63] op_sel:[0,1,0] op_sel_hi:[1,1,1]
	v_pk_fma_f32 v[62:63], v[94:95], v[54:55], v[62:63] op_sel_hi:[1,0,1]
	v_pk_fma_f32 v[62:63], v[96:97], v[54:55], v[62:63] op_sel:[0,1,0] op_sel_hi:[1,1,1]
	s_nop 1
	v_add_f32_dpp v62, v62, v62 quad_perm:[1,0,3,2] row_mask:0xf bank_mask:0xf bound_ctrl:1
	v_add_f32_dpp v63, v63, v63 quad_perm:[1,0,3,2] row_mask:0xf bank_mask:0xf bound_ctrl:1
	s_nop 0
	v_add_f32_dpp v62, v62, v62 quad_perm:[2,3,0,1] row_mask:0xf bank_mask:0xf bound_ctrl:1
	v_add_f32_dpp v63, v63, v63 quad_perm:[2,3,0,1] row_mask:0xf bank_mask:0xf bound_ctrl:1
	v_fma_f32 v63, -v99, v62, v63
	v_pk_fma_f32 v[58:59], v[62:63], v[68:69], v[58:59] op_sel_hi:[1,0,1]
	ds_read_b128 v[78:81], v14 offset:16448
	ds_read_b128 v[82:85], v14 offset:16512
	ds_read_b128 v[86:89], v14 offset:16576
	ds_read_b128 v[90:93], v14 offset:16640
	ds_read_b128 v[94:97], v14 offset:16704
	ds_read_b128 v[98:101], v14 offset:16768
	s_waitcnt lgkmcnt(6)
	v_pk_fma_f32 v[62:63], v[130:131], v[8:9], 0 op_sel_hi:[1,0,0]
	v_pk_fma_f32 v[62:63], v[132:133], v[8:9], v[62:63] op_sel:[0,1,0] op_sel_hi:[1,1,1]
	v_pk_fma_f32 v[62:63], v[38:39], v[10:11], v[62:63] op_sel_hi:[1,0,1]
	v_pk_fma_f32 v[62:63], v[40:41], v[10:11], v[62:63] op_sel:[0,1,0] op_sel_hi:[1,1,1]
	v_pk_fma_f32 v[62:63], v[42:43], v[18:19], v[62:63] op_sel_hi:[1,0,1]
	v_pk_fma_f32 v[62:63], v[44:45], v[18:19], v[62:63] op_sel:[0,1,0] op_sel_hi:[1,1,1]
	v_pk_fma_f32 v[62:63], v[46:47], v[50:51], v[62:63] op_sel_hi:[1,0,1]
	v_pk_fma_f32 v[62:63], v[48:49], v[50:51], v[62:63] op_sel:[0,1,0] op_sel_hi:[1,1,1]
	v_pk_fma_f32 v[62:63], v[102:103], v[54:55], v[62:63] op_sel_hi:[1,0,1]
	v_pk_fma_f32 v[62:63], v[104:105], v[54:55], v[62:63] op_sel:[0,1,0] op_sel_hi:[1,1,1]
	v_pk_fma_f32 v[62:63], v[242:243], v[58:59], v[62:63] op_sel_hi:[1,0,1]
	v_pk_fma_f32 v[62:63], v[244:245], v[58:59], v[62:63] op_sel:[0,1,0] op_sel_hi:[1,1,1]
	s_nop 1
	v_add_f32_dpp v62, v62, v62 quad_perm:[1,0,3,2] row_mask:0xf bank_mask:0xf bound_ctrl:1
	v_add_f32_dpp v63, v63, v63 quad_perm:[1,0,3,2] row_mask:0xf bank_mask:0xf bound_ctrl:1
	s_nop 0
	v_add_f32_dpp v62, v62, v62 quad_perm:[2,3,0,1] row_mask:0xf bank_mask:0xf bound_ctrl:1
	v_add_f32_dpp v63, v63, v63 quad_perm:[2,3,0,1] row_mask:0xf bank_mask:0xf bound_ctrl:1
	v_fma_f32 v63, -v243, v62, v63
	v_pk_fma_f32 v[58:59], v[62:63], v[112:113], v[58:59] op_sel_hi:[1,0,1]
	ds_read_b128 v[130:133], v14 offset:16992
	ds_read_b128 v[38:41], v14 offset:17056
	ds_read_b128 v[42:45], v14 offset:17120
	ds_read_b128 v[46:49], v14 offset:17184
	ds_read_b128 v[102:105], v14 offset:17248
	ds_read_b128 v[242:245], v14 offset:17312
	s_waitcnt lgkmcnt(6)
	v_pk_fma_f32 v[62:63], v[78:79], v[8:9], 0 op_sel_hi:[1,0,0]
	v_pk_fma_f32 v[62:63], v[80:81], v[8:9], v[62:63] op_sel:[0,1,0] op_sel_hi:[1,1,1]
	v_pk_fma_f32 v[62:63], v[82:83], v[10:11], v[62:63] op_sel_hi:[1,0,1]
	v_pk_fma_f32 v[62:63], v[84:85], v[10:11], v[62:63] op_sel:[0,1,0] op_sel_hi:[1,1,1]
	v_pk_fma_f32 v[62:63], v[86:87], v[18:19], v[62:63] op_sel_hi:[1,0,1]
	v_pk_fma_f32 v[62:63], v[88:89], v[18:19], v[62:63] op_sel:[0,1,0] op_sel_hi:[1,1,1]
	v_pk_fma_f32 v[62:63], v[90:91], v[50:51], v[62:63] op_sel_hi:[1,0,1]
	v_pk_fma_f32 v[62:63], v[92:93], v[50:51], v[62:63] op_sel:[0,1,0] op_sel_hi:[1,1,1]
	v_pk_fma_f32 v[62:63], v[94:95], v[54:55], v[62:63] op_sel_hi:[1,0,1]
	v_pk_fma_f32 v[62:63], v[96:97], v[54:55], v[62:63] op_sel:[0,1,0] op_sel_hi:[1,1,1]
	v_pk_fma_f32 v[62:63], v[98:99], v[58:59], v[62:63] op_sel_hi:[1,0,1]
	v_pk_fma_f32 v[62:63], v[100:101], v[58:59], v[62:63] op_sel:[0,1,0] op_sel_hi:[1,1,1]
	s_nop 1
	v_add_f32_dpp v62, v62, v62 quad_perm:[1,0,3,2] row_mask:0xf bank_mask:0xf bound_ctrl:1
	v_add_f32_dpp v63, v63, v63 quad_perm:[1,0,3,2] row_mask:0xf bank_mask:0xf bound_ctrl:1
	s_nop 0
	v_add_f32_dpp v62, v62, v62 quad_perm:[2,3,0,1] row_mask:0xf bank_mask:0xf bound_ctrl:1
	v_add_f32_dpp v63, v63, v63 quad_perm:[2,3,0,1] row_mask:0xf bank_mask:0xf bound_ctrl:1
	v_fma_f32 v63, -v99, v62, v63
	v_pk_fma_f32 v[58:59], v[62:63], v[116:117], v[58:59] op_sel_hi:[1,0,1]
	s_waitcnt lgkmcnt(0)
; #define LAS __attribute__((address_space(3)))
;     ...
;     if (w < 2) {
;         const int d = w; const LAS float* Ad = As + d * 4352;
;         float tr[64]; int lane_o = lane;
; #pragma unroll
;         for (int ip = 0; ip < 32; ++ip) {
;             const int i0 = 2 * ip;
;             f32x4 rv[32];
; #pragma unroll
;             for (int jp = 0; jp <= ip; ++jp) rv[jp] = *(const LAS f32x4*)(Ad + ip * 136 + 4 * jp);
;             asm volatile("" : "+v"(lane_o) :: "memory");
;             f32x2_ a0 = {0.f, 0.f}, a1 = {0.f, 0.f}, a2 = {0.f, 0.f}, a3 = {0.f, 0.f};
; #pragma unroll
;             for (int jp = 0; jp < ip; ++jp) {
;                 const f32x2_ ta = {tr[2 * jp], tr[2 * jp]}, tb = {tr[2 * jp + 1], tr[2 * jp + 1]};
;                 const f32x2_ va = {rv[jp][0], rv[jp][1]}, vb = {rv[jp][2], rv[jp][3]};
;                 if (jp & 1) { a2 += va * ta; a3 += vb * tb; } else { a0 += va * ta; a1 += vb * tb; }
;             }
;             const f32x2_ sum = (a0 + a1) + (a2 + a3);
;             const float t0 = (lane_o == i0 ? 1.f : 0.f) - sum[0];
;             tr[i0] = t0;
;             tr[i0 + 1] = (lane_o == i0 + 1 ? 1.f : 0.f) - sum[1] - rv[ip][1] * t0;
;         }
	v_pk_fma_f32 v[62:63], v[130:131], v[8:9], 0 op_sel_hi:[1,0,0]
	v_pk_fma_f32 v[62:63], v[132:133], v[8:9], v[62:63] op_sel:[0,1,0] op_sel_hi:[1,1,1]
	v_pk_fma_f32 v[62:63], v[38:39], v[10:11], v[62:63] op_sel_hi:[1,0,1]
	v_pk_fma_f32 v[62:63], v[40:41], v[10:11], v[62:63] op_sel:[0,1,0] op_sel_hi:[1,1,1]
	v_pk_fma_f32 v[62:63], v[42:43], v[18:19], v[62:63] op_sel_hi:[1,0,1]
	v_pk_fma_f32 v[62:63], v[44:45], v[18:19], v[62:63] op_sel:[0,1,0] op_sel_hi:[1,1,1]
	v_pk_fma_f32 v[62:63], v[46:47], v[50:51], v[62:63] op_sel_hi:[1,0,1]
	v_pk_fma_f32 v[62:63], v[48:49], v[50:51], v[62:63] op_sel:[0,1,0] op_sel_hi:[1,1,1]
	v_pk_fma_f32 v[62:63], v[102:103], v[54:55], v[62:63] op_sel_hi:[1,0,1]
	v_pk_fma_f32 v[62:63], v[104:105], v[54:55], v[62:63] op_sel:[0,1,0] op_sel_hi:[1,1,1]
	v_pk_fma_f32 v[62:63], v[242:243], v[58:59], v[62:63] op_sel_hi:[1,0,1]
	v_pk_fma_f32 v[62:63], v[244:245], v[58:59], v[62:63] op_sel:[0,1,0] op_sel_hi:[1,1,1]
	s_nop 1
	v_add_f32_dpp v62, v62, v62 quad_perm:[1,0,3,2] row_mask:0xf bank_mask:0xf bound_ctrl:1
	v_add_f32_dpp v63, v63, v63 quad_perm:[1,0,3,2] row_mask:0xf bank_mask:0xf bound_ctrl:1
	s_nop 0
	v_add_f32_dpp v62, v62, v62 quad_perm:[2,3,0,1] row_mask:0xf bank_mask:0xf bound_ctrl:1
	v_add_f32_dpp v63, v63, v63 quad_perm:[2,3,0,1] row_mask:0xf bank_mask:0xf bound_ctrl:1
	v_fma_f32 v63, -v243, v62, v63
	v_pk_fma_f32 v[58:59], v[62:63], v[120:121], v[58:59] op_sel_hi:[1,0,1]
	s_branch .Lfs_outsel
.Lfs_ent2:
	ds_read_b128 v[86:89], v14 offset:8960
	ds_read_b128 v[42:45], v14 offset:9504
	s_waitcnt lgkmcnt(1)
	v_pk_fma_f32 v[62:63], v[86:87], v[18:19], 0 op_sel_hi:[1,0,0]
	v_pk_fma_f32 v[62:63], v[88:89], v[18:19], v[62:63] op_sel:[0,1,0] op_sel_hi:[1,1,1]
	s_nop 1
	v_add_f32_dpp v62, v62, v62 quad_perm:[1,0,3,2] row_mask:0xf bank_mask:0xf bound_ctrl:1
	v_add_f32_dpp v63, v63, v63 quad_perm:[1,0,3,2] row_mask:0xf bank_mask:0xf bound_ctrl:1
	s_nop 0
	v_add_f32_dpp v62, v62, v62 quad_perm:[2,3,0,1] row_mask:0xf bank_mask:0xf bound_ctrl:1
	v_add_f32_dpp v63, v63, v63 quad_perm:[2,3,0,1] row_mask:0xf bank_mask:0xf bound_ctrl:1
	v_fma_f32 v63, -v87, v62, v63
	v_pk_fma_f32 v[18:19], v[62:63], v[68:69], v[18:19] op_sel_hi:[1,0,1]
	ds_read_b128 v[86:89], v14 offset:10048
	s_waitcnt lgkmcnt(1)
	v_pk_fma_f32 v[62:63], v[42:43], v[18:19], 0 op_sel_hi:[1,0,0]
	v_pk_fma_f32 v[62:63], v[44:45], v[18:19], v[62:63] op_sel:[0,1,0] op_sel_hi:[1,1,1]
	s_nop 1
	v_add_f32_dpp v62, v62, v62 quad_perm:[1,0,3,2] row_mask:0xf bank_mask:0xf bound_ctrl:1
	v_add_f32_dpp v63, v63, v63 quad_perm:[1,0,3,2] row_mask:0xf bank_mask:0xf bound_ctrl:1
	s_nop 0
	v_add_f32_dpp v62, v62, v62 quad_perm:[2,3,0,1] row_mask:0xf bank_mask:0xf bound_ctrl:1
	v_add_f32_dpp v63, v63, v63 quad_perm:[2,3,0,1] row_mask:0xf bank_mask:0xf bound_ctrl:1
	v_fma_f32 v63, -v43, v62, v63
	v_pk_fma_f32 v[18:19], v[62:63], v[112:113], v[18:19] op_sel_hi:[1,0,1]
	ds_read_b128 v[42:45], v14 offset:10592
	s_waitcnt lgkmcnt(1)
	v_pk_fma_f32 v[62:63], v[86:87], v[18:19], 0 op_sel_hi:[1,0,0]
	v_pk_fma_f32 v[62:63], v[88:89], v[18:19], v[62:63] op_sel:[0,1,0] op_sel_hi:[1,1,1]
	s_nop 1
	v_add_f32_dpp v62, v62, v62 quad_perm:[1,0,3,2] row_mask:0xf bank_mask:0xf bound_ctrl:1
	v_add_f32_dpp v63, v63, v63 quad_perm:[1,0,3,2] row_mask:0xf bank_mask:0xf bound_ctrl:1
	s_nop 0
	v_add_f32_dpp v62, v62, v62 quad_perm:[2,3,0,1] row_mask:0xf bank_mask:0xf bound_ctrl:1
	v_add_f32_dpp v63, v63, v63 quad_perm:[2,3,0,1] row_mask:0xf bank_mask:0xf bound_ctrl:1
	v_fma_f32 v63, -v87, v62, v63
	v_pk_fma_f32 v[18:19], v[62:63], v[116:117], v[18:19] op_sel_hi:[1,0,1]
	ds_read_b128 v[86:89], v14 offset:11136
	ds_read_b128 v[90:93], v14 offset:11200
	s_waitcnt lgkmcnt(2)
	v_pk_fma_f32 v[62:63], v[42:43], v[18:19], 0 op_sel_hi:[1,0,0]
	v_pk_fma_f32 v[62:63], v[44:45], v[18:19], v[62:63] op_sel:[0,1,0] op_sel_hi:[1,1,1]
	s_nop 1
	v_add_f32_dpp v62, v62, v62 quad_perm:[1,0,3,2] row_mask:0xf bank_mask:0xf bound_ctrl:1
	v_add_f32_dpp v63, v63, v63 quad_perm:[1,0,3,2] row_mask:0xf bank_mask:0xf bound_ctrl:1
	s_nop 0
	v_add_f32_dpp v62, v62, v62 quad_perm:[2,3,0,1] row_mask:0xf bank_mask:0xf bound_ctrl:1
	v_add_f32_dpp v63, v63, v63 quad_perm:[2,3,0,1] row_mask:0xf bank_mask:0xf bound_ctrl:1
	v_fma_f32 v63, -v43, v62, v63
	v_pk_fma_f32 v[18:19], v[62:63], v[120:121], v[18:19] op_sel_hi:[1,0,1]
	ds_read_b128 v[42:45], v14 offset:11680
	ds_read_b128 v[46:49], v14 offset:11744
	s_waitcnt lgkmcnt(2)
	v_pk_fma_f32 v[62:63], v[90:91], v[50:51], 0 op_sel_hi:[1,0,0]
	v_pk_fma_f32 v[62:63], v[92:93], v[50:51], v[62:63] op_sel:[0,1,0] op_sel_hi:[1,1,1]
	v_pk_fma_f32 v[62:63], v[86:87], v[18:19], v[62:63] op_sel_hi:[1,0,1]
	v_pk_fma_f32 v[62:63], v[88:89], v[18:19], v[62:63] op_sel:[0,1,0] op_sel_hi:[1,1,1]
	s_nop 1
	v_add_f32_dpp v62, v62, v62 quad_perm:[1,0,3,2] row_mask:0xf bank_mask:0xf bound_ctrl:1
	v_add_f32_dpp v63, v63, v63 quad_perm:[1,0,3,2] row_mask:0xf bank_mask:0xf bound_ctrl:1
	s_nop 0
	v_add_f32_dpp v62, v62, v62 quad_perm:[2,3,0,1] row_mask:0xf bank_mask:0xf bound_ctrl:1
	v_add_f32_dpp v63, v63, v63 quad_perm:[2,3,0,1] row_mask:0xf bank_mask:0xf bound_ctrl:1
	v_fma_f32 v63, -v91, v62, v63
	v_pk_fma_f32 v[50:51], v[62:63], v[68:69], v[50:51] op_sel_hi:[1,0,1]
	ds_read_b128 v[86:89], v14 offset:12224
	ds_read_b128 v[90:93], v14 offset:12288
	s_waitcnt lgkmcnt(2)
; #define LAS __attribute__((address_space(3)))
;     ...
; #pragma unroll
;         for (int ip = 0; ip < 32; ++ip) {
;             const int i0 = 2 * ip;
;             f32x4 rv[32];
; #pragma unroll
;             for (int jp = 0; jp <= ip; ++jp) rv[jp] = *(const LAS f32x4*)(Ad + ip * 136 + 4 * jp);
;             asm volatile("" : "+v"(lane_o) :: "memory");
;             f32x2_ a0 = {0.f, 0.f}, a1 = {0.f, 0.f}, a2 = {0.f, 0.f}, a3 = {0.f, 0.f};
; #pragma unroll
;             for (int jp = 0; jp < ip; ++jp) {
;                 const f32x2_ ta = {tr[2 * jp], tr[2 * jp]}, tb = {tr[2 * jp + 1], tr[2 * jp + 1]};
;                 const f32x2_ va = {rv[jp][0], rv[jp][1]}, vb = {rv[jp][2], rv[jp][3]};
;                 if (jp & 1) { a2 += va * ta; a3 += vb * tb; } else { a0 += va * ta; a1 += vb * tb; }
;             }
;             const f32x2_ sum = (a0 + a1) + (a2 + a3);
;             const float t0 = (lane_o == i0 ? 1.f : 0.f) - sum[0];
;             tr[i0] = t0;
;             tr[i0 + 1] = (lane_o == i0 + 1 ? 1.f : 0.f) - sum[1] - rv[ip][1] * t0;
;         }
	v_pk_fma_f32 v[62:63], v[42:43], v[18:19], 0 op_sel_hi:[1,0,0]
	v_pk_fma_f32 v[62:63], v[44:45], v[18:19], v[62:63] op_sel:[0,1,0] op_sel_hi:[1,1,1]
	v_pk_fma_f32 v[62:63], v[46:47], v[50:51], v[62:63] op_sel_hi:[1,0,1]
	v_pk_fma_f32 v[62:63], v[48:49], v[50:51], v[62:63] op_sel:[0,1,0] op_sel_hi:[1,1,1]
	s_nop 1
	v_add_f32_dpp v62, v62, v62 quad_perm:[1,0,3,2] row_mask:0xf bank_mask:0xf bound_ctrl:1
	v_add_f32_dpp v63, v63, v63 quad_perm:[1,0,3,2] row_mask:0xf bank_mask:0xf bound_ctrl:1
	s_nop 0
	v_add_f32_dpp v62, v62, v62 quad_perm:[2,3,0,1] row_mask:0xf bank_mask:0xf bound_ctrl:1
	v_add_f32_dpp v63, v63, v63 quad_perm:[2,3,0,1] row_mask:0xf bank_mask:0xf bound_ctrl:1
	v_fma_f32 v63, -v47, v62, v63
	v_pk_fma_f32 v[50:51], v[62:63], v[112:113], v[50:51] op_sel_hi:[1,0,1]
	ds_read_b128 v[42:45], v14 offset:12768
	ds_read_b128 v[46:49], v14 offset:12832
	s_waitcnt lgkmcnt(2)
	v_pk_fma_f32 v[62:63], v[86:87], v[18:19], 0 op_sel_hi:[1,0,0]
	v_pk_fma_f32 v[62:63], v[88:89], v[18:19], v[62:63] op_sel:[0,1,0] op_sel_hi:[1,1,1]
	v_pk_fma_f32 v[62:63], v[90:91], v[50:51], v[62:63] op_sel_hi:[1,0,1]
	v_pk_fma_f32 v[62:63], v[92:93], v[50:51], v[62:63] op_sel:[0,1,0] op_sel_hi:[1,1,1]
	s_nop 1
	v_add_f32_dpp v62, v62, v62 quad_perm:[1,0,3,2] row_mask:0xf bank_mask:0xf bound_ctrl:1
	v_add_f32_dpp v63, v63, v63 quad_perm:[1,0,3,2] row_mask:0xf bank_mask:0xf bound_ctrl:1
	s_nop 0
	v_add_f32_dpp v62, v62, v62 quad_perm:[2,3,0,1] row_mask:0xf bank_mask:0xf bound_ctrl:1
	v_add_f32_dpp v63, v63, v63 quad_perm:[2,3,0,1] row_mask:0xf bank_mask:0xf bound_ctrl:1
	v_fma_f32 v63, -v91, v62, v63
	v_pk_fma_f32 v[50:51], v[62:63], v[116:117], v[50:51] op_sel_hi:[1,0,1]
	ds_read_b128 v[86:89], v14 offset:13312
	ds_read_b128 v[90:93], v14 offset:13376
	ds_read_b128 v[94:97], v14 offset:13440
	s_waitcnt lgkmcnt(3)
	v_pk_fma_f32 v[62:63], v[42:43], v[18:19], 0 op_sel_hi:[1,0,0]
	v_pk_fma_f32 v[62:63], v[44:45], v[18:19], v[62:63] op_sel:[0,1,0] op_sel_hi:[1,1,1]
	v_pk_fma_f32 v[62:63], v[46:47], v[50:51], v[62:63] op_sel_hi:[1,0,1]
	v_pk_fma_f32 v[62:63], v[48:49], v[50:51], v[62:63] op_sel:[0,1,0] op_sel_hi:[1,1,1]
	s_nop 1
	v_add_f32_dpp v62, v62, v62 quad_perm:[1,0,3,2] row_mask:0xf bank_mask:0xf bound_ctrl:1
	v_add_f32_dpp v63, v63, v63 quad_perm:[1,0,3,2] row_mask:0xf bank_mask:0xf bound_ctrl:1
	s_nop 0
	v_add_f32_dpp v62, v62, v62 quad_perm:[2,3,0,1] row_mask:0xf bank_mask:0xf bound_ctrl:1
	v_add_f32_dpp v63, v63, v63 quad_perm:[2,3,0,1] row_mask:0xf bank_mask:0xf bound_ctrl:1
	v_fma_f32 v63, -v47, v62, v63
	v_pk_fma_f32 v[50:51], v[62:63], v[120:121], v[50:51] op_sel_hi:[1,0,1]
	ds_read_b128 v[42:45], v14 offset:13856
	ds_read_b128 v[46:49], v14 offset:13920
	ds_read_b128 v[102:105], v14 offset:13984
	s_waitcnt lgkmcnt(3)
	v_pk_fma_f32 v[62:63], v[86:87], v[18:19], 0 op_sel_hi:[1,0,0]
	v_pk_fma_f32 v[62:63], v[88:89], v[18:19], v[62:63] op_sel:[0,1,0] op_sel_hi:[1,1,1]
	v_pk_fma_f32 v[62:63], v[94:95], v[54:55], v[62:63] op_sel_hi:[1,0,1]
	v_pk_fma_f32 v[62:63], v[96:97], v[54:55], v[62:63] op_sel:[0,1,0] op_sel_hi:[1,1,1]
	v_pk_fma_f32 v[62:63], v[90:91], v[50:51], v[62:63] op_sel_hi:[1,0,1]
	v_pk_fma_f32 v[62:63], v[92:93], v[50:51], v[62:63] op_sel:[0,1,0] op_sel_hi:[1,1,1]
	s_nop 1
	v_add_f32_dpp v62, v62, v62 quad_perm:[1,0,3,2] row_mask:0xf bank_mask:0xf bound_ctrl:1
	v_add_f32_dpp v63, v63, v63 quad_perm:[1,0,3,2] row_mask:0xf bank_mask:0xf bound_ctrl:1
	s_nop 0
	v_add_f32_dpp v62, v62, v62 quad_perm:[2,3,0,1] row_mask:0xf bank_mask:0xf bound_ctrl:1
	v_add_f32_dpp v63, v63, v63 quad_perm:[2,3,0,1] row_mask:0xf bank_mask:0xf bound_ctrl:1
	v_fma_f32 v63, -v95, v62, v63
	v_pk_fma_f32 v[54:55], v[62:63], v[68:69], v[54:55] op_sel_hi:[1,0,1]
	ds_read_b128 v[86:89], v14 offset:14400
	ds_read_b128 v[90:93], v14 offset:14464
	ds_read_b128 v[94:97], v14 offset:14528
	s_waitcnt lgkmcnt(3)
	v_pk_fma_f32 v[62:63], v[42:43], v[18:19], 0 op_sel_hi:[1,0,0]
	v_pk_fma_f32 v[62:63], v[44:45], v[18:19], v[62:63] op_sel:[0,1,0] op_sel_hi:[1,1,1]
	v_pk_fma_f32 v[62:63], v[46:47], v[50:51], v[62:63] op_sel_hi:[1,0,1]
	v_pk_fma_f32 v[62:63], v[48:49], v[50:51], v[62:63] op_sel:[0,1,0] op_sel_hi:[1,1,1]
	v_pk_fma_f32 v[62:63], v[102:103], v[54:55], v[62:63] op_sel_hi:[1,0,1]
	v_pk_fma_f32 v[62:63], v[104:105], v[54:55], v[62:63] op_sel:[0,1,0] op_sel_hi:[1,1,1]
	s_nop 1
	v_add_f32_dpp v62, v62, v62 quad_perm:[1,0,3,2] row_mask:0xf bank_mask:0xf bound_ctrl:1
	v_add_f32_dpp v63, v63, v63 quad_perm:[1,0,3,2] row_mask:0xf bank_mask:0xf bound_ctrl:1
	s_nop 0
	v_add_f32_dpp v62, v62, v62 quad_perm:[2,3,0,1] row_mask:0xf bank_mask:0xf bound_ctrl:1
	v_add_f32_dpp v63, v63, v63 quad_perm:[2,3,0,1] row_mask:0xf bank_mask:0xf bound_ctrl:1
	v_fma_f32 v63, -v103, v62, v63
	v_pk_fma_f32 v[54:55], v[62:63], v[112:113], v[54:55] op_sel_hi:[1,0,1]
	ds_read_b128 v[42:45], v14 offset:14944
	ds_read_b128 v[46:49], v14 offset:15008
	ds_read_b128 v[102:105], v14 offset:15072
	s_waitcnt lgkmcnt(3)
	v_pk_fma_f32 v[62:63], v[86:87], v[18:19], 0 op_sel_hi:[1,0,0]
	v_pk_fma_f32 v[62:63], v[88:89], v[18:19], v[62:63] op_sel:[0,1,0] op_sel_hi:[1,1,1]
	v_pk_fma_f32 v[62:63], v[90:91], v[50:51], v[62:63] op_sel_hi:[1,0,1]
	v_pk_fma_f32 v[62:63], v[92:93], v[50:51], v[62:63] op_sel:[0,1,0] op_sel_hi:[1,1,1]
	v_pk_fma_f32 v[62:63], v[94:95], v[54:55], v[62:63] op_sel_hi:[1,0,1]
	v_pk_fma_f32 v[62:63], v[96:97], v[54:55], v[62:63] op_sel:[0,1,0] op_sel_hi:[1,1,1]
	s_nop 1
	v_add_f32_dpp v62, v62, v62 quad_perm:[1,0,3,2] row_mask:0xf bank_mask:0xf bound_ctrl:1
	v_add_f32_dpp v63, v63, v63 quad_perm:[1,0,3,2] row_mask:0xf bank_mask:0xf bound_ctrl:1
	s_nop 0
	v_add_f32_dpp v62, v62, v62 quad_perm:[2,3,0,1] row_mask:0xf bank_mask:0xf bound_ctrl:1
	v_add_f32_dpp v63, v63, v63 quad_perm:[2,3,0,1] row_mask:0xf bank_mask:0xf bound_ctrl:1
	v_fma_f32 v63, -v95, v62, v63
	v_pk_fma_f32 v[54:55], v[62:63], v[116:117], v[54:55] op_sel_hi:[1,0,1]
	ds_read_b128 v[86:89], v14 offset:15488
	ds_read_b128 v[90:93], v14 offset:15552
	ds_read_b128 v[94:97], v14 offset:15616
	ds_read_b128 v[98:101], v14 offset:15680
	s_waitcnt lgkmcnt(4)
; #define LAS __attribute__((address_space(3)))
;     ...
; #pragma unroll
;         for (int ip = 0; ip < 32; ++ip) {
;             const int i0 = 2 * ip;
;             f32x4 rv[32];
; #pragma unroll
;             for (int jp = 0; jp <= ip; ++jp) rv[jp] = *(const LAS f32x4*)(Ad + ip * 136 + 4 * jp);
;             asm volatile("" : "+v"(lane_o) :: "memory");
;             f32x2_ a0 = {0.f, 0.f}, a1 = {0.f, 0.f}, a2 = {0.f, 0.f}, a3 = {0.f, 0.f};
; #pragma unroll
;             for (int jp = 0; jp < ip; ++jp) {
;                 const f32x2_ ta = {tr[2 * jp], tr[2 * jp]}, tb = {tr[2 * jp + 1], tr[2 * jp + 1]};
;                 const f32x2_ va = {rv[jp][0], rv[jp][1]}, vb = {rv[jp][2], rv[jp][3]};
;                 if (jp & 1) { a2 += va * ta; a3 += vb * tb; } else { a0 += va * ta; a1 += vb * tb; }
;             }
;             const f32x2_ sum = (a0 + a1) + (a2 + a3);
;             const float t0 = (lane_o == i0 ? 1.f : 0.f) - sum[0];
;             tr[i0] = t0;
;             tr[i0 + 1] = (lane_o == i0 + 1 ? 1.f : 0.f) - sum[1] - rv[ip][1] * t0;
;         }
	v_pk_fma_f32 v[62:63], v[42:43], v[18:19], 0 op_sel_hi:[1,0,0]
	v_pk_fma_f32 v[62:63], v[44:45], v[18:19], v[62:63] op_sel:[0,1,0] op_sel_hi:[1,1,1]
	v_pk_fma_f32 v[62:63], v[46:47], v[50:51], v[62:63] op_sel_hi:[1,0,1]
	v_pk_fma_f32 v[62:63], v[48:49], v[50:51], v[62:63] op_sel:[0,1,0] op_sel_hi:[1,1,1]
	v_pk_fma_f32 v[62:63], v[102:103], v[54:55], v[62:63] op_sel_hi:[1,0,1]
	v_pk_fma_f32 v[62:63], v[104:105], v[54:55], v[62:63] op_sel:[0,1,0] op_sel_hi:[1,1,1]
	s_nop 1
	v_add_f32_dpp v62, v62, v62 quad_perm:[1,0,3,2] row_mask:0xf bank_mask:0xf bound_ctrl:1
	v_add_f32_dpp v63, v63, v63 quad_perm:[1,0,3,2] row_mask:0xf bank_mask:0xf bound_ctrl:1
	s_nop 0
	v_add_f32_dpp v62, v62, v62 quad_perm:[2,3,0,1] row_mask:0xf bank_mask:0xf bound_ctrl:1
	v_add_f32_dpp v63, v63, v63 quad_perm:[2,3,0,1] row_mask:0xf bank_mask:0xf bound_ctrl:1
	v_fma_f32 v63, -v103, v62, v63
	v_pk_fma_f32 v[54:55], v[62:63], v[120:121], v[54:55] op_sel_hi:[1,0,1]
	ds_read_b128 v[42:45], v14 offset:16032
	ds_read_b128 v[46:49], v14 offset:16096
	ds_read_b128 v[102:105], v14 offset:16160
	ds_read_b128 v[242:245], v14 offset:16224
	s_waitcnt lgkmcnt(4)
	v_pk_fma_f32 v[62:63], v[86:87], v[18:19], 0 op_sel_hi:[1,0,0]
	v_pk_fma_f32 v[62:63], v[88:89], v[18:19], v[62:63] op_sel:[0,1,0] op_sel_hi:[1,1,1]
	v_pk_fma_f32 v[62:63], v[90:91], v[50:51], v[62:63] op_sel_hi:[1,0,1]
	v_pk_fma_f32 v[62:63], v[92:93], v[50:51], v[62:63] op_sel:[0,1,0] op_sel_hi:[1,1,1]
	v_pk_fma_f32 v[62:63], v[98:99], v[58:59], v[62:63] op_sel_hi:[1,0,1]
	v_pk_fma_f32 v[62:63], v[100:101], v[58:59], v[62:63] op_sel:[0,1,0] op_sel_hi:[1,1,1]
	v_pk_fma_f32 v[62:63], v[94:95], v[54:55], v[62:63] op_sel_hi:[1,0,1]
	v_pk_fma_f32 v[62:63], v[96:97], v[54:55], v[62:63] op_sel:[0,1,0] op_sel_hi:[1,1,1]
	s_nop 1
	v_add_f32_dpp v62, v62, v62 quad_perm:[1,0,3,2] row_mask:0xf bank_mask:0xf bound_ctrl:1
	v_add_f32_dpp v63, v63, v63 quad_perm:[1,0,3,2] row_mask:0xf bank_mask:0xf bound_ctrl:1
	s_nop 0
	v_add_f32_dpp v62, v62, v62 quad_perm:[2,3,0,1] row_mask:0xf bank_mask:0xf bound_ctrl:1
	v_add_f32_dpp v63, v63, v63 quad_perm:[2,3,0,1] row_mask:0xf bank_mask:0xf bound_ctrl:1
	v_fma_f32 v63, -v99, v62, v63
	v_pk_fma_f32 v[58:59], v[62:63], v[68:69], v[58:59] op_sel_hi:[1,0,1]
	ds_read_b128 v[86:89], v14 offset:16576
	ds_read_b128 v[90:93], v14 offset:16640
	ds_read_b128 v[94:97], v14 offset:16704
	ds_read_b128 v[98:101], v14 offset:16768
	s_waitcnt lgkmcnt(4)
	v_pk_fma_f32 v[62:63], v[42:43], v[18:19], 0 op_sel_hi:[1,0,0]
	v_pk_fma_f32 v[62:63], v[44:45], v[18:19], v[62:63] op_sel:[0,1,0] op_sel_hi:[1,1,1]
	v_pk_fma_f32 v[62:63], v[46:47], v[50:51], v[62:63] op_sel_hi:[1,0,1]
	v_pk_fma_f32 v[62:63], v[48:49], v[50:51], v[62:63] op_sel:[0,1,0] op_sel_hi:[1,1,1]
	v_pk_fma_f32 v[62:63], v[102:103], v[54:55], v[62:63] op_sel_hi:[1,0,1]
	v_pk_fma_f32 v[62:63], v[104:105], v[54:55], v[62:63] op_sel:[0,1,0] op_sel_hi:[1,1,1]
	v_pk_fma_f32 v[62:63], v[242:243], v[58:59], v[62:63] op_sel_hi:[1,0,1]
	v_pk_fma_f32 v[62:63], v[244:245], v[58:59], v[62:63] op_sel:[0,1,0] op_sel_hi:[1,1,1]
	s_nop 1
	v_add_f32_dpp v62, v62, v62 quad_perm:[1,0,3,2] row_mask:0xf bank_mask:0xf bound_ctrl:1
	v_add_f32_dpp v63, v63, v63 quad_perm:[1,0,3,2] row_mask:0xf bank_mask:0xf bound_ctrl:1
	s_nop 0
	v_add_f32_dpp v62, v62, v62 quad_perm:[2,3,0,1] row_mask:0xf bank_mask:0xf bound_ctrl:1
	v_add_f32_dpp v63, v63, v63 quad_perm:[2,3,0,1] row_mask:0xf bank_mask:0xf bound_ctrl:1
	v_fma_f32 v63, -v243, v62, v63
	v_pk_fma_f32 v[58:59], v[62:63], v[112:113], v[58:59] op_sel_hi:[1,0,1]
	ds_read_b128 v[42:45], v14 offset:17120
	ds_read_b128 v[46:49], v14 offset:17184
	ds_read_b128 v[102:105], v14 offset:17248
	ds_read_b128 v[242:245], v14 offset:17312
	s_waitcnt lgkmcnt(4)
	v_pk_fma_f32 v[62:63], v[86:87], v[18:19], 0 op_sel_hi:[1,0,0]
	v_pk_fma_f32 v[62:63], v[88:89], v[18:19], v[62:63] op_sel:[0,1,0] op_sel_hi:[1,1,1]
	v_pk_fma_f32 v[62:63], v[90:91], v[50:51], v[62:63] op_sel_hi:[1,0,1]
	v_pk_fma_f32 v[62:63], v[92:93], v[50:51], v[62:63] op_sel:[0,1,0] op_sel_hi:[1,1,1]
	v_pk_fma_f32 v[62:63], v[94:95], v[54:55], v[62:63] op_sel_hi:[1,0,1]
	v_pk_fma_f32 v[62:63], v[96:97], v[54:55], v[62:63] op_sel:[0,1,0] op_sel_hi:[1,1,1]
	v_pk_fma_f32 v[62:63], v[98:99], v[58:59], v[62:63] op_sel_hi:[1,0,1]
	v_pk_fma_f32 v[62:63], v[100:101], v[58:59], v[62:63] op_sel:[0,1,0] op_sel_hi:[1,1,1]
	s_nop 1
	v_add_f32_dpp v62, v62, v62 quad_perm:[1,0,3,2] row_mask:0xf bank_mask:0xf bound_ctrl:1
	v_add_f32_dpp v63, v63, v63 quad_perm:[1,0,3,2] row_mask:0xf bank_mask:0xf bound_ctrl:1
	s_nop 0
	v_add_f32_dpp v62, v62, v62 quad_perm:[2,3,0,1] row_mask:0xf bank_mask:0xf bound_ctrl:1
	v_add_f32_dpp v63, v63, v63 quad_perm:[2,3,0,1] row_mask:0xf bank_mask:0xf bound_ctrl:1
	v_fma_f32 v63, -v99, v62, v63
	v_pk_fma_f32 v[58:59], v[62:63], v[116:117], v[58:59] op_sel_hi:[1,0,1]
	s_waitcnt lgkmcnt(0)
	v_pk_fma_f32 v[62:63], v[42:43], v[18:19], 0 op_sel_hi:[1,0,0]
	v_pk_fma_f32 v[62:63], v[44:45], v[18:19], v[62:63] op_sel:[0,1,0] op_sel_hi:[1,1,1]
	v_pk_fma_f32 v[62:63], v[46:47], v[50:51], v[62:63] op_sel_hi:[1,0,1]
	v_pk_fma_f32 v[62:63], v[48:49], v[50:51], v[62:63] op_sel:[0,1,0] op_sel_hi:[1,1,1]
	v_pk_fma_f32 v[62:63], v[102:103], v[54:55], v[62:63] op_sel_hi:[1,0,1]
	v_pk_fma_f32 v[62:63], v[104:105], v[54:55], v[62:63] op_sel:[0,1,0] op_sel_hi:[1,1,1]
	v_pk_fma_f32 v[62:63], v[242:243], v[58:59], v[62:63] op_sel_hi:[1,0,1]
	v_pk_fma_f32 v[62:63], v[244:245], v[58:59], v[62:63] op_sel:[0,1,0] op_sel_hi:[1,1,1]
	s_nop 1
	v_add_f32_dpp v62, v62, v62 quad_perm:[1,0,3,2] row_mask:0xf bank_mask:0xf bound_ctrl:1
	v_add_f32_dpp v63, v63, v63 quad_perm:[1,0,3,2] row_mask:0xf bank_mask:0xf bound_ctrl:1
	s_nop 0
	v_add_f32_dpp v62, v62, v62 quad_perm:[2,3,0,1] row_mask:0xf bank_mask:0xf bound_ctrl:1
	v_add_f32_dpp v63, v63, v63 quad_perm:[2,3,0,1] row_mask:0xf bank_mask:0xf bound_ctrl:1
	v_fma_f32 v63, -v243, v62, v63
	v_pk_fma_f32 v[58:59], v[62:63], v[120:121], v[58:59] op_sel_hi:[1,0,1]
	s_branch .Lfs_outsel
; #define LAS __attribute__((address_space(3)))
;     ...
; #pragma unroll
;         for (int ip = 0; ip < 32; ++ip) {
;             const int i0 = 2 * ip;
;             f32x4 rv[32];
; #pragma unroll
;             for (int jp = 0; jp <= ip; ++jp) rv[jp] = *(const LAS f32x4*)(Ad + ip * 136 + 4 * jp);
;             asm volatile("" : "+v"(lane_o) :: "memory");
;             f32x2_ a0 = {0.f, 0.f}, a1 = {0.f, 0.f}, a2 = {0.f, 0.f}, a3 = {0.f, 0.f};
; #pragma unroll
;             for (int jp = 0; jp < ip; ++jp) {
;                 const f32x2_ ta = {tr[2 * jp], tr[2 * jp]}, tb = {tr[2 * jp + 1], tr[2 * jp + 1]};
;                 const f32x2_ va = {rv[jp][0], rv[jp][1]}, vb = {rv[jp][2], rv[jp][3]};
;                 if (jp & 1) { a2 += va * ta; a3 += vb * tb; } else { a0 += va * ta; a1 += vb * tb; }
;             }
;             const f32x2_ sum = (a0 + a1) + (a2 + a3);
;             const float t0 = (lane_o == i0 ? 1.f : 0.f) - sum[0];
;             tr[i0] = t0;
;             tr[i0 + 1] = (lane_o == i0 + 1 ? 1.f : 0.f) - sum[1] - rv[ip][1] * t0;
;         }
.Lfs_ent3:
	ds_read_b128 v[94:97], v14 offset:13440
	ds_read_b128 v[102:105], v14 offset:13984
	s_waitcnt lgkmcnt(1)
	v_pk_fma_f32 v[62:63], v[94:95], v[54:55], 0 op_sel_hi:[1,0,0]
	v_pk_fma_f32 v[62:63], v[96:97], v[54:55], v[62:63] op_sel:[0,1,0] op_sel_hi:[1,1,1]
	s_nop 1
	v_add_f32_dpp v62, v62, v62 quad_perm:[1,0,3,2] row_mask:0xf bank_mask:0xf bound_ctrl:1
	v_add_f32_dpp v63, v63, v63 quad_perm:[1,0,3,2] row_mask:0xf bank_mask:0xf bound_ctrl:1
	s_nop 0
	v_add_f32_dpp v62, v62, v62 quad_perm:[2,3,0,1] row_mask:0xf bank_mask:0xf bound_ctrl:1
	v_add_f32_dpp v63, v63, v63 quad_perm:[2,3,0,1] row_mask:0xf bank_mask:0xf bound_ctrl:1
	v_fma_f32 v63, -v95, v62, v63
	v_pk_fma_f32 v[54:55], v[62:63], v[68:69], v[54:55] op_sel_hi:[1,0,1]
	ds_read_b128 v[94:97], v14 offset:14528
	s_waitcnt lgkmcnt(1)
	v_pk_fma_f32 v[62:63], v[102:103], v[54:55], 0 op_sel_hi:[1,0,0]
	v_pk_fma_f32 v[62:63], v[104:105], v[54:55], v[62:63] op_sel:[0,1,0] op_sel_hi:[1,1,1]
	s_nop 1
	v_add_f32_dpp v62, v62, v62 quad_perm:[1,0,3,2] row_mask:0xf bank_mask:0xf bound_ctrl:1
	v_add_f32_dpp v63, v63, v63 quad_perm:[1,0,3,2] row_mask:0xf bank_mask:0xf bound_ctrl:1
	s_nop 0
	v_add_f32_dpp v62, v62, v62 quad_perm:[2,3,0,1] row_mask:0xf bank_mask:0xf bound_ctrl:1
	v_add_f32_dpp v63, v63, v63 quad_perm:[2,3,0,1] row_mask:0xf bank_mask:0xf bound_ctrl:1
	v_fma_f32 v63, -v103, v62, v63
	v_pk_fma_f32 v[54:55], v[62:63], v[112:113], v[54:55] op_sel_hi:[1,0,1]
	ds_read_b128 v[102:105], v14 offset:15072
	s_waitcnt lgkmcnt(1)
	v_pk_fma_f32 v[62:63], v[94:95], v[54:55], 0 op_sel_hi:[1,0,0]
	v_pk_fma_f32 v[62:63], v[96:97], v[54:55], v[62:63] op_sel:[0,1,0] op_sel_hi:[1,1,1]
	s_nop 1
	v_add_f32_dpp v62, v62, v62 quad_perm:[1,0,3,2] row_mask:0xf bank_mask:0xf bound_ctrl:1
	v_add_f32_dpp v63, v63, v63 quad_perm:[1,0,3,2] row_mask:0xf bank_mask:0xf bound_ctrl:1
	s_nop 0
	v_add_f32_dpp v62, v62, v62 quad_perm:[2,3,0,1] row_mask:0xf bank_mask:0xf bound_ctrl:1
	v_add_f32_dpp v63, v63, v63 quad_perm:[2,3,0,1] row_mask:0xf bank_mask:0xf bound_ctrl:1
	v_fma_f32 v63, -v95, v62, v63
	v_pk_fma_f32 v[54:55], v[62:63], v[116:117], v[54:55] op_sel_hi:[1,0,1]
	ds_read_b128 v[94:97], v14 offset:15616
	ds_read_b128 v[98:101], v14 offset:15680
	s_waitcnt lgkmcnt(2)
	v_pk_fma_f32 v[62:63], v[102:103], v[54:55], 0 op_sel_hi:[1,0,0]
	v_pk_fma_f32 v[62:63], v[104:105], v[54:55], v[62:63] op_sel:[0,1,0] op_sel_hi:[1,1,1]
	s_nop 1
	v_add_f32_dpp v62, v62, v62 quad_perm:[1,0,3,2] row_mask:0xf bank_mask:0xf bound_ctrl:1
	v_add_f32_dpp v63, v63, v63 quad_perm:[1,0,3,2] row_mask:0xf bank_mask:0xf bound_ctrl:1
	s_nop 0
	v_add_f32_dpp v62, v62, v62 quad_perm:[2,3,0,1] row_mask:0xf bank_mask:0xf bound_ctrl:1
	v_add_f32_dpp v63, v63, v63 quad_perm:[2,3,0,1] row_mask:0xf bank_mask:0xf bound_ctrl:1
	v_fma_f32 v63, -v103, v62, v63
	v_pk_fma_f32 v[54:55], v[62:63], v[120:121], v[54:55] op_sel_hi:[1,0,1]
	ds_read_b128 v[102:105], v14 offset:16160
	ds_read_b128 v[242:245], v14 offset:16224
	s_waitcnt lgkmcnt(2)
	v_pk_fma_f32 v[62:63], v[98:99], v[58:59], 0 op_sel_hi:[1,0,0]
	v_pk_fma_f32 v[62:63], v[100:101], v[58:59], v[62:63] op_sel:[0,1,0] op_sel_hi:[1,1,1]
	v_pk_fma_f32 v[62:63], v[94:95], v[54:55], v[62:63] op_sel_hi:[1,0,1]
	v_pk_fma_f32 v[62:63], v[96:97], v[54:55], v[62:63] op_sel:[0,1,0] op_sel_hi:[1,1,1]
	s_nop 1
	v_add_f32_dpp v62, v62, v62 quad_perm:[1,0,3,2] row_mask:0xf bank_mask:0xf bound_ctrl:1
	v_add_f32_dpp v63, v63, v63 quad_perm:[1,0,3,2] row_mask:0xf bank_mask:0xf bound_ctrl:1
	s_nop 0
	v_add_f32_dpp v62, v62, v62 quad_perm:[2,3,0,1] row_mask:0xf bank_mask:0xf bound_ctrl:1
	v_add_f32_dpp v63, v63, v63 quad_perm:[2,3,0,1] row_mask:0xf bank_mask:0xf bound_ctrl:1
	v_fma_f32 v63, -v99, v62, v63
	v_pk_fma_f32 v[58:59], v[62:63], v[68:69], v[58:59] op_sel_hi:[1,0,1]
	ds_read_b128 v[94:97], v14 offset:16704
	ds_read_b128 v[98:101], v14 offset:16768
	s_waitcnt lgkmcnt(2)
	v_pk_fma_f32 v[62:63], v[102:103], v[54:55], 0 op_sel_hi:[1,0,0]
	v_pk_fma_f32 v[62:63], v[104:105], v[54:55], v[62:63] op_sel:[0,1,0] op_sel_hi:[1,1,1]
	v_pk_fma_f32 v[62:63], v[242:243], v[58:59], v[62:63] op_sel_hi:[1,0,1]
	v_pk_fma_f32 v[62:63], v[244:245], v[58:59], v[62:63] op_sel:[0,1,0] op_sel_hi:[1,1,1]
	s_nop 1
	v_add_f32_dpp v62, v62, v62 quad_perm:[1,0,3,2] row_mask:0xf bank_mask:0xf bound_ctrl:1
	v_add_f32_dpp v63, v63, v63 quad_perm:[1,0,3,2] row_mask:0xf bank_mask:0xf bound_ctrl:1
	s_nop 0
	v_add_f32_dpp v62, v62, v62 quad_perm:[2,3,0,1] row_mask:0xf bank_mask:0xf bound_ctrl:1
	v_add_f32_dpp v63, v63, v63 quad_perm:[2,3,0,1] row_mask:0xf bank_mask:0xf bound_ctrl:1
	v_fma_f32 v63, -v243, v62, v63
	v_pk_fma_f32 v[58:59], v[62:63], v[112:113], v[58:59] op_sel_hi:[1,0,1]
	ds_read_b128 v[102:105], v14 offset:17248
	ds_read_b128 v[242:245], v14 offset:17312
	s_waitcnt lgkmcnt(2)
	v_pk_fma_f32 v[62:63], v[94:95], v[54:55], 0 op_sel_hi:[1,0,0]
	v_pk_fma_f32 v[62:63], v[96:97], v[54:55], v[62:63] op_sel:[0,1,0] op_sel_hi:[1,1,1]
	v_pk_fma_f32 v[62:63], v[98:99], v[58:59], v[62:63] op_sel_hi:[1,0,1]
	v_pk_fma_f32 v[62:63], v[100:101], v[58:59], v[62:63] op_sel:[0,1,0] op_sel_hi:[1,1,1]
	s_nop 1
	v_add_f32_dpp v62, v62, v62 quad_perm:[1,0,3,2] row_mask:0xf bank_mask:0xf bound_ctrl:1
	v_add_f32_dpp v63, v63, v63 quad_perm:[1,0,3,2] row_mask:0xf bank_mask:0xf bound_ctrl:1
	s_nop 0
	v_add_f32_dpp v62, v62, v62 quad_perm:[2,3,0,1] row_mask:0xf bank_mask:0xf bound_ctrl:1
	v_add_f32_dpp v63, v63, v63 quad_perm:[2,3,0,1] row_mask:0xf bank_mask:0xf bound_ctrl:1
	v_fma_f32 v63, -v99, v62, v63
	v_pk_fma_f32 v[58:59], v[62:63], v[116:117], v[58:59] op_sel_hi:[1,0,1]
	s_waitcnt lgkmcnt(0)
	v_pk_fma_f32 v[62:63], v[102:103], v[54:55], 0 op_sel_hi:[1,0,0]
	v_pk_fma_f32 v[62:63], v[104:105], v[54:55], v[62:63] op_sel:[0,1,0] op_sel_hi:[1,1,1]
	v_pk_fma_f32 v[62:63], v[242:243], v[58:59], v[62:63] op_sel_hi:[1,0,1]
	v_pk_fma_f32 v[62:63], v[244:245], v[58:59], v[62:63] op_sel:[0,1,0] op_sel_hi:[1,1,1]
	s_nop 1
	v_add_f32_dpp v62, v62, v62 quad_perm:[1,0,3,2] row_mask:0xf bank_mask:0xf bound_ctrl:1
	v_add_f32_dpp v63, v63, v63 quad_perm:[1,0,3,2] row_mask:0xf bank_mask:0xf bound_ctrl:1
	s_nop 0
	v_add_f32_dpp v62, v62, v62 quad_perm:[2,3,0,1] row_mask:0xf bank_mask:0xf bound_ctrl:1
	v_add_f32_dpp v63, v63, v63 quad_perm:[2,3,0,1] row_mask:0xf bank_mask:0xf bound_ctrl:1
	v_fma_f32 v63, -v243, v62, v63
	v_pk_fma_f32 v[58:59], v[62:63], v[120:121], v[58:59] op_sel_hi:[1,0,1]

; #define LAS __attribute__((address_space(3)))
; __device__ __forceinline__ float fexp(float x) { return __builtin_amdgcn_exp2f(x * 1.4426950408889634f); }
; __device__ __forceinline__ v2u pack4(const f32x4 v) { v2u r; r.x = pk2(v[0], v[1]); r.y = pk2(v[2], v[3]); return r; }
; __device__ __forceinline__ f32x4 unpack4(const v2u w) { f32x4 r; r[0] = bflo(w.x); r[1] = bfhi(w.x); r[2] = bflo(w.y); r[3] = bfhi(w.y); return r; }
;     ...
;             for (int k8 = 0; k8 < 8; ++k8) { const int tt = (w & 1) * 8 + k8, mt = tt >> 2, nt = tt & 3;
;                 f32x4 acc = {0.f, 0.f, 0.f, 0.f}; acc = mma_ll<2>(Aop + mt * 16 * 72, 72, Bop + nt * 16 * 72, 72, acc, lane);
;                 const int n = nt * 16 + lr, m0 = mt * 16 + 4 * lq;
;                 if (prod == 2) { const f32x4 qv = unpack4(*(const LAS v2u*)(Qs + n * 72 + m0)); const float e = 0.125f * fexp(gcS[d * 64 + n]); acc = qv * e - acc; }
;                 if (prod == 0) acc = -acc;
;                 res[k8] = pack4(acc); }
.L5b_join:
.LBB0_662:
	s_nop 2
	s_and_b64 s[44:45], s[40:41], exec
	s_cselect_b32 s44, 0x80008000, 0
	v_cvt_pk_bf16_f32 v10, v36, v37
	v_cvt_pk_bf16_f32 v11, v38, v39
	v_cvt_pk_bf16_f32 v19, v18, v19
	v_cvt_pk_bf16_f32 v18, v16, v17
	v_cvt_pk_bf16_f32 v16, v24, v25
	v_cvt_pk_bf16_f32 v17, v26, v27
	v_cvt_pk_bf16_f32 v23, v22, v23
	v_cvt_pk_bf16_f32 v22, v20, v21
	v_cvt_pk_bf16_f32 v20, v12, v13
	v_cvt_pk_bf16_f32 v21, v14, v15
	v_cvt_pk_bf16_f32 v12, v28, v29
	v_cvt_pk_bf16_f32 v13, v30, v31
	v_cvt_pk_bf16_f32 v6, v6, v7
	v_cvt_pk_bf16_f32 v7, v8, v9
	v_cvt_pk_bf16_f32 v5, v4, v5
	v_cvt_pk_bf16_f32 v4, v2, v3
	v_xor_b32_e32 v10, s44, v10
	v_xor_b32_e32 v11, s44, v11
	v_xor_b32_e32 v19, s44, v19
	v_xor_b32_e32 v18, s44, v18
	v_xor_b32_e32 v16, s44, v16
	v_xor_b32_e32 v17, s44, v17
	v_xor_b32_e32 v23, s44, v23
	v_xor_b32_e32 v22, s44, v22
	v_xor_b32_e32 v20, s44, v20
	v_xor_b32_e32 v21, s44, v21
	v_xor_b32_e32 v12, s44, v12
	v_xor_b32_e32 v13, s44, v13
	v_xor_b32_e32 v6, s44, v6
	v_xor_b32_e32 v7, s44, v7
	v_xor_b32_e32 v5, s44, v5
	v_xor_b32_e32 v4, s44, v4
	s_and_saveexec_b64 s[12:13], s[38:39]
	s_xor_b64 s[12:13], exec, s[12:13]
	s_cbranch_execz .LBB0_664
	s_waitcnt vmcnt(0)
	v_mov_b32_e32 v2, v220
	v_mov_b32_e32 v3, v221
